# GEMM K-loops: LDS-DMA stage loads use SGPR-base + 32-bit lane offset addressing (216 sites), dropping the per-piece 64-bit v_lshl_add_u64
# speedup vs baseline: 1.0061x; 1.0061x over previous
; #define PG8_STAGE(bufoff, gbase, voff) do { _Pragma("unroll") for (int _i = 0; _i < 2; ++_i) \
;         __builtin_amdgcn_global_load_lds((const unsigned*)((const char*)(gbase) + (voff)[_i]), (LAS unsigned*)(lds + (bufoff) + ldsw + _i * 8192), 16, 0, 0); } while (0)
; #define PG8_WAIT_V(n) asm volatile("s_waitcnt vmcnt(" #n ")" ::: "memory")
; #define PG8_BAR __builtin_amdgcn_s_barrier()
; template <class Epi>
; __device__ __forceinline__ void gemm_phase(LAS unsigned char* lds, const Gemm g, const StaticOrder& S, const Epi& E) {
;     const int tid = threadIdx.x, wid = __builtin_amdgcn_readfirstlane(tid >> 6), lane = tid & 63, wr = wid >> 2, wc = wid & 3, fr = lane & 15, fq = lane >> 4;
;     const int K = g.K, nt = K / BK;
;     unsigned voffA[2], voffB[2];
; #pragma unroll
;     for (int i = 0; i < 2; ++i) { int R, C; stage_rc(tid * 16 + i * 8192, R, C); const int Rb = (R & ~31) + perm32(R & 31);
;         voffA[i] = (unsigned)(R * g.lda + C) * 2u; voffB[i] = (unsigned)(Rb * g.ldb + C) * 2u; }
;     const size_t kstep = (size_t)(BK * 2);
;     const size_t hstepA = (size_t)HALF * g.lda * 2, hstepB = (size_t)HALF * g.ldb * 2;
;     const size_t tstepA = 2 * hstepA, tstepB = 2 * hstepB;
;     const unsigned ldsw = (unsigned)wid * 1024u;
;     const int aoff = lds_byte(wr * 64 + fr, fq * 8), boff = lds_byte(wc * 32 + fr, fq * 8);
;     ...
;     PG8_STAGE(PG8_SB(0, 0), cB, voffB); PG8_STAGE(PG8_SB(0, 1), cB + hstepB, voffB); PG8_STAGE(PG8_SA(0, 0), cA, voffA); PG8_STAGE(PG8_SA(0, 1), cA + hstepA, voffA);
;     if (wr == 1) PG8_BAR;
;     PG8_WAIT_V(2); PG8_BAR;
;     PG8_STAGE(PG8_SB(1, 0), cB + kstep, voffB); PG8_STAGE(PG8_SA(1, 0), cA + kstep, voffA); PG8_STAGE(PG8_SB(1, 1), cB + hstepB + kstep, voffB);
;     PG8_WAIT_V(6); PG8_BAR;
.LBB0_186:
	s_lshl_b32 s41, s4, 6
	s_lshl_b32 s7, s4, 13
	s_lshl_b32 s4, s5, 5
	s_mov_b64 s[12:13], 0x80
	s_and_b32 s43, s4, 0x60
	s_add_i32 m0, s19, 0x18000
	v_lshl_add_u64 v[6:7], v[6:7], 0, s[12:13]
	s_lshl_b32 s15, s43, 7
	s_waitcnt vmcnt(2)
	s_barrier
	global_load_lds_dwordx4 v[6:7], off
	v_lshl_add_u64 v[4:5], v[4:5], 0, s[12:13]
	s_add_i32 m0, s19, 0x1a000
	s_add_i32 s57, s19, 0x8000
	s_add_i32 s80, s19, 0xa000
	global_load_lds_dwordx4 v[4:5], off
	v_lshl_add_u64 v[0:1], v[0:1], 0, s[12:13]
	s_mov_b32 m0, s57
	s_add_u32 s4, s76, 0x40080
	global_load_lds_dwordx4 v[0:1], off
	v_lshl_add_u64 v[0:1], v[2:3], 0, s[12:13]
	s_mov_b32 m0, s80
	s_addc_u32 s5, s77, 0
	global_load_lds_dwordx4 v[0:1], off
	s_add_i32 m0, s19, 0x1c000
	global_load_lds_dwordx4 v130, s[4:5]
	s_add_i32 m0, s19, 0x1e000
	v_bfe_u32 v151, v176, 4, 2
	global_load_lds_dwordx4 v134, s[4:5]
	v_and_b32_e32 v150, 15, v176
	v_lshlrev_b32_e32 v0, 4, v151
	v_lshlrev_b32_e32 v2, 2, v176
	v_lshlrev_b32_e32 v3, 6, v176
	s_movk_i32 s4, 0x3c0
	v_lshl_or_b32 v1, v150, 6, v0
	v_and_b32_e32 v2, 32, v2
	v_and_or_b32 v0, v3, s4, v0
	v_bitop3_b32 v152, s15, v0, v2 bitop3:0xf6
	v_lshlrev_b32_e32 v0, 8, v176
	v_bitop3_b32 v1, v1, s7, v2 bitop3:0xde
	v_and_b32_e32 v0, 0x38000, v0
	v_lshlrev_b32_e32 v2, 11, v10
	v_or3_b32 v0, v8, v0, v2
	v_add_u32_e32 v136, v0, v9
	v_lshlrev_b32_e32 v0, 4, v11
	s_waitcnt vmcnt(6)
	s_cmpk_lt_u32 s14, 0x100
	v_readlane_b32 s68, v254, 6
	v_and_b32_e32 v0, 0x78000, v0
	s_cselect_b64 s[14:15], -1, 0
	v_readlane_b32 s70, v254, 8
	v_or3_b32 v0, v8, v0, v2
	s_add_i32 s84, 0, 0x10000
	s_add_i32 s85, 0, 0x14000
	s_ashr_i32 s81, s70, 31
	s_mov_b32 s82, s70
	s_ashr_i32 s83, s2, 31
	v_mov_b32_e32 v137, v131
	v_add_u32_e32 v138, v0, v9
	v_mov_b32_e32 v139, v131
	v_mov_b64_e32 v[140:141], 0x500
	v_mov_b64_e32 v[142:143], 0x4ff
	v_add_u32_e32 v153, s84, v152
	v_add_u32_e32 v154, s85, v152
	v_add_u32_e32 v155, 0, v1
	v_mov_b32_e32 v156, 0x358637bd
	s_mov_b32 s18, 0x3e6d3388
	s_mov_b32 s22, 0x3f07dc22
	s_mov_b32 s34, 0xbf3a00e3
	s_mov_b32 s38, 0x3f35f0e3
	s_mov_b32 s40, 0xbe11a98e
	s_mov_b32 s42, 0x3e027906
	s_mov_b32 s56, 0xbf38aa3b
	s_movk_i32 s86, 0x1400
	s_barrier
	v_readlane_b32 s69, v254, 7
	v_readlane_b32 s71, v254, 9
	s_branch .LBB0_189

; #define PG8_STAGE(bufoff, gbase, voff) do { _Pragma("unroll") for (int _i = 0; _i < 2; ++_i) \
;         __builtin_amdgcn_global_load_lds((const unsigned*)((const char*)(gbase) + (voff)[_i]), (LAS unsigned*)(lds + (bufoff) + ldsw + _i * 8192), 16, 0, 0); } while (0)
; #define PG8_LDA(dst, b, h) do { _Pragma("unroll") for (int m = 0; m < 4; ++m) _Pragma("unroll") for (int k = 0; k < 2; ++k) dst[m][k] = *(const LAS bf16x8*)(lds + PG8_SA(b, h) + aoff + m * 2048 + k * 1024); } while (0)
; #define PG8_LDB(dst, b, h) do { _Pragma("unroll") for (int n = 0; n < 2; ++n) _Pragma("unroll") for (int k = 0; k < 2; ++k) dst[n][k] = *(const LAS bf16x8*)(lds + PG8_SB(b, h) + boff + n * 2048 + k * 1024); } while (0)
; #define PG8_MMA(ai, bj, At, Bt) do { __builtin_amdgcn_s_setprio(1); _Pragma("unroll") for (int m = 0; m < 4; ++m) _Pragma("unroll") for (int n = 0; n < 2; ++n) _Pragma("unroll") for (int k = 0; k < 2; ++k) \
;         acc[ai][bj][m][n] = __builtin_amdgcn_mfma_f32_16x16x32_bf16(Bt[n][k], At[m][k], acc[ai][bj][m][n], 0, 0, 0); __builtin_amdgcn_s_setprio(0); } while (0)
; #define PG8_BAR __builtin_amdgcn_s_barrier()
; template <class Epi>
; __device__ __forceinline__ void gemm_phase(LAS unsigned char* lds, const Gemm g, const StaticOrder& S, const Epi& E) {
;     ...
;         const bool has_next = S.next(ui + 1, nxt);
;         const char* nA = has_next ? (const char*)g.A + (size_t)nxt.pm * tstepA : cA; const char* nB = has_next ? (const char*)g.Bt + (size_t)nxt.pn * tstepB : cB;
; #pragma nounroll
;         for (int t = 0; t < nt; t += 2) {
;             const bool last = (t == nt - 2);
;             const char* a1 = cA + (size_t)(t + 1) * kstep;
;             const char* a2 = last ? nA : cA + (size_t)(t + 2) * kstep; const char* b2 = last ? nB : cB + (size_t)(t + 2) * kstep;
;             const char* a3 = a2 + kstep; const char* b3 = b2 + kstep;
;             PG8_LDB(B0, 0, 0); PG8_LDB(B1, 0, 1); PG8_SCHED; PG8_LDA(At, 0, 0); PG8_STAGE(PG8_SA(1, 1), a1 + hstepA, voffA);
;             PG8_WAIT_V(8); PG8_WAIT_L(0); PG8_BAR; PG8_MMA(0, 0, At, B0); PG8_MMA(0, 1, At, B1); PG8_BAR; PG8_SCHED;
;             PG8_LDA(At, 0, 1); PG8_STAGE(PG8_SB(0, 0), b2, voffB); PG8_STAGE(PG8_SB(0, 1), b2 + hstepB, voffB); PG8_STAGE(PG8_SA(0, 0), a2, voffA);
;             PG8_WAIT_V(8); PG8_WAIT_L(0); PG8_BAR; PG8_MMA(1, 0, At, B0); PG8_MMA(1, 1, At, B1); PG8_BAR; PG8_SCHED;
.LBB0_191:
	s_ashr_i32 s65, s64, 31
	s_lshl_b64 s[68:69], s[64:65], 19
	s_add_u32 s68, s24, s68
	s_addc_u32 s69, s25, s69
	s_and_b64 s[70:71], s[4:5], exec
	s_cselect_b32 s7, s69, s75
	s_cselect_b32 s65, s68, s74
	s_ashr_i32 s63, s62, 31
	s_lshl_b64 s[70:71], s[62:63], 19
	s_add_u32 s70, s10, s70
	s_addc_u32 s71, s11, s71
	s_and_b64 s[78:79], s[4:5], exec
	s_cselect_b32 s63, s71, s77
	s_cselect_b32 s73, s70, s76
	s_add_u32 s74, s74, 0x40080
	s_addc_u32 s75, s75, 0
	s_add_u32 s87, s76, 0x100
	s_addc_u32 s88, s77, 0
	s_mov_b32 s89, -2
	v_lshl_add_u32 v248, s72, 8, v150
	v_add_u32_e32 v248, s41, v248
	v_ashrrev_i32_e32 v249, 31, v248
	v_lshl_add_u64 v[248:249], v[248:249], 2, s[50:51]
	global_load_dword v240, v[248:249], off
	global_load_dword v241, v[248:249], off offset:64
	global_load_dword v242, v[248:249], off offset:128
	global_load_dword v243, v[248:249], off offset:192
	global_load_dword v244, v[248:249], off offset:512
	global_load_dword v245, v[248:249], off offset:576
	global_load_dword v246, v[248:249], off offset:640
	global_load_dword v247, v[248:249], off offset:704
	ds_read_b128 v[144:147], v153
	ds_read_b128 v[158:161], v153 offset:1024
	ds_read_b128 v[162:165], v153 offset:2048
	ds_read_b128 v[166:169], v153 offset:3072
	ds_read_b128 v[170:173], v154
	ds_read_b128 v[178:181], v154 offset:1024
	ds_read_b128 v[182:185], v154 offset:2048
	ds_read_b128 v[186:189], v154 offset:3072
	s_add_u32 s76, s74, 0xfffc0080
	s_addc_u32 s77, s75, -1
	s_cmp_eq_u32 s89, 12
	s_cselect_b32 s79, s7, s77
	s_cselect_b32 s78, s65, s76
	s_cselect_b32 s77, s63, s88
	s_cselect_b32 s76, s73, s87
	s_add_i32 m0, s19, 0xc000
	ds_read_b128 v[190:193], v155
	ds_read_b128 v[194:197], v155 offset:1024
	ds_read_b128 v[198:201], v155 offset:2048
	ds_read_b128 v[202:205], v155 offset:3072
	ds_read_b128 v[206:209], v155 offset:4096
	ds_read_b128 v[210:213], v155 offset:5120
	ds_read_b128 v[214:217], v155 offset:6144
	ds_read_b128 v[218:221], v155 offset:7168
	global_load_lds_dwordx4 v136, s[74:75]
	s_add_i32 m0, s19, 0xe000
	s_nop 0
	global_load_lds_dwordx4 v138, s[74:75]
	s_waitcnt vmcnt(8)
	s_waitcnt lgkmcnt(0)
	s_barrier
	s_setprio 1
	s_waitcnt lgkmcnt(0)
	v_mfma_f32_16x16x32_bf16 v[124:127], v[144:147], v[190:193], 0
	v_mfma_f32_16x16x32_bf16 v[120:123], v[162:165], v[190:193], 0
	v_mfma_f32_16x16x32_bf16 v[108:111], v[144:147], v[198:201], 0
	v_mfma_f32_16x16x32_bf16 v[104:107], v[162:165], v[198:201], 0
	v_mfma_f32_16x16x32_bf16 v[92:95], v[144:147], v[206:209], 0
	v_mfma_f32_16x16x32_bf16 v[88:91], v[162:165], v[206:209], 0
	v_mfma_f32_16x16x32_bf16 v[76:79], v[144:147], v[214:217], 0
	v_mfma_f32_16x16x32_bf16 v[72:75], v[162:165], v[214:217], 0
	v_mfma_f32_16x16x32_bf16 v[124:127], v[158:161], v[194:197], v[124:127]
	v_mfma_f32_16x16x32_bf16 v[120:123], v[166:169], v[194:197], v[120:123]
	v_mfma_f32_16x16x32_bf16 v[108:111], v[158:161], v[202:205], v[108:111]
	v_mfma_f32_16x16x32_bf16 v[104:107], v[166:169], v[202:205], v[104:107]
	v_mfma_f32_16x16x32_bf16 v[92:95], v[158:161], v[210:213], v[92:95]
	v_mfma_f32_16x16x32_bf16 v[88:91], v[166:169], v[210:213], v[88:91]
	v_mfma_f32_16x16x32_bf16 v[76:79], v[158:161], v[218:221], v[76:79]
	v_mfma_f32_16x16x32_bf16 v[72:75], v[166:169], v[218:221], v[72:75]
	s_setprio 0
	s_setprio 1
	v_mfma_f32_16x16x32_bf16 v[116:119], v[170:173], v[190:193], 0
	v_mfma_f32_16x16x32_bf16 v[112:115], v[182:185], v[190:193], 0
	v_mfma_f32_16x16x32_bf16 v[100:103], v[170:173], v[198:201], 0
	v_mfma_f32_16x16x32_bf16 v[96:99], v[182:185], v[198:201], 0
	v_mfma_f32_16x16x32_bf16 v[84:87], v[170:173], v[206:209], 0
	v_mfma_f32_16x16x32_bf16 v[80:83], v[182:185], v[206:209], 0
	v_mfma_f32_16x16x32_bf16 v[68:71], v[170:173], v[214:217], 0
	v_mfma_f32_16x16x32_bf16 v[64:67], v[182:185], v[214:217], 0
	v_mfma_f32_16x16x32_bf16 v[116:119], v[178:181], v[194:197], v[116:119]
	v_mfma_f32_16x16x32_bf16 v[112:115], v[186:189], v[194:197], v[112:115]
	v_mfma_f32_16x16x32_bf16 v[100:103], v[178:181], v[202:205], v[100:103]
	v_mfma_f32_16x16x32_bf16 v[96:99], v[186:189], v[202:205], v[96:99]
	v_mfma_f32_16x16x32_bf16 v[84:87], v[178:181], v[210:213], v[84:87]
	v_mfma_f32_16x16x32_bf16 v[80:83], v[186:189], v[210:213], v[80:83]
	v_mfma_f32_16x16x32_bf16 v[68:71], v[178:181], v[218:221], v[68:71]
	v_mfma_f32_16x16x32_bf16 v[64:67], v[186:189], v[218:221], v[64:67]
	s_setprio 0
	s_barrier
	s_add_i32 s90, s84, s3
	v_lshl_add_u64 v[148:149], s[76:77], 0, v[130:131]
	s_mov_b32 m0, s90
	ds_read_b128 v[190:193], v155 offset:16384
	ds_read_b128 v[194:197], v155 offset:17408
	ds_read_b128 v[198:201], v155 offset:18432
	ds_read_b128 v[202:205], v155 offset:19456
	ds_read_b128 v[206:209], v155 offset:20480
	ds_read_b128 v[210:213], v155 offset:21504
	ds_read_b128 v[214:217], v155 offset:22528
	ds_read_b128 v[218:221], v155 offset:23552
	global_load_lds_dwordx4 v[148:149], off
	s_add_i32 m0, s90, 0x2000
	s_add_u32 s90, s76, 0x40000
	v_lshl_add_u64 v[174:175], s[76:77], 0, v[134:135]
	s_addc_u32 s91, s77, 0
	s_add_i32 s92, s85, s3
	global_load_lds_dwordx4 v[174:175], off
	s_mov_b32 m0, s92
	v_lshl_add_u64 v[226:227], s[78:79], 0, v[132:133]
	global_load_lds_dwordx4 v130, s[90:91]
	s_add_i32 m0, s92, 0x2000
	s_nop 0
	global_load_lds_dwordx4 v134, s[90:91]
	v_lshl_add_u64 v[222:223], s[78:79], 0, v[128:129]
	s_mov_b32 m0, s19
	s_nop 0
	global_load_lds_dwordx4 v[222:223], off
	s_mov_b32 m0, s23
	s_nop 0
	global_load_lds_dwordx4 v[226:227], off
	s_waitcnt vmcnt(8)
	s_waitcnt lgkmcnt(0)
	s_barrier
; #define PG8_STAGE(bufoff, gbase, voff) do { _Pragma("unroll") for (int _i = 0; _i < 2; ++_i) \
;         __builtin_amdgcn_global_load_lds((const unsigned*)((const char*)(gbase) + (voff)[_i]), (LAS unsigned*)(lds + (bufoff) + ldsw + _i * 8192), 16, 0, 0); } while (0)
; #define PG8_LDA(dst, b, h) do { _Pragma("unroll") for (int m = 0; m < 4; ++m) _Pragma("unroll") for (int k = 0; k < 2; ++k) dst[m][k] = *(const LAS bf16x8*)(lds + PG8_SA(b, h) + aoff + m * 2048 + k * 1024); } while (0)
; #define PG8_LDB(dst, b, h) do { _Pragma("unroll") for (int n = 0; n < 2; ++n) _Pragma("unroll") for (int k = 0; k < 2; ++k) dst[n][k] = *(const LAS bf16x8*)(lds + PG8_SB(b, h) + boff + n * 2048 + k * 1024); } while (0)
; #define PG8_MMA(ai, bj, At, Bt) do { __builtin_amdgcn_s_setprio(1); _Pragma("unroll") for (int m = 0; m < 4; ++m) _Pragma("unroll") for (int n = 0; n < 2; ++n) _Pragma("unroll") for (int k = 0; k < 2; ++k) \
;         acc[ai][bj][m][n] = __builtin_amdgcn_mfma_f32_16x16x32_bf16(Bt[n][k], At[m][k], acc[ai][bj][m][n], 0, 0, 0); __builtin_amdgcn_s_setprio(0); } while (0)
; #define PG8_WAIT_V(n) asm volatile("s_waitcnt vmcnt(" #n ")" ::: "memory")
; #define PG8_WAIT_L(n) asm volatile("s_waitcnt lgkmcnt(" #n ")" ::: "memory")
; #define PG8_BAR __builtin_amdgcn_s_barrier()
; #define PG8_SCHED __builtin_amdgcn_sched_barrier(0)
; template <class Epi>
; __device__ __forceinline__ void gemm_phase(LAS unsigned char* lds, const Gemm g, const StaticOrder& S, const Epi& E) {
;     ...
;             PG8_LDB(B0, 0, 0); PG8_LDB(B1, 0, 1); PG8_SCHED; PG8_LDA(At, 0, 0); PG8_STAGE(PG8_SA(1, 1), a1 + hstepA, voffA);
;             PG8_WAIT_V(8); PG8_WAIT_L(0); PG8_BAR; PG8_MMA(0, 0, At, B0); PG8_MMA(0, 1, At, B1); PG8_BAR; PG8_SCHED;
;             PG8_LDA(At, 0, 1); PG8_STAGE(PG8_SB(0, 0), b2, voffB); PG8_STAGE(PG8_SB(0, 1), b2 + hstepB, voffB); PG8_STAGE(PG8_SA(0, 0), a2, voffA);
;             PG8_WAIT_V(8); PG8_WAIT_L(0); PG8_BAR; PG8_MMA(1, 0, At, B0); PG8_MMA(1, 1, At, B1); PG8_BAR; PG8_SCHED;
;             PG8_LDB(B0, 1, 0); PG8_LDB(B1, 1, 1); PG8_SCHED; PG8_LDA(At, 1, 0); PG8_STAGE(PG8_SA(0, 1), a2 + hstepA, voffA);
;             PG8_WAIT_V(8); PG8_WAIT_L(0); PG8_BAR; PG8_MMA(0, 0, At, B0); PG8_MMA(0, 1, At, B1); PG8_BAR; PG8_SCHED;
	s_setprio 1
	s_waitcnt lgkmcnt(0)
	v_mfma_f32_16x16x32_bf16 v[60:63], v[144:147], v[190:193], 0
	v_mfma_f32_16x16x32_bf16 v[56:59], v[162:165], v[190:193], 0
	v_mfma_f32_16x16x32_bf16 v[44:47], v[144:147], v[198:201], 0
	v_mfma_f32_16x16x32_bf16 v[40:43], v[162:165], v[198:201], 0
	v_mfma_f32_16x16x32_bf16 v[28:31], v[144:147], v[206:209], 0
	v_mfma_f32_16x16x32_bf16 v[24:27], v[162:165], v[206:209], 0
	v_mfma_f32_16x16x32_bf16 v[12:15], v[144:147], v[214:217], 0
	v_mfma_f32_16x16x32_bf16 v[8:11], v[162:165], v[214:217], 0
	v_mfma_f32_16x16x32_bf16 v[60:63], v[158:161], v[194:197], v[60:63]
	v_mfma_f32_16x16x32_bf16 v[56:59], v[166:169], v[194:197], v[56:59]
	v_mfma_f32_16x16x32_bf16 v[44:47], v[158:161], v[202:205], v[44:47]
	v_mfma_f32_16x16x32_bf16 v[40:43], v[166:169], v[202:205], v[40:43]
	v_mfma_f32_16x16x32_bf16 v[28:31], v[158:161], v[210:213], v[28:31]
	v_mfma_f32_16x16x32_bf16 v[24:27], v[166:169], v[210:213], v[24:27]
	v_mfma_f32_16x16x32_bf16 v[12:15], v[158:161], v[218:221], v[12:15]
	v_mfma_f32_16x16x32_bf16 v[8:11], v[166:169], v[218:221], v[8:11]
	s_setprio 0
	s_setprio 1
	v_mfma_f32_16x16x32_bf16 v[52:55], v[170:173], v[190:193], 0
	v_mfma_f32_16x16x32_bf16 v[48:51], v[182:185], v[190:193], 0
	v_mfma_f32_16x16x32_bf16 v[36:39], v[170:173], v[198:201], 0
	v_mfma_f32_16x16x32_bf16 v[32:35], v[182:185], v[198:201], 0
	v_mfma_f32_16x16x32_bf16 v[20:23], v[170:173], v[206:209], 0
	v_mfma_f32_16x16x32_bf16 v[16:19], v[182:185], v[206:209], 0
	v_mfma_f32_16x16x32_bf16 v[4:7], v[170:173], v[214:217], 0
	v_mfma_f32_16x16x32_bf16 v[0:3], v[182:185], v[214:217], 0
	v_mfma_f32_16x16x32_bf16 v[52:55], v[178:181], v[194:197], v[52:55]
	v_mfma_f32_16x16x32_bf16 v[48:51], v[186:189], v[194:197], v[48:51]
	v_mfma_f32_16x16x32_bf16 v[36:39], v[178:181], v[202:205], v[36:39]
	v_mfma_f32_16x16x32_bf16 v[32:35], v[186:189], v[202:205], v[32:35]
	v_mfma_f32_16x16x32_bf16 v[20:23], v[178:181], v[210:213], v[20:23]
	v_mfma_f32_16x16x32_bf16 v[16:19], v[186:189], v[210:213], v[16:19]
	v_mfma_f32_16x16x32_bf16 v[4:7], v[178:181], v[218:221], v[4:7]
	v_mfma_f32_16x16x32_bf16 v[0:3], v[186:189], v[218:221], v[0:3]
	s_setprio 0
	s_barrier
	s_add_i32 s90, 0, 0x18000
	v_add_u32_e32 v157, s90, v152
	s_add_i32 s91, 0, 0x1c000
	ds_read_b128 v[144:147], v157
	ds_read_b128 v[158:161], v157 offset:1024
	ds_read_b128 v[162:165], v157 offset:2048
	ds_read_b128 v[166:169], v157 offset:3072
	v_add_u32_e32 v157, s91, v152
	ds_read_b128 v[170:173], v157
	ds_read_b128 v[178:181], v157 offset:1024
	ds_read_b128 v[182:185], v157 offset:2048
	ds_read_b128 v[186:189], v157 offset:3072
	s_add_u32 s78, s78, 0x40000
	s_addc_u32 s79, s79, 0
	s_mov_b32 m0, s33
	ds_read_b128 v[190:193], v155 offset:32768
	ds_read_b128 v[194:197], v155 offset:33792
	ds_read_b128 v[198:201], v155 offset:34816
	ds_read_b128 v[202:205], v155 offset:35840
	ds_read_b128 v[206:209], v155 offset:36864
	ds_read_b128 v[210:213], v155 offset:37888
	ds_read_b128 v[214:217], v155 offset:38912
	ds_read_b128 v[218:221], v155 offset:39936
	global_load_lds_dwordx4 v128, s[78:79]
	s_mov_b32 m0, s35
	s_nop 0
	global_load_lds_dwordx4 v132, s[78:79]
	s_waitcnt vmcnt(8)
	s_waitcnt lgkmcnt(0)
	s_barrier
	s_setprio 1
	s_waitcnt lgkmcnt(0)
	v_mfma_f32_16x16x32_bf16 v[124:127], v[144:147], v[190:193], v[124:127]
	v_mfma_f32_16x16x32_bf16 v[120:123], v[162:165], v[190:193], v[120:123]
	v_mfma_f32_16x16x32_bf16 v[108:111], v[144:147], v[198:201], v[108:111]
	v_mfma_f32_16x16x32_bf16 v[104:107], v[162:165], v[198:201], v[104:107]
	v_mfma_f32_16x16x32_bf16 v[92:95], v[144:147], v[206:209], v[92:95]
	v_mfma_f32_16x16x32_bf16 v[88:91], v[162:165], v[206:209], v[88:91]
	v_mfma_f32_16x16x32_bf16 v[76:79], v[144:147], v[214:217], v[76:79]
	v_mfma_f32_16x16x32_bf16 v[72:75], v[162:165], v[214:217], v[72:75]
	v_mfma_f32_16x16x32_bf16 v[124:127], v[158:161], v[194:197], v[124:127]
	v_mfma_f32_16x16x32_bf16 v[120:123], v[166:169], v[194:197], v[120:123]
	v_mfma_f32_16x16x32_bf16 v[108:111], v[158:161], v[202:205], v[108:111]
	v_mfma_f32_16x16x32_bf16 v[104:107], v[166:169], v[202:205], v[104:107]
	v_mfma_f32_16x16x32_bf16 v[92:95], v[158:161], v[210:213], v[92:95]
	v_mfma_f32_16x16x32_bf16 v[88:91], v[166:169], v[210:213], v[88:91]
	v_mfma_f32_16x16x32_bf16 v[76:79], v[158:161], v[218:221], v[76:79]
	v_mfma_f32_16x16x32_bf16 v[72:75], v[166:169], v[218:221], v[72:75]
	s_setprio 0
	s_setprio 1
	v_mfma_f32_16x16x32_bf16 v[116:119], v[170:173], v[190:193], v[116:119]
	v_mfma_f32_16x16x32_bf16 v[112:115], v[182:185], v[190:193], v[112:115]
	v_mfma_f32_16x16x32_bf16 v[100:103], v[170:173], v[198:201], v[100:103]
	v_mfma_f32_16x16x32_bf16 v[96:99], v[182:185], v[198:201], v[96:99]
	v_mfma_f32_16x16x32_bf16 v[84:87], v[170:173], v[206:209], v[84:87]
	v_mfma_f32_16x16x32_bf16 v[80:83], v[182:185], v[206:209], v[80:83]
	v_mfma_f32_16x16x32_bf16 v[68:71], v[170:173], v[214:217], v[68:71]
	v_mfma_f32_16x16x32_bf16 v[64:67], v[182:185], v[214:217], v[64:67]
	v_mfma_f32_16x16x32_bf16 v[116:119], v[178:181], v[194:197], v[116:119]
	v_mfma_f32_16x16x32_bf16 v[112:115], v[186:189], v[194:197], v[112:115]
	v_mfma_f32_16x16x32_bf16 v[100:103], v[178:181], v[202:205], v[100:103]
	v_mfma_f32_16x16x32_bf16 v[96:99], v[186:189], v[202:205], v[96:99]
	v_mfma_f32_16x16x32_bf16 v[84:87], v[178:181], v[210:213], v[84:87]
	v_mfma_f32_16x16x32_bf16 v[80:83], v[186:189], v[210:213], v[80:83]
	v_mfma_f32_16x16x32_bf16 v[68:71], v[178:181], v[218:221], v[68:71]
	v_mfma_f32_16x16x32_bf16 v[64:67], v[186:189], v[218:221], v[64:67]
	s_setprio 0
	s_barrier
; #define PG8_STAGE(bufoff, gbase, voff) do { _Pragma("unroll") for (int _i = 0; _i < 2; ++_i) \
;         __builtin_amdgcn_global_load_lds((const unsigned*)((const char*)(gbase) + (voff)[_i]), (LAS unsigned*)(lds + (bufoff) + ldsw + _i * 8192), 16, 0, 0); } while (0)
; #define PG8_LDA(dst, b, h) do { _Pragma("unroll") for (int m = 0; m < 4; ++m) _Pragma("unroll") for (int k = 0; k < 2; ++k) dst[m][k] = *(const LAS bf16x8*)(lds + PG8_SA(b, h) + aoff + m * 2048 + k * 1024); } while (0)
; #define PG8_LDB(dst, b, h) do { _Pragma("unroll") for (int n = 0; n < 2; ++n) _Pragma("unroll") for (int k = 0; k < 2; ++k) dst[n][k] = *(const LAS bf16x8*)(lds + PG8_SB(b, h) + boff + n * 2048 + k * 1024); } while (0)
; #define PG8_MMA(ai, bj, At, Bt) do { __builtin_amdgcn_s_setprio(1); _Pragma("unroll") for (int m = 0; m < 4; ++m) _Pragma("unroll") for (int n = 0; n < 2; ++n) _Pragma("unroll") for (int k = 0; k < 2; ++k) \
;         acc[ai][bj][m][n] = __builtin_amdgcn_mfma_f32_16x16x32_bf16(Bt[n][k], At[m][k], acc[ai][bj][m][n], 0, 0, 0); __builtin_amdgcn_s_setprio(0); } while (0)
; #define PG8_WAIT_V(n) asm volatile("s_waitcnt vmcnt(" #n ")" ::: "memory")
; #define PG8_BAR __builtin_amdgcn_s_barrier()
; template <class Epi>
; __device__ __forceinline__ void gemm_phase(LAS unsigned char* lds, const Gemm g, const StaticOrder& S, const Epi& E) {
;     ...
;             PG8_LDB(B0, 0, 0); PG8_LDB(B1, 0, 1); PG8_SCHED; PG8_LDA(At, 0, 0); PG8_STAGE(PG8_SA(1, 1), a1 + hstepA, voffA);
;             PG8_WAIT_V(8); PG8_WAIT_L(0); PG8_BAR; PG8_MMA(0, 0, At, B0); PG8_MMA(0, 1, At, B1); PG8_BAR; PG8_SCHED;
;             PG8_LDA(At, 0, 1); PG8_STAGE(PG8_SB(0, 0), b2, voffB); PG8_STAGE(PG8_SB(0, 1), b2 + hstepB, voffB); PG8_STAGE(PG8_SA(0, 0), a2, voffA);
;             PG8_WAIT_V(8); PG8_WAIT_L(0); PG8_BAR; PG8_MMA(1, 0, At, B0); PG8_MMA(1, 1, At, B1); PG8_BAR; PG8_SCHED;
;             PG8_LDB(B0, 1, 0); PG8_LDB(B1, 1, 1); PG8_SCHED; PG8_LDA(At, 1, 0); PG8_STAGE(PG8_SA(0, 1), a2 + hstepA, voffA);
;             PG8_WAIT_V(8); PG8_WAIT_L(0); PG8_BAR; PG8_MMA(0, 0, At, B0); PG8_MMA(0, 1, At, B1); PG8_BAR; PG8_SCHED;
;             PG8_LDA(At, 1, 1); PG8_STAGE(PG8_SB(1, 0), b3, voffB); PG8_STAGE(PG8_SB(1, 1), b3 + hstepB, voffB); PG8_STAGE(PG8_SA(1, 0), a3, voffA);
;             PG8_WAIT_V(8); PG8_WAIT_L(0); PG8_BAR; PG8_MMA(1, 0, At, B0); PG8_MMA(1, 1, At, B1); PG8_BAR; PG8_SCHED;
	s_add_i32 s78, s90, s3
	v_lshl_add_u64 v[148:149], v[148:149], 0, s[12:13]
	s_mov_b32 m0, s78
	ds_read_b128 v[190:193], v155 offset:49152
	ds_read_b128 v[194:197], v155 offset:50176
	ds_read_b128 v[198:201], v155 offset:51200
	ds_read_b128 v[202:205], v155 offset:52224
	ds_read_b128 v[206:209], v155 offset:53248
	ds_read_b128 v[210:213], v155 offset:54272
	ds_read_b128 v[214:217], v155 offset:55296
	ds_read_b128 v[218:221], v155 offset:56320
	global_load_lds_dwordx4 v[148:149], off
	s_add_i32 m0, s78, 0x2000
	s_add_u32 s76, s76, 0x40080
	v_lshl_add_u64 v[148:149], v[174:175], 0, s[12:13]
	s_addc_u32 s77, s77, 0
	s_add_i32 s78, s91, s3
	global_load_lds_dwordx4 v[148:149], off
	s_mov_b32 m0, s78
	s_nop 0
	global_load_lds_dwordx4 v130, s[76:77]
	s_add_i32 m0, s78, 0x2000
	s_nop 0
	global_load_lds_dwordx4 v134, s[76:77]
	v_lshl_add_u64 v[148:149], v[222:223], 0, s[12:13]
	s_mov_b32 m0, s57
	s_nop 0
	global_load_lds_dwordx4 v[148:149], off
	v_lshl_add_u64 v[148:149], v[226:227], 0, s[12:13]
	s_mov_b32 m0, s80
	s_nop 0
	global_load_lds_dwordx4 v[148:149], off
	s_waitcnt vmcnt(8)
	s_waitcnt lgkmcnt(0)
	s_barrier
	s_setprio 1
	s_waitcnt lgkmcnt(0)
	v_mfma_f32_16x16x32_bf16 v[60:63], v[144:147], v[190:193], v[60:63]
	v_mfma_f32_16x16x32_bf16 v[56:59], v[162:165], v[190:193], v[56:59]
	v_mfma_f32_16x16x32_bf16 v[44:47], v[144:147], v[198:201], v[44:47]
	v_mfma_f32_16x16x32_bf16 v[40:43], v[162:165], v[198:201], v[40:43]
	v_mfma_f32_16x16x32_bf16 v[28:31], v[144:147], v[206:209], v[28:31]
	v_mfma_f32_16x16x32_bf16 v[24:27], v[162:165], v[206:209], v[24:27]
	v_mfma_f32_16x16x32_bf16 v[12:15], v[144:147], v[214:217], v[12:15]
	v_mfma_f32_16x16x32_bf16 v[8:11], v[162:165], v[214:217], v[8:11]
	v_mfma_f32_16x16x32_bf16 v[60:63], v[158:161], v[194:197], v[60:63]
	v_mfma_f32_16x16x32_bf16 v[56:59], v[166:169], v[194:197], v[56:59]
	v_mfma_f32_16x16x32_bf16 v[44:47], v[158:161], v[202:205], v[44:47]
	v_mfma_f32_16x16x32_bf16 v[40:43], v[166:169], v[202:205], v[40:43]
	v_mfma_f32_16x16x32_bf16 v[28:31], v[158:161], v[210:213], v[28:31]
	v_mfma_f32_16x16x32_bf16 v[24:27], v[166:169], v[210:213], v[24:27]
	v_mfma_f32_16x16x32_bf16 v[12:15], v[158:161], v[218:221], v[12:15]
	v_mfma_f32_16x16x32_bf16 v[8:11], v[166:169], v[218:221], v[8:11]
	s_setprio 0
	s_setprio 1
	v_mfma_f32_16x16x32_bf16 v[52:55], v[170:173], v[190:193], v[52:55]
	v_mfma_f32_16x16x32_bf16 v[48:51], v[182:185], v[190:193], v[48:51]
	v_mfma_f32_16x16x32_bf16 v[36:39], v[170:173], v[198:201], v[36:39]
	v_mfma_f32_16x16x32_bf16 v[32:35], v[182:185], v[198:201], v[32:35]
	v_mfma_f32_16x16x32_bf16 v[20:23], v[170:173], v[206:209], v[20:23]
	v_mfma_f32_16x16x32_bf16 v[16:19], v[182:185], v[206:209], v[16:19]
	v_mfma_f32_16x16x32_bf16 v[4:7], v[170:173], v[214:217], v[4:7]
	v_mfma_f32_16x16x32_bf16 v[0:3], v[182:185], v[214:217], v[0:3]
	v_mfma_f32_16x16x32_bf16 v[52:55], v[178:181], v[194:197], v[52:55]
	v_mfma_f32_16x16x32_bf16 v[48:51], v[186:189], v[194:197], v[48:51]
	v_mfma_f32_16x16x32_bf16 v[36:39], v[178:181], v[202:205], v[36:39]
	v_mfma_f32_16x16x32_bf16 v[32:35], v[186:189], v[202:205], v[32:35]
	v_mfma_f32_16x16x32_bf16 v[20:23], v[178:181], v[210:213], v[20:23]
	v_mfma_f32_16x16x32_bf16 v[16:19], v[186:189], v[210:213], v[16:19]
	v_mfma_f32_16x16x32_bf16 v[4:7], v[178:181], v[218:221], v[4:7]
	v_mfma_f32_16x16x32_bf16 v[0:3], v[186:189], v[218:221], v[0:3]
	s_setprio 0
	s_barrier
	s_add_i32 s89, s89, 2
	s_add_u32 s74, s74, 0x100
	s_addc_u32 s75, s75, 0
	s_add_u32 s87, s87, 0x100
	s_addc_u32 s88, s88, 0
	s_cmp_gt_u32 s89, 13
.LBB0_192:
	ds_read_b128 v[144:147], v153
	ds_read_b128 v[158:161], v153 offset:1024
	ds_read_b128 v[162:165], v153 offset:2048
	ds_read_b128 v[166:169], v153 offset:3072
	ds_read_b128 v[170:173], v154
	ds_read_b128 v[178:181], v154 offset:1024
	ds_read_b128 v[182:185], v154 offset:2048
	ds_read_b128 v[186:189], v154 offset:3072
	s_add_u32 s76, s74, 0xfffc0080
	s_addc_u32 s77, s75, -1
	s_cmp_eq_u32 s89, 12
	s_cselect_b32 s79, s7, s77
	s_cselect_b32 s78, s65, s76
	s_cselect_b32 s77, s63, s88
	s_cselect_b32 s76, s73, s87
	s_add_i32 m0, s19, 0xc000
	ds_read_b128 v[190:193], v155
	ds_read_b128 v[194:197], v155 offset:1024
	ds_read_b128 v[198:201], v155 offset:2048
	ds_read_b128 v[202:205], v155 offset:3072
	ds_read_b128 v[206:209], v155 offset:4096
	ds_read_b128 v[210:213], v155 offset:5120
	ds_read_b128 v[214:217], v155 offset:6144
	ds_read_b128 v[218:221], v155 offset:7168
	global_load_lds_dwordx4 v136, s[74:75]
	s_add_i32 m0, s19, 0xe000
	s_nop 0
	global_load_lds_dwordx4 v138, s[74:75]
	s_waitcnt vmcnt(8)
	s_waitcnt lgkmcnt(0)
	s_barrier
; #define PG8_STAGE(bufoff, gbase, voff) do { _Pragma("unroll") for (int _i = 0; _i < 2; ++_i) \
;         __builtin_amdgcn_global_load_lds((const unsigned*)((const char*)(gbase) + (voff)[_i]), (LAS unsigned*)(lds + (bufoff) + ldsw + _i * 8192), 16, 0, 0); } while (0)
; #define PG8_LDA(dst, b, h) do { _Pragma("unroll") for (int m = 0; m < 4; ++m) _Pragma("unroll") for (int k = 0; k < 2; ++k) dst[m][k] = *(const LAS bf16x8*)(lds + PG8_SA(b, h) + aoff + m * 2048 + k * 1024); } while (0)
; #define PG8_MMA(ai, bj, At, Bt) do { __builtin_amdgcn_s_setprio(1); _Pragma("unroll") for (int m = 0; m < 4; ++m) _Pragma("unroll") for (int n = 0; n < 2; ++n) _Pragma("unroll") for (int k = 0; k < 2; ++k) \
;         acc[ai][bj][m][n] = __builtin_amdgcn_mfma_f32_16x16x32_bf16(Bt[n][k], At[m][k], acc[ai][bj][m][n], 0, 0, 0); __builtin_amdgcn_s_setprio(0); } while (0)
; #define PG8_WAIT_V(n) asm volatile("s_waitcnt vmcnt(" #n ")" ::: "memory")
; #define PG8_WAIT_L(n) asm volatile("s_waitcnt lgkmcnt(" #n ")" ::: "memory")
; #define PG8_BAR __builtin_amdgcn_s_barrier()
; #define PG8_SCHED __builtin_amdgcn_sched_barrier(0)
; template <class Epi>
; __device__ __forceinline__ void gemm_phase(LAS unsigned char* lds, const Gemm g, const StaticOrder& S, const Epi& E) {
;     ...
;             PG8_WAIT_V(8); PG8_WAIT_L(0); PG8_BAR; PG8_MMA(0, 0, At, B0); PG8_MMA(0, 1, At, B1); PG8_BAR; PG8_SCHED;
;             PG8_LDA(At, 0, 1); PG8_STAGE(PG8_SB(0, 0), b2, voffB); PG8_STAGE(PG8_SB(0, 1), b2 + hstepB, voffB); PG8_STAGE(PG8_SA(0, 0), a2, voffA);
;             PG8_WAIT_V(8); PG8_WAIT_L(0); PG8_BAR; PG8_MMA(1, 0, At, B0); PG8_MMA(1, 1, At, B1); PG8_BAR; PG8_SCHED;
	s_setprio 1
	s_waitcnt lgkmcnt(0)
	v_mfma_f32_16x16x32_bf16 v[124:127], v[144:147], v[190:193], v[124:127]
	v_mfma_f32_16x16x32_bf16 v[120:123], v[162:165], v[190:193], v[120:123]
	v_mfma_f32_16x16x32_bf16 v[108:111], v[144:147], v[198:201], v[108:111]
	v_mfma_f32_16x16x32_bf16 v[104:107], v[162:165], v[198:201], v[104:107]
	v_mfma_f32_16x16x32_bf16 v[92:95], v[144:147], v[206:209], v[92:95]
	v_mfma_f32_16x16x32_bf16 v[88:91], v[162:165], v[206:209], v[88:91]
	v_mfma_f32_16x16x32_bf16 v[76:79], v[144:147], v[214:217], v[76:79]
	v_mfma_f32_16x16x32_bf16 v[72:75], v[162:165], v[214:217], v[72:75]
	v_mfma_f32_16x16x32_bf16 v[124:127], v[158:161], v[194:197], v[124:127]
	v_mfma_f32_16x16x32_bf16 v[120:123], v[166:169], v[194:197], v[120:123]
	v_mfma_f32_16x16x32_bf16 v[108:111], v[158:161], v[202:205], v[108:111]
	v_mfma_f32_16x16x32_bf16 v[104:107], v[166:169], v[202:205], v[104:107]
	v_mfma_f32_16x16x32_bf16 v[92:95], v[158:161], v[210:213], v[92:95]
	v_mfma_f32_16x16x32_bf16 v[88:91], v[166:169], v[210:213], v[88:91]
	v_mfma_f32_16x16x32_bf16 v[76:79], v[158:161], v[218:221], v[76:79]
	v_mfma_f32_16x16x32_bf16 v[72:75], v[166:169], v[218:221], v[72:75]
	s_setprio 0
	s_setprio 1
	v_mfma_f32_16x16x32_bf16 v[116:119], v[170:173], v[190:193], v[116:119]
	v_mfma_f32_16x16x32_bf16 v[112:115], v[182:185], v[190:193], v[112:115]
	v_mfma_f32_16x16x32_bf16 v[100:103], v[170:173], v[198:201], v[100:103]
	v_mfma_f32_16x16x32_bf16 v[96:99], v[182:185], v[198:201], v[96:99]
	v_mfma_f32_16x16x32_bf16 v[84:87], v[170:173], v[206:209], v[84:87]
	v_mfma_f32_16x16x32_bf16 v[80:83], v[182:185], v[206:209], v[80:83]
	v_mfma_f32_16x16x32_bf16 v[68:71], v[170:173], v[214:217], v[68:71]
	v_mfma_f32_16x16x32_bf16 v[64:67], v[182:185], v[214:217], v[64:67]
	v_mfma_f32_16x16x32_bf16 v[116:119], v[178:181], v[194:197], v[116:119]
	v_mfma_f32_16x16x32_bf16 v[112:115], v[186:189], v[194:197], v[112:115]
	v_mfma_f32_16x16x32_bf16 v[100:103], v[178:181], v[202:205], v[100:103]
	v_mfma_f32_16x16x32_bf16 v[96:99], v[186:189], v[202:205], v[96:99]
	v_mfma_f32_16x16x32_bf16 v[84:87], v[178:181], v[210:213], v[84:87]
	v_mfma_f32_16x16x32_bf16 v[80:83], v[186:189], v[210:213], v[80:83]
	v_mfma_f32_16x16x32_bf16 v[68:71], v[178:181], v[218:221], v[68:71]
	v_mfma_f32_16x16x32_bf16 v[64:67], v[186:189], v[218:221], v[64:67]
	s_setprio 0
	s_barrier
	s_add_i32 s90, s84, s3
	v_lshl_add_u64 v[148:149], s[76:77], 0, v[130:131]
	s_mov_b32 m0, s90
	ds_read_b128 v[190:193], v155 offset:16384
	ds_read_b128 v[194:197], v155 offset:17408
	ds_read_b128 v[198:201], v155 offset:18432
	ds_read_b128 v[202:205], v155 offset:19456
	ds_read_b128 v[206:209], v155 offset:20480
	ds_read_b128 v[210:213], v155 offset:21504
	ds_read_b128 v[214:217], v155 offset:22528
	ds_read_b128 v[218:221], v155 offset:23552
	global_load_lds_dwordx4 v[148:149], off
	s_add_i32 m0, s90, 0x2000
	s_add_u32 s90, s76, 0x40000
	v_lshl_add_u64 v[174:175], s[76:77], 0, v[134:135]
	s_addc_u32 s91, s77, 0
	s_add_i32 s92, s85, s3
	global_load_lds_dwordx4 v[174:175], off
	s_mov_b32 m0, s92
	v_lshl_add_u64 v[226:227], s[78:79], 0, v[132:133]
	global_load_lds_dwordx4 v130, s[90:91]
	s_add_i32 m0, s92, 0x2000
	s_nop 0
	global_load_lds_dwordx4 v134, s[90:91]
	v_lshl_add_u64 v[222:223], s[78:79], 0, v[128:129]
	s_mov_b32 m0, s19
	s_nop 0
	global_load_lds_dwordx4 v[222:223], off
	s_mov_b32 m0, s23
	s_nop 0
	global_load_lds_dwordx4 v[226:227], off
	s_waitcnt vmcnt(8)
	s_waitcnt lgkmcnt(0)
	s_barrier
	s_setprio 1
	s_waitcnt lgkmcnt(0)
	v_mfma_f32_16x16x32_bf16 v[60:63], v[144:147], v[190:193], v[60:63]
	v_mfma_f32_16x16x32_bf16 v[56:59], v[162:165], v[190:193], v[56:59]
	v_mfma_f32_16x16x32_bf16 v[44:47], v[144:147], v[198:201], v[44:47]
	v_mfma_f32_16x16x32_bf16 v[40:43], v[162:165], v[198:201], v[40:43]
	v_mfma_f32_16x16x32_bf16 v[28:31], v[144:147], v[206:209], v[28:31]
	v_mfma_f32_16x16x32_bf16 v[24:27], v[162:165], v[206:209], v[24:27]
	v_mfma_f32_16x16x32_bf16 v[12:15], v[144:147], v[214:217], v[12:15]
	v_mfma_f32_16x16x32_bf16 v[8:11], v[162:165], v[214:217], v[8:11]
	v_mfma_f32_16x16x32_bf16 v[60:63], v[158:161], v[194:197], v[60:63]
	v_mfma_f32_16x16x32_bf16 v[56:59], v[166:169], v[194:197], v[56:59]
	v_mfma_f32_16x16x32_bf16 v[44:47], v[158:161], v[202:205], v[44:47]
	v_mfma_f32_16x16x32_bf16 v[40:43], v[166:169], v[202:205], v[40:43]
	v_mfma_f32_16x16x32_bf16 v[28:31], v[158:161], v[210:213], v[28:31]
	v_mfma_f32_16x16x32_bf16 v[24:27], v[166:169], v[210:213], v[24:27]
	v_mfma_f32_16x16x32_bf16 v[12:15], v[158:161], v[218:221], v[12:15]
	v_mfma_f32_16x16x32_bf16 v[8:11], v[166:169], v[218:221], v[8:11]
	s_setprio 0
	s_setprio 1
	v_mfma_f32_16x16x32_bf16 v[52:55], v[170:173], v[190:193], v[52:55]
	v_mfma_f32_16x16x32_bf16 v[48:51], v[182:185], v[190:193], v[48:51]
	v_mfma_f32_16x16x32_bf16 v[36:39], v[170:173], v[198:201], v[36:39]
	v_mfma_f32_16x16x32_bf16 v[32:35], v[182:185], v[198:201], v[32:35]
	v_mfma_f32_16x16x32_bf16 v[20:23], v[170:173], v[206:209], v[20:23]
	v_mfma_f32_16x16x32_bf16 v[16:19], v[182:185], v[206:209], v[16:19]
	v_mfma_f32_16x16x32_bf16 v[4:7], v[170:173], v[214:217], v[4:7]
	v_mfma_f32_16x16x32_bf16 v[0:3], v[182:185], v[214:217], v[0:3]
	v_mfma_f32_16x16x32_bf16 v[52:55], v[178:181], v[194:197], v[52:55]
	v_mfma_f32_16x16x32_bf16 v[48:51], v[186:189], v[194:197], v[48:51]
	v_mfma_f32_16x16x32_bf16 v[36:39], v[178:181], v[202:205], v[36:39]
	v_mfma_f32_16x16x32_bf16 v[32:35], v[186:189], v[202:205], v[32:35]
	v_mfma_f32_16x16x32_bf16 v[20:23], v[178:181], v[210:213], v[20:23]
	v_mfma_f32_16x16x32_bf16 v[16:19], v[186:189], v[210:213], v[16:19]
	v_mfma_f32_16x16x32_bf16 v[4:7], v[178:181], v[218:221], v[4:7]
	v_mfma_f32_16x16x32_bf16 v[0:3], v[186:189], v[218:221], v[0:3]
	s_setprio 0
	s_barrier
; #define PG8_STAGE(bufoff, gbase, voff) do { _Pragma("unroll") for (int _i = 0; _i < 2; ++_i) \
;         __builtin_amdgcn_global_load_lds((const unsigned*)((const char*)(gbase) + (voff)[_i]), (LAS unsigned*)(lds + (bufoff) + ldsw + _i * 8192), 16, 0, 0); } while (0)
; #define PG8_LDA(dst, b, h) do { _Pragma("unroll") for (int m = 0; m < 4; ++m) _Pragma("unroll") for (int k = 0; k < 2; ++k) dst[m][k] = *(const LAS bf16x8*)(lds + PG8_SA(b, h) + aoff + m * 2048 + k * 1024); } while (0)
; #define PG8_LDB(dst, b, h) do { _Pragma("unroll") for (int n = 0; n < 2; ++n) _Pragma("unroll") for (int k = 0; k < 2; ++k) dst[n][k] = *(const LAS bf16x8*)(lds + PG8_SB(b, h) + boff + n * 2048 + k * 1024); } while (0)
; #define PG8_MMA(ai, bj, At, Bt) do { __builtin_amdgcn_s_setprio(1); _Pragma("unroll") for (int m = 0; m < 4; ++m) _Pragma("unroll") for (int n = 0; n < 2; ++n) _Pragma("unroll") for (int k = 0; k < 2; ++k) \
;         acc[ai][bj][m][n] = __builtin_amdgcn_mfma_f32_16x16x32_bf16(Bt[n][k], At[m][k], acc[ai][bj][m][n], 0, 0, 0); __builtin_amdgcn_s_setprio(0); } while (0)
; #define PG8_WAIT_V(n) asm volatile("s_waitcnt vmcnt(" #n ")" ::: "memory")
; #define PG8_WAIT_L(n) asm volatile("s_waitcnt lgkmcnt(" #n ")" ::: "memory")
; #define PG8_BAR __builtin_amdgcn_s_barrier()
; #define PG8_SCHED __builtin_amdgcn_sched_barrier(0)
; template <class Epi>
; __device__ __forceinline__ void gemm_phase(LAS unsigned char* lds, const Gemm g, const StaticOrder& S, const Epi& E) {
;     ...
;             PG8_WAIT_V(8); PG8_WAIT_L(0); PG8_BAR; PG8_MMA(1, 0, At, B0); PG8_MMA(1, 1, At, B1); PG8_BAR; PG8_SCHED;
;             PG8_LDB(B0, 1, 0); PG8_LDB(B1, 1, 1); PG8_SCHED; PG8_LDA(At, 1, 0); PG8_STAGE(PG8_SA(0, 1), a2 + hstepA, voffA);
;             PG8_WAIT_V(8); PG8_WAIT_L(0); PG8_BAR; PG8_MMA(0, 0, At, B0); PG8_MMA(0, 1, At, B1); PG8_BAR; PG8_SCHED;
;             PG8_LDA(At, 1, 1); PG8_STAGE(PG8_SB(1, 0), b3, voffB); PG8_STAGE(PG8_SB(1, 1), b3 + hstepB, voffB); PG8_STAGE(PG8_SA(1, 0), a3, voffA);
;             PG8_WAIT_V(8); PG8_WAIT_L(0); PG8_BAR; PG8_MMA(1, 0, At, B0); PG8_MMA(1, 1, At, B1); PG8_BAR; PG8_SCHED;
	s_add_i32 s90, 0, 0x18000
	v_add_u32_e32 v157, s90, v152
	s_add_i32 s91, 0, 0x1c000
	ds_read_b128 v[144:147], v157
	ds_read_b128 v[158:161], v157 offset:1024
	ds_read_b128 v[162:165], v157 offset:2048
	ds_read_b128 v[166:169], v157 offset:3072
	v_add_u32_e32 v157, s91, v152
	ds_read_b128 v[170:173], v157
	ds_read_b128 v[178:181], v157 offset:1024
	ds_read_b128 v[182:185], v157 offset:2048
	ds_read_b128 v[186:189], v157 offset:3072
	s_add_u32 s78, s78, 0x40000
	s_addc_u32 s79, s79, 0
	s_mov_b32 m0, s33
	ds_read_b128 v[190:193], v155 offset:32768
	ds_read_b128 v[194:197], v155 offset:33792
	ds_read_b128 v[198:201], v155 offset:34816
	ds_read_b128 v[202:205], v155 offset:35840
	ds_read_b128 v[206:209], v155 offset:36864
	ds_read_b128 v[210:213], v155 offset:37888
	ds_read_b128 v[214:217], v155 offset:38912
	ds_read_b128 v[218:221], v155 offset:39936
	global_load_lds_dwordx4 v128, s[78:79]
	s_mov_b32 m0, s35
	s_nop 0
	global_load_lds_dwordx4 v132, s[78:79]
	s_waitcnt vmcnt(8)
	s_waitcnt lgkmcnt(0)
	s_barrier
	s_setprio 1
	s_waitcnt lgkmcnt(0)
	v_mfma_f32_16x16x32_bf16 v[124:127], v[144:147], v[190:193], v[124:127]
	v_mfma_f32_16x16x32_bf16 v[120:123], v[162:165], v[190:193], v[120:123]
	v_mfma_f32_16x16x32_bf16 v[108:111], v[144:147], v[198:201], v[108:111]
	v_mfma_f32_16x16x32_bf16 v[104:107], v[162:165], v[198:201], v[104:107]
	v_mfma_f32_16x16x32_bf16 v[92:95], v[144:147], v[206:209], v[92:95]
	v_mfma_f32_16x16x32_bf16 v[88:91], v[162:165], v[206:209], v[88:91]
	v_mfma_f32_16x16x32_bf16 v[76:79], v[144:147], v[214:217], v[76:79]
	v_mfma_f32_16x16x32_bf16 v[72:75], v[162:165], v[214:217], v[72:75]
	v_mfma_f32_16x16x32_bf16 v[124:127], v[158:161], v[194:197], v[124:127]
	v_mfma_f32_16x16x32_bf16 v[120:123], v[166:169], v[194:197], v[120:123]
	v_mfma_f32_16x16x32_bf16 v[108:111], v[158:161], v[202:205], v[108:111]
	v_mfma_f32_16x16x32_bf16 v[104:107], v[166:169], v[202:205], v[104:107]
	v_mfma_f32_16x16x32_bf16 v[92:95], v[158:161], v[210:213], v[92:95]
	v_mfma_f32_16x16x32_bf16 v[88:91], v[166:169], v[210:213], v[88:91]
	v_mfma_f32_16x16x32_bf16 v[76:79], v[158:161], v[218:221], v[76:79]
	v_mfma_f32_16x16x32_bf16 v[72:75], v[166:169], v[218:221], v[72:75]
	s_setprio 0
	s_setprio 1
	v_mfma_f32_16x16x32_bf16 v[116:119], v[170:173], v[190:193], v[116:119]
	v_mfma_f32_16x16x32_bf16 v[112:115], v[182:185], v[190:193], v[112:115]
	v_mfma_f32_16x16x32_bf16 v[100:103], v[170:173], v[198:201], v[100:103]
	v_mfma_f32_16x16x32_bf16 v[96:99], v[182:185], v[198:201], v[96:99]
	v_mfma_f32_16x16x32_bf16 v[84:87], v[170:173], v[206:209], v[84:87]
	v_mfma_f32_16x16x32_bf16 v[80:83], v[182:185], v[206:209], v[80:83]
	v_mfma_f32_16x16x32_bf16 v[68:71], v[170:173], v[214:217], v[68:71]
	v_mfma_f32_16x16x32_bf16 v[64:67], v[182:185], v[214:217], v[64:67]
	v_mfma_f32_16x16x32_bf16 v[116:119], v[178:181], v[194:197], v[116:119]
	v_mfma_f32_16x16x32_bf16 v[112:115], v[186:189], v[194:197], v[112:115]
	v_mfma_f32_16x16x32_bf16 v[100:103], v[178:181], v[202:205], v[100:103]
	v_mfma_f32_16x16x32_bf16 v[96:99], v[186:189], v[202:205], v[96:99]
	v_mfma_f32_16x16x32_bf16 v[84:87], v[178:181], v[210:213], v[84:87]
	v_mfma_f32_16x16x32_bf16 v[80:83], v[186:189], v[210:213], v[80:83]
	v_mfma_f32_16x16x32_bf16 v[68:71], v[178:181], v[218:221], v[68:71]
	v_mfma_f32_16x16x32_bf16 v[64:67], v[186:189], v[218:221], v[64:67]
	s_setprio 0
	s_barrier
	s_add_i32 s78, s90, s3
	v_lshl_add_u64 v[148:149], v[148:149], 0, s[12:13]
	s_mov_b32 m0, s78
	ds_read_b128 v[190:193], v155 offset:49152
	ds_read_b128 v[194:197], v155 offset:50176
	ds_read_b128 v[198:201], v155 offset:51200
	ds_read_b128 v[202:205], v155 offset:52224
	ds_read_b128 v[206:209], v155 offset:53248
	ds_read_b128 v[210:213], v155 offset:54272
	ds_read_b128 v[214:217], v155 offset:55296
	ds_read_b128 v[218:221], v155 offset:56320
	global_load_lds_dwordx4 v[148:149], off
	s_add_i32 m0, s78, 0x2000
	s_add_u32 s76, s76, 0x40080
	v_lshl_add_u64 v[148:149], v[174:175], 0, s[12:13]
	s_addc_u32 s77, s77, 0
	s_add_i32 s78, s91, s3
	global_load_lds_dwordx4 v[148:149], off
	s_mov_b32 m0, s78
	s_nop 0
	global_load_lds_dwordx4 v130, s[76:77]
	s_add_i32 m0, s78, 0x2000
	s_nop 0
	global_load_lds_dwordx4 v134, s[76:77]
	v_lshl_add_u64 v[148:149], v[222:223], 0, s[12:13]
	s_mov_b32 m0, s57
	s_nop 0
	global_load_lds_dwordx4 v[148:149], off
	v_lshl_add_u64 v[148:149], v[226:227], 0, s[12:13]
	s_mov_b32 m0, s80
	s_nop 0
	global_load_lds_dwordx4 v[148:149], off
	s_waitcnt vmcnt(8)
	s_waitcnt lgkmcnt(0)
	s_barrier
	s_setprio 1
	s_waitcnt lgkmcnt(0)
	v_mfma_f32_16x16x32_bf16 v[60:63], v[144:147], v[190:193], v[60:63]
	v_mfma_f32_16x16x32_bf16 v[56:59], v[162:165], v[190:193], v[56:59]
	v_mfma_f32_16x16x32_bf16 v[44:47], v[144:147], v[198:201], v[44:47]
	v_mfma_f32_16x16x32_bf16 v[40:43], v[162:165], v[198:201], v[40:43]
	v_mfma_f32_16x16x32_bf16 v[28:31], v[144:147], v[206:209], v[28:31]
	v_mfma_f32_16x16x32_bf16 v[24:27], v[162:165], v[206:209], v[24:27]
	v_mfma_f32_16x16x32_bf16 v[12:15], v[144:147], v[214:217], v[12:15]
	v_mfma_f32_16x16x32_bf16 v[8:11], v[162:165], v[214:217], v[8:11]
	v_mfma_f32_16x16x32_bf16 v[60:63], v[158:161], v[194:197], v[60:63]
	v_mfma_f32_16x16x32_bf16 v[56:59], v[166:169], v[194:197], v[56:59]
	v_mfma_f32_16x16x32_bf16 v[44:47], v[158:161], v[202:205], v[44:47]
	v_mfma_f32_16x16x32_bf16 v[40:43], v[166:169], v[202:205], v[40:43]
	v_mfma_f32_16x16x32_bf16 v[28:31], v[158:161], v[210:213], v[28:31]
	v_mfma_f32_16x16x32_bf16 v[24:27], v[166:169], v[210:213], v[24:27]
	v_mfma_f32_16x16x32_bf16 v[12:15], v[158:161], v[218:221], v[12:15]
	v_mfma_f32_16x16x32_bf16 v[8:11], v[166:169], v[218:221], v[8:11]
	s_setprio 0
	s_setprio 1
	v_mfma_f32_16x16x32_bf16 v[52:55], v[170:173], v[190:193], v[52:55]
	v_mfma_f32_16x16x32_bf16 v[48:51], v[182:185], v[190:193], v[48:51]
	v_mfma_f32_16x16x32_bf16 v[36:39], v[170:173], v[198:201], v[36:39]
	v_mfma_f32_16x16x32_bf16 v[32:35], v[182:185], v[198:201], v[32:35]
	v_mfma_f32_16x16x32_bf16 v[20:23], v[170:173], v[206:209], v[20:23]
	v_mfma_f32_16x16x32_bf16 v[16:19], v[182:185], v[206:209], v[16:19]
	v_mfma_f32_16x16x32_bf16 v[4:7], v[170:173], v[214:217], v[4:7]
	v_mfma_f32_16x16x32_bf16 v[0:3], v[182:185], v[214:217], v[0:3]
	v_mfma_f32_16x16x32_bf16 v[52:55], v[178:181], v[194:197], v[52:55]
	v_mfma_f32_16x16x32_bf16 v[48:51], v[186:189], v[194:197], v[48:51]
	v_mfma_f32_16x16x32_bf16 v[36:39], v[178:181], v[202:205], v[36:39]
	v_mfma_f32_16x16x32_bf16 v[32:35], v[186:189], v[202:205], v[32:35]
	v_mfma_f32_16x16x32_bf16 v[20:23], v[178:181], v[210:213], v[20:23]
	v_mfma_f32_16x16x32_bf16 v[16:19], v[186:189], v[210:213], v[16:19]
	v_mfma_f32_16x16x32_bf16 v[4:7], v[178:181], v[218:221], v[4:7]
	v_mfma_f32_16x16x32_bf16 v[0:3], v[186:189], v[218:221], v[0:3]
	s_setprio 0
	s_barrier
	s_add_i32 s89, s89, 2
	s_add_u32 s74, s74, 0x100
	s_addc_u32 s75, s75, 0
	s_add_u32 s87, s87, 0x100
	s_addc_u32 s88, s88, 0
	s_cmp_gt_u32 s89, 13
	s_cbranch_scc0 .LBB0_192
	s_and_b64 vcc, exec, s[14:15]
	s_cbranch_vccz .LBB0_195
	s_barrier

; #define PG8_STAGE(bufoff, gbase, voff) do { _Pragma("unroll") for (int _i = 0; _i < 2; ++_i) \
;         __builtin_amdgcn_global_load_lds((const unsigned*)((const char*)(gbase) + (voff)[_i]), (LAS unsigned*)(lds + (bufoff) + ldsw + _i * 8192), 16, 0, 0); } while (0)
; #define PG8_WAIT_V(n) asm volatile("s_waitcnt vmcnt(" #n ")" ::: "memory")
; #define PG8_BAR __builtin_amdgcn_s_barrier()
; template <class Epi>
; __device__ __forceinline__ void gemm_phase(LAS unsigned char* lds, const Gemm g, const StaticOrder& S, const Epi& E) {
;     ...
;     for (int i = 0; i < 2; ++i) { int R, C; stage_rc(tid * 16 + i * 8192, R, C); const int Rb = (R & ~31) + perm32(R & 31);
;         voffA[i] = (unsigned)(R * g.lda + C) * 2u; voffB[i] = (unsigned)(Rb * g.ldb + C) * 2u; }
;     const size_t kstep = (size_t)(BK * 2);
;     const size_t hstepA = (size_t)HALF * g.lda * 2, hstepB = (size_t)HALF * g.ldb * 2;
;     const size_t tstepA = 2 * hstepA, tstepB = 2 * hstepB;
;     const unsigned ldsw = (unsigned)wid * 1024u;
;     const int aoff = lds_byte(wr * 64 + fr, fq * 8), boff = lds_byte(wc * 32 + fr, fq * 8);
;     ...
;     PG8_STAGE(PG8_SB(0, 0), cB, voffB); PG8_STAGE(PG8_SB(0, 1), cB + hstepB, voffB); PG8_STAGE(PG8_SA(0, 0), cA, voffA); PG8_STAGE(PG8_SA(0, 1), cA + hstepA, voffA);
;     if (wr == 1) PG8_BAR;
;     PG8_WAIT_V(2); PG8_BAR;
;     PG8_STAGE(PG8_SB(1, 0), cB + kstep, voffB); PG8_STAGE(PG8_SA(1, 0), cA + kstep, voffA); PG8_STAGE(PG8_SB(1, 1), cB + hstepB + kstep, voffB);
;     PG8_WAIT_V(6); PG8_BAR;
.LBB0_447:
	s_add_u32 s10, s50, 0x20000
	s_addc_u32 s11, s51, 0
	s_lshl_b32 s63, s4, 6
	s_lshl_b32 s1, s4, 13
	s_lshl_b32 s4, s5, 5
	s_mov_b64 s[12:13], 0x80
	s_and_b32 s64, s4, 0x60
	s_add_i32 m0, s35, 0x18000
	v_lshl_add_u64 v[6:7], v[6:7], 0, s[12:13]
	s_lshl_b32 s15, s64, 7
	s_waitcnt vmcnt(2)
	s_barrier
	global_load_lds_dwordx4 v[6:7], off
	v_lshl_add_u64 v[4:5], v[4:5], 0, s[12:13]
	s_add_i32 m0, s35, 0x1a000
	s_add_i32 s65, s35, 0x8000
	s_add_i32 s68, s35, 0xa000
	global_load_lds_dwordx4 v[4:5], off
	v_lshl_add_u64 v[0:1], v[0:1], 0, s[12:13]
	s_mov_b32 m0, s65
	s_add_u32 s4, s42, 0x40080
	global_load_lds_dwordx4 v[0:1], off
	v_lshl_add_u64 v[0:1], v[2:3], 0, s[12:13]
	s_mov_b32 m0, s68
	s_addc_u32 s5, s43, 0
	global_load_lds_dwordx4 v[0:1], off
	s_add_i32 m0, s35, 0x1c000
	global_load_lds_dwordx4 v146, s[4:5]
	s_add_i32 m0, s35, 0x1e000
	v_bfe_u32 v170, v176, 4, 2
	global_load_lds_dwordx4 v150, s[4:5]
	v_and_b32_e32 v171, 15, v176
	v_lshlrev_b32_e32 v0, 4, v170
	v_lshlrev_b32_e32 v2, 2, v176
	v_lshl_or_b32 v1, v171, 6, v0
	v_and_b32_e32 v2, 32, v2
	v_bitop3_b32 v1, v1, s1, v2 bitop3:0xde
	v_lshlrev_b32_e32 v3, 6, v176
	s_movk_i32 s1, 0x3c0
	v_and_or_b32 v0, v3, s1, v0
	v_bitop3_b32 v172, s15, v0, v2 bitop3:0xf6
	v_lshlrev_b32_e32 v0, 8, v176
	v_and_b32_e32 v0, 0x38000, v0
	v_lshlrev_b32_e32 v2, 11, v10
	v_or3_b32 v0, v8, v0, v2
	v_add_u32_e32 v152, v0, v9
	v_lshlrev_b32_e32 v0, 4, v11
	v_and_b32_e32 v0, 0x78000, v0
	s_waitcnt vmcnt(6)
	s_cmpk_lt_u32 s14, 0x100
	v_or3_b32 v0, v8, v0, v2
	s_cselect_b64 s[14:15], -1, 0
	v_add_u32_e32 v154, v0, v9
	s_add_i32 s72, 0, 0x10000
	s_add_i32 s73, 0, 0x14000
	v_mbcnt_lo_u32_b32 v0, -1, 0
	s_ashr_i32 s69, s74, 31
	s_mov_b32 s70, s74
	s_ashr_i32 s71, s2, 31
	v_mov_b32_e32 v153, v147
	v_mov_b32_e32 v155, v147
	v_mov_b64_e32 v[156:157], 0x200
	v_mov_b64_e32 v[158:159], 0x1ff
	v_add_u32_e32 v173, s72, v172
	v_add_u32_e32 v174, s73, v172
	v_add_u32_e32 v175, 0, v1
	v_mbcnt_hi_u32_b32 v177, -1, v0
	s_barrier
	s_branch .LBB0_450

; #define PG8_STAGE(bufoff, gbase, voff) do { _Pragma("unroll") for (int _i = 0; _i < 2; ++_i) \
;         __builtin_amdgcn_global_load_lds((const unsigned*)((const char*)(gbase) + (voff)[_i]), (LAS unsigned*)(lds + (bufoff) + ldsw + _i * 8192), 16, 0, 0); } while (0)
; #define PG8_LDA(dst, b, h) do { _Pragma("unroll") for (int m = 0; m < 4; ++m) _Pragma("unroll") for (int k = 0; k < 2; ++k) dst[m][k] = *(const LAS bf16x8*)(lds + PG8_SA(b, h) + aoff + m * 2048 + k * 1024); } while (0)
; #define PG8_LDB(dst, b, h) do { _Pragma("unroll") for (int n = 0; n < 2; ++n) _Pragma("unroll") for (int k = 0; k < 2; ++k) dst[n][k] = *(const LAS bf16x8*)(lds + PG8_SB(b, h) + boff + n * 2048 + k * 1024); } while (0)
; #define PG8_MMA(ai, bj, At, Bt) do { __builtin_amdgcn_s_setprio(1); _Pragma("unroll") for (int m = 0; m < 4; ++m) _Pragma("unroll") for (int n = 0; n < 2; ++n) _Pragma("unroll") for (int k = 0; k < 2; ++k) \
;         acc[ai][bj][m][n] = __builtin_amdgcn_mfma_f32_16x16x32_bf16(Bt[n][k], At[m][k], acc[ai][bj][m][n], 0, 0, 0); __builtin_amdgcn_s_setprio(0); } while (0)
; #define PG8_WAIT_V(n) asm volatile("s_waitcnt vmcnt(" #n ")" ::: "memory")
; #define PG8_WAIT_L(n) asm volatile("s_waitcnt lgkmcnt(" #n ")" ::: "memory")
; #define PG8_BAR __builtin_amdgcn_s_barrier()
; #define PG8_SCHED __builtin_amdgcn_sched_barrier(0)
; template <class Epi>
; __device__ __forceinline__ void gemm_phase(LAS unsigned char* lds, const Gemm g, const StaticOrder& S, const Epi& E) {
;     ...
;         for (int t = 0; t < nt; t += 2) {
;             const bool last = (t == nt - 2);
;             const char* a1 = cA + (size_t)(t + 1) * kstep;
;             const char* a2 = last ? nA : cA + (size_t)(t + 2) * kstep; const char* b2 = last ? nB : cB + (size_t)(t + 2) * kstep;
;             const char* a3 = a2 + kstep; const char* b3 = b2 + kstep;
;             PG8_LDB(B0, 0, 0); PG8_LDB(B1, 0, 1); PG8_SCHED; PG8_LDA(At, 0, 0); PG8_STAGE(PG8_SA(1, 1), a1 + hstepA, voffA);
;             PG8_WAIT_V(8); PG8_WAIT_L(0); PG8_BAR; PG8_MMA(0, 0, At, B0); PG8_MMA(0, 1, At, B1); PG8_BAR; PG8_SCHED;
;             PG8_LDA(At, 0, 1); PG8_STAGE(PG8_SB(0, 0), b2, voffB); PG8_STAGE(PG8_SB(0, 1), b2 + hstepB, voffB); PG8_STAGE(PG8_SA(0, 0), a2, voffA);
;             PG8_WAIT_V(8); PG8_WAIT_L(0); PG8_BAR; PG8_MMA(1, 0, At, B0); PG8_MMA(1, 1, At, B1); PG8_BAR; PG8_SCHED;
.LBB0_456:
	s_ashr_i32 s23, s22, 31
	s_lshl_b64 s[28:29], s[22:23], 19
	s_add_u32 s28, s40, s28
	s_addc_u32 s29, s41, s29
	s_and_b64 s[30:31], s[4:5], exec
	s_cselect_b32 s1, s29, s39
	s_cselect_b32 s23, s28, s38
	s_ashr_i32 s19, s18, 31
	s_lshl_b64 s[30:31], s[18:19], 19
	s_add_u32 s30, s3, s30
	s_addc_u32 s31, s33, s31
	s_and_b64 s[52:53], s[4:5], exec
	s_cselect_b32 s19, s31, s43
	s_cselect_b32 s74, s30, s42
	s_add_u32 s38, s38, 0x40080
	s_addc_u32 s39, s39, 0
	s_add_u32 s75, s42, 0x100
	s_addc_u32 s76, s43, 0
	s_mov_b32 s77, -2
	s_waitcnt lgkmcnt(0)
	s_nop 0
	ds_read_b128 v[128:131], v173
	ds_read_b128 v[132:135], v173 offset:1024
	ds_read_b128 v[136:139], v173 offset:2048
	ds_read_b128 v[140:143], v173 offset:3072
	ds_read_b128 v[160:163], v174
	ds_read_b128 v[164:167], v174 offset:1024
	ds_read_b128 v[178:181], v174 offset:2048
	ds_read_b128 v[182:185], v174 offset:3072
	s_add_u32 s42, s38, 0xfffc0080
	s_addc_u32 s43, s39, -1
	s_cmp_eq_u32 s77, 12
	s_cselect_b32 s53, s1, s43
	s_cselect_b32 s52, s23, s42
	s_cselect_b32 s43, s19, s76
	s_cselect_b32 s42, s74, s75
	s_add_i32 m0, s35, 0xc000
	ds_read_b128 v[186:189], v175
	ds_read_b128 v[190:193], v175 offset:1024
	ds_read_b128 v[194:197], v175 offset:2048
	ds_read_b128 v[198:201], v175 offset:3072
	ds_read_b128 v[202:205], v175 offset:4096
	ds_read_b128 v[206:209], v175 offset:5120
	ds_read_b128 v[210:213], v175 offset:6144
	ds_read_b128 v[214:217], v175 offset:7168
	global_load_lds_dwordx4 v152, s[38:39]
	s_add_i32 m0, s35, 0xe000
	s_nop 0
	global_load_lds_dwordx4 v154, s[38:39]
	s_waitcnt vmcnt(8)
	s_waitcnt lgkmcnt(0)
	s_barrier
	s_setprio 1
	s_waitcnt lgkmcnt(0)
	v_mfma_f32_16x16x32_bf16 v[124:127], v[128:131], v[186:189], 0
	v_mfma_f32_16x16x32_bf16 v[120:123], v[136:139], v[186:189], 0
	v_mfma_f32_16x16x32_bf16 v[108:111], v[128:131], v[194:197], 0
	v_mfma_f32_16x16x32_bf16 v[104:107], v[136:139], v[194:197], 0
	v_mfma_f32_16x16x32_bf16 v[92:95], v[128:131], v[202:205], 0
	v_mfma_f32_16x16x32_bf16 v[88:91], v[136:139], v[202:205], 0
	v_mfma_f32_16x16x32_bf16 v[76:79], v[128:131], v[210:213], 0
	v_mfma_f32_16x16x32_bf16 v[72:75], v[136:139], v[210:213], 0
	v_mfma_f32_16x16x32_bf16 v[124:127], v[132:135], v[190:193], v[124:127]
	v_mfma_f32_16x16x32_bf16 v[120:123], v[140:143], v[190:193], v[120:123]
	v_mfma_f32_16x16x32_bf16 v[108:111], v[132:135], v[198:201], v[108:111]
	v_mfma_f32_16x16x32_bf16 v[104:107], v[140:143], v[198:201], v[104:107]
	v_mfma_f32_16x16x32_bf16 v[92:95], v[132:135], v[206:209], v[92:95]
	v_mfma_f32_16x16x32_bf16 v[88:91], v[140:143], v[206:209], v[88:91]
	v_mfma_f32_16x16x32_bf16 v[76:79], v[132:135], v[214:217], v[76:79]
	v_mfma_f32_16x16x32_bf16 v[72:75], v[140:143], v[214:217], v[72:75]
	s_setprio 0
	s_setprio 1
	v_mfma_f32_16x16x32_bf16 v[116:119], v[160:163], v[186:189], 0
	v_mfma_f32_16x16x32_bf16 v[112:115], v[178:181], v[186:189], 0
	v_mfma_f32_16x16x32_bf16 v[100:103], v[160:163], v[194:197], 0
	v_mfma_f32_16x16x32_bf16 v[96:99], v[178:181], v[194:197], 0
	v_mfma_f32_16x16x32_bf16 v[84:87], v[160:163], v[202:205], 0
	v_mfma_f32_16x16x32_bf16 v[80:83], v[178:181], v[202:205], 0
	v_mfma_f32_16x16x32_bf16 v[68:71], v[160:163], v[210:213], 0
	v_mfma_f32_16x16x32_bf16 v[64:67], v[178:181], v[210:213], 0
	v_mfma_f32_16x16x32_bf16 v[116:119], v[164:167], v[190:193], v[116:119]
	v_mfma_f32_16x16x32_bf16 v[112:115], v[182:185], v[190:193], v[112:115]
	v_mfma_f32_16x16x32_bf16 v[100:103], v[164:167], v[198:201], v[100:103]
	v_mfma_f32_16x16x32_bf16 v[96:99], v[182:185], v[198:201], v[96:99]
	v_mfma_f32_16x16x32_bf16 v[84:87], v[164:167], v[206:209], v[84:87]
	v_mfma_f32_16x16x32_bf16 v[80:83], v[182:185], v[206:209], v[80:83]
	v_mfma_f32_16x16x32_bf16 v[68:71], v[164:167], v[214:217], v[68:71]
	v_mfma_f32_16x16x32_bf16 v[64:67], v[182:185], v[214:217], v[64:67]
	s_setprio 0
	s_barrier
	s_add_i32 s78, s72, s54
	v_lshl_add_u64 v[168:169], s[42:43], 0, v[146:147]
	s_mov_b32 m0, s78
	ds_read_b128 v[186:189], v175 offset:16384
	ds_read_b128 v[190:193], v175 offset:17408
	ds_read_b128 v[194:197], v175 offset:18432
	ds_read_b128 v[198:201], v175 offset:19456
	ds_read_b128 v[202:205], v175 offset:20480
	ds_read_b128 v[206:209], v175 offset:21504
	ds_read_b128 v[210:213], v175 offset:22528
	ds_read_b128 v[214:217], v175 offset:23552
	global_load_lds_dwordx4 v[168:169], off
	s_add_i32 m0, s78, 0x2000
	s_add_u32 s78, s42, 0x40000
	v_lshl_add_u64 v[218:219], s[42:43], 0, v[150:151]
	s_addc_u32 s79, s43, 0
	s_add_i32 s80, s73, s54
	global_load_lds_dwordx4 v[218:219], off
	s_mov_b32 m0, s80
	v_lshl_add_u64 v[222:223], s[52:53], 0, v[148:149]
	global_load_lds_dwordx4 v146, s[78:79]
	s_add_i32 m0, s80, 0x2000
	s_nop 0
	global_load_lds_dwordx4 v150, s[78:79]
	v_lshl_add_u64 v[220:221], s[52:53], 0, v[144:145]
	s_mov_b32 m0, s35
	s_nop 0
	global_load_lds_dwordx4 v[220:221], off
	s_mov_b32 m0, s55
	s_nop 0
	global_load_lds_dwordx4 v[222:223], off
	s_waitcnt vmcnt(8)
	s_waitcnt lgkmcnt(0)
	s_barrier
; #define PG8_STAGE(bufoff, gbase, voff) do { _Pragma("unroll") for (int _i = 0; _i < 2; ++_i) \
;         __builtin_amdgcn_global_load_lds((const unsigned*)((const char*)(gbase) + (voff)[_i]), (LAS unsigned*)(lds + (bufoff) + ldsw + _i * 8192), 16, 0, 0); } while (0)
; #define PG8_LDA(dst, b, h) do { _Pragma("unroll") for (int m = 0; m < 4; ++m) _Pragma("unroll") for (int k = 0; k < 2; ++k) dst[m][k] = *(const LAS bf16x8*)(lds + PG8_SA(b, h) + aoff + m * 2048 + k * 1024); } while (0)
; #define PG8_LDB(dst, b, h) do { _Pragma("unroll") for (int n = 0; n < 2; ++n) _Pragma("unroll") for (int k = 0; k < 2; ++k) dst[n][k] = *(const LAS bf16x8*)(lds + PG8_SB(b, h) + boff + n * 2048 + k * 1024); } while (0)
; #define PG8_MMA(ai, bj, At, Bt) do { __builtin_amdgcn_s_setprio(1); _Pragma("unroll") for (int m = 0; m < 4; ++m) _Pragma("unroll") for (int n = 0; n < 2; ++n) _Pragma("unroll") for (int k = 0; k < 2; ++k) \
;         acc[ai][bj][m][n] = __builtin_amdgcn_mfma_f32_16x16x32_bf16(Bt[n][k], At[m][k], acc[ai][bj][m][n], 0, 0, 0); __builtin_amdgcn_s_setprio(0); } while (0)
; #define PG8_WAIT_V(n) asm volatile("s_waitcnt vmcnt(" #n ")" ::: "memory")
; #define PG8_WAIT_L(n) asm volatile("s_waitcnt lgkmcnt(" #n ")" ::: "memory")
; #define PG8_BAR __builtin_amdgcn_s_barrier()
; #define PG8_SCHED __builtin_amdgcn_sched_barrier(0)
; template <class Epi>
; __device__ __forceinline__ void gemm_phase(LAS unsigned char* lds, const Gemm g, const StaticOrder& S, const Epi& E) {
;     ...
;             PG8_WAIT_V(8); PG8_WAIT_L(0); PG8_BAR; PG8_MMA(1, 0, At, B0); PG8_MMA(1, 1, At, B1); PG8_BAR; PG8_SCHED;
;             PG8_LDB(B0, 1, 0); PG8_LDB(B1, 1, 1); PG8_SCHED; PG8_LDA(At, 1, 0); PG8_STAGE(PG8_SA(0, 1), a2 + hstepA, voffA);
;             PG8_WAIT_V(8); PG8_WAIT_L(0); PG8_BAR; PG8_MMA(0, 0, At, B0); PG8_MMA(0, 1, At, B1); PG8_BAR; PG8_SCHED;
	s_setprio 1
	s_waitcnt lgkmcnt(0)
	v_mfma_f32_16x16x32_bf16 v[60:63], v[128:131], v[186:189], 0
	v_mfma_f32_16x16x32_bf16 v[56:59], v[136:139], v[186:189], 0
	v_mfma_f32_16x16x32_bf16 v[44:47], v[128:131], v[194:197], 0
	v_mfma_f32_16x16x32_bf16 v[40:43], v[136:139], v[194:197], 0
	v_mfma_f32_16x16x32_bf16 v[28:31], v[128:131], v[202:205], 0
	v_mfma_f32_16x16x32_bf16 v[24:27], v[136:139], v[202:205], 0
	v_mfma_f32_16x16x32_bf16 v[12:15], v[128:131], v[210:213], 0
	v_mfma_f32_16x16x32_bf16 v[8:11], v[136:139], v[210:213], 0
	v_mfma_f32_16x16x32_bf16 v[60:63], v[132:135], v[190:193], v[60:63]
	v_mfma_f32_16x16x32_bf16 v[56:59], v[140:143], v[190:193], v[56:59]
	v_mfma_f32_16x16x32_bf16 v[44:47], v[132:135], v[198:201], v[44:47]
	v_mfma_f32_16x16x32_bf16 v[40:43], v[140:143], v[198:201], v[40:43]
	v_mfma_f32_16x16x32_bf16 v[28:31], v[132:135], v[206:209], v[28:31]
	v_mfma_f32_16x16x32_bf16 v[24:27], v[140:143], v[206:209], v[24:27]
	v_mfma_f32_16x16x32_bf16 v[12:15], v[132:135], v[214:217], v[12:15]
	v_mfma_f32_16x16x32_bf16 v[8:11], v[140:143], v[214:217], v[8:11]
	s_setprio 0
	s_setprio 1
	v_mfma_f32_16x16x32_bf16 v[52:55], v[160:163], v[186:189], 0
	v_mfma_f32_16x16x32_bf16 v[48:51], v[178:181], v[186:189], 0
	v_mfma_f32_16x16x32_bf16 v[36:39], v[160:163], v[194:197], 0
	v_mfma_f32_16x16x32_bf16 v[32:35], v[178:181], v[194:197], 0
	v_mfma_f32_16x16x32_bf16 v[20:23], v[160:163], v[202:205], 0
	v_mfma_f32_16x16x32_bf16 v[16:19], v[178:181], v[202:205], 0
	v_mfma_f32_16x16x32_bf16 v[4:7], v[160:163], v[210:213], 0
	v_mfma_f32_16x16x32_bf16 v[0:3], v[178:181], v[210:213], 0
	v_mfma_f32_16x16x32_bf16 v[52:55], v[164:167], v[190:193], v[52:55]
	v_mfma_f32_16x16x32_bf16 v[48:51], v[182:185], v[190:193], v[48:51]
	v_mfma_f32_16x16x32_bf16 v[36:39], v[164:167], v[198:201], v[36:39]
	v_mfma_f32_16x16x32_bf16 v[32:35], v[182:185], v[198:201], v[32:35]
	v_mfma_f32_16x16x32_bf16 v[20:23], v[164:167], v[206:209], v[20:23]
	v_mfma_f32_16x16x32_bf16 v[16:19], v[182:185], v[206:209], v[16:19]
	v_mfma_f32_16x16x32_bf16 v[4:7], v[164:167], v[214:217], v[4:7]
	v_mfma_f32_16x16x32_bf16 v[0:3], v[182:185], v[214:217], v[0:3]
	s_setprio 0
	s_barrier
	s_add_i32 s78, 0, 0x18000
	s_add_i32 s79, 0, 0x1c000
	v_add_u32_e32 v140, s78, v172
	v_add_u32_e32 v182, s79, v172
	ds_read_b128 v[128:131], v140
	ds_read_b128 v[132:135], v140 offset:1024
	ds_read_b128 v[136:139], v140 offset:2048
	ds_read_b128 v[140:143], v140 offset:3072
	ds_read_b128 v[160:163], v182
	ds_read_b128 v[164:167], v182 offset:1024
	ds_read_b128 v[178:181], v182 offset:2048
	ds_read_b128 v[182:185], v182 offset:3072
	s_add_u32 s52, s52, 0x40000
	s_addc_u32 s53, s53, 0
	s_mov_b32 m0, s56
	ds_read_b128 v[186:189], v175 offset:32768
	ds_read_b128 v[190:193], v175 offset:33792
	ds_read_b128 v[194:197], v175 offset:34816
	ds_read_b128 v[198:201], v175 offset:35840
	ds_read_b128 v[202:205], v175 offset:36864
	ds_read_b128 v[206:209], v175 offset:37888
	ds_read_b128 v[210:213], v175 offset:38912
	ds_read_b128 v[214:217], v175 offset:39936
	global_load_lds_dwordx4 v144, s[52:53]
	s_mov_b32 m0, s57
	s_nop 0
	global_load_lds_dwordx4 v148, s[52:53]
	s_waitcnt vmcnt(8)
	s_waitcnt lgkmcnt(0)
	s_barrier
	s_setprio 1
	s_waitcnt lgkmcnt(0)
	v_mfma_f32_16x16x32_bf16 v[124:127], v[128:131], v[186:189], v[124:127]
	v_mfma_f32_16x16x32_bf16 v[120:123], v[136:139], v[186:189], v[120:123]
	v_mfma_f32_16x16x32_bf16 v[108:111], v[128:131], v[194:197], v[108:111]
	v_mfma_f32_16x16x32_bf16 v[104:107], v[136:139], v[194:197], v[104:107]
	v_mfma_f32_16x16x32_bf16 v[92:95], v[128:131], v[202:205], v[92:95]
	v_mfma_f32_16x16x32_bf16 v[88:91], v[136:139], v[202:205], v[88:91]
	v_mfma_f32_16x16x32_bf16 v[76:79], v[128:131], v[210:213], v[76:79]
	v_mfma_f32_16x16x32_bf16 v[72:75], v[136:139], v[210:213], v[72:75]
	v_mfma_f32_16x16x32_bf16 v[124:127], v[132:135], v[190:193], v[124:127]
	v_mfma_f32_16x16x32_bf16 v[120:123], v[140:143], v[190:193], v[120:123]
	v_mfma_f32_16x16x32_bf16 v[108:111], v[132:135], v[198:201], v[108:111]
	v_mfma_f32_16x16x32_bf16 v[104:107], v[140:143], v[198:201], v[104:107]
	v_mfma_f32_16x16x32_bf16 v[92:95], v[132:135], v[206:209], v[92:95]
	v_mfma_f32_16x16x32_bf16 v[88:91], v[140:143], v[206:209], v[88:91]
	v_mfma_f32_16x16x32_bf16 v[76:79], v[132:135], v[214:217], v[76:79]
	v_mfma_f32_16x16x32_bf16 v[72:75], v[140:143], v[214:217], v[72:75]
	s_setprio 0
	s_setprio 1
	v_mfma_f32_16x16x32_bf16 v[116:119], v[160:163], v[186:189], v[116:119]
	v_mfma_f32_16x16x32_bf16 v[112:115], v[178:181], v[186:189], v[112:115]
	v_mfma_f32_16x16x32_bf16 v[100:103], v[160:163], v[194:197], v[100:103]
	v_mfma_f32_16x16x32_bf16 v[96:99], v[178:181], v[194:197], v[96:99]
	v_mfma_f32_16x16x32_bf16 v[84:87], v[160:163], v[202:205], v[84:87]
	v_mfma_f32_16x16x32_bf16 v[80:83], v[178:181], v[202:205], v[80:83]
	v_mfma_f32_16x16x32_bf16 v[68:71], v[160:163], v[210:213], v[68:71]
	v_mfma_f32_16x16x32_bf16 v[64:67], v[178:181], v[210:213], v[64:67]
	v_mfma_f32_16x16x32_bf16 v[116:119], v[164:167], v[190:193], v[116:119]
	v_mfma_f32_16x16x32_bf16 v[112:115], v[182:185], v[190:193], v[112:115]
	v_mfma_f32_16x16x32_bf16 v[100:103], v[164:167], v[198:201], v[100:103]
	v_mfma_f32_16x16x32_bf16 v[96:99], v[182:185], v[198:201], v[96:99]
	v_mfma_f32_16x16x32_bf16 v[84:87], v[164:167], v[206:209], v[84:87]
	v_mfma_f32_16x16x32_bf16 v[80:83], v[182:185], v[206:209], v[80:83]
	v_mfma_f32_16x16x32_bf16 v[68:71], v[164:167], v[214:217], v[68:71]
	v_mfma_f32_16x16x32_bf16 v[64:67], v[182:185], v[214:217], v[64:67]
	s_setprio 0
	s_barrier
; #define PG8_STAGE(bufoff, gbase, voff) do { _Pragma("unroll") for (int _i = 0; _i < 2; ++_i) \
;         __builtin_amdgcn_global_load_lds((const unsigned*)((const char*)(gbase) + (voff)[_i]), (LAS unsigned*)(lds + (bufoff) + ldsw + _i * 8192), 16, 0, 0); } while (0)
; #define PG8_LDA(dst, b, h) do { _Pragma("unroll") for (int m = 0; m < 4; ++m) _Pragma("unroll") for (int k = 0; k < 2; ++k) dst[m][k] = *(const LAS bf16x8*)(lds + PG8_SA(b, h) + aoff + m * 2048 + k * 1024); } while (0)
; #define PG8_LDB(dst, b, h) do { _Pragma("unroll") for (int n = 0; n < 2; ++n) _Pragma("unroll") for (int k = 0; k < 2; ++k) dst[n][k] = *(const LAS bf16x8*)(lds + PG8_SB(b, h) + boff + n * 2048 + k * 1024); } while (0)
; #define PG8_MMA(ai, bj, At, Bt) do { __builtin_amdgcn_s_setprio(1); _Pragma("unroll") for (int m = 0; m < 4; ++m) _Pragma("unroll") for (int n = 0; n < 2; ++n) _Pragma("unroll") for (int k = 0; k < 2; ++k) \
;         acc[ai][bj][m][n] = __builtin_amdgcn_mfma_f32_16x16x32_bf16(Bt[n][k], At[m][k], acc[ai][bj][m][n], 0, 0, 0); __builtin_amdgcn_s_setprio(0); } while (0)
; #define PG8_WAIT_V(n) asm volatile("s_waitcnt vmcnt(" #n ")" ::: "memory")
; #define PG8_WAIT_L(n) asm volatile("s_waitcnt lgkmcnt(" #n ")" ::: "memory")
; #define PG8_BAR __builtin_amdgcn_s_barrier()
; #define PG8_SCHED __builtin_amdgcn_sched_barrier(0)
; template <class Epi>
; __device__ __forceinline__ void gemm_phase(LAS unsigned char* lds, const Gemm g, const StaticOrder& S, const Epi& E) {
;     ...
;             PG8_LDB(B0, 0, 0); PG8_LDB(B1, 0, 1); PG8_SCHED; PG8_LDA(At, 0, 0); PG8_STAGE(PG8_SA(1, 1), a1 + hstepA, voffA);
;     ...
;             PG8_LDA(At, 1, 1); PG8_STAGE(PG8_SB(1, 0), b3, voffB); PG8_STAGE(PG8_SB(1, 1), b3 + hstepB, voffB); PG8_STAGE(PG8_SA(1, 0), a3, voffA);
;             PG8_WAIT_V(8); PG8_WAIT_L(0); PG8_BAR; PG8_MMA(1, 0, At, B0); PG8_MMA(1, 1, At, B1); PG8_BAR; PG8_SCHED;
	s_add_i32 s52, s78, s54
	v_lshl_add_u64 v[168:169], v[168:169], 0, s[12:13]
	s_mov_b32 m0, s52
	ds_read_b128 v[186:189], v175 offset:49152
	ds_read_b128 v[190:193], v175 offset:50176
	ds_read_b128 v[194:197], v175 offset:51200
	ds_read_b128 v[198:201], v175 offset:52224
	ds_read_b128 v[202:205], v175 offset:53248
	ds_read_b128 v[206:209], v175 offset:54272
	ds_read_b128 v[210:213], v175 offset:55296
	ds_read_b128 v[214:217], v175 offset:56320
	global_load_lds_dwordx4 v[168:169], off
	s_add_i32 m0, s52, 0x2000
	s_add_u32 s42, s42, 0x40080
	v_lshl_add_u64 v[168:169], v[218:219], 0, s[12:13]
	s_addc_u32 s43, s43, 0
	s_add_i32 s52, s79, s54
	global_load_lds_dwordx4 v[168:169], off
	s_mov_b32 m0, s52
	s_nop 0
	global_load_lds_dwordx4 v146, s[42:43]
	s_add_i32 m0, s52, 0x2000
	s_nop 0
	global_load_lds_dwordx4 v150, s[42:43]
	v_lshl_add_u64 v[168:169], v[220:221], 0, s[12:13]
	s_mov_b32 m0, s65
	s_nop 0
	global_load_lds_dwordx4 v[168:169], off
	v_lshl_add_u64 v[168:169], v[222:223], 0, s[12:13]
	s_mov_b32 m0, s68
	s_nop 0
	global_load_lds_dwordx4 v[168:169], off
	s_waitcnt vmcnt(8)
	s_waitcnt lgkmcnt(0)
	s_barrier
	s_setprio 1
	s_waitcnt lgkmcnt(0)
	v_mfma_f32_16x16x32_bf16 v[60:63], v[128:131], v[186:189], v[60:63]
	v_mfma_f32_16x16x32_bf16 v[56:59], v[136:139], v[186:189], v[56:59]
	v_mfma_f32_16x16x32_bf16 v[44:47], v[128:131], v[194:197], v[44:47]
	v_mfma_f32_16x16x32_bf16 v[40:43], v[136:139], v[194:197], v[40:43]
	v_mfma_f32_16x16x32_bf16 v[28:31], v[128:131], v[202:205], v[28:31]
	v_mfma_f32_16x16x32_bf16 v[24:27], v[136:139], v[202:205], v[24:27]
	v_mfma_f32_16x16x32_bf16 v[12:15], v[128:131], v[210:213], v[12:15]
	v_mfma_f32_16x16x32_bf16 v[8:11], v[136:139], v[210:213], v[8:11]
	v_mfma_f32_16x16x32_bf16 v[60:63], v[132:135], v[190:193], v[60:63]
	v_mfma_f32_16x16x32_bf16 v[56:59], v[140:143], v[190:193], v[56:59]
	v_mfma_f32_16x16x32_bf16 v[44:47], v[132:135], v[198:201], v[44:47]
	v_mfma_f32_16x16x32_bf16 v[40:43], v[140:143], v[198:201], v[40:43]
	v_mfma_f32_16x16x32_bf16 v[28:31], v[132:135], v[206:209], v[28:31]
	v_mfma_f32_16x16x32_bf16 v[24:27], v[140:143], v[206:209], v[24:27]
	v_mfma_f32_16x16x32_bf16 v[12:15], v[132:135], v[214:217], v[12:15]
	v_mfma_f32_16x16x32_bf16 v[8:11], v[140:143], v[214:217], v[8:11]
	s_setprio 0
	s_setprio 1
	v_mfma_f32_16x16x32_bf16 v[52:55], v[160:163], v[186:189], v[52:55]
	v_mfma_f32_16x16x32_bf16 v[48:51], v[178:181], v[186:189], v[48:51]
	v_mfma_f32_16x16x32_bf16 v[36:39], v[160:163], v[194:197], v[36:39]
	v_mfma_f32_16x16x32_bf16 v[32:35], v[178:181], v[194:197], v[32:35]
	v_mfma_f32_16x16x32_bf16 v[20:23], v[160:163], v[202:205], v[20:23]
	v_mfma_f32_16x16x32_bf16 v[16:19], v[178:181], v[202:205], v[16:19]
	v_mfma_f32_16x16x32_bf16 v[4:7], v[160:163], v[210:213], v[4:7]
	v_mfma_f32_16x16x32_bf16 v[0:3], v[178:181], v[210:213], v[0:3]
	v_mfma_f32_16x16x32_bf16 v[52:55], v[164:167], v[190:193], v[52:55]
	v_mfma_f32_16x16x32_bf16 v[48:51], v[182:185], v[190:193], v[48:51]
	v_mfma_f32_16x16x32_bf16 v[36:39], v[164:167], v[198:201], v[36:39]
	v_mfma_f32_16x16x32_bf16 v[32:35], v[182:185], v[198:201], v[32:35]
	v_mfma_f32_16x16x32_bf16 v[20:23], v[164:167], v[206:209], v[20:23]
	v_mfma_f32_16x16x32_bf16 v[16:19], v[182:185], v[206:209], v[16:19]
	v_mfma_f32_16x16x32_bf16 v[4:7], v[164:167], v[214:217], v[4:7]
	v_mfma_f32_16x16x32_bf16 v[0:3], v[182:185], v[214:217], v[0:3]
	s_setprio 0
	s_barrier
	s_add_i32 s77, s77, 2
	s_add_u32 s38, s38, 0x100
	s_addc_u32 s39, s39, 0
	s_add_u32 s75, s75, 0x100
	s_addc_u32 s76, s76, 0
	s_cmp_gt_u32 s77, 13
.LBB0_457:
	ds_read_b128 v[128:131], v173
	ds_read_b128 v[132:135], v173 offset:1024
	ds_read_b128 v[136:139], v173 offset:2048
	ds_read_b128 v[140:143], v173 offset:3072
	ds_read_b128 v[160:163], v174
	ds_read_b128 v[164:167], v174 offset:1024
	ds_read_b128 v[178:181], v174 offset:2048
	ds_read_b128 v[182:185], v174 offset:3072
	s_add_u32 s42, s38, 0xfffc0080
	s_addc_u32 s43, s39, -1
	s_cmp_eq_u32 s77, 12
	s_cselect_b32 s53, s1, s43
	s_cselect_b32 s52, s23, s42
	s_cselect_b32 s43, s19, s76
	s_cselect_b32 s42, s74, s75
	s_add_i32 m0, s35, 0xc000
	ds_read_b128 v[186:189], v175
	ds_read_b128 v[190:193], v175 offset:1024
	ds_read_b128 v[194:197], v175 offset:2048
	ds_read_b128 v[198:201], v175 offset:3072
	ds_read_b128 v[202:205], v175 offset:4096
	ds_read_b128 v[206:209], v175 offset:5120
	ds_read_b128 v[210:213], v175 offset:6144
	ds_read_b128 v[214:217], v175 offset:7168
	global_load_lds_dwordx4 v152, s[38:39]
	s_add_i32 m0, s35, 0xe000
	s_nop 0
	global_load_lds_dwordx4 v154, s[38:39]
	s_waitcnt vmcnt(8)
	s_waitcnt lgkmcnt(0)
	s_barrier
; #define PG8_STAGE(bufoff, gbase, voff) do { _Pragma("unroll") for (int _i = 0; _i < 2; ++_i) \
;         __builtin_amdgcn_global_load_lds((const unsigned*)((const char*)(gbase) + (voff)[_i]), (LAS unsigned*)(lds + (bufoff) + ldsw + _i * 8192), 16, 0, 0); } while (0)
; #define PG8_LDA(dst, b, h) do { _Pragma("unroll") for (int m = 0; m < 4; ++m) _Pragma("unroll") for (int k = 0; k < 2; ++k) dst[m][k] = *(const LAS bf16x8*)(lds + PG8_SA(b, h) + aoff + m * 2048 + k * 1024); } while (0)
; #define PG8_MMA(ai, bj, At, Bt) do { __builtin_amdgcn_s_setprio(1); _Pragma("unroll") for (int m = 0; m < 4; ++m) _Pragma("unroll") for (int n = 0; n < 2; ++n) _Pragma("unroll") for (int k = 0; k < 2; ++k) \
;         acc[ai][bj][m][n] = __builtin_amdgcn_mfma_f32_16x16x32_bf16(Bt[n][k], At[m][k], acc[ai][bj][m][n], 0, 0, 0); __builtin_amdgcn_s_setprio(0); } while (0)
; #define PG8_WAIT_V(n) asm volatile("s_waitcnt vmcnt(" #n ")" ::: "memory")
; #define PG8_WAIT_L(n) asm volatile("s_waitcnt lgkmcnt(" #n ")" ::: "memory")
; #define PG8_BAR __builtin_amdgcn_s_barrier()
; #define PG8_SCHED __builtin_amdgcn_sched_barrier(0)
; template <class Epi>
; __device__ __forceinline__ void gemm_phase(LAS unsigned char* lds, const Gemm g, const StaticOrder& S, const Epi& E) {
;     ...
;             PG8_WAIT_V(8); PG8_WAIT_L(0); PG8_BAR; PG8_MMA(0, 0, At, B0); PG8_MMA(0, 1, At, B1); PG8_BAR; PG8_SCHED;
;             PG8_LDA(At, 0, 1); PG8_STAGE(PG8_SB(0, 0), b2, voffB); PG8_STAGE(PG8_SB(0, 1), b2 + hstepB, voffB); PG8_STAGE(PG8_SA(0, 0), a2, voffA);
;             PG8_WAIT_V(8); PG8_WAIT_L(0); PG8_BAR; PG8_MMA(1, 0, At, B0); PG8_MMA(1, 1, At, B1); PG8_BAR; PG8_SCHED;
	s_setprio 1
	s_waitcnt lgkmcnt(0)
	v_mfma_f32_16x16x32_bf16 v[124:127], v[128:131], v[186:189], v[124:127]
	v_mfma_f32_16x16x32_bf16 v[120:123], v[136:139], v[186:189], v[120:123]
	v_mfma_f32_16x16x32_bf16 v[108:111], v[128:131], v[194:197], v[108:111]
	v_mfma_f32_16x16x32_bf16 v[104:107], v[136:139], v[194:197], v[104:107]
	v_mfma_f32_16x16x32_bf16 v[92:95], v[128:131], v[202:205], v[92:95]
	v_mfma_f32_16x16x32_bf16 v[88:91], v[136:139], v[202:205], v[88:91]
	v_mfma_f32_16x16x32_bf16 v[76:79], v[128:131], v[210:213], v[76:79]
	v_mfma_f32_16x16x32_bf16 v[72:75], v[136:139], v[210:213], v[72:75]
	v_mfma_f32_16x16x32_bf16 v[124:127], v[132:135], v[190:193], v[124:127]
	v_mfma_f32_16x16x32_bf16 v[120:123], v[140:143], v[190:193], v[120:123]
	v_mfma_f32_16x16x32_bf16 v[108:111], v[132:135], v[198:201], v[108:111]
	v_mfma_f32_16x16x32_bf16 v[104:107], v[140:143], v[198:201], v[104:107]
	v_mfma_f32_16x16x32_bf16 v[92:95], v[132:135], v[206:209], v[92:95]
	v_mfma_f32_16x16x32_bf16 v[88:91], v[140:143], v[206:209], v[88:91]
	v_mfma_f32_16x16x32_bf16 v[76:79], v[132:135], v[214:217], v[76:79]
	v_mfma_f32_16x16x32_bf16 v[72:75], v[140:143], v[214:217], v[72:75]
	s_setprio 0
	s_setprio 1
	v_mfma_f32_16x16x32_bf16 v[116:119], v[160:163], v[186:189], v[116:119]
	v_mfma_f32_16x16x32_bf16 v[112:115], v[178:181], v[186:189], v[112:115]
	v_mfma_f32_16x16x32_bf16 v[100:103], v[160:163], v[194:197], v[100:103]
	v_mfma_f32_16x16x32_bf16 v[96:99], v[178:181], v[194:197], v[96:99]
	v_mfma_f32_16x16x32_bf16 v[84:87], v[160:163], v[202:205], v[84:87]
	v_mfma_f32_16x16x32_bf16 v[80:83], v[178:181], v[202:205], v[80:83]
	v_mfma_f32_16x16x32_bf16 v[68:71], v[160:163], v[210:213], v[68:71]
	v_mfma_f32_16x16x32_bf16 v[64:67], v[178:181], v[210:213], v[64:67]
	v_mfma_f32_16x16x32_bf16 v[116:119], v[164:167], v[190:193], v[116:119]
	v_mfma_f32_16x16x32_bf16 v[112:115], v[182:185], v[190:193], v[112:115]
	v_mfma_f32_16x16x32_bf16 v[100:103], v[164:167], v[198:201], v[100:103]
	v_mfma_f32_16x16x32_bf16 v[96:99], v[182:185], v[198:201], v[96:99]
	v_mfma_f32_16x16x32_bf16 v[84:87], v[164:167], v[206:209], v[84:87]
	v_mfma_f32_16x16x32_bf16 v[80:83], v[182:185], v[206:209], v[80:83]
	v_mfma_f32_16x16x32_bf16 v[68:71], v[164:167], v[214:217], v[68:71]
	v_mfma_f32_16x16x32_bf16 v[64:67], v[182:185], v[214:217], v[64:67]
	s_setprio 0
	s_barrier
	s_add_i32 s78, s72, s54
	v_lshl_add_u64 v[168:169], s[42:43], 0, v[146:147]
	s_mov_b32 m0, s78
	ds_read_b128 v[186:189], v175 offset:16384
	ds_read_b128 v[190:193], v175 offset:17408
	ds_read_b128 v[194:197], v175 offset:18432
	ds_read_b128 v[198:201], v175 offset:19456
	ds_read_b128 v[202:205], v175 offset:20480
	ds_read_b128 v[206:209], v175 offset:21504
	ds_read_b128 v[210:213], v175 offset:22528
	ds_read_b128 v[214:217], v175 offset:23552
	global_load_lds_dwordx4 v[168:169], off
	s_add_i32 m0, s78, 0x2000
	s_add_u32 s78, s42, 0x40000
	v_lshl_add_u64 v[218:219], s[42:43], 0, v[150:151]
	s_addc_u32 s79, s43, 0
	s_add_i32 s80, s73, s54
	global_load_lds_dwordx4 v[218:219], off
	s_mov_b32 m0, s80
	v_lshl_add_u64 v[222:223], s[52:53], 0, v[148:149]
	global_load_lds_dwordx4 v146, s[78:79]
	s_add_i32 m0, s80, 0x2000
	s_nop 0
	global_load_lds_dwordx4 v150, s[78:79]
	v_lshl_add_u64 v[220:221], s[52:53], 0, v[144:145]
	s_mov_b32 m0, s35
	s_nop 0
	global_load_lds_dwordx4 v[220:221], off
	s_mov_b32 m0, s55
	s_nop 0
	global_load_lds_dwordx4 v[222:223], off
	s_waitcnt vmcnt(8)
	s_waitcnt lgkmcnt(0)
	s_barrier
	s_setprio 1
	s_waitcnt lgkmcnt(0)
	v_mfma_f32_16x16x32_bf16 v[60:63], v[128:131], v[186:189], v[60:63]
	v_mfma_f32_16x16x32_bf16 v[56:59], v[136:139], v[186:189], v[56:59]
	v_mfma_f32_16x16x32_bf16 v[44:47], v[128:131], v[194:197], v[44:47]
	v_mfma_f32_16x16x32_bf16 v[40:43], v[136:139], v[194:197], v[40:43]
	v_mfma_f32_16x16x32_bf16 v[28:31], v[128:131], v[202:205], v[28:31]
	v_mfma_f32_16x16x32_bf16 v[24:27], v[136:139], v[202:205], v[24:27]
	v_mfma_f32_16x16x32_bf16 v[12:15], v[128:131], v[210:213], v[12:15]
	v_mfma_f32_16x16x32_bf16 v[8:11], v[136:139], v[210:213], v[8:11]
	v_mfma_f32_16x16x32_bf16 v[60:63], v[132:135], v[190:193], v[60:63]
	v_mfma_f32_16x16x32_bf16 v[56:59], v[140:143], v[190:193], v[56:59]
	v_mfma_f32_16x16x32_bf16 v[44:47], v[132:135], v[198:201], v[44:47]
	v_mfma_f32_16x16x32_bf16 v[40:43], v[140:143], v[198:201], v[40:43]
	v_mfma_f32_16x16x32_bf16 v[28:31], v[132:135], v[206:209], v[28:31]
	v_mfma_f32_16x16x32_bf16 v[24:27], v[140:143], v[206:209], v[24:27]
	v_mfma_f32_16x16x32_bf16 v[12:15], v[132:135], v[214:217], v[12:15]
	v_mfma_f32_16x16x32_bf16 v[8:11], v[140:143], v[214:217], v[8:11]
	s_setprio 0
	s_setprio 1
	v_mfma_f32_16x16x32_bf16 v[52:55], v[160:163], v[186:189], v[52:55]
	v_mfma_f32_16x16x32_bf16 v[48:51], v[178:181], v[186:189], v[48:51]
	v_mfma_f32_16x16x32_bf16 v[36:39], v[160:163], v[194:197], v[36:39]
	v_mfma_f32_16x16x32_bf16 v[32:35], v[178:181], v[194:197], v[32:35]
	v_mfma_f32_16x16x32_bf16 v[20:23], v[160:163], v[202:205], v[20:23]
	v_mfma_f32_16x16x32_bf16 v[16:19], v[178:181], v[202:205], v[16:19]
	v_mfma_f32_16x16x32_bf16 v[4:7], v[160:163], v[210:213], v[4:7]
	v_mfma_f32_16x16x32_bf16 v[0:3], v[178:181], v[210:213], v[0:3]
	v_mfma_f32_16x16x32_bf16 v[52:55], v[164:167], v[190:193], v[52:55]
	v_mfma_f32_16x16x32_bf16 v[48:51], v[182:185], v[190:193], v[48:51]
	v_mfma_f32_16x16x32_bf16 v[36:39], v[164:167], v[198:201], v[36:39]
	v_mfma_f32_16x16x32_bf16 v[32:35], v[182:185], v[198:201], v[32:35]
	v_mfma_f32_16x16x32_bf16 v[20:23], v[164:167], v[206:209], v[20:23]
	v_mfma_f32_16x16x32_bf16 v[16:19], v[182:185], v[206:209], v[16:19]
	v_mfma_f32_16x16x32_bf16 v[4:7], v[164:167], v[214:217], v[4:7]
	v_mfma_f32_16x16x32_bf16 v[0:3], v[182:185], v[214:217], v[0:3]
	s_setprio 0
	s_barrier
; #define PG8_STAGE(bufoff, gbase, voff) do { _Pragma("unroll") for (int _i = 0; _i < 2; ++_i) \
;         __builtin_amdgcn_global_load_lds((const unsigned*)((const char*)(gbase) + (voff)[_i]), (LAS unsigned*)(lds + (bufoff) + ldsw + _i * 8192), 16, 0, 0); } while (0)
; #define PG8_LDA(dst, b, h) do { _Pragma("unroll") for (int m = 0; m < 4; ++m) _Pragma("unroll") for (int k = 0; k < 2; ++k) dst[m][k] = *(const LAS bf16x8*)(lds + PG8_SA(b, h) + aoff + m * 2048 + k * 1024); } while (0)
; #define PG8_LDB(dst, b, h) do { _Pragma("unroll") for (int n = 0; n < 2; ++n) _Pragma("unroll") for (int k = 0; k < 2; ++k) dst[n][k] = *(const LAS bf16x8*)(lds + PG8_SB(b, h) + boff + n * 2048 + k * 1024); } while (0)
; #define PG8_MMA(ai, bj, At, Bt) do { __builtin_amdgcn_s_setprio(1); _Pragma("unroll") for (int m = 0; m < 4; ++m) _Pragma("unroll") for (int n = 0; n < 2; ++n) _Pragma("unroll") for (int k = 0; k < 2; ++k) \
;         acc[ai][bj][m][n] = __builtin_amdgcn_mfma_f32_16x16x32_bf16(Bt[n][k], At[m][k], acc[ai][bj][m][n], 0, 0, 0); __builtin_amdgcn_s_setprio(0); } while (0)
; #define PG8_WAIT_V(n) asm volatile("s_waitcnt vmcnt(" #n ")" ::: "memory")
; #define PG8_WAIT_L(n) asm volatile("s_waitcnt lgkmcnt(" #n ")" ::: "memory")
; #define PG8_BAR __builtin_amdgcn_s_barrier()
; #define PG8_SCHED __builtin_amdgcn_sched_barrier(0)
; template <class Epi>
; __device__ __forceinline__ void gemm_phase(LAS unsigned char* lds, const Gemm g, const StaticOrder& S, const Epi& E) {
;     ...
;             PG8_WAIT_V(8); PG8_WAIT_L(0); PG8_BAR; PG8_MMA(1, 0, At, B0); PG8_MMA(1, 1, At, B1); PG8_BAR; PG8_SCHED;
;             PG8_LDB(B0, 1, 0); PG8_LDB(B1, 1, 1); PG8_SCHED; PG8_LDA(At, 1, 0); PG8_STAGE(PG8_SA(0, 1), a2 + hstepA, voffA);
;             PG8_WAIT_V(8); PG8_WAIT_L(0); PG8_BAR; PG8_MMA(0, 0, At, B0); PG8_MMA(0, 1, At, B1); PG8_BAR; PG8_SCHED;
;             PG8_LDA(At, 1, 1); PG8_STAGE(PG8_SB(1, 0), b3, voffB); PG8_STAGE(PG8_SB(1, 1), b3 + hstepB, voffB); PG8_STAGE(PG8_SA(1, 0), a3, voffA);
;             PG8_WAIT_V(8); PG8_WAIT_L(0); PG8_BAR; PG8_MMA(1, 0, At, B0); PG8_MMA(1, 1, At, B1); PG8_BAR; PG8_SCHED;
	s_add_i32 s78, 0, 0x18000
	s_add_i32 s79, 0, 0x1c000
	v_add_u32_e32 v140, s78, v172
	v_add_u32_e32 v182, s79, v172
	ds_read_b128 v[128:131], v140
	ds_read_b128 v[132:135], v140 offset:1024
	ds_read_b128 v[136:139], v140 offset:2048
	ds_read_b128 v[140:143], v140 offset:3072
	ds_read_b128 v[160:163], v182
	ds_read_b128 v[164:167], v182 offset:1024
	ds_read_b128 v[178:181], v182 offset:2048
	ds_read_b128 v[182:185], v182 offset:3072
	s_add_u32 s52, s52, 0x40000
	s_addc_u32 s53, s53, 0
	s_mov_b32 m0, s56
	ds_read_b128 v[186:189], v175 offset:32768
	ds_read_b128 v[190:193], v175 offset:33792
	ds_read_b128 v[194:197], v175 offset:34816
	ds_read_b128 v[198:201], v175 offset:35840
	ds_read_b128 v[202:205], v175 offset:36864
	ds_read_b128 v[206:209], v175 offset:37888
	ds_read_b128 v[210:213], v175 offset:38912
	ds_read_b128 v[214:217], v175 offset:39936
	global_load_lds_dwordx4 v144, s[52:53]
	s_mov_b32 m0, s57
	s_nop 0
	global_load_lds_dwordx4 v148, s[52:53]
	s_waitcnt vmcnt(8)
	s_waitcnt lgkmcnt(0)
	s_barrier
	s_setprio 1
	s_waitcnt lgkmcnt(0)
	v_mfma_f32_16x16x32_bf16 v[124:127], v[128:131], v[186:189], v[124:127]
	v_mfma_f32_16x16x32_bf16 v[120:123], v[136:139], v[186:189], v[120:123]
	v_mfma_f32_16x16x32_bf16 v[108:111], v[128:131], v[194:197], v[108:111]
	v_mfma_f32_16x16x32_bf16 v[104:107], v[136:139], v[194:197], v[104:107]
	v_mfma_f32_16x16x32_bf16 v[92:95], v[128:131], v[202:205], v[92:95]
	v_mfma_f32_16x16x32_bf16 v[88:91], v[136:139], v[202:205], v[88:91]
	v_mfma_f32_16x16x32_bf16 v[76:79], v[128:131], v[210:213], v[76:79]
	v_mfma_f32_16x16x32_bf16 v[72:75], v[136:139], v[210:213], v[72:75]
	v_mfma_f32_16x16x32_bf16 v[124:127], v[132:135], v[190:193], v[124:127]
	v_mfma_f32_16x16x32_bf16 v[120:123], v[140:143], v[190:193], v[120:123]
	v_mfma_f32_16x16x32_bf16 v[108:111], v[132:135], v[198:201], v[108:111]
	v_mfma_f32_16x16x32_bf16 v[104:107], v[140:143], v[198:201], v[104:107]
	v_mfma_f32_16x16x32_bf16 v[92:95], v[132:135], v[206:209], v[92:95]
	v_mfma_f32_16x16x32_bf16 v[88:91], v[140:143], v[206:209], v[88:91]
	v_mfma_f32_16x16x32_bf16 v[76:79], v[132:135], v[214:217], v[76:79]
	v_mfma_f32_16x16x32_bf16 v[72:75], v[140:143], v[214:217], v[72:75]
	s_setprio 0
	s_setprio 1
	v_mfma_f32_16x16x32_bf16 v[116:119], v[160:163], v[186:189], v[116:119]
	v_mfma_f32_16x16x32_bf16 v[112:115], v[178:181], v[186:189], v[112:115]
	v_mfma_f32_16x16x32_bf16 v[100:103], v[160:163], v[194:197], v[100:103]
	v_mfma_f32_16x16x32_bf16 v[96:99], v[178:181], v[194:197], v[96:99]
	v_mfma_f32_16x16x32_bf16 v[84:87], v[160:163], v[202:205], v[84:87]
	v_mfma_f32_16x16x32_bf16 v[80:83], v[178:181], v[202:205], v[80:83]
	v_mfma_f32_16x16x32_bf16 v[68:71], v[160:163], v[210:213], v[68:71]
	v_mfma_f32_16x16x32_bf16 v[64:67], v[178:181], v[210:213], v[64:67]
	v_mfma_f32_16x16x32_bf16 v[116:119], v[164:167], v[190:193], v[116:119]
	v_mfma_f32_16x16x32_bf16 v[112:115], v[182:185], v[190:193], v[112:115]
	v_mfma_f32_16x16x32_bf16 v[100:103], v[164:167], v[198:201], v[100:103]
	v_mfma_f32_16x16x32_bf16 v[96:99], v[182:185], v[198:201], v[96:99]
	v_mfma_f32_16x16x32_bf16 v[84:87], v[164:167], v[206:209], v[84:87]
	v_mfma_f32_16x16x32_bf16 v[80:83], v[182:185], v[206:209], v[80:83]
	v_mfma_f32_16x16x32_bf16 v[68:71], v[164:167], v[214:217], v[68:71]
	v_mfma_f32_16x16x32_bf16 v[64:67], v[182:185], v[214:217], v[64:67]
	s_setprio 0
	s_barrier
	s_add_i32 s52, s78, s54
	v_lshl_add_u64 v[168:169], v[168:169], 0, s[12:13]
	s_mov_b32 m0, s52
	ds_read_b128 v[186:189], v175 offset:49152
	ds_read_b128 v[190:193], v175 offset:50176
	ds_read_b128 v[194:197], v175 offset:51200
	ds_read_b128 v[198:201], v175 offset:52224
	ds_read_b128 v[202:205], v175 offset:53248
	ds_read_b128 v[206:209], v175 offset:54272
	ds_read_b128 v[210:213], v175 offset:55296
	ds_read_b128 v[214:217], v175 offset:56320
	global_load_lds_dwordx4 v[168:169], off
	s_add_i32 m0, s52, 0x2000
	s_add_u32 s42, s42, 0x40080
	v_lshl_add_u64 v[168:169], v[218:219], 0, s[12:13]
	s_addc_u32 s43, s43, 0
	s_add_i32 s52, s79, s54
	global_load_lds_dwordx4 v[168:169], off
	s_mov_b32 m0, s52
	s_nop 0
	global_load_lds_dwordx4 v146, s[42:43]
	s_add_i32 m0, s52, 0x2000
	s_nop 0
	global_load_lds_dwordx4 v150, s[42:43]
	v_lshl_add_u64 v[168:169], v[220:221], 0, s[12:13]
	s_mov_b32 m0, s65
	s_nop 0
	global_load_lds_dwordx4 v[168:169], off
	v_lshl_add_u64 v[168:169], v[222:223], 0, s[12:13]
	s_mov_b32 m0, s68
	s_nop 0
	global_load_lds_dwordx4 v[168:169], off
	s_waitcnt vmcnt(8)
	s_waitcnt lgkmcnt(0)
	s_barrier
	s_setprio 1
	s_waitcnt lgkmcnt(0)
	v_mfma_f32_16x16x32_bf16 v[60:63], v[128:131], v[186:189], v[60:63]
	v_mfma_f32_16x16x32_bf16 v[56:59], v[136:139], v[186:189], v[56:59]
	v_mfma_f32_16x16x32_bf16 v[44:47], v[128:131], v[194:197], v[44:47]
	v_mfma_f32_16x16x32_bf16 v[40:43], v[136:139], v[194:197], v[40:43]
	v_mfma_f32_16x16x32_bf16 v[28:31], v[128:131], v[202:205], v[28:31]
	v_mfma_f32_16x16x32_bf16 v[24:27], v[136:139], v[202:205], v[24:27]
	v_mfma_f32_16x16x32_bf16 v[12:15], v[128:131], v[210:213], v[12:15]
	v_mfma_f32_16x16x32_bf16 v[8:11], v[136:139], v[210:213], v[8:11]
	v_mfma_f32_16x16x32_bf16 v[60:63], v[132:135], v[190:193], v[60:63]
	v_mfma_f32_16x16x32_bf16 v[56:59], v[140:143], v[190:193], v[56:59]
	v_mfma_f32_16x16x32_bf16 v[44:47], v[132:135], v[198:201], v[44:47]
	v_mfma_f32_16x16x32_bf16 v[40:43], v[140:143], v[198:201], v[40:43]
	v_mfma_f32_16x16x32_bf16 v[28:31], v[132:135], v[206:209], v[28:31]
	v_mfma_f32_16x16x32_bf16 v[24:27], v[140:143], v[206:209], v[24:27]
	v_mfma_f32_16x16x32_bf16 v[12:15], v[132:135], v[214:217], v[12:15]
	v_mfma_f32_16x16x32_bf16 v[8:11], v[140:143], v[214:217], v[8:11]
	s_setprio 0
	s_setprio 1
	v_mfma_f32_16x16x32_bf16 v[52:55], v[160:163], v[186:189], v[52:55]
	v_mfma_f32_16x16x32_bf16 v[48:51], v[178:181], v[186:189], v[48:51]
	v_mfma_f32_16x16x32_bf16 v[36:39], v[160:163], v[194:197], v[36:39]
	v_mfma_f32_16x16x32_bf16 v[32:35], v[178:181], v[194:197], v[32:35]
	v_mfma_f32_16x16x32_bf16 v[20:23], v[160:163], v[202:205], v[20:23]
	v_mfma_f32_16x16x32_bf16 v[16:19], v[178:181], v[202:205], v[16:19]
	v_mfma_f32_16x16x32_bf16 v[4:7], v[160:163], v[210:213], v[4:7]
	v_mfma_f32_16x16x32_bf16 v[0:3], v[178:181], v[210:213], v[0:3]
	v_mfma_f32_16x16x32_bf16 v[52:55], v[164:167], v[190:193], v[52:55]
	v_mfma_f32_16x16x32_bf16 v[48:51], v[182:185], v[190:193], v[48:51]
	v_mfma_f32_16x16x32_bf16 v[36:39], v[164:167], v[198:201], v[36:39]
	v_mfma_f32_16x16x32_bf16 v[32:35], v[182:185], v[198:201], v[32:35]
	v_mfma_f32_16x16x32_bf16 v[20:23], v[164:167], v[206:209], v[20:23]
	v_mfma_f32_16x16x32_bf16 v[16:19], v[182:185], v[206:209], v[16:19]
	v_mfma_f32_16x16x32_bf16 v[4:7], v[164:167], v[214:217], v[4:7]
	v_mfma_f32_16x16x32_bf16 v[0:3], v[182:185], v[214:217], v[0:3]
	s_setprio 0
	s_barrier
	s_add_i32 s77, s77, 2
	s_add_u32 s38, s38, 0x100
	s_addc_u32 s39, s39, 0
	s_add_u32 s75, s75, 0x100
	s_addc_u32 s76, s76, 0
	s_cmp_gt_u32 s77, 13
	s_cbranch_scc0 .LBB0_457
	s_and_b64 vcc, exec, s[14:15]
	s_cbranch_vccz .LBB0_460
	s_barrier

; #define PG8_STAGE(bufoff, gbase, voff) do { _Pragma("unroll") for (int _i = 0; _i < 2; ++_i) \
;         __builtin_amdgcn_global_load_lds((const unsigned*)((const char*)(gbase) + (voff)[_i]), (LAS unsigned*)(lds + (bufoff) + ldsw + _i * 8192), 16, 0, 0); } while (0)
; #define PG8_WAIT_V(n) asm volatile("s_waitcnt vmcnt(" #n ")" ::: "memory")
; #define PG8_BAR __builtin_amdgcn_s_barrier()
; template <class Epi>
; __device__ __forceinline__ void gemm_phase(LAS unsigned char* lds, const Gemm g, const StaticOrder& S, const Epi& E) {
;     ...
;     for (int i = 0; i < 2; ++i) { int R, C; stage_rc(tid * 16 + i * 8192, R, C); const int Rb = (R & ~31) + perm32(R & 31);
;         voffA[i] = (unsigned)(R * g.lda + C) * 2u; voffB[i] = (unsigned)(Rb * g.ldb + C) * 2u; }
;     const size_t kstep = (size_t)(BK * 2);
;     const size_t hstepA = (size_t)HALF * g.lda * 2, hstepB = (size_t)HALF * g.ldb * 2;
;     const size_t tstepA = 2 * hstepA, tstepB = 2 * hstepB;
;     const unsigned ldsw = (unsigned)wid * 1024u;
;     const int aoff = lds_byte(wr * 64 + fr, fq * 8), boff = lds_byte(wc * 32 + fr, fq * 8);
;     ...
;     PG8_STAGE(PG8_SB(0, 0), cB, voffB); PG8_STAGE(PG8_SB(0, 1), cB + hstepB, voffB); PG8_STAGE(PG8_SA(0, 0), cA, voffA); PG8_STAGE(PG8_SA(0, 1), cA + hstepA, voffA);
;     if (wr == 1) PG8_BAR;
;     PG8_WAIT_V(2); PG8_BAR;
;     PG8_STAGE(PG8_SB(1, 0), cB + kstep, voffB); PG8_STAGE(PG8_SA(1, 0), cA + kstep, voffA); PG8_STAGE(PG8_SB(1, 1), cB + hstepB + kstep, voffB);
;     PG8_WAIT_V(6); PG8_BAR;
.LBB0_540:
	s_add_u32 s22, s50, 0x20000
	s_mov_b64 s[30:31], 0x80
	s_addc_u32 s23, s51, 0
	s_lshl_b32 s65, s4, 6
	s_lshl_b32 s1, s4, 13
	s_lshl_b32 s4, s5, 5
	s_add_i32 m0, s43, 0x18000
	v_lshl_add_u64 v[6:7], v[6:7], 0, s[30:31]
	s_and_b32 s78, s4, 0x60
	s_waitcnt vmcnt(2)
	s_barrier
	global_load_lds_dwordx4 v[6:7], off
	v_lshl_add_u64 v[4:5], v[4:5], 0, s[30:31]
	s_add_i32 m0, s43, 0x1a000
	s_add_i32 s79, s43, 0x8000
	s_add_i32 s80, s43, 0xa000
	global_load_lds_dwordx4 v[4:5], off
	v_lshl_add_u64 v[0:1], v[0:1], 0, s[30:31]
	s_mov_b32 m0, s79
	s_add_u32 s4, s10, 0x40080
	global_load_lds_dwordx4 v[0:1], off
	v_lshl_add_u64 v[0:1], v[2:3], 0, s[30:31]
	s_mov_b32 m0, s80
	s_addc_u32 s5, s11, 0
	global_load_lds_dwordx4 v[0:1], off
	s_add_i32 m0, s43, 0x1c000
	global_load_lds_dwordx4 v130, s[4:5]
	s_add_i32 m0, s43, 0x1e000
	v_lshlrev_b32_e32 v2, 11, v10
	global_load_lds_dwordx4 v134, s[4:5]
	v_lshlrev_b32_e32 v1, 2, v151
	v_lshl_or_b32 v0, v151, 6, v154
	v_and_b32_e32 v1, 32, v1
	v_bitop3_b32 v0, v0, s1, v1 bitop3:0xde
	v_lshlrev_b32_e32 v1, 8, v176
	v_and_b32_e32 v1, 0x38000, v1
	v_or3_b32 v1, v8, v1, v2
	v_add_u32_e32 v138, v1, v9
	v_lshlrev_b32_e32 v1, 4, v11
	s_waitcnt vmcnt(6)
	s_cmpk_lt_u32 s12, 0x100
	v_and_b32_e32 v1, 0x78000, v1
	v_lshl_or_b32 v161, s78, 7, v155
	s_cselect_b64 s[34:35], -1, 0
	v_or3_b32 v1, v8, v1, v2
	s_add_i32 s85, 0, 0x10000
	s_add_i32 s86, 0, 0x14000
	s_ashr_i32 s81, s74, 31
	s_mov_b32 s82, s74
	s_ashr_i32 s83, s2, 31
	v_mov_b32_e32 v139, v137
	v_add_u32_e32 v140, v1, v9
	v_mov_b32_e32 v141, v137
	v_mov_b64_e32 v[142:143], 0xb00
	v_mov_b64_e32 v[144:145], 0xaff
	s_movk_i32 s84, 0x161
	v_add_u32_e32 v162, s85, v161
	v_add_u32_e32 v163, s86, v161
	v_add_u32_e32 v164, 0, v0
	v_mov_b32_e32 v165, 0x358637bd
	s_movk_i32 s87, 0x1600
	s_movk_i32 s88, 0xb00
	s_mov_b32 s38, 0xbf38aa3b
	s_mov_b32 s42, 0x3e6d3388
	s_mov_b32 s52, 0x3f07dc22
	s_mov_b32 s54, 0xbf3a00e3
	s_mov_b32 s56, 0x3f35f0e3
	s_mov_b32 s62, 0xbe11a98e
	s_mov_b32 s64, 0x3e027906
	s_barrier
	s_branch .LBB0_543

; #define PG8_STAGE(bufoff, gbase, voff) do { _Pragma("unroll") for (int _i = 0; _i < 2; ++_i) \
;         __builtin_amdgcn_global_load_lds((const unsigned*)((const char*)(gbase) + (voff)[_i]), (LAS unsigned*)(lds + (bufoff) + ldsw + _i * 8192), 16, 0, 0); } while (0)
; #define PG8_LDA(dst, b, h) do { _Pragma("unroll") for (int m = 0; m < 4; ++m) _Pragma("unroll") for (int k = 0; k < 2; ++k) dst[m][k] = *(const LAS bf16x8*)(lds + PG8_SA(b, h) + aoff + m * 2048 + k * 1024); } while (0)
; #define PG8_LDB(dst, b, h) do { _Pragma("unroll") for (int n = 0; n < 2; ++n) _Pragma("unroll") for (int k = 0; k < 2; ++k) dst[n][k] = *(const LAS bf16x8*)(lds + PG8_SB(b, h) + boff + n * 2048 + k * 1024); } while (0)
; #define PG8_MMA(ai, bj, At, Bt) do { __builtin_amdgcn_s_setprio(1); _Pragma("unroll") for (int m = 0; m < 4; ++m) _Pragma("unroll") for (int n = 0; n < 2; ++n) _Pragma("unroll") for (int k = 0; k < 2; ++k) \
;         acc[ai][bj][m][n] = __builtin_amdgcn_mfma_f32_16x16x32_bf16(Bt[n][k], At[m][k], acc[ai][bj][m][n], 0, 0, 0); __builtin_amdgcn_s_setprio(0); } while (0)
; #define PG8_WAIT_V(n) asm volatile("s_waitcnt vmcnt(" #n ")" ::: "memory")
; #define PG8_WAIT_L(n) asm volatile("s_waitcnt lgkmcnt(" #n ")" ::: "memory")
; #define PG8_BAR __builtin_amdgcn_s_barrier()
; #define PG8_SCHED __builtin_amdgcn_sched_barrier(0)
; template <class Epi>
; __device__ __forceinline__ void gemm_phase(LAS unsigned char* lds, const Gemm g, const StaticOrder& S, const Epi& E) {
;     ...
;             PG8_LDB(B0, 0, 0); PG8_LDB(B1, 0, 1); PG8_SCHED; PG8_LDA(At, 0, 0); PG8_STAGE(PG8_SA(1, 1), a1 + hstepA, voffA);
;             PG8_WAIT_V(8); PG8_WAIT_L(0); PG8_BAR; PG8_MMA(0, 0, At, B0); PG8_MMA(0, 1, At, B1); PG8_BAR; PG8_SCHED;
;             PG8_LDA(At, 0, 1); PG8_STAGE(PG8_SB(0, 0), b2, voffB); PG8_STAGE(PG8_SB(0, 1), b2 + hstepB, voffB); PG8_STAGE(PG8_SA(0, 0), a2, voffA);
;             PG8_WAIT_V(8); PG8_WAIT_L(0); PG8_BAR; PG8_MMA(1, 0, At, B0); PG8_MMA(1, 1, At, B1); PG8_BAR; PG8_SCHED;
.LBB0_545:
	s_ashr_i32 s71, s70, 31
	s_lshl_b64 s[12:13], s[70:71], 19
	s_add_u32 s72, s24, s12
	s_addc_u32 s73, s25, s13
	s_and_b64 s[12:13], s[4:5], exec
	s_cselect_b32 s1, s73, s9
	s_cselect_b32 s7, s72, s8
	s_ashr_i32 s69, s68, 31
	s_lshl_b64 s[12:13], s[68:69], 19
	s_add_u32 s74, s3, s12
	s_addc_u32 s75, s33, s13
	s_and_b64 s[12:13], s[4:5], exec
	s_cselect_b32 s69, s75, s11
	s_cselect_b32 s71, s74, s10
	s_add_u32 s8, s8, 0x40080
	s_addc_u32 s9, s9, 0
	s_add_u32 s76, s10, 0x100
	s_addc_u32 s77, s11, 0
	s_mov_b32 s89, -2
	s_nop 0
	v_lshl_add_u32 v248, s6, 8, v151
	v_add_u32_e32 v248, s65, v248
	v_ashrrev_i32_e32 v249, 31, v248
	v_lshl_add_u64 v[248:249], v[248:249], 2, s[22:23]
	global_load_dword v240, v[248:249], off
	global_load_dword v241, v[248:249], off offset:64
	global_load_dword v242, v[248:249], off offset:128
	global_load_dword v243, v[248:249], off offset:192
	global_load_dword v244, v[248:249], off offset:512
	global_load_dword v245, v[248:249], off offset:576
	global_load_dword v246, v[248:249], off offset:640
	global_load_dword v247, v[248:249], off offset:704
	ds_read_b128 v[146:149], v162
	ds_read_b128 v[166:169], v162 offset:1024
	ds_read_b128 v[170:173], v162 offset:2048
	ds_read_b128 v[178:181], v162 offset:3072
	ds_read_b128 v[182:185], v163
	ds_read_b128 v[186:189], v163 offset:1024
	ds_read_b128 v[190:193], v163 offset:2048
	ds_read_b128 v[194:197], v163 offset:3072
	s_add_u32 s10, s8, 0xfffc0080
	s_addc_u32 s11, s9, -1
	s_cmp_eq_u32 s89, 12
	s_cselect_b32 s13, s1, s11
	s_cselect_b32 s12, s7, s10
	s_cselect_b32 s11, s69, s77
	s_cselect_b32 s10, s71, s76
	s_add_i32 m0, s43, 0xc000
	ds_read_b128 v[198:201], v164
	ds_read_b128 v[202:205], v164 offset:1024
	ds_read_b128 v[206:209], v164 offset:2048
	ds_read_b128 v[210:213], v164 offset:3072
	ds_read_b128 v[214:217], v164 offset:4096
	ds_read_b128 v[218:221], v164 offset:5120
	ds_read_b128 v[226:229], v164 offset:6144
	ds_read_b128 v[230:233], v164 offset:7168
	global_load_lds_dwordx4 v138, s[8:9]
	s_add_i32 m0, s43, 0xe000
	s_nop 0
	global_load_lds_dwordx4 v140, s[8:9]
	s_waitcnt vmcnt(8)
	s_waitcnt lgkmcnt(0)
	s_barrier
	s_setprio 1
	s_waitcnt lgkmcnt(0)
	v_mfma_f32_16x16x32_bf16 v[124:127], v[146:149], v[198:201], 0
	v_mfma_f32_16x16x32_bf16 v[120:123], v[170:173], v[198:201], 0
	v_mfma_f32_16x16x32_bf16 v[112:115], v[146:149], v[206:209], 0
	v_mfma_f32_16x16x32_bf16 v[104:107], v[170:173], v[206:209], 0
	v_mfma_f32_16x16x32_bf16 v[100:103], v[146:149], v[214:217], 0
	v_mfma_f32_16x16x32_bf16 v[92:95], v[170:173], v[214:217], 0
	v_mfma_f32_16x16x32_bf16 v[84:87], v[146:149], v[226:229], 0
	v_mfma_f32_16x16x32_bf16 v[76:79], v[170:173], v[226:229], 0
	v_mfma_f32_16x16x32_bf16 v[124:127], v[166:169], v[202:205], v[124:127]
	v_mfma_f32_16x16x32_bf16 v[120:123], v[178:181], v[202:205], v[120:123]
	v_mfma_f32_16x16x32_bf16 v[112:115], v[166:169], v[210:213], v[112:115]
	v_mfma_f32_16x16x32_bf16 v[104:107], v[178:181], v[210:213], v[104:107]
	v_mfma_f32_16x16x32_bf16 v[100:103], v[166:169], v[218:221], v[100:103]
	v_mfma_f32_16x16x32_bf16 v[92:95], v[178:181], v[218:221], v[92:95]
	v_mfma_f32_16x16x32_bf16 v[84:87], v[166:169], v[230:233], v[84:87]
	v_mfma_f32_16x16x32_bf16 v[76:79], v[178:181], v[230:233], v[76:79]
	s_setprio 0
	s_setprio 1
	v_mfma_f32_16x16x32_bf16 v[116:119], v[182:185], v[198:201], 0
	v_mfma_f32_16x16x32_bf16 v[108:111], v[190:193], v[198:201], 0
	v_mfma_f32_16x16x32_bf16 v[96:99], v[182:185], v[206:209], 0
	v_mfma_f32_16x16x32_bf16 v[88:91], v[190:193], v[206:209], 0
	v_mfma_f32_16x16x32_bf16 v[80:83], v[182:185], v[214:217], 0
	v_mfma_f32_16x16x32_bf16 v[72:75], v[190:193], v[214:217], 0
	v_mfma_f32_16x16x32_bf16 v[68:71], v[182:185], v[226:229], 0
	v_mfma_f32_16x16x32_bf16 v[64:67], v[190:193], v[226:229], 0
	v_mfma_f32_16x16x32_bf16 v[116:119], v[186:189], v[202:205], v[116:119]
	v_mfma_f32_16x16x32_bf16 v[108:111], v[194:197], v[202:205], v[108:111]
	v_mfma_f32_16x16x32_bf16 v[96:99], v[186:189], v[210:213], v[96:99]
	v_mfma_f32_16x16x32_bf16 v[88:91], v[194:197], v[210:213], v[88:91]
	v_mfma_f32_16x16x32_bf16 v[80:83], v[186:189], v[218:221], v[80:83]
	v_mfma_f32_16x16x32_bf16 v[72:75], v[194:197], v[218:221], v[72:75]
	v_mfma_f32_16x16x32_bf16 v[68:71], v[186:189], v[230:233], v[68:71]
	v_mfma_f32_16x16x32_bf16 v[64:67], v[194:197], v[230:233], v[64:67]
	s_setprio 0
	s_barrier
	s_add_i32 s90, s85, s39
	v_lshl_add_u64 v[174:175], s[10:11], 0, v[130:131]
	s_mov_b32 m0, s90
	ds_read_b128 v[198:201], v164 offset:16384
	ds_read_b128 v[202:205], v164 offset:17408
	ds_read_b128 v[206:209], v164 offset:18432
	ds_read_b128 v[210:213], v164 offset:19456
	ds_read_b128 v[214:217], v164 offset:20480
	ds_read_b128 v[218:221], v164 offset:21504
	ds_read_b128 v[226:229], v164 offset:22528
	ds_read_b128 v[230:233], v164 offset:23552
	global_load_lds_dwordx4 v[174:175], off
	s_add_i32 m0, s90, 0x2000
	s_add_u32 s90, s10, 0x40000
	v_lshl_add_u64 v[222:223], s[10:11], 0, v[134:135]
	s_addc_u32 s91, s11, 0
	s_add_i32 s92, s86, s39
	global_load_lds_dwordx4 v[222:223], off
	s_mov_b32 m0, s92
	v_lshl_add_u64 v[236:237], s[12:13], 0, v[132:133]
	global_load_lds_dwordx4 v130, s[90:91]
	s_add_i32 m0, s92, 0x2000
	s_nop 0
	global_load_lds_dwordx4 v134, s[90:91]
	v_lshl_add_u64 v[234:235], s[12:13], 0, v[128:129]
	s_mov_b32 m0, s43
	s_nop 0
	global_load_lds_dwordx4 v[234:235], off
	s_mov_b32 m0, s53
	s_nop 0
	global_load_lds_dwordx4 v[236:237], off
	s_waitcnt vmcnt(8)
	s_waitcnt lgkmcnt(0)
	s_barrier
; #define PG8_STAGE(bufoff, gbase, voff) do { _Pragma("unroll") for (int _i = 0; _i < 2; ++_i) \
;         __builtin_amdgcn_global_load_lds((const unsigned*)((const char*)(gbase) + (voff)[_i]), (LAS unsigned*)(lds + (bufoff) + ldsw + _i * 8192), 16, 0, 0); } while (0)
; #define PG8_LDA(dst, b, h) do { _Pragma("unroll") for (int m = 0; m < 4; ++m) _Pragma("unroll") for (int k = 0; k < 2; ++k) dst[m][k] = *(const LAS bf16x8*)(lds + PG8_SA(b, h) + aoff + m * 2048 + k * 1024); } while (0)
; #define PG8_LDB(dst, b, h) do { _Pragma("unroll") for (int n = 0; n < 2; ++n) _Pragma("unroll") for (int k = 0; k < 2; ++k) dst[n][k] = *(const LAS bf16x8*)(lds + PG8_SB(b, h) + boff + n * 2048 + k * 1024); } while (0)
; #define PG8_MMA(ai, bj, At, Bt) do { __builtin_amdgcn_s_setprio(1); _Pragma("unroll") for (int m = 0; m < 4; ++m) _Pragma("unroll") for (int n = 0; n < 2; ++n) _Pragma("unroll") for (int k = 0; k < 2; ++k) \
;         acc[ai][bj][m][n] = __builtin_amdgcn_mfma_f32_16x16x32_bf16(Bt[n][k], At[m][k], acc[ai][bj][m][n], 0, 0, 0); __builtin_amdgcn_s_setprio(0); } while (0)
; #define PG8_WAIT_V(n) asm volatile("s_waitcnt vmcnt(" #n ")" ::: "memory")
; #define PG8_WAIT_L(n) asm volatile("s_waitcnt lgkmcnt(" #n ")" ::: "memory")
; #define PG8_BAR __builtin_amdgcn_s_barrier()
; #define PG8_SCHED __builtin_amdgcn_sched_barrier(0)
; template <class Epi>
; __device__ __forceinline__ void gemm_phase(LAS unsigned char* lds, const Gemm g, const StaticOrder& S, const Epi& E) {
;     ...
;             PG8_WAIT_V(8); PG8_WAIT_L(0); PG8_BAR; PG8_MMA(1, 0, At, B0); PG8_MMA(1, 1, At, B1); PG8_BAR; PG8_SCHED;
;             PG8_LDB(B0, 1, 0); PG8_LDB(B1, 1, 1); PG8_SCHED; PG8_LDA(At, 1, 0); PG8_STAGE(PG8_SA(0, 1), a2 + hstepA, voffA);
;             PG8_WAIT_V(8); PG8_WAIT_L(0); PG8_BAR; PG8_MMA(0, 0, At, B0); PG8_MMA(0, 1, At, B1); PG8_BAR; PG8_SCHED;
	s_setprio 1
	s_waitcnt lgkmcnt(0)
	v_mfma_f32_16x16x32_bf16 v[60:63], v[146:149], v[198:201], 0
	v_mfma_f32_16x16x32_bf16 v[56:59], v[170:173], v[198:201], 0
	v_mfma_f32_16x16x32_bf16 v[52:55], v[146:149], v[206:209], 0
	v_mfma_f32_16x16x32_bf16 v[44:47], v[170:173], v[206:209], 0
	v_mfma_f32_16x16x32_bf16 v[36:39], v[146:149], v[214:217], 0
	v_mfma_f32_16x16x32_bf16 v[28:31], v[170:173], v[214:217], 0
	v_mfma_f32_16x16x32_bf16 v[20:23], v[146:149], v[226:229], 0
	v_mfma_f32_16x16x32_bf16 v[12:15], v[170:173], v[226:229], 0
	v_mfma_f32_16x16x32_bf16 v[60:63], v[166:169], v[202:205], v[60:63]
	v_mfma_f32_16x16x32_bf16 v[56:59], v[178:181], v[202:205], v[56:59]
	v_mfma_f32_16x16x32_bf16 v[52:55], v[166:169], v[210:213], v[52:55]
	v_mfma_f32_16x16x32_bf16 v[44:47], v[178:181], v[210:213], v[44:47]
	v_mfma_f32_16x16x32_bf16 v[36:39], v[166:169], v[218:221], v[36:39]
	v_mfma_f32_16x16x32_bf16 v[28:31], v[178:181], v[218:221], v[28:31]
	v_mfma_f32_16x16x32_bf16 v[20:23], v[166:169], v[230:233], v[20:23]
	v_mfma_f32_16x16x32_bf16 v[12:15], v[178:181], v[230:233], v[12:15]
	s_setprio 0
	s_setprio 1
	v_mfma_f32_16x16x32_bf16 v[48:51], v[182:185], v[198:201], 0
	v_mfma_f32_16x16x32_bf16 v[40:43], v[190:193], v[198:201], 0
	v_mfma_f32_16x16x32_bf16 v[32:35], v[182:185], v[206:209], 0
	v_mfma_f32_16x16x32_bf16 v[24:27], v[190:193], v[206:209], 0
	v_mfma_f32_16x16x32_bf16 v[16:19], v[182:185], v[214:217], 0
	v_mfma_f32_16x16x32_bf16 v[8:11], v[190:193], v[214:217], 0
	v_mfma_f32_16x16x32_bf16 v[4:7], v[182:185], v[226:229], 0
	v_mfma_f32_16x16x32_bf16 v[0:3], v[190:193], v[226:229], 0
	v_mfma_f32_16x16x32_bf16 v[48:51], v[186:189], v[202:205], v[48:51]
	v_mfma_f32_16x16x32_bf16 v[40:43], v[194:197], v[202:205], v[40:43]
	v_mfma_f32_16x16x32_bf16 v[32:35], v[186:189], v[210:213], v[32:35]
	v_mfma_f32_16x16x32_bf16 v[24:27], v[194:197], v[210:213], v[24:27]
	v_mfma_f32_16x16x32_bf16 v[16:19], v[186:189], v[218:221], v[16:19]
	v_mfma_f32_16x16x32_bf16 v[8:11], v[194:197], v[218:221], v[8:11]
	v_mfma_f32_16x16x32_bf16 v[4:7], v[186:189], v[230:233], v[4:7]
	v_mfma_f32_16x16x32_bf16 v[0:3], v[194:197], v[230:233], v[0:3]
	s_setprio 0
	s_barrier
	s_add_i32 s90, 0, 0x18000
	v_add_u32_e32 v136, s90, v161
	s_add_i32 s91, 0, 0x1c000
	ds_read_b128 v[146:149], v136
	ds_read_b128 v[166:169], v136 offset:1024
	ds_read_b128 v[170:173], v136 offset:2048
	ds_read_b128 v[178:181], v136 offset:3072
	v_add_u32_e32 v136, s91, v161
	ds_read_b128 v[182:185], v136
	ds_read_b128 v[186:189], v136 offset:1024
	ds_read_b128 v[190:193], v136 offset:2048
	ds_read_b128 v[194:197], v136 offset:3072
	s_add_u32 s12, s12, 0x40000
	s_addc_u32 s13, s13, 0
	s_mov_b32 m0, s55
	ds_read_b128 v[198:201], v164 offset:32768
	ds_read_b128 v[202:205], v164 offset:33792
	ds_read_b128 v[206:209], v164 offset:34816
	ds_read_b128 v[210:213], v164 offset:35840
	ds_read_b128 v[214:217], v164 offset:36864
	ds_read_b128 v[218:221], v164 offset:37888
	ds_read_b128 v[226:229], v164 offset:38912
	ds_read_b128 v[230:233], v164 offset:39936
	global_load_lds_dwordx4 v128, s[12:13]
	s_mov_b32 m0, s57
	s_nop 0
	global_load_lds_dwordx4 v132, s[12:13]
	s_waitcnt vmcnt(8)
	s_waitcnt lgkmcnt(0)
	s_barrier
	s_setprio 1
	s_waitcnt lgkmcnt(0)
	v_mfma_f32_16x16x32_bf16 v[124:127], v[146:149], v[198:201], v[124:127]
	v_mfma_f32_16x16x32_bf16 v[120:123], v[170:173], v[198:201], v[120:123]
	v_mfma_f32_16x16x32_bf16 v[112:115], v[146:149], v[206:209], v[112:115]
	v_mfma_f32_16x16x32_bf16 v[104:107], v[170:173], v[206:209], v[104:107]
	v_mfma_f32_16x16x32_bf16 v[100:103], v[146:149], v[214:217], v[100:103]
	v_mfma_f32_16x16x32_bf16 v[92:95], v[170:173], v[214:217], v[92:95]
	v_mfma_f32_16x16x32_bf16 v[84:87], v[146:149], v[226:229], v[84:87]
	v_mfma_f32_16x16x32_bf16 v[76:79], v[170:173], v[226:229], v[76:79]
	v_mfma_f32_16x16x32_bf16 v[124:127], v[166:169], v[202:205], v[124:127]
	v_mfma_f32_16x16x32_bf16 v[120:123], v[178:181], v[202:205], v[120:123]
	v_mfma_f32_16x16x32_bf16 v[112:115], v[166:169], v[210:213], v[112:115]
	v_mfma_f32_16x16x32_bf16 v[104:107], v[178:181], v[210:213], v[104:107]
	v_mfma_f32_16x16x32_bf16 v[100:103], v[166:169], v[218:221], v[100:103]
	v_mfma_f32_16x16x32_bf16 v[92:95], v[178:181], v[218:221], v[92:95]
	v_mfma_f32_16x16x32_bf16 v[84:87], v[166:169], v[230:233], v[84:87]
	v_mfma_f32_16x16x32_bf16 v[76:79], v[178:181], v[230:233], v[76:79]
	s_setprio 0
	s_setprio 1
	v_mfma_f32_16x16x32_bf16 v[116:119], v[182:185], v[198:201], v[116:119]
	v_mfma_f32_16x16x32_bf16 v[108:111], v[190:193], v[198:201], v[108:111]
	v_mfma_f32_16x16x32_bf16 v[96:99], v[182:185], v[206:209], v[96:99]
	v_mfma_f32_16x16x32_bf16 v[88:91], v[190:193], v[206:209], v[88:91]
	v_mfma_f32_16x16x32_bf16 v[80:83], v[182:185], v[214:217], v[80:83]
	v_mfma_f32_16x16x32_bf16 v[72:75], v[190:193], v[214:217], v[72:75]
	v_mfma_f32_16x16x32_bf16 v[68:71], v[182:185], v[226:229], v[68:71]
	v_mfma_f32_16x16x32_bf16 v[64:67], v[190:193], v[226:229], v[64:67]
	v_mfma_f32_16x16x32_bf16 v[116:119], v[186:189], v[202:205], v[116:119]
	v_mfma_f32_16x16x32_bf16 v[108:111], v[194:197], v[202:205], v[108:111]
	v_mfma_f32_16x16x32_bf16 v[96:99], v[186:189], v[210:213], v[96:99]
	v_mfma_f32_16x16x32_bf16 v[88:91], v[194:197], v[210:213], v[88:91]
	v_mfma_f32_16x16x32_bf16 v[80:83], v[186:189], v[218:221], v[80:83]
	v_mfma_f32_16x16x32_bf16 v[72:75], v[194:197], v[218:221], v[72:75]
	v_mfma_f32_16x16x32_bf16 v[68:71], v[186:189], v[230:233], v[68:71]
	v_mfma_f32_16x16x32_bf16 v[64:67], v[194:197], v[230:233], v[64:67]
	s_setprio 0
	s_barrier
; #define PG8_STAGE(bufoff, gbase, voff) do { _Pragma("unroll") for (int _i = 0; _i < 2; ++_i) \
;         __builtin_amdgcn_global_load_lds((const unsigned*)((const char*)(gbase) + (voff)[_i]), (LAS unsigned*)(lds + (bufoff) + ldsw + _i * 8192), 16, 0, 0); } while (0)
; #define PG8_LDA(dst, b, h) do { _Pragma("unroll") for (int m = 0; m < 4; ++m) _Pragma("unroll") for (int k = 0; k < 2; ++k) dst[m][k] = *(const LAS bf16x8*)(lds + PG8_SA(b, h) + aoff + m * 2048 + k * 1024); } while (0)
; #define PG8_LDB(dst, b, h) do { _Pragma("unroll") for (int n = 0; n < 2; ++n) _Pragma("unroll") for (int k = 0; k < 2; ++k) dst[n][k] = *(const LAS bf16x8*)(lds + PG8_SB(b, h) + boff + n * 2048 + k * 1024); } while (0)
; #define PG8_MMA(ai, bj, At, Bt) do { __builtin_amdgcn_s_setprio(1); _Pragma("unroll") for (int m = 0; m < 4; ++m) _Pragma("unroll") for (int n = 0; n < 2; ++n) _Pragma("unroll") for (int k = 0; k < 2; ++k) \
;         acc[ai][bj][m][n] = __builtin_amdgcn_mfma_f32_16x16x32_bf16(Bt[n][k], At[m][k], acc[ai][bj][m][n], 0, 0, 0); __builtin_amdgcn_s_setprio(0); } while (0)
; #define PG8_WAIT_V(n) asm volatile("s_waitcnt vmcnt(" #n ")" ::: "memory")
; #define PG8_WAIT_L(n) asm volatile("s_waitcnt lgkmcnt(" #n ")" ::: "memory")
; #define PG8_BAR __builtin_amdgcn_s_barrier()
; #define PG8_SCHED __builtin_amdgcn_sched_barrier(0)
; template <class Epi>
; __device__ __forceinline__ void gemm_phase(LAS unsigned char* lds, const Gemm g, const StaticOrder& S, const Epi& E) {
;     ...
;             PG8_LDB(B0, 0, 0); PG8_LDB(B1, 0, 1); PG8_SCHED; PG8_LDA(At, 0, 0); PG8_STAGE(PG8_SA(1, 1), a1 + hstepA, voffA);
;     ...
;             PG8_LDA(At, 1, 1); PG8_STAGE(PG8_SB(1, 0), b3, voffB); PG8_STAGE(PG8_SB(1, 1), b3 + hstepB, voffB); PG8_STAGE(PG8_SA(1, 0), a3, voffA);
;             PG8_WAIT_V(8); PG8_WAIT_L(0); PG8_BAR; PG8_MMA(1, 0, At, B0); PG8_MMA(1, 1, At, B1); PG8_BAR; PG8_SCHED;
	s_add_i32 s12, s90, s39
	v_lshl_add_u64 v[174:175], v[174:175], 0, s[30:31]
	s_mov_b32 m0, s12
	ds_read_b128 v[198:201], v164 offset:49152
	ds_read_b128 v[202:205], v164 offset:50176
	ds_read_b128 v[206:209], v164 offset:51200
	ds_read_b128 v[210:213], v164 offset:52224
	ds_read_b128 v[214:217], v164 offset:53248
	ds_read_b128 v[218:221], v164 offset:54272
	ds_read_b128 v[226:229], v164 offset:55296
	ds_read_b128 v[230:233], v164 offset:56320
	global_load_lds_dwordx4 v[174:175], off
	s_add_i32 m0, s12, 0x2000
	s_add_u32 s10, s10, 0x40080
	v_lshl_add_u64 v[174:175], v[222:223], 0, s[30:31]
	s_addc_u32 s11, s11, 0
	s_add_i32 s12, s91, s39
	global_load_lds_dwordx4 v[174:175], off
	s_mov_b32 m0, s12
	s_nop 0
	global_load_lds_dwordx4 v130, s[10:11]
	s_add_i32 m0, s12, 0x2000
	s_nop 0
	global_load_lds_dwordx4 v134, s[10:11]
	v_lshl_add_u64 v[174:175], v[234:235], 0, s[30:31]
	s_mov_b32 m0, s79
	s_nop 0
	global_load_lds_dwordx4 v[174:175], off
	v_lshl_add_u64 v[174:175], v[236:237], 0, s[30:31]
	s_mov_b32 m0, s80
	s_nop 0
	global_load_lds_dwordx4 v[174:175], off
	s_waitcnt vmcnt(8)
	s_waitcnt lgkmcnt(0)
	s_barrier
	s_setprio 1
	s_waitcnt lgkmcnt(0)
	v_mfma_f32_16x16x32_bf16 v[60:63], v[146:149], v[198:201], v[60:63]
	v_mfma_f32_16x16x32_bf16 v[56:59], v[170:173], v[198:201], v[56:59]
	v_mfma_f32_16x16x32_bf16 v[52:55], v[146:149], v[206:209], v[52:55]
	v_mfma_f32_16x16x32_bf16 v[44:47], v[170:173], v[206:209], v[44:47]
	v_mfma_f32_16x16x32_bf16 v[36:39], v[146:149], v[214:217], v[36:39]
	v_mfma_f32_16x16x32_bf16 v[28:31], v[170:173], v[214:217], v[28:31]
	v_mfma_f32_16x16x32_bf16 v[20:23], v[146:149], v[226:229], v[20:23]
	v_mfma_f32_16x16x32_bf16 v[12:15], v[170:173], v[226:229], v[12:15]
	v_mfma_f32_16x16x32_bf16 v[60:63], v[166:169], v[202:205], v[60:63]
	v_mfma_f32_16x16x32_bf16 v[56:59], v[178:181], v[202:205], v[56:59]
	v_mfma_f32_16x16x32_bf16 v[52:55], v[166:169], v[210:213], v[52:55]
	v_mfma_f32_16x16x32_bf16 v[44:47], v[178:181], v[210:213], v[44:47]
	v_mfma_f32_16x16x32_bf16 v[36:39], v[166:169], v[218:221], v[36:39]
	v_mfma_f32_16x16x32_bf16 v[28:31], v[178:181], v[218:221], v[28:31]
	v_mfma_f32_16x16x32_bf16 v[20:23], v[166:169], v[230:233], v[20:23]
	v_mfma_f32_16x16x32_bf16 v[12:15], v[178:181], v[230:233], v[12:15]
	s_setprio 0
	s_setprio 1
	v_mfma_f32_16x16x32_bf16 v[48:51], v[182:185], v[198:201], v[48:51]
	v_mfma_f32_16x16x32_bf16 v[40:43], v[190:193], v[198:201], v[40:43]
	v_mfma_f32_16x16x32_bf16 v[32:35], v[182:185], v[206:209], v[32:35]
	v_mfma_f32_16x16x32_bf16 v[24:27], v[190:193], v[206:209], v[24:27]
	v_mfma_f32_16x16x32_bf16 v[16:19], v[182:185], v[214:217], v[16:19]
	v_mfma_f32_16x16x32_bf16 v[8:11], v[190:193], v[214:217], v[8:11]
	v_mfma_f32_16x16x32_bf16 v[4:7], v[182:185], v[226:229], v[4:7]
	v_mfma_f32_16x16x32_bf16 v[0:3], v[190:193], v[226:229], v[0:3]
	v_mfma_f32_16x16x32_bf16 v[48:51], v[186:189], v[202:205], v[48:51]
	v_mfma_f32_16x16x32_bf16 v[40:43], v[194:197], v[202:205], v[40:43]
	v_mfma_f32_16x16x32_bf16 v[32:35], v[186:189], v[210:213], v[32:35]
	v_mfma_f32_16x16x32_bf16 v[24:27], v[194:197], v[210:213], v[24:27]
	v_mfma_f32_16x16x32_bf16 v[16:19], v[186:189], v[218:221], v[16:19]
	v_mfma_f32_16x16x32_bf16 v[8:11], v[194:197], v[218:221], v[8:11]
	v_mfma_f32_16x16x32_bf16 v[4:7], v[186:189], v[230:233], v[4:7]
	v_mfma_f32_16x16x32_bf16 v[0:3], v[194:197], v[230:233], v[0:3]
	s_setprio 0
	s_barrier
	s_add_i32 s89, s89, 2
	s_add_u32 s8, s8, 0x100
	s_addc_u32 s9, s9, 0
	s_add_u32 s76, s76, 0x100
	s_addc_u32 s77, s77, 0
	s_cmp_gt_u32 s89, 13
.LBB0_546:
	ds_read_b128 v[146:149], v162
	ds_read_b128 v[166:169], v162 offset:1024
	ds_read_b128 v[170:173], v162 offset:2048
	ds_read_b128 v[178:181], v162 offset:3072
	ds_read_b128 v[182:185], v163
	ds_read_b128 v[186:189], v163 offset:1024
	ds_read_b128 v[190:193], v163 offset:2048
	ds_read_b128 v[194:197], v163 offset:3072
	s_add_u32 s10, s8, 0xfffc0080
	s_addc_u32 s11, s9, -1
	s_cmp_eq_u32 s89, 12
	s_cselect_b32 s13, s1, s11
	s_cselect_b32 s12, s7, s10
	s_cselect_b32 s11, s69, s77
	s_cselect_b32 s10, s71, s76
	s_add_i32 m0, s43, 0xc000
	ds_read_b128 v[198:201], v164
	ds_read_b128 v[202:205], v164 offset:1024
	ds_read_b128 v[206:209], v164 offset:2048
	ds_read_b128 v[210:213], v164 offset:3072
	ds_read_b128 v[214:217], v164 offset:4096
	ds_read_b128 v[218:221], v164 offset:5120
	ds_read_b128 v[226:229], v164 offset:6144
	ds_read_b128 v[230:233], v164 offset:7168
	global_load_lds_dwordx4 v138, s[8:9]
	s_add_i32 m0, s43, 0xe000
	s_nop 0
	global_load_lds_dwordx4 v140, s[8:9]
	s_waitcnt vmcnt(8)
	s_waitcnt lgkmcnt(0)
	s_barrier
; #define PG8_STAGE(bufoff, gbase, voff) do { _Pragma("unroll") for (int _i = 0; _i < 2; ++_i) \
;         __builtin_amdgcn_global_load_lds((const unsigned*)((const char*)(gbase) + (voff)[_i]), (LAS unsigned*)(lds + (bufoff) + ldsw + _i * 8192), 16, 0, 0); } while (0)
; #define PG8_LDA(dst, b, h) do { _Pragma("unroll") for (int m = 0; m < 4; ++m) _Pragma("unroll") for (int k = 0; k < 2; ++k) dst[m][k] = *(const LAS bf16x8*)(lds + PG8_SA(b, h) + aoff + m * 2048 + k * 1024); } while (0)
; #define PG8_MMA(ai, bj, At, Bt) do { __builtin_amdgcn_s_setprio(1); _Pragma("unroll") for (int m = 0; m < 4; ++m) _Pragma("unroll") for (int n = 0; n < 2; ++n) _Pragma("unroll") for (int k = 0; k < 2; ++k) \
;         acc[ai][bj][m][n] = __builtin_amdgcn_mfma_f32_16x16x32_bf16(Bt[n][k], At[m][k], acc[ai][bj][m][n], 0, 0, 0); __builtin_amdgcn_s_setprio(0); } while (0)
; #define PG8_WAIT_V(n) asm volatile("s_waitcnt vmcnt(" #n ")" ::: "memory")
; #define PG8_WAIT_L(n) asm volatile("s_waitcnt lgkmcnt(" #n ")" ::: "memory")
; #define PG8_BAR __builtin_amdgcn_s_barrier()
; #define PG8_SCHED __builtin_amdgcn_sched_barrier(0)
; template <class Epi>
; __device__ __forceinline__ void gemm_phase(LAS unsigned char* lds, const Gemm g, const StaticOrder& S, const Epi& E) {
;     ...
;             PG8_WAIT_V(8); PG8_WAIT_L(0); PG8_BAR; PG8_MMA(0, 0, At, B0); PG8_MMA(0, 1, At, B1); PG8_BAR; PG8_SCHED;
;             PG8_LDA(At, 0, 1); PG8_STAGE(PG8_SB(0, 0), b2, voffB); PG8_STAGE(PG8_SB(0, 1), b2 + hstepB, voffB); PG8_STAGE(PG8_SA(0, 0), a2, voffA);
;             PG8_WAIT_V(8); PG8_WAIT_L(0); PG8_BAR; PG8_MMA(1, 0, At, B0); PG8_MMA(1, 1, At, B1); PG8_BAR; PG8_SCHED;
	s_setprio 1
	s_waitcnt lgkmcnt(0)
	v_mfma_f32_16x16x32_bf16 v[124:127], v[146:149], v[198:201], v[124:127]
	v_mfma_f32_16x16x32_bf16 v[120:123], v[170:173], v[198:201], v[120:123]
	v_mfma_f32_16x16x32_bf16 v[112:115], v[146:149], v[206:209], v[112:115]
	v_mfma_f32_16x16x32_bf16 v[104:107], v[170:173], v[206:209], v[104:107]
	v_mfma_f32_16x16x32_bf16 v[100:103], v[146:149], v[214:217], v[100:103]
	v_mfma_f32_16x16x32_bf16 v[92:95], v[170:173], v[214:217], v[92:95]
	v_mfma_f32_16x16x32_bf16 v[84:87], v[146:149], v[226:229], v[84:87]
	v_mfma_f32_16x16x32_bf16 v[76:79], v[170:173], v[226:229], v[76:79]
	v_mfma_f32_16x16x32_bf16 v[124:127], v[166:169], v[202:205], v[124:127]
	v_mfma_f32_16x16x32_bf16 v[120:123], v[178:181], v[202:205], v[120:123]
	v_mfma_f32_16x16x32_bf16 v[112:115], v[166:169], v[210:213], v[112:115]
	v_mfma_f32_16x16x32_bf16 v[104:107], v[178:181], v[210:213], v[104:107]
	v_mfma_f32_16x16x32_bf16 v[100:103], v[166:169], v[218:221], v[100:103]
	v_mfma_f32_16x16x32_bf16 v[92:95], v[178:181], v[218:221], v[92:95]
	v_mfma_f32_16x16x32_bf16 v[84:87], v[166:169], v[230:233], v[84:87]
	v_mfma_f32_16x16x32_bf16 v[76:79], v[178:181], v[230:233], v[76:79]
	s_setprio 0
	s_setprio 1
	v_mfma_f32_16x16x32_bf16 v[116:119], v[182:185], v[198:201], v[116:119]
	v_mfma_f32_16x16x32_bf16 v[108:111], v[190:193], v[198:201], v[108:111]
	v_mfma_f32_16x16x32_bf16 v[96:99], v[182:185], v[206:209], v[96:99]
	v_mfma_f32_16x16x32_bf16 v[88:91], v[190:193], v[206:209], v[88:91]
	v_mfma_f32_16x16x32_bf16 v[80:83], v[182:185], v[214:217], v[80:83]
	v_mfma_f32_16x16x32_bf16 v[72:75], v[190:193], v[214:217], v[72:75]
	v_mfma_f32_16x16x32_bf16 v[68:71], v[182:185], v[226:229], v[68:71]
	v_mfma_f32_16x16x32_bf16 v[64:67], v[190:193], v[226:229], v[64:67]
	v_mfma_f32_16x16x32_bf16 v[116:119], v[186:189], v[202:205], v[116:119]
	v_mfma_f32_16x16x32_bf16 v[108:111], v[194:197], v[202:205], v[108:111]
	v_mfma_f32_16x16x32_bf16 v[96:99], v[186:189], v[210:213], v[96:99]
	v_mfma_f32_16x16x32_bf16 v[88:91], v[194:197], v[210:213], v[88:91]
	v_mfma_f32_16x16x32_bf16 v[80:83], v[186:189], v[218:221], v[80:83]
	v_mfma_f32_16x16x32_bf16 v[72:75], v[194:197], v[218:221], v[72:75]
	v_mfma_f32_16x16x32_bf16 v[68:71], v[186:189], v[230:233], v[68:71]
	v_mfma_f32_16x16x32_bf16 v[64:67], v[194:197], v[230:233], v[64:67]
	s_setprio 0
	s_barrier
	s_add_i32 s90, s85, s39
	v_lshl_add_u64 v[174:175], s[10:11], 0, v[130:131]
	s_mov_b32 m0, s90
	ds_read_b128 v[198:201], v164 offset:16384
	ds_read_b128 v[202:205], v164 offset:17408
	ds_read_b128 v[206:209], v164 offset:18432
	ds_read_b128 v[210:213], v164 offset:19456
	ds_read_b128 v[214:217], v164 offset:20480
	ds_read_b128 v[218:221], v164 offset:21504
	ds_read_b128 v[226:229], v164 offset:22528
	ds_read_b128 v[230:233], v164 offset:23552
	global_load_lds_dwordx4 v[174:175], off
	s_add_i32 m0, s90, 0x2000
	s_add_u32 s90, s10, 0x40000
	v_lshl_add_u64 v[222:223], s[10:11], 0, v[134:135]
	s_addc_u32 s91, s11, 0
	s_add_i32 s92, s86, s39
	global_load_lds_dwordx4 v[222:223], off
	s_mov_b32 m0, s92
	v_lshl_add_u64 v[236:237], s[12:13], 0, v[132:133]
	global_load_lds_dwordx4 v130, s[90:91]
	s_add_i32 m0, s92, 0x2000
	s_nop 0
	global_load_lds_dwordx4 v134, s[90:91]
	v_lshl_add_u64 v[234:235], s[12:13], 0, v[128:129]
	s_mov_b32 m0, s43
	s_nop 0
	global_load_lds_dwordx4 v[234:235], off
	s_mov_b32 m0, s53
	s_nop 0
	global_load_lds_dwordx4 v[236:237], off
	s_waitcnt vmcnt(8)
	s_waitcnt lgkmcnt(0)
	s_barrier
	s_setprio 1
	s_waitcnt lgkmcnt(0)
	v_mfma_f32_16x16x32_bf16 v[60:63], v[146:149], v[198:201], v[60:63]
	v_mfma_f32_16x16x32_bf16 v[56:59], v[170:173], v[198:201], v[56:59]
	v_mfma_f32_16x16x32_bf16 v[52:55], v[146:149], v[206:209], v[52:55]
	v_mfma_f32_16x16x32_bf16 v[44:47], v[170:173], v[206:209], v[44:47]
	v_mfma_f32_16x16x32_bf16 v[36:39], v[146:149], v[214:217], v[36:39]
	v_mfma_f32_16x16x32_bf16 v[28:31], v[170:173], v[214:217], v[28:31]
	v_mfma_f32_16x16x32_bf16 v[20:23], v[146:149], v[226:229], v[20:23]
	v_mfma_f32_16x16x32_bf16 v[12:15], v[170:173], v[226:229], v[12:15]
	v_mfma_f32_16x16x32_bf16 v[60:63], v[166:169], v[202:205], v[60:63]
	v_mfma_f32_16x16x32_bf16 v[56:59], v[178:181], v[202:205], v[56:59]
	v_mfma_f32_16x16x32_bf16 v[52:55], v[166:169], v[210:213], v[52:55]
	v_mfma_f32_16x16x32_bf16 v[44:47], v[178:181], v[210:213], v[44:47]
	v_mfma_f32_16x16x32_bf16 v[36:39], v[166:169], v[218:221], v[36:39]
	v_mfma_f32_16x16x32_bf16 v[28:31], v[178:181], v[218:221], v[28:31]
	v_mfma_f32_16x16x32_bf16 v[20:23], v[166:169], v[230:233], v[20:23]
	v_mfma_f32_16x16x32_bf16 v[12:15], v[178:181], v[230:233], v[12:15]
	s_setprio 0
	s_setprio 1
	v_mfma_f32_16x16x32_bf16 v[48:51], v[182:185], v[198:201], v[48:51]
	v_mfma_f32_16x16x32_bf16 v[40:43], v[190:193], v[198:201], v[40:43]
	v_mfma_f32_16x16x32_bf16 v[32:35], v[182:185], v[206:209], v[32:35]
	v_mfma_f32_16x16x32_bf16 v[24:27], v[190:193], v[206:209], v[24:27]
	v_mfma_f32_16x16x32_bf16 v[16:19], v[182:185], v[214:217], v[16:19]
	v_mfma_f32_16x16x32_bf16 v[8:11], v[190:193], v[214:217], v[8:11]
	v_mfma_f32_16x16x32_bf16 v[4:7], v[182:185], v[226:229], v[4:7]
	v_mfma_f32_16x16x32_bf16 v[0:3], v[190:193], v[226:229], v[0:3]
	v_mfma_f32_16x16x32_bf16 v[48:51], v[186:189], v[202:205], v[48:51]
	v_mfma_f32_16x16x32_bf16 v[40:43], v[194:197], v[202:205], v[40:43]
	v_mfma_f32_16x16x32_bf16 v[32:35], v[186:189], v[210:213], v[32:35]
	v_mfma_f32_16x16x32_bf16 v[24:27], v[194:197], v[210:213], v[24:27]
	v_mfma_f32_16x16x32_bf16 v[16:19], v[186:189], v[218:221], v[16:19]
	v_mfma_f32_16x16x32_bf16 v[8:11], v[194:197], v[218:221], v[8:11]
	v_mfma_f32_16x16x32_bf16 v[4:7], v[186:189], v[230:233], v[4:7]
	v_mfma_f32_16x16x32_bf16 v[0:3], v[194:197], v[230:233], v[0:3]
	s_setprio 0
	s_barrier
; #define PG8_STAGE(bufoff, gbase, voff) do { _Pragma("unroll") for (int _i = 0; _i < 2; ++_i) \
;         __builtin_amdgcn_global_load_lds((const unsigned*)((const char*)(gbase) + (voff)[_i]), (LAS unsigned*)(lds + (bufoff) + ldsw + _i * 8192), 16, 0, 0); } while (0)
; #define PG8_LDA(dst, b, h) do { _Pragma("unroll") for (int m = 0; m < 4; ++m) _Pragma("unroll") for (int k = 0; k < 2; ++k) dst[m][k] = *(const LAS bf16x8*)(lds + PG8_SA(b, h) + aoff + m * 2048 + k * 1024); } while (0)
; #define PG8_LDB(dst, b, h) do { _Pragma("unroll") for (int n = 0; n < 2; ++n) _Pragma("unroll") for (int k = 0; k < 2; ++k) dst[n][k] = *(const LAS bf16x8*)(lds + PG8_SB(b, h) + boff + n * 2048 + k * 1024); } while (0)
; #define PG8_MMA(ai, bj, At, Bt) do { __builtin_amdgcn_s_setprio(1); _Pragma("unroll") for (int m = 0; m < 4; ++m) _Pragma("unroll") for (int n = 0; n < 2; ++n) _Pragma("unroll") for (int k = 0; k < 2; ++k) \
;         acc[ai][bj][m][n] = __builtin_amdgcn_mfma_f32_16x16x32_bf16(Bt[n][k], At[m][k], acc[ai][bj][m][n], 0, 0, 0); __builtin_amdgcn_s_setprio(0); } while (0)
; #define PG8_WAIT_V(n) asm volatile("s_waitcnt vmcnt(" #n ")" ::: "memory")
; #define PG8_WAIT_L(n) asm volatile("s_waitcnt lgkmcnt(" #n ")" ::: "memory")
; #define PG8_BAR __builtin_amdgcn_s_barrier()
; #define PG8_SCHED __builtin_amdgcn_sched_barrier(0)
; template <class Epi>
; __device__ __forceinline__ void gemm_phase(LAS unsigned char* lds, const Gemm g, const StaticOrder& S, const Epi& E) {
;     ...
;             PG8_WAIT_V(8); PG8_WAIT_L(0); PG8_BAR; PG8_MMA(1, 0, At, B0); PG8_MMA(1, 1, At, B1); PG8_BAR; PG8_SCHED;
;             PG8_LDB(B0, 1, 0); PG8_LDB(B1, 1, 1); PG8_SCHED; PG8_LDA(At, 1, 0); PG8_STAGE(PG8_SA(0, 1), a2 + hstepA, voffA);
;             PG8_WAIT_V(8); PG8_WAIT_L(0); PG8_BAR; PG8_MMA(0, 0, At, B0); PG8_MMA(0, 1, At, B1); PG8_BAR; PG8_SCHED;
;             PG8_LDA(At, 1, 1); PG8_STAGE(PG8_SB(1, 0), b3, voffB); PG8_STAGE(PG8_SB(1, 1), b3 + hstepB, voffB); PG8_STAGE(PG8_SA(1, 0), a3, voffA);
;             PG8_WAIT_V(8); PG8_WAIT_L(0); PG8_BAR; PG8_MMA(1, 0, At, B0); PG8_MMA(1, 1, At, B1); PG8_BAR; PG8_SCHED;
	s_add_i32 s90, 0, 0x18000
	v_add_u32_e32 v136, s90, v161
	s_add_i32 s91, 0, 0x1c000
	ds_read_b128 v[146:149], v136
	ds_read_b128 v[166:169], v136 offset:1024
	ds_read_b128 v[170:173], v136 offset:2048
	ds_read_b128 v[178:181], v136 offset:3072
	v_add_u32_e32 v136, s91, v161
	ds_read_b128 v[182:185], v136
	ds_read_b128 v[186:189], v136 offset:1024
	ds_read_b128 v[190:193], v136 offset:2048
	ds_read_b128 v[194:197], v136 offset:3072
	s_add_u32 s12, s12, 0x40000
	s_addc_u32 s13, s13, 0
	s_mov_b32 m0, s55
	ds_read_b128 v[198:201], v164 offset:32768
	ds_read_b128 v[202:205], v164 offset:33792
	ds_read_b128 v[206:209], v164 offset:34816
	ds_read_b128 v[210:213], v164 offset:35840
	ds_read_b128 v[214:217], v164 offset:36864
	ds_read_b128 v[218:221], v164 offset:37888
	ds_read_b128 v[226:229], v164 offset:38912
	ds_read_b128 v[230:233], v164 offset:39936
	global_load_lds_dwordx4 v128, s[12:13]
	s_mov_b32 m0, s57
	s_nop 0
	global_load_lds_dwordx4 v132, s[12:13]
	s_waitcnt vmcnt(8)
	s_waitcnt lgkmcnt(0)
	s_barrier
	s_setprio 1
	s_waitcnt lgkmcnt(0)
	v_mfma_f32_16x16x32_bf16 v[124:127], v[146:149], v[198:201], v[124:127]
	v_mfma_f32_16x16x32_bf16 v[120:123], v[170:173], v[198:201], v[120:123]
	v_mfma_f32_16x16x32_bf16 v[112:115], v[146:149], v[206:209], v[112:115]
	v_mfma_f32_16x16x32_bf16 v[104:107], v[170:173], v[206:209], v[104:107]
	v_mfma_f32_16x16x32_bf16 v[100:103], v[146:149], v[214:217], v[100:103]
	v_mfma_f32_16x16x32_bf16 v[92:95], v[170:173], v[214:217], v[92:95]
	v_mfma_f32_16x16x32_bf16 v[84:87], v[146:149], v[226:229], v[84:87]
	v_mfma_f32_16x16x32_bf16 v[76:79], v[170:173], v[226:229], v[76:79]
	v_mfma_f32_16x16x32_bf16 v[124:127], v[166:169], v[202:205], v[124:127]
	v_mfma_f32_16x16x32_bf16 v[120:123], v[178:181], v[202:205], v[120:123]
	v_mfma_f32_16x16x32_bf16 v[112:115], v[166:169], v[210:213], v[112:115]
	v_mfma_f32_16x16x32_bf16 v[104:107], v[178:181], v[210:213], v[104:107]
	v_mfma_f32_16x16x32_bf16 v[100:103], v[166:169], v[218:221], v[100:103]
	v_mfma_f32_16x16x32_bf16 v[92:95], v[178:181], v[218:221], v[92:95]
	v_mfma_f32_16x16x32_bf16 v[84:87], v[166:169], v[230:233], v[84:87]
	v_mfma_f32_16x16x32_bf16 v[76:79], v[178:181], v[230:233], v[76:79]
	s_setprio 0
	s_setprio 1
	v_mfma_f32_16x16x32_bf16 v[116:119], v[182:185], v[198:201], v[116:119]
	v_mfma_f32_16x16x32_bf16 v[108:111], v[190:193], v[198:201], v[108:111]
	v_mfma_f32_16x16x32_bf16 v[96:99], v[182:185], v[206:209], v[96:99]
	v_mfma_f32_16x16x32_bf16 v[88:91], v[190:193], v[206:209], v[88:91]
	v_mfma_f32_16x16x32_bf16 v[80:83], v[182:185], v[214:217], v[80:83]
	v_mfma_f32_16x16x32_bf16 v[72:75], v[190:193], v[214:217], v[72:75]
	v_mfma_f32_16x16x32_bf16 v[68:71], v[182:185], v[226:229], v[68:71]
	v_mfma_f32_16x16x32_bf16 v[64:67], v[190:193], v[226:229], v[64:67]
	v_mfma_f32_16x16x32_bf16 v[116:119], v[186:189], v[202:205], v[116:119]
	v_mfma_f32_16x16x32_bf16 v[108:111], v[194:197], v[202:205], v[108:111]
	v_mfma_f32_16x16x32_bf16 v[96:99], v[186:189], v[210:213], v[96:99]
	v_mfma_f32_16x16x32_bf16 v[88:91], v[194:197], v[210:213], v[88:91]
	v_mfma_f32_16x16x32_bf16 v[80:83], v[186:189], v[218:221], v[80:83]
	v_mfma_f32_16x16x32_bf16 v[72:75], v[194:197], v[218:221], v[72:75]
	v_mfma_f32_16x16x32_bf16 v[68:71], v[186:189], v[230:233], v[68:71]
	v_mfma_f32_16x16x32_bf16 v[64:67], v[194:197], v[230:233], v[64:67]
	s_setprio 0
	s_barrier
	s_add_i32 s12, s90, s39
	v_lshl_add_u64 v[174:175], v[174:175], 0, s[30:31]
	s_mov_b32 m0, s12
	ds_read_b128 v[198:201], v164 offset:49152
	ds_read_b128 v[202:205], v164 offset:50176
	ds_read_b128 v[206:209], v164 offset:51200
	ds_read_b128 v[210:213], v164 offset:52224
	ds_read_b128 v[214:217], v164 offset:53248
	ds_read_b128 v[218:221], v164 offset:54272
	ds_read_b128 v[226:229], v164 offset:55296
	ds_read_b128 v[230:233], v164 offset:56320
	global_load_lds_dwordx4 v[174:175], off
	s_add_i32 m0, s12, 0x2000
	s_add_u32 s10, s10, 0x40080
	v_lshl_add_u64 v[174:175], v[222:223], 0, s[30:31]
	s_addc_u32 s11, s11, 0
	s_add_i32 s12, s91, s39
	global_load_lds_dwordx4 v[174:175], off
	s_mov_b32 m0, s12
	s_nop 0
	global_load_lds_dwordx4 v130, s[10:11]
	s_add_i32 m0, s12, 0x2000
	s_nop 0
	global_load_lds_dwordx4 v134, s[10:11]
	v_lshl_add_u64 v[174:175], v[234:235], 0, s[30:31]
	s_mov_b32 m0, s79
	s_nop 0
	global_load_lds_dwordx4 v[174:175], off
	v_lshl_add_u64 v[174:175], v[236:237], 0, s[30:31]
	s_mov_b32 m0, s80
	s_nop 0
	global_load_lds_dwordx4 v[174:175], off
	s_waitcnt vmcnt(8)
	s_waitcnt lgkmcnt(0)
	s_barrier
	s_setprio 1
	s_waitcnt lgkmcnt(0)
	v_mfma_f32_16x16x32_bf16 v[60:63], v[146:149], v[198:201], v[60:63]
	v_mfma_f32_16x16x32_bf16 v[56:59], v[170:173], v[198:201], v[56:59]
	v_mfma_f32_16x16x32_bf16 v[52:55], v[146:149], v[206:209], v[52:55]
	v_mfma_f32_16x16x32_bf16 v[44:47], v[170:173], v[206:209], v[44:47]
	v_mfma_f32_16x16x32_bf16 v[36:39], v[146:149], v[214:217], v[36:39]
	v_mfma_f32_16x16x32_bf16 v[28:31], v[170:173], v[214:217], v[28:31]
	v_mfma_f32_16x16x32_bf16 v[20:23], v[146:149], v[226:229], v[20:23]
	v_mfma_f32_16x16x32_bf16 v[12:15], v[170:173], v[226:229], v[12:15]
	v_mfma_f32_16x16x32_bf16 v[60:63], v[166:169], v[202:205], v[60:63]
	v_mfma_f32_16x16x32_bf16 v[56:59], v[178:181], v[202:205], v[56:59]
	v_mfma_f32_16x16x32_bf16 v[52:55], v[166:169], v[210:213], v[52:55]
	v_mfma_f32_16x16x32_bf16 v[44:47], v[178:181], v[210:213], v[44:47]
	v_mfma_f32_16x16x32_bf16 v[36:39], v[166:169], v[218:221], v[36:39]
	v_mfma_f32_16x16x32_bf16 v[28:31], v[178:181], v[218:221], v[28:31]
	v_mfma_f32_16x16x32_bf16 v[20:23], v[166:169], v[230:233], v[20:23]
	v_mfma_f32_16x16x32_bf16 v[12:15], v[178:181], v[230:233], v[12:15]
	s_setprio 0
	s_setprio 1
	v_mfma_f32_16x16x32_bf16 v[48:51], v[182:185], v[198:201], v[48:51]
	v_mfma_f32_16x16x32_bf16 v[40:43], v[190:193], v[198:201], v[40:43]
	v_mfma_f32_16x16x32_bf16 v[32:35], v[182:185], v[206:209], v[32:35]
	v_mfma_f32_16x16x32_bf16 v[24:27], v[190:193], v[206:209], v[24:27]
	v_mfma_f32_16x16x32_bf16 v[16:19], v[182:185], v[214:217], v[16:19]
	v_mfma_f32_16x16x32_bf16 v[8:11], v[190:193], v[214:217], v[8:11]
	v_mfma_f32_16x16x32_bf16 v[4:7], v[182:185], v[226:229], v[4:7]
	v_mfma_f32_16x16x32_bf16 v[0:3], v[190:193], v[226:229], v[0:3]
	v_mfma_f32_16x16x32_bf16 v[48:51], v[186:189], v[202:205], v[48:51]
	v_mfma_f32_16x16x32_bf16 v[40:43], v[194:197], v[202:205], v[40:43]
	v_mfma_f32_16x16x32_bf16 v[32:35], v[186:189], v[210:213], v[32:35]
	v_mfma_f32_16x16x32_bf16 v[24:27], v[194:197], v[210:213], v[24:27]
	v_mfma_f32_16x16x32_bf16 v[16:19], v[186:189], v[218:221], v[16:19]
	v_mfma_f32_16x16x32_bf16 v[8:11], v[194:197], v[218:221], v[8:11]
	v_mfma_f32_16x16x32_bf16 v[4:7], v[186:189], v[230:233], v[4:7]
	v_mfma_f32_16x16x32_bf16 v[0:3], v[194:197], v[230:233], v[0:3]
	s_setprio 0
	s_barrier
	s_add_i32 s89, s89, 2
	s_add_u32 s8, s8, 0x100
	s_addc_u32 s9, s9, 0
	s_add_u32 s76, s76, 0x100
	s_addc_u32 s77, s77, 0
	s_cmp_gt_u32 s89, 13
	s_cbranch_scc0 .LBB0_546
	s_and_b64 vcc, exec, s[34:35]
	s_cbranch_vccz .LBB0_549
	s_barrier

; #define PG8_STAGE(bufoff, gbase, voff) do { _Pragma("unroll") for (int _i = 0; _i < 2; ++_i) \
;         __builtin_amdgcn_global_load_lds((const unsigned*)((const char*)(gbase) + (voff)[_i]), (LAS unsigned*)(lds + (bufoff) + ldsw + _i * 8192), 16, 0, 0); } while (0)
; #define PG8_WAIT_V(n) asm volatile("s_waitcnt vmcnt(" #n ")" ::: "memory")
; #define PG8_BAR __builtin_amdgcn_s_barrier()
; template <class Epi>
; __device__ __forceinline__ void gemm_phase(LAS unsigned char* lds, const Gemm g, const StaticOrder& S, const Epi& E) {
;     ...
;     for (int i = 0; i < 2; ++i) { int R, C; stage_rc(tid * 16 + i * 8192, R, C); const int Rb = (R & ~31) + perm32(R & 31);
;         voffA[i] = (unsigned)(R * g.lda + C) * 2u; voffB[i] = (unsigned)(Rb * g.ldb + C) * 2u; }
;     const size_t kstep = (size_t)(BK * 2);
;     const size_t hstepA = (size_t)HALF * g.lda * 2, hstepB = (size_t)HALF * g.ldb * 2;
;     const size_t tstepA = 2 * hstepA, tstepB = 2 * hstepB;
;     const unsigned ldsw = (unsigned)wid * 1024u;
;     const int aoff = lds_byte(wr * 64 + fr, fq * 8), boff = lds_byte(wc * 32 + fr, fq * 8);
;     ...
;     PG8_STAGE(PG8_SB(0, 0), cB, voffB); PG8_STAGE(PG8_SB(0, 1), cB + hstepB, voffB); PG8_STAGE(PG8_SA(0, 0), cA, voffA); PG8_STAGE(PG8_SA(0, 1), cA + hstepA, voffA);
;     if (wr == 1) PG8_BAR;
;     PG8_WAIT_V(2); PG8_BAR;
;     PG8_STAGE(PG8_SB(1, 0), cB + kstep, voffB); PG8_STAGE(PG8_SA(1, 0), cA + kstep, voffA); PG8_STAGE(PG8_SB(1, 1), cB + hstepB + kstep, voffB);
;     PG8_WAIT_V(6); PG8_BAR;
.LBB0_602:
	s_mov_b64 s[8:9], 0x80
	s_lshl_b32 s79, s4, 6
	s_lshl_b32 s1, s4, 13
	s_lshl_b32 s4, s5, 5
	s_add_i32 m0, s35, 0x18000
	v_lshl_add_u64 v[6:7], v[6:7], 0, s[8:9]
	s_and_b32 s80, s4, 0x60
	s_waitcnt vmcnt(2)
	s_barrier
	global_load_lds_dwordx4 v[6:7], off
	v_lshl_add_u64 v[4:5], v[4:5], 0, s[8:9]
	s_add_i32 m0, s35, 0x1a000
	s_add_i32 s81, s35, 0x8000
	s_add_i32 s82, s35, 0xa000
	global_load_lds_dwordx4 v[4:5], off
	v_lshl_add_u64 v[0:1], v[0:1], 0, s[8:9]
	s_mov_b32 m0, s81
	s_add_u32 s4, s38, 0x10080
	global_load_lds_dwordx4 v[0:1], off
	v_lshl_add_u64 v[0:1], v[2:3], 0, s[8:9]
	s_mov_b32 m0, s82
	s_addc_u32 s5, s39, 0
	global_load_lds_dwordx4 v[0:1], off
	s_add_i32 m0, s35, 0x1c000
	global_load_lds_dwordx4 v130, s[4:5]
	s_add_i32 m0, s35, 0x1e000
	s_cmpk_lt_u32 s10, 0x100
	global_load_lds_dwordx4 v134, s[4:5]
	v_lshlrev_b32_e32 v1, 2, v151
	v_lshl_or_b32 v0, v151, 6, v154
	v_and_b32_e32 v1, 32, v1
	v_bitop3_b32 v0, v0, s1, v1 bitop3:0xde
	s_waitcnt vmcnt(6)
	v_readlane_b32 s52, v254, 6
	v_lshl_or_b32 v144, s80, 7, v155
	s_cselect_b64 s[10:11], -1, 0
	v_readlane_b32 s54, v254, 8
	s_add_i32 s86, 0, 0x10000
	s_add_i32 s87, 0, 0x14000
	v_add_u32_e32 v147, 0, v0
	v_mbcnt_lo_u32_b32 v0, -1, 0
	s_ashr_i32 s83, s54, 31
	s_mov_b32 s84, s54
	s_ashr_i32 s85, s2, 31
	v_mov_b64_e32 v[136:137], 0x200
	v_mov_b64_e32 v[138:139], 0x1ff
	v_add_u32_e32 v145, s86, v144
	v_add_u32_e32 v146, s87, v144
	v_mbcnt_hi_u32_b32 v148, -1, v0
	s_barrier
	v_readlane_b32 s53, v254, 7
	v_readlane_b32 s55, v254, 9
	s_waitcnt vmcnt(0)
	s_branch .LBB0_605

; #define PG8_STAGE(bufoff, gbase, voff) do { _Pragma("unroll") for (int _i = 0; _i < 2; ++_i) \
;         __builtin_amdgcn_global_load_lds((const unsigned*)((const char*)(gbase) + (voff)[_i]), (LAS unsigned*)(lds + (bufoff) + ldsw + _i * 8192), 16, 0, 0); } while (0)
; #define PG8_LDA(dst, b, h) do { _Pragma("unroll") for (int m = 0; m < 4; ++m) _Pragma("unroll") for (int k = 0; k < 2; ++k) dst[m][k] = *(const LAS bf16x8*)(lds + PG8_SA(b, h) + aoff + m * 2048 + k * 1024); } while (0)
; #define PG8_LDB(dst, b, h) do { _Pragma("unroll") for (int n = 0; n < 2; ++n) _Pragma("unroll") for (int k = 0; k < 2; ++k) dst[n][k] = *(const LAS bf16x8*)(lds + PG8_SB(b, h) + boff + n * 2048 + k * 1024); } while (0)
; #define PG8_MMA(ai, bj, At, Bt) do { __builtin_amdgcn_s_setprio(1); _Pragma("unroll") for (int m = 0; m < 4; ++m) _Pragma("unroll") for (int n = 0; n < 2; ++n) _Pragma("unroll") for (int k = 0; k < 2; ++k) \
;         acc[ai][bj][m][n] = __builtin_amdgcn_mfma_f32_16x16x32_bf16(Bt[n][k], At[m][k], acc[ai][bj][m][n], 0, 0, 0); __builtin_amdgcn_s_setprio(0); } while (0)
; #define PG8_WAIT_V(n) asm volatile("s_waitcnt vmcnt(" #n ")" ::: "memory")
; #define PG8_WAIT_L(n) asm volatile("s_waitcnt lgkmcnt(" #n ")" ::: "memory")
; #define PG8_BAR __builtin_amdgcn_s_barrier()
; #define PG8_SCHED __builtin_amdgcn_sched_barrier(0)
; template <class Epi>
; __device__ __forceinline__ void gemm_phase(LAS unsigned char* lds, const Gemm g, const StaticOrder& S, const Epi& E) {
;     ...
;             const char* a2 = last ? nA : cA + (size_t)(t + 2) * kstep; const char* b2 = last ? nB : cB + (size_t)(t + 2) * kstep;
;             const char* a3 = a2 + kstep; const char* b3 = b2 + kstep;
;             PG8_LDB(B0, 0, 0); PG8_LDB(B1, 0, 1); PG8_SCHED; PG8_LDA(At, 0, 0); PG8_STAGE(PG8_SA(1, 1), a1 + hstepA, voffA);
;             PG8_WAIT_V(8); PG8_WAIT_L(0); PG8_BAR; PG8_MMA(0, 0, At, B0); PG8_MMA(0, 1, At, B1); PG8_BAR; PG8_SCHED;
;             PG8_LDA(At, 0, 1); PG8_STAGE(PG8_SB(0, 0), b2, voffB); PG8_STAGE(PG8_SB(0, 1), b2 + hstepB, voffB); PG8_STAGE(PG8_SA(0, 0), a2, voffA);
;             PG8_WAIT_V(8); PG8_WAIT_L(0); PG8_BAR; PG8_MMA(1, 0, At, B0); PG8_MMA(1, 1, At, B1); PG8_BAR; PG8_SCHED;
.LBB0_612:
	s_add_u32 s68, s42, s56
	s_addc_u32 s69, s43, s57
	s_add_u32 s64, s68, 0x100
	s_addc_u32 s65, s69, 0
	s_and_b64 s[62:63], s[54:55], exec
	s_cselect_b32 s63, s1, s65
	s_cselect_b32 s62, s19, s64
	s_add_u32 s56, s38, s56
	s_addc_u32 s57, s39, s57
	s_add_u32 s56, s56, 0x100
	s_addc_u32 s57, s57, 0
	s_and_b64 s[54:55], s[54:55], exec
	s_cselect_b32 s65, s13, s57
	s_cselect_b32 s64, s88, s56
	s_add_u32 s70, s68, 0x10080
	ds_read_b128 v[140:143], v145
	ds_read_b128 v[154:157], v145 offset:1024
	ds_read_b128 v[158:161], v145 offset:2048
	ds_read_b128 v[162:165], v145 offset:3072
	ds_read_b128 v[166:169], v146
	ds_read_b128 v[170:173], v146 offset:1024
	ds_read_b128 v[178:181], v146 offset:2048
	ds_read_b128 v[182:185], v146 offset:3072
	s_addc_u32 s71, s69, 0
	s_add_i32 vcc_lo, s86, s72
	s_add_i32 m0, s35, 0xc000
	s_add_i32 vcc_hi, s35, 0xe000
	s_add_i32 s95, vcc_lo, 0x2000
	s_add_u32 s68, s64, 0x10000
	s_addc_u32 s69, s65, 0
	s_add_i32 s97, s87, s72
	s_add_i32 s96, s97, 0x2000
	s_add_i32 s94, 0, 0x18000
	s_add_i32 s93, 0, 0x1c000
	s_add_u32 s56, s62, 0x10000
	s_addc_u32 s57, s63, 0
	s_add_i32 s92, s94, s72
	s_add_i32 s90, s92, 0x2000
	s_add_u32 s54, s64, 0x10080
	s_addc_u32 s55, s65, 0
	s_add_i32 s91, s93, s72
	s_add_i32 s89, s91, 0x2000
	ds_read_b128 v[186:189], v147
	ds_read_b128 v[190:193], v147 offset:1024
	ds_read_b128 v[194:197], v147 offset:2048
	ds_read_b128 v[198:201], v147 offset:3072
	ds_read_b128 v[202:205], v147 offset:4096
	ds_read_b128 v[206:209], v147 offset:5120
	ds_read_b128 v[210:213], v147 offset:6144
	ds_read_b128 v[214:217], v147 offset:7168
	global_load_lds_dwordx4 v128, s[70:71]
	s_mov_b32 m0, vcc_hi
	s_nop 0
	global_load_lds_dwordx4 v132, s[70:71]
	s_waitcnt vmcnt(8)
	s_waitcnt lgkmcnt(0)
	s_barrier
	s_setprio 1
	s_waitcnt lgkmcnt(0)
	v_mfma_f32_16x16x32_bf16 v[124:127], v[140:143], v[186:189], v[124:127]
	v_mfma_f32_16x16x32_bf16 v[120:123], v[158:161], v[186:189], v[120:123]
	v_mfma_f32_16x16x32_bf16 v[108:111], v[140:143], v[194:197], v[108:111]
	v_mfma_f32_16x16x32_bf16 v[104:107], v[158:161], v[194:197], v[104:107]
	v_mfma_f32_16x16x32_bf16 v[92:95], v[140:143], v[202:205], v[92:95]
	v_mfma_f32_16x16x32_bf16 v[88:91], v[158:161], v[202:205], v[88:91]
	v_mfma_f32_16x16x32_bf16 v[76:79], v[140:143], v[210:213], v[76:79]
	v_mfma_f32_16x16x32_bf16 v[72:75], v[158:161], v[210:213], v[72:75]
	v_mfma_f32_16x16x32_bf16 v[124:127], v[154:157], v[190:193], v[124:127]
	v_mfma_f32_16x16x32_bf16 v[120:123], v[162:165], v[190:193], v[120:123]
	v_mfma_f32_16x16x32_bf16 v[108:111], v[154:157], v[198:201], v[108:111]
	v_mfma_f32_16x16x32_bf16 v[104:107], v[162:165], v[198:201], v[104:107]
	v_mfma_f32_16x16x32_bf16 v[92:95], v[154:157], v[206:209], v[92:95]
	v_mfma_f32_16x16x32_bf16 v[88:91], v[162:165], v[206:209], v[88:91]
	v_mfma_f32_16x16x32_bf16 v[76:79], v[154:157], v[214:217], v[76:79]
	v_mfma_f32_16x16x32_bf16 v[72:75], v[162:165], v[214:217], v[72:75]
	s_setprio 0
	s_setprio 1
	v_mfma_f32_16x16x32_bf16 v[116:119], v[166:169], v[186:189], v[116:119]
	v_mfma_f32_16x16x32_bf16 v[112:115], v[178:181], v[186:189], v[112:115]
	v_mfma_f32_16x16x32_bf16 v[100:103], v[166:169], v[194:197], v[100:103]
	v_mfma_f32_16x16x32_bf16 v[96:99], v[178:181], v[194:197], v[96:99]
	v_mfma_f32_16x16x32_bf16 v[84:87], v[166:169], v[202:205], v[84:87]
	v_mfma_f32_16x16x32_bf16 v[80:83], v[178:181], v[202:205], v[80:83]
	v_mfma_f32_16x16x32_bf16 v[68:71], v[166:169], v[210:213], v[68:71]
	v_mfma_f32_16x16x32_bf16 v[64:67], v[178:181], v[210:213], v[64:67]
	v_mfma_f32_16x16x32_bf16 v[116:119], v[170:173], v[190:193], v[116:119]
	v_mfma_f32_16x16x32_bf16 v[112:115], v[182:185], v[190:193], v[112:115]
	v_mfma_f32_16x16x32_bf16 v[100:103], v[170:173], v[198:201], v[100:103]
	v_mfma_f32_16x16x32_bf16 v[96:99], v[182:185], v[198:201], v[96:99]
	v_mfma_f32_16x16x32_bf16 v[84:87], v[170:173], v[206:209], v[84:87]
	v_mfma_f32_16x16x32_bf16 v[80:83], v[182:185], v[206:209], v[80:83]
	v_mfma_f32_16x16x32_bf16 v[68:71], v[170:173], v[214:217], v[68:71]
	v_mfma_f32_16x16x32_bf16 v[64:67], v[182:185], v[214:217], v[64:67]
	s_setprio 0
	s_barrier
	s_mov_b32 m0, vcc_lo
	v_lshl_add_u64 v[174:175], s[64:65], 0, v[130:131]
	ds_read_b128 v[186:189], v147 offset:16384
	ds_read_b128 v[190:193], v147 offset:17408
	ds_read_b128 v[194:197], v147 offset:18432
	ds_read_b128 v[198:201], v147 offset:19456
	ds_read_b128 v[202:205], v147 offset:20480
	ds_read_b128 v[206:209], v147 offset:21504
	ds_read_b128 v[210:213], v147 offset:22528
	ds_read_b128 v[214:217], v147 offset:23552
	global_load_lds_dwordx4 v[174:175], off
	v_lshl_add_u64 v[218:219], s[64:65], 0, v[134:135]
	s_mov_b32 m0, s95
	global_load_lds_dwordx4 v[218:219], off
	s_mov_b32 m0, s97
	v_lshl_add_u64 v[222:223], s[62:63], 0, v[132:133]
	global_load_lds_dwordx4 v130, s[68:69]
	s_mov_b32 m0, s96
	s_nop 0
	global_load_lds_dwordx4 v134, s[68:69]
	v_lshl_add_u64 v[220:221], s[62:63], 0, v[128:129]
	s_mov_b32 m0, s35
	s_nop 0
	global_load_lds_dwordx4 v[220:221], off
	s_mov_b32 m0, s75
	s_nop 0
	global_load_lds_dwordx4 v[222:223], off
	s_waitcnt vmcnt(8)
	s_waitcnt lgkmcnt(0)
	s_barrier
; #define PG8_STAGE(bufoff, gbase, voff) do { _Pragma("unroll") for (int _i = 0; _i < 2; ++_i) \
;         __builtin_amdgcn_global_load_lds((const unsigned*)((const char*)(gbase) + (voff)[_i]), (LAS unsigned*)(lds + (bufoff) + ldsw + _i * 8192), 16, 0, 0); } while (0)
; #define PG8_LDA(dst, b, h) do { _Pragma("unroll") for (int m = 0; m < 4; ++m) _Pragma("unroll") for (int k = 0; k < 2; ++k) dst[m][k] = *(const LAS bf16x8*)(lds + PG8_SA(b, h) + aoff + m * 2048 + k * 1024); } while (0)
; #define PG8_LDB(dst, b, h) do { _Pragma("unroll") for (int n = 0; n < 2; ++n) _Pragma("unroll") for (int k = 0; k < 2; ++k) dst[n][k] = *(const LAS bf16x8*)(lds + PG8_SB(b, h) + boff + n * 2048 + k * 1024); } while (0)
; #define PG8_MMA(ai, bj, At, Bt) do { __builtin_amdgcn_s_setprio(1); _Pragma("unroll") for (int m = 0; m < 4; ++m) _Pragma("unroll") for (int n = 0; n < 2; ++n) _Pragma("unroll") for (int k = 0; k < 2; ++k) \
;         acc[ai][bj][m][n] = __builtin_amdgcn_mfma_f32_16x16x32_bf16(Bt[n][k], At[m][k], acc[ai][bj][m][n], 0, 0, 0); __builtin_amdgcn_s_setprio(0); } while (0)
; #define PG8_WAIT_V(n) asm volatile("s_waitcnt vmcnt(" #n ")" ::: "memory")
; #define PG8_WAIT_L(n) asm volatile("s_waitcnt lgkmcnt(" #n ")" ::: "memory")
; #define PG8_BAR __builtin_amdgcn_s_barrier()
; #define PG8_SCHED __builtin_amdgcn_sched_barrier(0)
; template <class Epi>
; __device__ __forceinline__ void gemm_phase(LAS unsigned char* lds, const Gemm g, const StaticOrder& S, const Epi& E) {
;     ...
;             PG8_WAIT_V(8); PG8_WAIT_L(0); PG8_BAR; PG8_MMA(1, 0, At, B0); PG8_MMA(1, 1, At, B1); PG8_BAR; PG8_SCHED;
;             PG8_LDB(B0, 1, 0); PG8_LDB(B1, 1, 1); PG8_SCHED; PG8_LDA(At, 1, 0); PG8_STAGE(PG8_SA(0, 1), a2 + hstepA, voffA);
;             PG8_WAIT_V(8); PG8_WAIT_L(0); PG8_BAR; PG8_MMA(0, 0, At, B0); PG8_MMA(0, 1, At, B1); PG8_BAR; PG8_SCHED;
	s_setprio 1
	s_waitcnt lgkmcnt(0)
	v_mfma_f32_16x16x32_bf16 v[60:63], v[140:143], v[186:189], v[60:63]
	v_mfma_f32_16x16x32_bf16 v[56:59], v[158:161], v[186:189], v[56:59]
	v_mfma_f32_16x16x32_bf16 v[44:47], v[140:143], v[194:197], v[44:47]
	v_mfma_f32_16x16x32_bf16 v[40:43], v[158:161], v[194:197], v[40:43]
	v_mfma_f32_16x16x32_bf16 v[28:31], v[140:143], v[202:205], v[28:31]
	v_mfma_f32_16x16x32_bf16 v[24:27], v[158:161], v[202:205], v[24:27]
	v_mfma_f32_16x16x32_bf16 v[12:15], v[140:143], v[210:213], v[12:15]
	v_mfma_f32_16x16x32_bf16 v[8:11], v[158:161], v[210:213], v[8:11]
	v_mfma_f32_16x16x32_bf16 v[60:63], v[154:157], v[190:193], v[60:63]
	v_mfma_f32_16x16x32_bf16 v[56:59], v[162:165], v[190:193], v[56:59]
	v_mfma_f32_16x16x32_bf16 v[44:47], v[154:157], v[198:201], v[44:47]
	v_mfma_f32_16x16x32_bf16 v[40:43], v[162:165], v[198:201], v[40:43]
	v_mfma_f32_16x16x32_bf16 v[28:31], v[154:157], v[206:209], v[28:31]
	v_mfma_f32_16x16x32_bf16 v[24:27], v[162:165], v[206:209], v[24:27]
	v_mfma_f32_16x16x32_bf16 v[12:15], v[154:157], v[214:217], v[12:15]
	v_mfma_f32_16x16x32_bf16 v[8:11], v[162:165], v[214:217], v[8:11]
	s_setprio 0
	s_setprio 1
	v_mfma_f32_16x16x32_bf16 v[52:55], v[166:169], v[186:189], v[52:55]
	v_mfma_f32_16x16x32_bf16 v[48:51], v[178:181], v[186:189], v[48:51]
	v_mfma_f32_16x16x32_bf16 v[36:39], v[166:169], v[194:197], v[36:39]
	v_mfma_f32_16x16x32_bf16 v[32:35], v[178:181], v[194:197], v[32:35]
	v_mfma_f32_16x16x32_bf16 v[20:23], v[166:169], v[202:205], v[20:23]
	v_mfma_f32_16x16x32_bf16 v[16:19], v[178:181], v[202:205], v[16:19]
	v_mfma_f32_16x16x32_bf16 v[4:7], v[166:169], v[210:213], v[4:7]
	v_mfma_f32_16x16x32_bf16 v[0:3], v[178:181], v[210:213], v[0:3]
	v_mfma_f32_16x16x32_bf16 v[52:55], v[170:173], v[190:193], v[52:55]
	v_mfma_f32_16x16x32_bf16 v[48:51], v[182:185], v[190:193], v[48:51]
	v_mfma_f32_16x16x32_bf16 v[36:39], v[170:173], v[198:201], v[36:39]
	v_mfma_f32_16x16x32_bf16 v[32:35], v[182:185], v[198:201], v[32:35]
	v_mfma_f32_16x16x32_bf16 v[20:23], v[170:173], v[206:209], v[20:23]
	v_mfma_f32_16x16x32_bf16 v[16:19], v[182:185], v[206:209], v[16:19]
	v_mfma_f32_16x16x32_bf16 v[4:7], v[170:173], v[214:217], v[4:7]
	v_mfma_f32_16x16x32_bf16 v[0:3], v[182:185], v[214:217], v[0:3]
	s_setprio 0
	s_barrier
	v_add_u32_e32 v149, s94, v144
	ds_read_b128 v[140:143], v149
	ds_read_b128 v[154:157], v149 offset:1024
	ds_read_b128 v[158:161], v149 offset:2048
	ds_read_b128 v[162:165], v149 offset:3072
	v_add_u32_e32 v149, s93, v144
	ds_read_b128 v[166:169], v149
	ds_read_b128 v[170:173], v149 offset:1024
	ds_read_b128 v[178:181], v149 offset:2048
	ds_read_b128 v[182:185], v149 offset:3072
	s_mov_b32 m0, s76
	ds_read_b128 v[186:189], v147 offset:32768
	ds_read_b128 v[190:193], v147 offset:33792
	ds_read_b128 v[194:197], v147 offset:34816
	ds_read_b128 v[198:201], v147 offset:35840
	ds_read_b128 v[202:205], v147 offset:36864
	ds_read_b128 v[206:209], v147 offset:37888
	ds_read_b128 v[210:213], v147 offset:38912
	ds_read_b128 v[214:217], v147 offset:39936
	global_load_lds_dwordx4 v128, s[56:57]
	s_mov_b32 m0, s77
	s_nop 0
	global_load_lds_dwordx4 v132, s[56:57]
	s_waitcnt vmcnt(8)
	s_waitcnt lgkmcnt(0)
	s_barrier
	s_setprio 1
	s_waitcnt lgkmcnt(0)
	v_mfma_f32_16x16x32_bf16 v[124:127], v[140:143], v[186:189], v[124:127]
	v_mfma_f32_16x16x32_bf16 v[120:123], v[158:161], v[186:189], v[120:123]
	v_mfma_f32_16x16x32_bf16 v[108:111], v[140:143], v[194:197], v[108:111]
	v_mfma_f32_16x16x32_bf16 v[104:107], v[158:161], v[194:197], v[104:107]
	v_mfma_f32_16x16x32_bf16 v[92:95], v[140:143], v[202:205], v[92:95]
	v_mfma_f32_16x16x32_bf16 v[88:91], v[158:161], v[202:205], v[88:91]
	v_mfma_f32_16x16x32_bf16 v[76:79], v[140:143], v[210:213], v[76:79]
	v_mfma_f32_16x16x32_bf16 v[72:75], v[158:161], v[210:213], v[72:75]
	v_mfma_f32_16x16x32_bf16 v[124:127], v[154:157], v[190:193], v[124:127]
	v_mfma_f32_16x16x32_bf16 v[120:123], v[162:165], v[190:193], v[120:123]
	v_mfma_f32_16x16x32_bf16 v[108:111], v[154:157], v[198:201], v[108:111]
	v_mfma_f32_16x16x32_bf16 v[104:107], v[162:165], v[198:201], v[104:107]
	v_mfma_f32_16x16x32_bf16 v[92:95], v[154:157], v[206:209], v[92:95]
	v_mfma_f32_16x16x32_bf16 v[88:91], v[162:165], v[206:209], v[88:91]
	v_mfma_f32_16x16x32_bf16 v[76:79], v[154:157], v[214:217], v[76:79]
	v_mfma_f32_16x16x32_bf16 v[72:75], v[162:165], v[214:217], v[72:75]
	s_setprio 0
	s_setprio 1
	v_mfma_f32_16x16x32_bf16 v[116:119], v[166:169], v[186:189], v[116:119]
	v_mfma_f32_16x16x32_bf16 v[112:115], v[178:181], v[186:189], v[112:115]
	v_mfma_f32_16x16x32_bf16 v[100:103], v[166:169], v[194:197], v[100:103]
	v_mfma_f32_16x16x32_bf16 v[96:99], v[178:181], v[194:197], v[96:99]
	v_mfma_f32_16x16x32_bf16 v[84:87], v[166:169], v[202:205], v[84:87]
	v_mfma_f32_16x16x32_bf16 v[80:83], v[178:181], v[202:205], v[80:83]
	v_mfma_f32_16x16x32_bf16 v[68:71], v[166:169], v[210:213], v[68:71]
	v_mfma_f32_16x16x32_bf16 v[64:67], v[178:181], v[210:213], v[64:67]
	v_mfma_f32_16x16x32_bf16 v[116:119], v[170:173], v[190:193], v[116:119]
	v_mfma_f32_16x16x32_bf16 v[112:115], v[182:185], v[190:193], v[112:115]
	v_mfma_f32_16x16x32_bf16 v[100:103], v[170:173], v[198:201], v[100:103]
	v_mfma_f32_16x16x32_bf16 v[96:99], v[182:185], v[198:201], v[96:99]
	v_mfma_f32_16x16x32_bf16 v[84:87], v[170:173], v[206:209], v[84:87]
	v_mfma_f32_16x16x32_bf16 v[80:83], v[182:185], v[206:209], v[80:83]
	v_mfma_f32_16x16x32_bf16 v[68:71], v[170:173], v[214:217], v[68:71]
	v_mfma_f32_16x16x32_bf16 v[64:67], v[182:185], v[214:217], v[64:67]
	s_setprio 0
	s_barrier
; #define PG8_STAGE(bufoff, gbase, voff) do { _Pragma("unroll") for (int _i = 0; _i < 2; ++_i) \
;         __builtin_amdgcn_global_load_lds((const unsigned*)((const char*)(gbase) + (voff)[_i]), (LAS unsigned*)(lds + (bufoff) + ldsw + _i * 8192), 16, 0, 0); } while (0)
; #define PG8_LDA(dst, b, h) do { _Pragma("unroll") for (int m = 0; m < 4; ++m) _Pragma("unroll") for (int k = 0; k < 2; ++k) dst[m][k] = *(const LAS bf16x8*)(lds + PG8_SA(b, h) + aoff + m * 2048 + k * 1024); } while (0)
; #define PG8_MMA(ai, bj, At, Bt) do { __builtin_amdgcn_s_setprio(1); _Pragma("unroll") for (int m = 0; m < 4; ++m) _Pragma("unroll") for (int n = 0; n < 2; ++n) _Pragma("unroll") for (int k = 0; k < 2; ++k) \
;         acc[ai][bj][m][n] = __builtin_amdgcn_mfma_f32_16x16x32_bf16(Bt[n][k], At[m][k], acc[ai][bj][m][n], 0, 0, 0); __builtin_amdgcn_s_setprio(0); } while (0)
; #define PG8_WAIT_V(n) asm volatile("s_waitcnt vmcnt(" #n ")" ::: "memory")
; #define PG8_WAIT_L(n) asm volatile("s_waitcnt lgkmcnt(" #n ")" ::: "memory")
; #define PG8_BAR __builtin_amdgcn_s_barrier()
; #define PG8_SCHED __builtin_amdgcn_sched_barrier(0)
; template <class Epi>
; __device__ __forceinline__ void gemm_phase(LAS unsigned char* lds, const Gemm g, const StaticOrder& S, const Epi& E) {
;     ...
;             PG8_LDA(At, 1, 1); PG8_STAGE(PG8_SB(1, 0), b3, voffB); PG8_STAGE(PG8_SB(1, 1), b3 + hstepB, voffB); PG8_STAGE(PG8_SA(1, 0), a3, voffA);
;             PG8_WAIT_V(8); PG8_WAIT_L(0); PG8_BAR; PG8_MMA(1, 0, At, B0); PG8_MMA(1, 1, At, B1); PG8_BAR; PG8_SCHED;
	s_mov_b32 m0, s92
	v_lshl_add_u64 v[174:175], v[174:175], 0, s[8:9]
	ds_read_b128 v[186:189], v147 offset:49152
	ds_read_b128 v[190:193], v147 offset:50176
	ds_read_b128 v[194:197], v147 offset:51200
	ds_read_b128 v[198:201], v147 offset:52224
	ds_read_b128 v[202:205], v147 offset:53248
	ds_read_b128 v[206:209], v147 offset:54272
	ds_read_b128 v[210:213], v147 offset:55296
	ds_read_b128 v[214:217], v147 offset:56320
	global_load_lds_dwordx4 v[174:175], off
	v_lshl_add_u64 v[174:175], v[218:219], 0, s[8:9]
	s_mov_b32 m0, s90
	s_nop 0
	global_load_lds_dwordx4 v[174:175], off
	s_mov_b32 m0, s91
	s_nop 0
	global_load_lds_dwordx4 v130, s[54:55]
	s_mov_b32 m0, s89
	s_nop 0
	global_load_lds_dwordx4 v134, s[54:55]
	v_lshl_add_u64 v[174:175], v[220:221], 0, s[8:9]
	s_mov_b32 m0, s81
	s_nop 0
	global_load_lds_dwordx4 v[174:175], off
	v_lshl_add_u64 v[174:175], v[222:223], 0, s[8:9]
	s_mov_b32 m0, s82
	s_nop 0
	global_load_lds_dwordx4 v[174:175], off
	s_waitcnt vmcnt(8)
	s_waitcnt lgkmcnt(0)
	s_barrier
	s_setprio 1
	s_waitcnt lgkmcnt(0)
	v_mfma_f32_16x16x32_bf16 v[60:63], v[140:143], v[186:189], v[60:63]
	v_mfma_f32_16x16x32_bf16 v[56:59], v[158:161], v[186:189], v[56:59]
	v_mfma_f32_16x16x32_bf16 v[44:47], v[140:143], v[194:197], v[44:47]
	v_mfma_f32_16x16x32_bf16 v[40:43], v[158:161], v[194:197], v[40:43]
	v_mfma_f32_16x16x32_bf16 v[28:31], v[140:143], v[202:205], v[28:31]
	v_mfma_f32_16x16x32_bf16 v[24:27], v[158:161], v[202:205], v[24:27]
	v_mfma_f32_16x16x32_bf16 v[12:15], v[140:143], v[210:213], v[12:15]
	v_mfma_f32_16x16x32_bf16 v[8:11], v[158:161], v[210:213], v[8:11]
	v_mfma_f32_16x16x32_bf16 v[60:63], v[154:157], v[190:193], v[60:63]
	v_mfma_f32_16x16x32_bf16 v[56:59], v[162:165], v[190:193], v[56:59]
	v_mfma_f32_16x16x32_bf16 v[44:47], v[154:157], v[198:201], v[44:47]
	v_mfma_f32_16x16x32_bf16 v[40:43], v[162:165], v[198:201], v[40:43]
	v_mfma_f32_16x16x32_bf16 v[28:31], v[154:157], v[206:209], v[28:31]
	v_mfma_f32_16x16x32_bf16 v[24:27], v[162:165], v[206:209], v[24:27]
	v_mfma_f32_16x16x32_bf16 v[12:15], v[154:157], v[214:217], v[12:15]
	v_mfma_f32_16x16x32_bf16 v[8:11], v[162:165], v[214:217], v[8:11]
	s_setprio 0
	s_setprio 1
	v_mfma_f32_16x16x32_bf16 v[52:55], v[166:169], v[186:189], v[52:55]
	v_mfma_f32_16x16x32_bf16 v[48:51], v[178:181], v[186:189], v[48:51]
	v_mfma_f32_16x16x32_bf16 v[36:39], v[166:169], v[194:197], v[36:39]
	v_mfma_f32_16x16x32_bf16 v[32:35], v[178:181], v[194:197], v[32:35]
	v_mfma_f32_16x16x32_bf16 v[20:23], v[166:169], v[202:205], v[20:23]
	v_mfma_f32_16x16x32_bf16 v[16:19], v[178:181], v[202:205], v[16:19]
	v_mfma_f32_16x16x32_bf16 v[4:7], v[166:169], v[210:213], v[4:7]
	v_mfma_f32_16x16x32_bf16 v[0:3], v[178:181], v[210:213], v[0:3]
	v_mfma_f32_16x16x32_bf16 v[52:55], v[170:173], v[190:193], v[52:55]
	v_mfma_f32_16x16x32_bf16 v[48:51], v[182:185], v[190:193], v[48:51]
	v_mfma_f32_16x16x32_bf16 v[36:39], v[170:173], v[198:201], v[36:39]
	v_mfma_f32_16x16x32_bf16 v[32:35], v[182:185], v[198:201], v[32:35]
	v_mfma_f32_16x16x32_bf16 v[20:23], v[170:173], v[206:209], v[20:23]
	v_mfma_f32_16x16x32_bf16 v[16:19], v[182:185], v[206:209], v[16:19]
	v_mfma_f32_16x16x32_bf16 v[4:7], v[170:173], v[214:217], v[4:7]
	v_mfma_f32_16x16x32_bf16 v[0:3], v[182:185], v[214:217], v[0:3]
	s_setprio 0
	s_barrier
	s_andn2_b64 vcc, exec, s[52:53]
	s_mov_b64 s[54:55], -1
	s_mov_b64 s[52:53], 0
	s_mov_b64 s[56:57], 0x100
	s_cbranch_vccz .LBB0_612
	s_and_b64 vcc, exec, s[10:11]
	s_cbranch_vccz .LBB0_615
	s_barrier

; #define PG8_STAGE(bufoff, gbase, voff) do { _Pragma("unroll") for (int _i = 0; _i < 2; ++_i) \
;         __builtin_amdgcn_global_load_lds((const unsigned*)((const char*)(gbase) + (voff)[_i]), (LAS unsigned*)(lds + (bufoff) + ldsw + _i * 8192), 16, 0, 0); } while (0)
; #define PG8_WAIT_V(n) asm volatile("s_waitcnt vmcnt(" #n ")" ::: "memory")
; #define PG8_BAR __builtin_amdgcn_s_barrier()
; template <class Epi>
; __device__ __forceinline__ void gemm_phase(LAS unsigned char* lds, const Gemm g, const StaticOrder& S, const Epi& E) {
;     ...
;     for (int i = 0; i < 2; ++i) { int R, C; stage_rc(tid * 16 + i * 8192, R, C); const int Rb = (R & ~31) + perm32(R & 31);
;         voffA[i] = (unsigned)(R * g.lda + C) * 2u; voffB[i] = (unsigned)(Rb * g.ldb + C) * 2u; }
;     const size_t kstep = (size_t)(BK * 2);
;     const size_t hstepA = (size_t)HALF * g.lda * 2, hstepB = (size_t)HALF * g.ldb * 2;
;     const size_t tstepA = 2 * hstepA, tstepB = 2 * hstepB;
;     const unsigned ldsw = (unsigned)wid * 1024u;
;     const int aoff = lds_byte(wr * 64 + fr, fq * 8), boff = lds_byte(wc * 32 + fr, fq * 8);
;     ...
;     PG8_STAGE(PG8_SB(0, 0), cB, voffB); PG8_STAGE(PG8_SB(0, 1), cB + hstepB, voffB); PG8_STAGE(PG8_SA(0, 0), cA, voffA); PG8_STAGE(PG8_SA(0, 1), cA + hstepA, voffA);
;     if (wr == 1) PG8_BAR;
;     PG8_WAIT_V(2); PG8_BAR;
;     PG8_STAGE(PG8_SB(1, 0), cB + kstep, voffB); PG8_STAGE(PG8_SA(1, 0), cA + kstep, voffA); PG8_STAGE(PG8_SB(1, 1), cB + hstepB + kstep, voffB);
;     PG8_WAIT_V(6); PG8_BAR;
.LBB0_778:
	s_add_u32 s12, s50, 0x40000
	s_addc_u32 s13, s51, 0
	s_lshl_b32 s56, s4, 6
	s_lshl_b32 s7, s4, 13
	s_lshl_b32 s4, s5, 5
	s_mov_b64 s[16:17], 0x80
	s_and_b32 s57, s4, 0x60
	s_add_i32 m0, s43, 0x18000
	v_lshl_add_u64 v[6:7], v[6:7], 0, s[16:17]
	s_lshl_b32 s18, s57, 7
	s_waitcnt vmcnt(2)
	s_barrier
	global_load_lds_dwordx4 v[6:7], off
	v_lshl_add_u64 v[4:5], v[4:5], 0, s[16:17]
	s_add_i32 m0, s43, 0x1a000
	s_add_i32 s62, s43, 0x8000
	s_add_i32 s63, s43, 0xa000
	global_load_lds_dwordx4 v[4:5], off
	v_lshl_add_u64 v[0:1], v[0:1], 0, s[16:17]
	s_mov_b32 m0, s62
	s_add_u32 s4, s34, 0xb0080
	global_load_lds_dwordx4 v[0:1], off
	v_lshl_add_u64 v[0:1], v[2:3], 0, s[16:17]
	s_mov_b32 m0, s63
	s_addc_u32 s5, s35, 0
	global_load_lds_dwordx4 v[0:1], off
	s_add_i32 m0, s43, 0x1c000
	global_load_lds_dwordx4 v146, s[4:5]
	s_add_i32 m0, s43, 0x1e000
	v_bfe_u32 v177, v176, 4, 2
	global_load_lds_dwordx4 v150, s[4:5]
	v_and_b32_e32 v180, 15, v176
	v_lshlrev_b32_e32 v0, 4, v177
	v_lshlrev_b32_e32 v2, 2, v176
	v_lshlrev_b32_e32 v3, 6, v176
	s_movk_i32 s4, 0x3c0
	v_lshl_or_b32 v1, v180, 6, v0
	v_and_b32_e32 v2, 32, v2
	v_and_or_b32 v0, v3, s4, v0
	v_bitop3_b32 v181, s18, v0, v2 bitop3:0xf6
	v_add_u16_e32 v0, v8, v9
	v_bitop3_b32 v1, v1, s7, v2 bitop3:0xde
	s_waitcnt vmcnt(6)
	s_cmpk_lt_u32 s6, 0x100
	v_readlane_b32 s4, v254, 6
	v_lshrrev_b16_e32 v0, 1, v0
	s_cselect_b64 s[18:19], -1, 0
	v_readlane_b32 s6, v254, 8
	v_add_lshl_u32 v152, v10, v0, 1
	v_add_lshl_u32 v154, v11, v0, 1
	s_add_i32 s69, 0, 0x10000
	s_add_i32 s70, 0, 0x14000
	v_mbcnt_lo_u32_b32 v0, -1, 0
	s_ashr_i32 s64, s6, 31
	s_mov_b32 s65, s6
	s_ashr_i32 s68, s2, 31
	v_mov_b32_e32 v153, v147
	v_mov_b32_e32 v155, v147
	v_mov_b64_e32 v[156:157], 0x200
	v_mov_b64_e32 v[158:159], 0x1ff
	v_add_u32_e32 v182, s69, v181
	v_add_u32_e32 v183, s70, v181
	v_add_u32_e32 v184, 0, v1
	v_mbcnt_hi_u32_b32 v185, -1, v0
	s_barrier
	v_readlane_b32 s5, v254, 7
	v_readlane_b32 s7, v254, 9
	s_branch .LBB0_781

; #define PG8_STAGE(bufoff, gbase, voff) do { _Pragma("unroll") for (int _i = 0; _i < 2; ++_i) \
;         __builtin_amdgcn_global_load_lds((const unsigned*)((const char*)(gbase) + (voff)[_i]), (LAS unsigned*)(lds + (bufoff) + ldsw + _i * 8192), 16, 0, 0); } while (0)
; #define PG8_LDA(dst, b, h) do { _Pragma("unroll") for (int m = 0; m < 4; ++m) _Pragma("unroll") for (int k = 0; k < 2; ++k) dst[m][k] = *(const LAS bf16x8*)(lds + PG8_SA(b, h) + aoff + m * 2048 + k * 1024); } while (0)
; #define PG8_LDB(dst, b, h) do { _Pragma("unroll") for (int n = 0; n < 2; ++n) _Pragma("unroll") for (int k = 0; k < 2; ++k) dst[n][k] = *(const LAS bf16x8*)(lds + PG8_SB(b, h) + boff + n * 2048 + k * 1024); } while (0)
; #define PG8_MMA(ai, bj, At, Bt) do { __builtin_amdgcn_s_setprio(1); _Pragma("unroll") for (int m = 0; m < 4; ++m) _Pragma("unroll") for (int n = 0; n < 2; ++n) _Pragma("unroll") for (int k = 0; k < 2; ++k) \
;         acc[ai][bj][m][n] = __builtin_amdgcn_mfma_f32_16x16x32_bf16(Bt[n][k], At[m][k], acc[ai][bj][m][n], 0, 0, 0); __builtin_amdgcn_s_setprio(0); } while (0)
; #define PG8_WAIT_V(n) asm volatile("s_waitcnt vmcnt(" #n ")" ::: "memory")
; #define PG8_WAIT_L(n) asm volatile("s_waitcnt lgkmcnt(" #n ")" ::: "memory")
; #define PG8_BAR __builtin_amdgcn_s_barrier()
; #define PG8_SCHED __builtin_amdgcn_sched_barrier(0)
; template <class Epi>
; __device__ __forceinline__ void gemm_phase(LAS unsigned char* lds, const Gemm g, const StaticOrder& S, const Epi& E) {
;     ...
;         for (int t = 0; t < nt; t += 2) {
;             const bool last = (t == nt - 2);
;             const char* a1 = cA + (size_t)(t + 1) * kstep;
;             const char* a2 = last ? nA : cA + (size_t)(t + 2) * kstep; const char* b2 = last ? nB : cB + (size_t)(t + 2) * kstep;
;             const char* a3 = a2 + kstep; const char* b3 = b2 + kstep;
;             PG8_LDB(B0, 0, 0); PG8_LDB(B1, 0, 1); PG8_SCHED; PG8_LDA(At, 0, 0); PG8_STAGE(PG8_SA(1, 1), a1 + hstepA, voffA);
;             PG8_WAIT_V(8); PG8_WAIT_L(0); PG8_BAR; PG8_MMA(0, 0, At, B0); PG8_MMA(0, 1, At, B1); PG8_BAR; PG8_SCHED;
;             PG8_LDA(At, 0, 1); PG8_STAGE(PG8_SB(0, 0), b2, voffB); PG8_STAGE(PG8_SB(0, 1), b2 + hstepB, voffB); PG8_STAGE(PG8_SA(0, 0), a2, voffA);
;             PG8_WAIT_V(8); PG8_WAIT_L(0); PG8_BAR; PG8_MMA(1, 0, At, B0); PG8_MMA(1, 1, At, B1); PG8_BAR; PG8_SCHED;
.LBB0_791:
	s_add_u32 s0, s0, 0xb0080
	s_addc_u32 s1, s1, 0
	s_add_u32 s75, s34, 0x100
	s_addc_u32 s76, s35, 0
	s_mov_b32 s77, -2
	s_waitcnt lgkmcnt(0)
	s_nop 0
	ds_read_b128 v[128:131], v182
	ds_read_b128 v[132:135], v182 offset:1024
	ds_read_b128 v[136:139], v182 offset:2048
	ds_read_b128 v[140:143], v182 offset:3072
	ds_read_b128 v[160:163], v183
	ds_read_b128 v[164:167], v183 offset:1024
	ds_read_b128 v[168:171], v183 offset:2048
	ds_read_b128 v[172:175], v183 offset:3072
	s_add_u32 s34, s0, 0xfff50080
	s_addc_u32 s35, s1, -1
	s_cmp_eq_u32 s77, 40
	s_cselect_b32 s39, s7, s35
	s_cselect_b32 s38, s6, s34
	s_cselect_b32 s35, s23, s76
	s_cselect_b32 s34, s22, s75
	s_add_i32 m0, s43, 0xc000
	ds_read_b128 v[186:189], v184
	ds_read_b128 v[190:193], v184 offset:1024
	ds_read_b128 v[194:197], v184 offset:2048
	ds_read_b128 v[198:201], v184 offset:3072
	ds_read_b128 v[202:205], v184 offset:4096
	ds_read_b128 v[206:209], v184 offset:5120
	ds_read_b128 v[210:213], v184 offset:6144
	ds_read_b128 v[214:217], v184 offset:7168
	global_load_lds_dwordx4 v152, s[0:1]
	s_add_i32 m0, s43, 0xe000
	s_nop 0
	global_load_lds_dwordx4 v154, s[0:1]
	s_waitcnt vmcnt(8)
	s_waitcnt lgkmcnt(0)
	s_barrier
	s_setprio 1
	s_waitcnt lgkmcnt(0)
	v_mfma_f32_16x16x32_bf16 v[124:127], v[128:131], v[186:189], 0
	v_mfma_f32_16x16x32_bf16 v[120:123], v[136:139], v[186:189], 0
	v_mfma_f32_16x16x32_bf16 v[108:111], v[128:131], v[194:197], 0
	v_mfma_f32_16x16x32_bf16 v[104:107], v[136:139], v[194:197], 0
	v_mfma_f32_16x16x32_bf16 v[92:95], v[128:131], v[202:205], 0
	v_mfma_f32_16x16x32_bf16 v[88:91], v[136:139], v[202:205], 0
	v_mfma_f32_16x16x32_bf16 v[76:79], v[128:131], v[210:213], 0
	v_mfma_f32_16x16x32_bf16 v[72:75], v[136:139], v[210:213], 0
	v_mfma_f32_16x16x32_bf16 v[124:127], v[132:135], v[190:193], v[124:127]
	v_mfma_f32_16x16x32_bf16 v[120:123], v[140:143], v[190:193], v[120:123]
	v_mfma_f32_16x16x32_bf16 v[108:111], v[132:135], v[198:201], v[108:111]
	v_mfma_f32_16x16x32_bf16 v[104:107], v[140:143], v[198:201], v[104:107]
	v_mfma_f32_16x16x32_bf16 v[92:95], v[132:135], v[206:209], v[92:95]
	v_mfma_f32_16x16x32_bf16 v[88:91], v[140:143], v[206:209], v[88:91]
	v_mfma_f32_16x16x32_bf16 v[76:79], v[132:135], v[214:217], v[76:79]
	v_mfma_f32_16x16x32_bf16 v[72:75], v[140:143], v[214:217], v[72:75]
	s_setprio 0
	s_setprio 1
	v_mfma_f32_16x16x32_bf16 v[116:119], v[160:163], v[186:189], 0
	v_mfma_f32_16x16x32_bf16 v[112:115], v[168:171], v[186:189], 0
	v_mfma_f32_16x16x32_bf16 v[100:103], v[160:163], v[194:197], 0
	v_mfma_f32_16x16x32_bf16 v[96:99], v[168:171], v[194:197], 0
	v_mfma_f32_16x16x32_bf16 v[84:87], v[160:163], v[202:205], 0
	v_mfma_f32_16x16x32_bf16 v[80:83], v[168:171], v[202:205], 0
	v_mfma_f32_16x16x32_bf16 v[68:71], v[160:163], v[210:213], 0
	v_mfma_f32_16x16x32_bf16 v[64:67], v[168:171], v[210:213], 0
	v_mfma_f32_16x16x32_bf16 v[116:119], v[164:167], v[190:193], v[116:119]
	v_mfma_f32_16x16x32_bf16 v[112:115], v[172:175], v[190:193], v[112:115]
	v_mfma_f32_16x16x32_bf16 v[100:103], v[164:167], v[198:201], v[100:103]
	v_mfma_f32_16x16x32_bf16 v[96:99], v[172:175], v[198:201], v[96:99]
	v_mfma_f32_16x16x32_bf16 v[84:87], v[164:167], v[206:209], v[84:87]
	v_mfma_f32_16x16x32_bf16 v[80:83], v[172:175], v[206:209], v[80:83]
	v_mfma_f32_16x16x32_bf16 v[68:71], v[164:167], v[214:217], v[68:71]
	v_mfma_f32_16x16x32_bf16 v[64:67], v[172:175], v[214:217], v[64:67]
	s_setprio 0
	s_barrier
	s_add_i32 s78, s69, s42
	v_lshl_add_u64 v[178:179], s[34:35], 0, v[146:147]
	s_mov_b32 m0, s78
	ds_read_b128 v[186:189], v184 offset:16384
	ds_read_b128 v[190:193], v184 offset:17408
	ds_read_b128 v[194:197], v184 offset:18432
	ds_read_b128 v[198:201], v184 offset:19456
	ds_read_b128 v[202:205], v184 offset:20480
	ds_read_b128 v[206:209], v184 offset:21504
	ds_read_b128 v[210:213], v184 offset:22528
	ds_read_b128 v[214:217], v184 offset:23552
	global_load_lds_dwordx4 v[178:179], off
	s_add_i32 m0, s78, 0x2000
	s_add_u32 s78, s34, 0xb0000
	v_lshl_add_u64 v[218:219], s[34:35], 0, v[150:151]
	s_addc_u32 s79, s35, 0
	s_add_i32 s80, s70, s42
	global_load_lds_dwordx4 v[218:219], off
	s_mov_b32 m0, s80
	v_lshl_add_u64 v[222:223], s[38:39], 0, v[148:149]
	global_load_lds_dwordx4 v146, s[78:79]
	s_add_i32 m0, s80, 0x2000
	s_nop 0
	global_load_lds_dwordx4 v150, s[78:79]
	v_lshl_add_u64 v[220:221], s[38:39], 0, v[144:145]
	s_mov_b32 m0, s43
	s_nop 0
	global_load_lds_dwordx4 v[220:221], off
	s_mov_b32 m0, s52
	s_nop 0
	global_load_lds_dwordx4 v[222:223], off
	s_waitcnt vmcnt(8)
	s_waitcnt lgkmcnt(0)
	s_barrier
	s_setprio 1
	s_waitcnt lgkmcnt(0)
	v_mfma_f32_16x16x32_bf16 v[60:63], v[128:131], v[186:189], 0
	v_mfma_f32_16x16x32_bf16 v[56:59], v[136:139], v[186:189], 0
	v_mfma_f32_16x16x32_bf16 v[44:47], v[128:131], v[194:197], 0
	v_mfma_f32_16x16x32_bf16 v[40:43], v[136:139], v[194:197], 0
	v_mfma_f32_16x16x32_bf16 v[28:31], v[128:131], v[202:205], 0
	v_mfma_f32_16x16x32_bf16 v[24:27], v[136:139], v[202:205], 0
	v_mfma_f32_16x16x32_bf16 v[12:15], v[128:131], v[210:213], 0
	v_mfma_f32_16x16x32_bf16 v[8:11], v[136:139], v[210:213], 0
	v_mfma_f32_16x16x32_bf16 v[60:63], v[132:135], v[190:193], v[60:63]
	v_mfma_f32_16x16x32_bf16 v[56:59], v[140:143], v[190:193], v[56:59]
	v_mfma_f32_16x16x32_bf16 v[44:47], v[132:135], v[198:201], v[44:47]
	v_mfma_f32_16x16x32_bf16 v[40:43], v[140:143], v[198:201], v[40:43]
	v_mfma_f32_16x16x32_bf16 v[28:31], v[132:135], v[206:209], v[28:31]
	v_mfma_f32_16x16x32_bf16 v[24:27], v[140:143], v[206:209], v[24:27]
	v_mfma_f32_16x16x32_bf16 v[12:15], v[132:135], v[214:217], v[12:15]
	v_mfma_f32_16x16x32_bf16 v[8:11], v[140:143], v[214:217], v[8:11]
	s_setprio 0
	s_setprio 1
	v_mfma_f32_16x16x32_bf16 v[52:55], v[160:163], v[186:189], 0
	v_mfma_f32_16x16x32_bf16 v[48:51], v[168:171], v[186:189], 0
	v_mfma_f32_16x16x32_bf16 v[36:39], v[160:163], v[194:197], 0
	v_mfma_f32_16x16x32_bf16 v[32:35], v[168:171], v[194:197], 0
	v_mfma_f32_16x16x32_bf16 v[20:23], v[160:163], v[202:205], 0
	v_mfma_f32_16x16x32_bf16 v[16:19], v[168:171], v[202:205], 0
	v_mfma_f32_16x16x32_bf16 v[4:7], v[160:163], v[210:213], 0
	v_mfma_f32_16x16x32_bf16 v[0:3], v[168:171], v[210:213], 0
	v_mfma_f32_16x16x32_bf16 v[52:55], v[164:167], v[190:193], v[52:55]
	v_mfma_f32_16x16x32_bf16 v[48:51], v[172:175], v[190:193], v[48:51]
	v_mfma_f32_16x16x32_bf16 v[36:39], v[164:167], v[198:201], v[36:39]
	v_mfma_f32_16x16x32_bf16 v[32:35], v[172:175], v[198:201], v[32:35]
	v_mfma_f32_16x16x32_bf16 v[20:23], v[164:167], v[206:209], v[20:23]
	v_mfma_f32_16x16x32_bf16 v[16:19], v[172:175], v[206:209], v[16:19]
	v_mfma_f32_16x16x32_bf16 v[4:7], v[164:167], v[214:217], v[4:7]
	v_mfma_f32_16x16x32_bf16 v[0:3], v[172:175], v[214:217], v[0:3]
	s_setprio 0
	s_barrier
; #define PG8_STAGE(bufoff, gbase, voff) do { _Pragma("unroll") for (int _i = 0; _i < 2; ++_i) \
;         __builtin_amdgcn_global_load_lds((const unsigned*)((const char*)(gbase) + (voff)[_i]), (LAS unsigned*)(lds + (bufoff) + ldsw + _i * 8192), 16, 0, 0); } while (0)
; #define PG8_LDA(dst, b, h) do { _Pragma("unroll") for (int m = 0; m < 4; ++m) _Pragma("unroll") for (int k = 0; k < 2; ++k) dst[m][k] = *(const LAS bf16x8*)(lds + PG8_SA(b, h) + aoff + m * 2048 + k * 1024); } while (0)
; #define PG8_LDB(dst, b, h) do { _Pragma("unroll") for (int n = 0; n < 2; ++n) _Pragma("unroll") for (int k = 0; k < 2; ++k) dst[n][k] = *(const LAS bf16x8*)(lds + PG8_SB(b, h) + boff + n * 2048 + k * 1024); } while (0)
; #define PG8_MMA(ai, bj, At, Bt) do { __builtin_amdgcn_s_setprio(1); _Pragma("unroll") for (int m = 0; m < 4; ++m) _Pragma("unroll") for (int n = 0; n < 2; ++n) _Pragma("unroll") for (int k = 0; k < 2; ++k) \
;         acc[ai][bj][m][n] = __builtin_amdgcn_mfma_f32_16x16x32_bf16(Bt[n][k], At[m][k], acc[ai][bj][m][n], 0, 0, 0); __builtin_amdgcn_s_setprio(0); } while (0)
; #define PG8_WAIT_V(n) asm volatile("s_waitcnt vmcnt(" #n ")" ::: "memory")
; #define PG8_WAIT_L(n) asm volatile("s_waitcnt lgkmcnt(" #n ")" ::: "memory")
; #define PG8_BAR __builtin_amdgcn_s_barrier()
; #define PG8_SCHED __builtin_amdgcn_sched_barrier(0)
; template <class Epi>
; __device__ __forceinline__ void gemm_phase(LAS unsigned char* lds, const Gemm g, const StaticOrder& S, const Epi& E) {
;     ...
;             PG8_WAIT_V(8); PG8_WAIT_L(0); PG8_BAR; PG8_MMA(1, 0, At, B0); PG8_MMA(1, 1, At, B1); PG8_BAR; PG8_SCHED;
;             PG8_LDB(B0, 1, 0); PG8_LDB(B1, 1, 1); PG8_SCHED; PG8_LDA(At, 1, 0); PG8_STAGE(PG8_SA(0, 1), a2 + hstepA, voffA);
;             PG8_WAIT_V(8); PG8_WAIT_L(0); PG8_BAR; PG8_MMA(0, 0, At, B0); PG8_MMA(0, 1, At, B1); PG8_BAR; PG8_SCHED;
;             PG8_LDA(At, 1, 1); PG8_STAGE(PG8_SB(1, 0), b3, voffB); PG8_STAGE(PG8_SB(1, 1), b3 + hstepB, voffB); PG8_STAGE(PG8_SA(1, 0), a3, voffA);
;             PG8_WAIT_V(8); PG8_WAIT_L(0); PG8_BAR; PG8_MMA(1, 0, At, B0); PG8_MMA(1, 1, At, B1); PG8_BAR; PG8_SCHED;
	s_add_i32 s78, 0, 0x18000
	s_add_i32 s79, 0, 0x1c000
	v_add_u32_e32 v140, s78, v181
	v_add_u32_e32 v172, s79, v181
	ds_read_b128 v[128:131], v140
	ds_read_b128 v[132:135], v140 offset:1024
	ds_read_b128 v[136:139], v140 offset:2048
	ds_read_b128 v[140:143], v140 offset:3072
	ds_read_b128 v[160:163], v172
	ds_read_b128 v[164:167], v172 offset:1024
	ds_read_b128 v[168:171], v172 offset:2048
	ds_read_b128 v[172:175], v172 offset:3072
	s_add_u32 s38, s38, 0xb0000
	s_addc_u32 s39, s39, 0
	s_mov_b32 m0, s53
	ds_read_b128 v[186:189], v184 offset:32768
	ds_read_b128 v[190:193], v184 offset:33792
	ds_read_b128 v[194:197], v184 offset:34816
	ds_read_b128 v[198:201], v184 offset:35840
	ds_read_b128 v[202:205], v184 offset:36864
	ds_read_b128 v[206:209], v184 offset:37888
	ds_read_b128 v[210:213], v184 offset:38912
	ds_read_b128 v[214:217], v184 offset:39936
	global_load_lds_dwordx4 v144, s[38:39]
	s_mov_b32 m0, s54
	s_nop 0
	global_load_lds_dwordx4 v148, s[38:39]
	s_waitcnt vmcnt(8)
	s_waitcnt lgkmcnt(0)
	s_barrier
	s_setprio 1
	s_waitcnt lgkmcnt(0)
	v_mfma_f32_16x16x32_bf16 v[124:127], v[128:131], v[186:189], v[124:127]
	v_mfma_f32_16x16x32_bf16 v[120:123], v[136:139], v[186:189], v[120:123]
	v_mfma_f32_16x16x32_bf16 v[108:111], v[128:131], v[194:197], v[108:111]
	v_mfma_f32_16x16x32_bf16 v[104:107], v[136:139], v[194:197], v[104:107]
	v_mfma_f32_16x16x32_bf16 v[92:95], v[128:131], v[202:205], v[92:95]
	v_mfma_f32_16x16x32_bf16 v[88:91], v[136:139], v[202:205], v[88:91]
	v_mfma_f32_16x16x32_bf16 v[76:79], v[128:131], v[210:213], v[76:79]
	v_mfma_f32_16x16x32_bf16 v[72:75], v[136:139], v[210:213], v[72:75]
	v_mfma_f32_16x16x32_bf16 v[124:127], v[132:135], v[190:193], v[124:127]
	v_mfma_f32_16x16x32_bf16 v[120:123], v[140:143], v[190:193], v[120:123]
	v_mfma_f32_16x16x32_bf16 v[108:111], v[132:135], v[198:201], v[108:111]
	v_mfma_f32_16x16x32_bf16 v[104:107], v[140:143], v[198:201], v[104:107]
	v_mfma_f32_16x16x32_bf16 v[92:95], v[132:135], v[206:209], v[92:95]
	v_mfma_f32_16x16x32_bf16 v[88:91], v[140:143], v[206:209], v[88:91]
	v_mfma_f32_16x16x32_bf16 v[76:79], v[132:135], v[214:217], v[76:79]
	v_mfma_f32_16x16x32_bf16 v[72:75], v[140:143], v[214:217], v[72:75]
	s_setprio 0
	s_setprio 1
	v_mfma_f32_16x16x32_bf16 v[116:119], v[160:163], v[186:189], v[116:119]
	v_mfma_f32_16x16x32_bf16 v[112:115], v[168:171], v[186:189], v[112:115]
	v_mfma_f32_16x16x32_bf16 v[100:103], v[160:163], v[194:197], v[100:103]
	v_mfma_f32_16x16x32_bf16 v[96:99], v[168:171], v[194:197], v[96:99]
	v_mfma_f32_16x16x32_bf16 v[84:87], v[160:163], v[202:205], v[84:87]
	v_mfma_f32_16x16x32_bf16 v[80:83], v[168:171], v[202:205], v[80:83]
	v_mfma_f32_16x16x32_bf16 v[68:71], v[160:163], v[210:213], v[68:71]
	v_mfma_f32_16x16x32_bf16 v[64:67], v[168:171], v[210:213], v[64:67]
	v_mfma_f32_16x16x32_bf16 v[116:119], v[164:167], v[190:193], v[116:119]
	v_mfma_f32_16x16x32_bf16 v[112:115], v[172:175], v[190:193], v[112:115]
	v_mfma_f32_16x16x32_bf16 v[100:103], v[164:167], v[198:201], v[100:103]
	v_mfma_f32_16x16x32_bf16 v[96:99], v[172:175], v[198:201], v[96:99]
	v_mfma_f32_16x16x32_bf16 v[84:87], v[164:167], v[206:209], v[84:87]
	v_mfma_f32_16x16x32_bf16 v[80:83], v[172:175], v[206:209], v[80:83]
	v_mfma_f32_16x16x32_bf16 v[68:71], v[164:167], v[214:217], v[68:71]
	v_mfma_f32_16x16x32_bf16 v[64:67], v[172:175], v[214:217], v[64:67]
	s_setprio 0
	s_barrier
	s_add_i32 s38, s78, s42
	v_lshl_add_u64 v[178:179], v[178:179], 0, s[16:17]
	s_mov_b32 m0, s38
	ds_read_b128 v[186:189], v184 offset:49152
	ds_read_b128 v[190:193], v184 offset:50176
	ds_read_b128 v[194:197], v184 offset:51200
	ds_read_b128 v[198:201], v184 offset:52224
	ds_read_b128 v[202:205], v184 offset:53248
	ds_read_b128 v[206:209], v184 offset:54272
	ds_read_b128 v[210:213], v184 offset:55296
	ds_read_b128 v[214:217], v184 offset:56320
	global_load_lds_dwordx4 v[178:179], off
	s_add_i32 m0, s38, 0x2000
	s_add_u32 s34, s34, 0xb0080
	v_lshl_add_u64 v[178:179], v[218:219], 0, s[16:17]
	s_addc_u32 s35, s35, 0
	s_add_i32 s38, s79, s42
	global_load_lds_dwordx4 v[178:179], off
	s_mov_b32 m0, s38
	s_nop 0
	global_load_lds_dwordx4 v146, s[34:35]
	s_add_i32 m0, s38, 0x2000
	s_nop 0
	global_load_lds_dwordx4 v150, s[34:35]
	v_lshl_add_u64 v[178:179], v[220:221], 0, s[16:17]
	s_mov_b32 m0, s62
	s_nop 0
	global_load_lds_dwordx4 v[178:179], off
	v_lshl_add_u64 v[178:179], v[222:223], 0, s[16:17]
	s_mov_b32 m0, s63
	s_nop 0
	global_load_lds_dwordx4 v[178:179], off
	s_waitcnt vmcnt(8)
	s_waitcnt lgkmcnt(0)
	s_barrier
	s_setprio 1
	s_waitcnt lgkmcnt(0)
	v_mfma_f32_16x16x32_bf16 v[60:63], v[128:131], v[186:189], v[60:63]
	v_mfma_f32_16x16x32_bf16 v[56:59], v[136:139], v[186:189], v[56:59]
	v_mfma_f32_16x16x32_bf16 v[44:47], v[128:131], v[194:197], v[44:47]
	v_mfma_f32_16x16x32_bf16 v[40:43], v[136:139], v[194:197], v[40:43]
	v_mfma_f32_16x16x32_bf16 v[28:31], v[128:131], v[202:205], v[28:31]
	v_mfma_f32_16x16x32_bf16 v[24:27], v[136:139], v[202:205], v[24:27]
	v_mfma_f32_16x16x32_bf16 v[12:15], v[128:131], v[210:213], v[12:15]
	v_mfma_f32_16x16x32_bf16 v[8:11], v[136:139], v[210:213], v[8:11]
	v_mfma_f32_16x16x32_bf16 v[60:63], v[132:135], v[190:193], v[60:63]
	v_mfma_f32_16x16x32_bf16 v[56:59], v[140:143], v[190:193], v[56:59]
	v_mfma_f32_16x16x32_bf16 v[44:47], v[132:135], v[198:201], v[44:47]
	v_mfma_f32_16x16x32_bf16 v[40:43], v[140:143], v[198:201], v[40:43]
	v_mfma_f32_16x16x32_bf16 v[28:31], v[132:135], v[206:209], v[28:31]
	v_mfma_f32_16x16x32_bf16 v[24:27], v[140:143], v[206:209], v[24:27]
	v_mfma_f32_16x16x32_bf16 v[12:15], v[132:135], v[214:217], v[12:15]
	v_mfma_f32_16x16x32_bf16 v[8:11], v[140:143], v[214:217], v[8:11]
	s_setprio 0
	s_setprio 1
	v_mfma_f32_16x16x32_bf16 v[52:55], v[160:163], v[186:189], v[52:55]
	v_mfma_f32_16x16x32_bf16 v[48:51], v[168:171], v[186:189], v[48:51]
	v_mfma_f32_16x16x32_bf16 v[36:39], v[160:163], v[194:197], v[36:39]
	v_mfma_f32_16x16x32_bf16 v[32:35], v[168:171], v[194:197], v[32:35]
	v_mfma_f32_16x16x32_bf16 v[20:23], v[160:163], v[202:205], v[20:23]
	v_mfma_f32_16x16x32_bf16 v[16:19], v[168:171], v[202:205], v[16:19]
	v_mfma_f32_16x16x32_bf16 v[4:7], v[160:163], v[210:213], v[4:7]
	v_mfma_f32_16x16x32_bf16 v[0:3], v[168:171], v[210:213], v[0:3]
	v_mfma_f32_16x16x32_bf16 v[52:55], v[164:167], v[190:193], v[52:55]
	v_mfma_f32_16x16x32_bf16 v[48:51], v[172:175], v[190:193], v[48:51]
	v_mfma_f32_16x16x32_bf16 v[36:39], v[164:167], v[198:201], v[36:39]
	v_mfma_f32_16x16x32_bf16 v[32:35], v[172:175], v[198:201], v[32:35]
	v_mfma_f32_16x16x32_bf16 v[20:23], v[164:167], v[206:209], v[20:23]
	v_mfma_f32_16x16x32_bf16 v[16:19], v[172:175], v[206:209], v[16:19]
	v_mfma_f32_16x16x32_bf16 v[4:7], v[164:167], v[214:217], v[4:7]
	v_mfma_f32_16x16x32_bf16 v[0:3], v[172:175], v[214:217], v[0:3]
	s_setprio 0
	s_barrier
	s_add_i32 s77, s77, 2
	s_add_u32 s0, s0, 0x100
	s_addc_u32 s1, s1, 0
	s_add_u32 s75, s75, 0x100
	s_addc_u32 s76, s76, 0
	s_cmp_gt_u32 s77, 41
; #define PG8_STAGE(bufoff, gbase, voff) do { _Pragma("unroll") for (int _i = 0; _i < 2; ++_i) \
;         __builtin_amdgcn_global_load_lds((const unsigned*)((const char*)(gbase) + (voff)[_i]), (LAS unsigned*)(lds + (bufoff) + ldsw + _i * 8192), 16, 0, 0); } while (0)
; #define PG8_LDA(dst, b, h) do { _Pragma("unroll") for (int m = 0; m < 4; ++m) _Pragma("unroll") for (int k = 0; k < 2; ++k) dst[m][k] = *(const LAS bf16x8*)(lds + PG8_SA(b, h) + aoff + m * 2048 + k * 1024); } while (0)
; #define PG8_LDB(dst, b, h) do { _Pragma("unroll") for (int n = 0; n < 2; ++n) _Pragma("unroll") for (int k = 0; k < 2; ++k) dst[n][k] = *(const LAS bf16x8*)(lds + PG8_SB(b, h) + boff + n * 2048 + k * 1024); } while (0)
; #define PG8_MMA(ai, bj, At, Bt) do { __builtin_amdgcn_s_setprio(1); _Pragma("unroll") for (int m = 0; m < 4; ++m) _Pragma("unroll") for (int n = 0; n < 2; ++n) _Pragma("unroll") for (int k = 0; k < 2; ++k) \
;         acc[ai][bj][m][n] = __builtin_amdgcn_mfma_f32_16x16x32_bf16(Bt[n][k], At[m][k], acc[ai][bj][m][n], 0, 0, 0); __builtin_amdgcn_s_setprio(0); } while (0)
; #define PG8_WAIT_V(n) asm volatile("s_waitcnt vmcnt(" #n ")" ::: "memory")
; #define PG8_WAIT_L(n) asm volatile("s_waitcnt lgkmcnt(" #n ")" ::: "memory")
; #define PG8_BAR __builtin_amdgcn_s_barrier()
; #define PG8_SCHED __builtin_amdgcn_sched_barrier(0)
; template <class Epi>
; __device__ __forceinline__ void gemm_phase(LAS unsigned char* lds, const Gemm g, const StaticOrder& S, const Epi& E) {
;     ...
;             const bool last = (t == nt - 2);
;             const char* a1 = cA + (size_t)(t + 1) * kstep;
;             const char* a2 = last ? nA : cA + (size_t)(t + 2) * kstep; const char* b2 = last ? nB : cB + (size_t)(t + 2) * kstep;
;             const char* a3 = a2 + kstep; const char* b3 = b2 + kstep;
;             PG8_LDB(B0, 0, 0); PG8_LDB(B1, 0, 1); PG8_SCHED; PG8_LDA(At, 0, 0); PG8_STAGE(PG8_SA(1, 1), a1 + hstepA, voffA);
;             PG8_WAIT_V(8); PG8_WAIT_L(0); PG8_BAR; PG8_MMA(0, 0, At, B0); PG8_MMA(0, 1, At, B1); PG8_BAR; PG8_SCHED;
;             PG8_LDA(At, 0, 1); PG8_STAGE(PG8_SB(0, 0), b2, voffB); PG8_STAGE(PG8_SB(0, 1), b2 + hstepB, voffB); PG8_STAGE(PG8_SA(0, 0), a2, voffA);
;             PG8_WAIT_V(8); PG8_WAIT_L(0); PG8_BAR; PG8_MMA(1, 0, At, B0); PG8_MMA(1, 1, At, B1); PG8_BAR; PG8_SCHED;
.LBB0_792:
	ds_read_b128 v[128:131], v182
	ds_read_b128 v[132:135], v182 offset:1024
	ds_read_b128 v[136:139], v182 offset:2048
	ds_read_b128 v[140:143], v182 offset:3072
	ds_read_b128 v[160:163], v183
	ds_read_b128 v[164:167], v183 offset:1024
	ds_read_b128 v[168:171], v183 offset:2048
	ds_read_b128 v[172:175], v183 offset:3072
	s_add_u32 s34, s0, 0xfff50080
	s_addc_u32 s35, s1, -1
	s_cmp_eq_u32 s77, 40
	s_cselect_b32 s39, s7, s35
	s_cselect_b32 s38, s6, s34
	s_cselect_b32 s35, s23, s76
	s_cselect_b32 s34, s22, s75
	s_add_i32 m0, s43, 0xc000
	ds_read_b128 v[186:189], v184
	ds_read_b128 v[190:193], v184 offset:1024
	ds_read_b128 v[194:197], v184 offset:2048
	ds_read_b128 v[198:201], v184 offset:3072
	ds_read_b128 v[202:205], v184 offset:4096
	ds_read_b128 v[206:209], v184 offset:5120
	ds_read_b128 v[210:213], v184 offset:6144
	ds_read_b128 v[214:217], v184 offset:7168
	global_load_lds_dwordx4 v152, s[0:1]
	s_add_i32 m0, s43, 0xe000
	s_nop 0
	global_load_lds_dwordx4 v154, s[0:1]
	s_waitcnt vmcnt(8)
	s_waitcnt lgkmcnt(0)
	s_barrier
	s_setprio 1
	s_waitcnt lgkmcnt(0)
	v_mfma_f32_16x16x32_bf16 v[124:127], v[128:131], v[186:189], v[124:127]
	v_mfma_f32_16x16x32_bf16 v[120:123], v[136:139], v[186:189], v[120:123]
	v_mfma_f32_16x16x32_bf16 v[108:111], v[128:131], v[194:197], v[108:111]
	v_mfma_f32_16x16x32_bf16 v[104:107], v[136:139], v[194:197], v[104:107]
	v_mfma_f32_16x16x32_bf16 v[92:95], v[128:131], v[202:205], v[92:95]
	v_mfma_f32_16x16x32_bf16 v[88:91], v[136:139], v[202:205], v[88:91]
	v_mfma_f32_16x16x32_bf16 v[76:79], v[128:131], v[210:213], v[76:79]
	v_mfma_f32_16x16x32_bf16 v[72:75], v[136:139], v[210:213], v[72:75]
	v_mfma_f32_16x16x32_bf16 v[124:127], v[132:135], v[190:193], v[124:127]
	v_mfma_f32_16x16x32_bf16 v[120:123], v[140:143], v[190:193], v[120:123]
	v_mfma_f32_16x16x32_bf16 v[108:111], v[132:135], v[198:201], v[108:111]
	v_mfma_f32_16x16x32_bf16 v[104:107], v[140:143], v[198:201], v[104:107]
	v_mfma_f32_16x16x32_bf16 v[92:95], v[132:135], v[206:209], v[92:95]
	v_mfma_f32_16x16x32_bf16 v[88:91], v[140:143], v[206:209], v[88:91]
	v_mfma_f32_16x16x32_bf16 v[76:79], v[132:135], v[214:217], v[76:79]
	v_mfma_f32_16x16x32_bf16 v[72:75], v[140:143], v[214:217], v[72:75]
	s_setprio 0
	s_setprio 1
	v_mfma_f32_16x16x32_bf16 v[116:119], v[160:163], v[186:189], v[116:119]
	v_mfma_f32_16x16x32_bf16 v[112:115], v[168:171], v[186:189], v[112:115]
	v_mfma_f32_16x16x32_bf16 v[100:103], v[160:163], v[194:197], v[100:103]
	v_mfma_f32_16x16x32_bf16 v[96:99], v[168:171], v[194:197], v[96:99]
	v_mfma_f32_16x16x32_bf16 v[84:87], v[160:163], v[202:205], v[84:87]
	v_mfma_f32_16x16x32_bf16 v[80:83], v[168:171], v[202:205], v[80:83]
	v_mfma_f32_16x16x32_bf16 v[68:71], v[160:163], v[210:213], v[68:71]
	v_mfma_f32_16x16x32_bf16 v[64:67], v[168:171], v[210:213], v[64:67]
	v_mfma_f32_16x16x32_bf16 v[116:119], v[164:167], v[190:193], v[116:119]
	v_mfma_f32_16x16x32_bf16 v[112:115], v[172:175], v[190:193], v[112:115]
	v_mfma_f32_16x16x32_bf16 v[100:103], v[164:167], v[198:201], v[100:103]
	v_mfma_f32_16x16x32_bf16 v[96:99], v[172:175], v[198:201], v[96:99]
	v_mfma_f32_16x16x32_bf16 v[84:87], v[164:167], v[206:209], v[84:87]
	v_mfma_f32_16x16x32_bf16 v[80:83], v[172:175], v[206:209], v[80:83]
	v_mfma_f32_16x16x32_bf16 v[68:71], v[164:167], v[214:217], v[68:71]
	v_mfma_f32_16x16x32_bf16 v[64:67], v[172:175], v[214:217], v[64:67]
	s_setprio 0
	s_barrier
	s_add_i32 s78, s69, s42
	v_lshl_add_u64 v[178:179], s[34:35], 0, v[146:147]
	s_mov_b32 m0, s78
	ds_read_b128 v[186:189], v184 offset:16384
	ds_read_b128 v[190:193], v184 offset:17408
	ds_read_b128 v[194:197], v184 offset:18432
	ds_read_b128 v[198:201], v184 offset:19456
	ds_read_b128 v[202:205], v184 offset:20480
	ds_read_b128 v[206:209], v184 offset:21504
	ds_read_b128 v[210:213], v184 offset:22528
	ds_read_b128 v[214:217], v184 offset:23552
	global_load_lds_dwordx4 v[178:179], off
	s_add_i32 m0, s78, 0x2000
	s_add_u32 s78, s34, 0xb0000
	v_lshl_add_u64 v[218:219], s[34:35], 0, v[150:151]
	s_addc_u32 s79, s35, 0
	s_add_i32 s80, s70, s42
	global_load_lds_dwordx4 v[218:219], off
	s_mov_b32 m0, s80
	v_lshl_add_u64 v[222:223], s[38:39], 0, v[148:149]
	global_load_lds_dwordx4 v146, s[78:79]
	s_add_i32 m0, s80, 0x2000
	s_nop 0
	global_load_lds_dwordx4 v150, s[78:79]
	v_lshl_add_u64 v[220:221], s[38:39], 0, v[144:145]
	s_mov_b32 m0, s43
	s_nop 0
	global_load_lds_dwordx4 v[220:221], off
	s_mov_b32 m0, s52
	s_nop 0
	global_load_lds_dwordx4 v[222:223], off
	s_waitcnt vmcnt(8)
	s_waitcnt lgkmcnt(0)
	s_barrier
; #define PG8_STAGE(bufoff, gbase, voff) do { _Pragma("unroll") for (int _i = 0; _i < 2; ++_i) \
;         __builtin_amdgcn_global_load_lds((const unsigned*)((const char*)(gbase) + (voff)[_i]), (LAS unsigned*)(lds + (bufoff) + ldsw + _i * 8192), 16, 0, 0); } while (0)
; #define PG8_LDA(dst, b, h) do { _Pragma("unroll") for (int m = 0; m < 4; ++m) _Pragma("unroll") for (int k = 0; k < 2; ++k) dst[m][k] = *(const LAS bf16x8*)(lds + PG8_SA(b, h) + aoff + m * 2048 + k * 1024); } while (0)
; #define PG8_LDB(dst, b, h) do { _Pragma("unroll") for (int n = 0; n < 2; ++n) _Pragma("unroll") for (int k = 0; k < 2; ++k) dst[n][k] = *(const LAS bf16x8*)(lds + PG8_SB(b, h) + boff + n * 2048 + k * 1024); } while (0)
; #define PG8_MMA(ai, bj, At, Bt) do { __builtin_amdgcn_s_setprio(1); _Pragma("unroll") for (int m = 0; m < 4; ++m) _Pragma("unroll") for (int n = 0; n < 2; ++n) _Pragma("unroll") for (int k = 0; k < 2; ++k) \
;         acc[ai][bj][m][n] = __builtin_amdgcn_mfma_f32_16x16x32_bf16(Bt[n][k], At[m][k], acc[ai][bj][m][n], 0, 0, 0); __builtin_amdgcn_s_setprio(0); } while (0)
; #define PG8_WAIT_V(n) asm volatile("s_waitcnt vmcnt(" #n ")" ::: "memory")
; #define PG8_WAIT_L(n) asm volatile("s_waitcnt lgkmcnt(" #n ")" ::: "memory")
; #define PG8_BAR __builtin_amdgcn_s_barrier()
; #define PG8_SCHED __builtin_amdgcn_sched_barrier(0)
; template <class Epi>
; __device__ __forceinline__ void gemm_phase(LAS unsigned char* lds, const Gemm g, const StaticOrder& S, const Epi& E) {
;     ...
;             PG8_WAIT_V(8); PG8_WAIT_L(0); PG8_BAR; PG8_MMA(1, 0, At, B0); PG8_MMA(1, 1, At, B1); PG8_BAR; PG8_SCHED;
;             PG8_LDB(B0, 1, 0); PG8_LDB(B1, 1, 1); PG8_SCHED; PG8_LDA(At, 1, 0); PG8_STAGE(PG8_SA(0, 1), a2 + hstepA, voffA);
;             PG8_WAIT_V(8); PG8_WAIT_L(0); PG8_BAR; PG8_MMA(0, 0, At, B0); PG8_MMA(0, 1, At, B1); PG8_BAR; PG8_SCHED;
	s_setprio 1
	s_waitcnt lgkmcnt(0)
	v_mfma_f32_16x16x32_bf16 v[60:63], v[128:131], v[186:189], v[60:63]
	v_mfma_f32_16x16x32_bf16 v[56:59], v[136:139], v[186:189], v[56:59]
	v_mfma_f32_16x16x32_bf16 v[44:47], v[128:131], v[194:197], v[44:47]
	v_mfma_f32_16x16x32_bf16 v[40:43], v[136:139], v[194:197], v[40:43]
	v_mfma_f32_16x16x32_bf16 v[28:31], v[128:131], v[202:205], v[28:31]
	v_mfma_f32_16x16x32_bf16 v[24:27], v[136:139], v[202:205], v[24:27]
	v_mfma_f32_16x16x32_bf16 v[12:15], v[128:131], v[210:213], v[12:15]
	v_mfma_f32_16x16x32_bf16 v[8:11], v[136:139], v[210:213], v[8:11]
	v_mfma_f32_16x16x32_bf16 v[60:63], v[132:135], v[190:193], v[60:63]
	v_mfma_f32_16x16x32_bf16 v[56:59], v[140:143], v[190:193], v[56:59]
	v_mfma_f32_16x16x32_bf16 v[44:47], v[132:135], v[198:201], v[44:47]
	v_mfma_f32_16x16x32_bf16 v[40:43], v[140:143], v[198:201], v[40:43]
	v_mfma_f32_16x16x32_bf16 v[28:31], v[132:135], v[206:209], v[28:31]
	v_mfma_f32_16x16x32_bf16 v[24:27], v[140:143], v[206:209], v[24:27]
	v_mfma_f32_16x16x32_bf16 v[12:15], v[132:135], v[214:217], v[12:15]
	v_mfma_f32_16x16x32_bf16 v[8:11], v[140:143], v[214:217], v[8:11]
	s_setprio 0
	s_setprio 1
	v_mfma_f32_16x16x32_bf16 v[52:55], v[160:163], v[186:189], v[52:55]
	v_mfma_f32_16x16x32_bf16 v[48:51], v[168:171], v[186:189], v[48:51]
	v_mfma_f32_16x16x32_bf16 v[36:39], v[160:163], v[194:197], v[36:39]
	v_mfma_f32_16x16x32_bf16 v[32:35], v[168:171], v[194:197], v[32:35]
	v_mfma_f32_16x16x32_bf16 v[20:23], v[160:163], v[202:205], v[20:23]
	v_mfma_f32_16x16x32_bf16 v[16:19], v[168:171], v[202:205], v[16:19]
	v_mfma_f32_16x16x32_bf16 v[4:7], v[160:163], v[210:213], v[4:7]
	v_mfma_f32_16x16x32_bf16 v[0:3], v[168:171], v[210:213], v[0:3]
	v_mfma_f32_16x16x32_bf16 v[52:55], v[164:167], v[190:193], v[52:55]
	v_mfma_f32_16x16x32_bf16 v[48:51], v[172:175], v[190:193], v[48:51]
	v_mfma_f32_16x16x32_bf16 v[36:39], v[164:167], v[198:201], v[36:39]
	v_mfma_f32_16x16x32_bf16 v[32:35], v[172:175], v[198:201], v[32:35]
	v_mfma_f32_16x16x32_bf16 v[20:23], v[164:167], v[206:209], v[20:23]
	v_mfma_f32_16x16x32_bf16 v[16:19], v[172:175], v[206:209], v[16:19]
	v_mfma_f32_16x16x32_bf16 v[4:7], v[164:167], v[214:217], v[4:7]
	v_mfma_f32_16x16x32_bf16 v[0:3], v[172:175], v[214:217], v[0:3]
	s_setprio 0
	s_barrier
	s_add_i32 s78, 0, 0x18000
	s_add_i32 s79, 0, 0x1c000
	v_add_u32_e32 v140, s78, v181
	v_add_u32_e32 v172, s79, v181
	ds_read_b128 v[128:131], v140
	ds_read_b128 v[132:135], v140 offset:1024
	ds_read_b128 v[136:139], v140 offset:2048
	ds_read_b128 v[140:143], v140 offset:3072
	ds_read_b128 v[160:163], v172
	ds_read_b128 v[164:167], v172 offset:1024
	ds_read_b128 v[168:171], v172 offset:2048
	ds_read_b128 v[172:175], v172 offset:3072
	s_add_u32 s38, s38, 0xb0000
	s_addc_u32 s39, s39, 0
	s_mov_b32 m0, s53
	ds_read_b128 v[186:189], v184 offset:32768
	ds_read_b128 v[190:193], v184 offset:33792
	ds_read_b128 v[194:197], v184 offset:34816
	ds_read_b128 v[198:201], v184 offset:35840
	ds_read_b128 v[202:205], v184 offset:36864
	ds_read_b128 v[206:209], v184 offset:37888
	ds_read_b128 v[210:213], v184 offset:38912
	ds_read_b128 v[214:217], v184 offset:39936
	global_load_lds_dwordx4 v144, s[38:39]
	s_mov_b32 m0, s54
	s_nop 0
	global_load_lds_dwordx4 v148, s[38:39]
	s_waitcnt vmcnt(8)
	s_waitcnt lgkmcnt(0)
	s_barrier
	s_setprio 1
	s_waitcnt lgkmcnt(0)
	v_mfma_f32_16x16x32_bf16 v[124:127], v[128:131], v[186:189], v[124:127]
	v_mfma_f32_16x16x32_bf16 v[120:123], v[136:139], v[186:189], v[120:123]
	v_mfma_f32_16x16x32_bf16 v[108:111], v[128:131], v[194:197], v[108:111]
	v_mfma_f32_16x16x32_bf16 v[104:107], v[136:139], v[194:197], v[104:107]
	v_mfma_f32_16x16x32_bf16 v[92:95], v[128:131], v[202:205], v[92:95]
	v_mfma_f32_16x16x32_bf16 v[88:91], v[136:139], v[202:205], v[88:91]
	v_mfma_f32_16x16x32_bf16 v[76:79], v[128:131], v[210:213], v[76:79]
	v_mfma_f32_16x16x32_bf16 v[72:75], v[136:139], v[210:213], v[72:75]
	v_mfma_f32_16x16x32_bf16 v[124:127], v[132:135], v[190:193], v[124:127]
	v_mfma_f32_16x16x32_bf16 v[120:123], v[140:143], v[190:193], v[120:123]
	v_mfma_f32_16x16x32_bf16 v[108:111], v[132:135], v[198:201], v[108:111]
	v_mfma_f32_16x16x32_bf16 v[104:107], v[140:143], v[198:201], v[104:107]
	v_mfma_f32_16x16x32_bf16 v[92:95], v[132:135], v[206:209], v[92:95]
	v_mfma_f32_16x16x32_bf16 v[88:91], v[140:143], v[206:209], v[88:91]
	v_mfma_f32_16x16x32_bf16 v[76:79], v[132:135], v[214:217], v[76:79]
	v_mfma_f32_16x16x32_bf16 v[72:75], v[140:143], v[214:217], v[72:75]
	s_setprio 0
	s_setprio 1
	v_mfma_f32_16x16x32_bf16 v[116:119], v[160:163], v[186:189], v[116:119]
	v_mfma_f32_16x16x32_bf16 v[112:115], v[168:171], v[186:189], v[112:115]
	v_mfma_f32_16x16x32_bf16 v[100:103], v[160:163], v[194:197], v[100:103]
	v_mfma_f32_16x16x32_bf16 v[96:99], v[168:171], v[194:197], v[96:99]
	v_mfma_f32_16x16x32_bf16 v[84:87], v[160:163], v[202:205], v[84:87]
	v_mfma_f32_16x16x32_bf16 v[80:83], v[168:171], v[202:205], v[80:83]
	v_mfma_f32_16x16x32_bf16 v[68:71], v[160:163], v[210:213], v[68:71]
	v_mfma_f32_16x16x32_bf16 v[64:67], v[168:171], v[210:213], v[64:67]
	v_mfma_f32_16x16x32_bf16 v[116:119], v[164:167], v[190:193], v[116:119]
	v_mfma_f32_16x16x32_bf16 v[112:115], v[172:175], v[190:193], v[112:115]
	v_mfma_f32_16x16x32_bf16 v[100:103], v[164:167], v[198:201], v[100:103]
	v_mfma_f32_16x16x32_bf16 v[96:99], v[172:175], v[198:201], v[96:99]
	v_mfma_f32_16x16x32_bf16 v[84:87], v[164:167], v[206:209], v[84:87]
	v_mfma_f32_16x16x32_bf16 v[80:83], v[172:175], v[206:209], v[80:83]
	v_mfma_f32_16x16x32_bf16 v[68:71], v[164:167], v[214:217], v[68:71]
	v_mfma_f32_16x16x32_bf16 v[64:67], v[172:175], v[214:217], v[64:67]
	s_setprio 0
	s_barrier
; #define PG8_STAGE(bufoff, gbase, voff) do { _Pragma("unroll") for (int _i = 0; _i < 2; ++_i) \
;         __builtin_amdgcn_global_load_lds((const unsigned*)((const char*)(gbase) + (voff)[_i]), (LAS unsigned*)(lds + (bufoff) + ldsw + _i * 8192), 16, 0, 0); } while (0)
; #define PG8_LDA(dst, b, h) do { _Pragma("unroll") for (int m = 0; m < 4; ++m) _Pragma("unroll") for (int k = 0; k < 2; ++k) dst[m][k] = *(const LAS bf16x8*)(lds + PG8_SA(b, h) + aoff + m * 2048 + k * 1024); } while (0)
; #define PG8_MMA(ai, bj, At, Bt) do { __builtin_amdgcn_s_setprio(1); _Pragma("unroll") for (int m = 0; m < 4; ++m) _Pragma("unroll") for (int n = 0; n < 2; ++n) _Pragma("unroll") for (int k = 0; k < 2; ++k) \
;         acc[ai][bj][m][n] = __builtin_amdgcn_mfma_f32_16x16x32_bf16(Bt[n][k], At[m][k], acc[ai][bj][m][n], 0, 0, 0); __builtin_amdgcn_s_setprio(0); } while (0)
; #define PG8_WAIT_V(n) asm volatile("s_waitcnt vmcnt(" #n ")" ::: "memory")
; #define PG8_WAIT_L(n) asm volatile("s_waitcnt lgkmcnt(" #n ")" ::: "memory")
; #define PG8_BAR __builtin_amdgcn_s_barrier()
; #define PG8_SCHED __builtin_amdgcn_sched_barrier(0)
; template <class Epi>
; __device__ __forceinline__ void gemm_phase(LAS unsigned char* lds, const Gemm g, const StaticOrder& S, const Epi& E) {
;     ...
;             PG8_LDA(At, 1, 1); PG8_STAGE(PG8_SB(1, 0), b3, voffB); PG8_STAGE(PG8_SB(1, 1), b3 + hstepB, voffB); PG8_STAGE(PG8_SA(1, 0), a3, voffA);
;             PG8_WAIT_V(8); PG8_WAIT_L(0); PG8_BAR; PG8_MMA(1, 0, At, B0); PG8_MMA(1, 1, At, B1); PG8_BAR; PG8_SCHED;
;         }
;         if (wr == 0) PG8_BAR;
	s_add_i32 s38, s78, s42
	v_lshl_add_u64 v[178:179], v[178:179], 0, s[16:17]
	s_mov_b32 m0, s38
	ds_read_b128 v[186:189], v184 offset:49152
	ds_read_b128 v[190:193], v184 offset:50176
	ds_read_b128 v[194:197], v184 offset:51200
	ds_read_b128 v[198:201], v184 offset:52224
	ds_read_b128 v[202:205], v184 offset:53248
	ds_read_b128 v[206:209], v184 offset:54272
	ds_read_b128 v[210:213], v184 offset:55296
	ds_read_b128 v[214:217], v184 offset:56320
	global_load_lds_dwordx4 v[178:179], off
	s_add_i32 m0, s38, 0x2000
	s_add_u32 s34, s34, 0xb0080
	v_lshl_add_u64 v[178:179], v[218:219], 0, s[16:17]
	s_addc_u32 s35, s35, 0
	s_add_i32 s38, s79, s42
	global_load_lds_dwordx4 v[178:179], off
	s_mov_b32 m0, s38
	s_nop 0
	global_load_lds_dwordx4 v146, s[34:35]
	s_add_i32 m0, s38, 0x2000
	s_nop 0
	global_load_lds_dwordx4 v150, s[34:35]
	v_lshl_add_u64 v[178:179], v[220:221], 0, s[16:17]
	s_mov_b32 m0, s62
	s_nop 0
	global_load_lds_dwordx4 v[178:179], off
	v_lshl_add_u64 v[178:179], v[222:223], 0, s[16:17]
	s_mov_b32 m0, s63
	s_nop 0
	global_load_lds_dwordx4 v[178:179], off
	s_waitcnt vmcnt(8)
	s_waitcnt lgkmcnt(0)
	s_barrier
	s_setprio 1
	s_waitcnt lgkmcnt(0)
	v_mfma_f32_16x16x32_bf16 v[60:63], v[128:131], v[186:189], v[60:63]
	v_mfma_f32_16x16x32_bf16 v[56:59], v[136:139], v[186:189], v[56:59]
	v_mfma_f32_16x16x32_bf16 v[44:47], v[128:131], v[194:197], v[44:47]
	v_mfma_f32_16x16x32_bf16 v[40:43], v[136:139], v[194:197], v[40:43]
	v_mfma_f32_16x16x32_bf16 v[28:31], v[128:131], v[202:205], v[28:31]
	v_mfma_f32_16x16x32_bf16 v[24:27], v[136:139], v[202:205], v[24:27]
	v_mfma_f32_16x16x32_bf16 v[12:15], v[128:131], v[210:213], v[12:15]
	v_mfma_f32_16x16x32_bf16 v[8:11], v[136:139], v[210:213], v[8:11]
	v_mfma_f32_16x16x32_bf16 v[60:63], v[132:135], v[190:193], v[60:63]
	v_mfma_f32_16x16x32_bf16 v[56:59], v[140:143], v[190:193], v[56:59]
	v_mfma_f32_16x16x32_bf16 v[44:47], v[132:135], v[198:201], v[44:47]
	v_mfma_f32_16x16x32_bf16 v[40:43], v[140:143], v[198:201], v[40:43]
	v_mfma_f32_16x16x32_bf16 v[28:31], v[132:135], v[206:209], v[28:31]
	v_mfma_f32_16x16x32_bf16 v[24:27], v[140:143], v[206:209], v[24:27]
	v_mfma_f32_16x16x32_bf16 v[12:15], v[132:135], v[214:217], v[12:15]
	v_mfma_f32_16x16x32_bf16 v[8:11], v[140:143], v[214:217], v[8:11]
	s_setprio 0
	s_setprio 1
	v_mfma_f32_16x16x32_bf16 v[52:55], v[160:163], v[186:189], v[52:55]
	v_mfma_f32_16x16x32_bf16 v[48:51], v[168:171], v[186:189], v[48:51]
	v_mfma_f32_16x16x32_bf16 v[36:39], v[160:163], v[194:197], v[36:39]
	v_mfma_f32_16x16x32_bf16 v[32:35], v[168:171], v[194:197], v[32:35]
	v_mfma_f32_16x16x32_bf16 v[20:23], v[160:163], v[202:205], v[20:23]
	v_mfma_f32_16x16x32_bf16 v[16:19], v[168:171], v[202:205], v[16:19]
	v_mfma_f32_16x16x32_bf16 v[4:7], v[160:163], v[210:213], v[4:7]
	v_mfma_f32_16x16x32_bf16 v[0:3], v[168:171], v[210:213], v[0:3]
	v_mfma_f32_16x16x32_bf16 v[52:55], v[164:167], v[190:193], v[52:55]
	v_mfma_f32_16x16x32_bf16 v[48:51], v[172:175], v[190:193], v[48:51]
	v_mfma_f32_16x16x32_bf16 v[36:39], v[164:167], v[198:201], v[36:39]
	v_mfma_f32_16x16x32_bf16 v[32:35], v[172:175], v[198:201], v[32:35]
	v_mfma_f32_16x16x32_bf16 v[20:23], v[164:167], v[206:209], v[20:23]
	v_mfma_f32_16x16x32_bf16 v[16:19], v[172:175], v[206:209], v[16:19]
	v_mfma_f32_16x16x32_bf16 v[4:7], v[164:167], v[214:217], v[4:7]
	v_mfma_f32_16x16x32_bf16 v[0:3], v[172:175], v[214:217], v[0:3]
	s_setprio 0
	s_barrier
	s_add_i32 s77, s77, 2
	s_add_u32 s0, s0, 0x100
	s_addc_u32 s1, s1, 0
	s_add_u32 s75, s75, 0x100
	s_addc_u32 s76, s76, 0
	s_cmp_gt_u32 s77, 41
	s_cbranch_scc0 .LBB0_792
	s_and_b64 vcc, exec, s[18:19]
	s_cbranch_vccz .LBB0_795
	s_barrier

; #define PG8_STAGE(bufoff, gbase, voff) do { _Pragma("unroll") for (int _i = 0; _i < 2; ++_i) \
;         __builtin_amdgcn_global_load_lds((const unsigned*)((const char*)(gbase) + (voff)[_i]), (LAS unsigned*)(lds + (bufoff) + ldsw + _i * 8192), 16, 0, 0); } while (0)
; #define PG8_WAIT_V(n) asm volatile("s_waitcnt vmcnt(" #n ")" ::: "memory")
; #define PG8_BAR __builtin_amdgcn_s_barrier()
; template <class Epi>
; __device__ __forceinline__ void gemm_phase(LAS unsigned char* lds, const Gemm g, const StaticOrder& S, const Epi& E) {
;     const int tid = threadIdx.x, wid = __builtin_amdgcn_readfirstlane(tid >> 6), lane = tid & 63, wr = wid >> 2, wc = wid & 3, fr = lane & 15, fq = lane >> 4;
;     const int K = g.K, nt = K / BK;
;     unsigned voffA[2], voffB[2];
; #pragma unroll
;     for (int i = 0; i < 2; ++i) { int R, C; stage_rc(tid * 16 + i * 8192, R, C); const int Rb = (R & ~31) + perm32(R & 31);
;         voffA[i] = (unsigned)(R * g.lda + C) * 2u; voffB[i] = (unsigned)(Rb * g.ldb + C) * 2u; }
;     const size_t kstep = (size_t)(BK * 2);
;     const size_t hstepA = (size_t)HALF * g.lda * 2, hstepB = (size_t)HALF * g.ldb * 2;
;     const size_t tstepA = 2 * hstepA, tstepB = 2 * hstepB;
;     const unsigned ldsw = (unsigned)wid * 1024u;
;     const int aoff = lds_byte(wr * 64 + fr, fq * 8), boff = lds_byte(wc * 32 + fr, fq * 8);
;     ...
;     PG8_STAGE(PG8_SB(0, 0), cB, voffB); PG8_STAGE(PG8_SB(0, 1), cB + hstepB, voffB); PG8_STAGE(PG8_SA(0, 0), cA, voffA); PG8_STAGE(PG8_SA(0, 1), cA + hstepA, voffA);
;     if (wr == 1) PG8_BAR;
;     PG8_WAIT_V(2); PG8_BAR;
;     PG8_STAGE(PG8_SB(1, 0), cB + kstep, voffB); PG8_STAGE(PG8_SA(1, 0), cA + kstep, voffA); PG8_STAGE(PG8_SB(1, 1), cB + hstepB + kstep, voffB);
;     PG8_WAIT_V(6); PG8_BAR;
.LBB0_879:
	s_add_u32 s12, s50, 0x40000
	s_addc_u32 s13, s51, 0
	s_add_u32 s16, s50, 0x60000
	s_addc_u32 s17, s51, 0
	s_lshl_b32 s74, s4, 6
	s_lshl_b32 s7, s4, 13
	s_lshl_b32 s4, s5, 5
	s_mov_b64 s[18:19], 0x80
	s_and_b32 s75, s4, 0x60
	s_add_i32 m0, s69, 0x18000
	v_lshl_add_u64 v[6:7], v[6:7], 0, s[18:19]
	s_lshl_b32 s9, s75, 7
	s_waitcnt vmcnt(2)
	s_barrier
	global_load_lds_dwordx4 v[6:7], off
	v_lshl_add_u64 v[4:5], v[4:5], 0, s[18:19]
	s_add_i32 m0, s69, 0x1a000
	s_add_i32 s76, s69, 0x8000
	s_add_i32 s77, s69, 0xa000
	global_load_lds_dwordx4 v[4:5], off
	v_lshl_add_u64 v[0:1], v[0:1], 0, s[18:19]
	s_mov_b32 m0, s76
	s_add_u32 s4, s62, 0x40080
	global_load_lds_dwordx4 v[0:1], off
	v_lshl_add_u64 v[0:1], v[2:3], 0, s[18:19]
	s_mov_b32 m0, s77
	s_addc_u32 s5, s63, 0
	global_load_lds_dwordx4 v[0:1], off
	s_add_i32 m0, s69, 0x1c000
	global_load_lds_dwordx4 v170, s[4:5]
	s_add_i32 m0, s69, 0x1e000
	v_bfe_u32 v206, v176, 4, 2
	global_load_lds_dwordx4 v174, s[4:5]
	v_and_b32_e32 v177, 15, v176
	v_lshlrev_b32_e32 v0, 4, v206
	v_lshlrev_b32_e32 v2, 2, v176
	v_lshlrev_b32_e32 v3, 6, v176
	s_movk_i32 s4, 0x3c0
	v_lshl_or_b32 v1, v177, 6, v0
	v_and_b32_e32 v2, 32, v2
	v_and_or_b32 v0, v3, s4, v0
	v_bitop3_b32 v207, s9, v0, v2 bitop3:0xf6
	v_lshlrev_b32_e32 v0, 8, v176
	v_bitop3_b32 v1, v1, s7, v2 bitop3:0xde
	v_and_b32_e32 v0, 0x38000, v0
	v_lshlrev_b32_e32 v2, 11, v10
	v_readlane_b32 s52, v254, 6
	v_or3_b32 v0, v8, v0, v2
	s_cmpk_lt_u32 s22, 0x100
	v_readlane_b32 s54, v254, 8
	v_add_u32_e32 v178, v0, v9
	v_lshlrev_b32_e32 v0, 4, v11
	s_cselect_b64 s[22:23], -1, 0
	s_ashr_i32 s78, s54, 31
	s_ashr_i32 s80, s2, 31
	v_and_b32_e32 v0, 0x78000, v0
	s_waitcnt vmcnt(6)
	s_cmp_lg_u64 s[48:49], 0
	v_or3_b32 v0, v8, v0, v2
	s_cselect_b64 s[34:35], -1, 0
	v_add_u32_e32 v180, v0, v9
	s_add_i32 s81, 0, 0x10000
	s_add_i32 s82, 0, 0x14000
	v_mbcnt_lo_u32_b32 v0, -1, 0
	s_mov_b32 s79, s54
	v_mov_b32_e32 v179, v171
	v_mov_b32_e32 v181, v171
	v_mov_b64_e32 v[182:183], 0x200
	v_mov_b64_e32 v[184:185], 0x1ff
	v_add_u32_e32 v208, s81, v207
	v_add_u32_e32 v209, s82, v207
	v_add_u32_e32 v210, 0, v1
	v_mov_b32_e32 v211, 0x358637bd
	v_mbcnt_hi_u32_b32 v212, -1, v0
	s_barrier
	v_readlane_b32 s53, v254, 7
	v_readlane_b32 s55, v254, 9
	s_branch .LBB0_882

; #define PG8_STAGE(bufoff, gbase, voff) do { _Pragma("unroll") for (int _i = 0; _i < 2; ++_i) \
;         __builtin_amdgcn_global_load_lds((const unsigned*)((const char*)(gbase) + (voff)[_i]), (LAS unsigned*)(lds + (bufoff) + ldsw + _i * 8192), 16, 0, 0); } while (0)
; #define PG8_LDA(dst, b, h) do { _Pragma("unroll") for (int m = 0; m < 4; ++m) _Pragma("unroll") for (int k = 0; k < 2; ++k) dst[m][k] = *(const LAS bf16x8*)(lds + PG8_SA(b, h) + aoff + m * 2048 + k * 1024); } while (0)
; #define PG8_LDB(dst, b, h) do { _Pragma("unroll") for (int n = 0; n < 2; ++n) _Pragma("unroll") for (int k = 0; k < 2; ++k) dst[n][k] = *(const LAS bf16x8*)(lds + PG8_SB(b, h) + boff + n * 2048 + k * 1024); } while (0)
; #define PG8_MMA(ai, bj, At, Bt) do { __builtin_amdgcn_s_setprio(1); _Pragma("unroll") for (int m = 0; m < 4; ++m) _Pragma("unroll") for (int n = 0; n < 2; ++n) _Pragma("unroll") for (int k = 0; k < 2; ++k) \
;         acc[ai][bj][m][n] = __builtin_amdgcn_mfma_f32_16x16x32_bf16(Bt[n][k], At[m][k], acc[ai][bj][m][n], 0, 0, 0); __builtin_amdgcn_s_setprio(0); } while (0)
; #define PG8_BAR __builtin_amdgcn_s_barrier()
; template <class Epi>
; __device__ __forceinline__ void gemm_phase(LAS unsigned char* lds, const Gemm g, const StaticOrder& S, const Epi& E) {
;     ...
;         const bool has_next = S.next(ui + 1, nxt);
;         const char* nA = has_next ? (const char*)g.A + (size_t)nxt.pm * tstepA : cA; const char* nB = has_next ? (const char*)g.Bt + (size_t)nxt.pn * tstepB : cB;
; #pragma nounroll
;         for (int t = 0; t < nt; t += 2) {
;             const bool last = (t == nt - 2);
;             const char* a1 = cA + (size_t)(t + 1) * kstep;
;             const char* a2 = last ? nA : cA + (size_t)(t + 2) * kstep; const char* b2 = last ? nB : cB + (size_t)(t + 2) * kstep;
;             const char* a3 = a2 + kstep; const char* b3 = b2 + kstep;
;             PG8_LDB(B0, 0, 0); PG8_LDB(B1, 0, 1); PG8_SCHED; PG8_LDA(At, 0, 0); PG8_STAGE(PG8_SA(1, 1), a1 + hstepA, voffA);
;             PG8_WAIT_V(8); PG8_WAIT_L(0); PG8_BAR; PG8_MMA(0, 0, At, B0); PG8_MMA(0, 1, At, B1); PG8_BAR; PG8_SCHED;
;             PG8_LDA(At, 0, 1); PG8_STAGE(PG8_SB(0, 0), b2, voffB); PG8_STAGE(PG8_SB(0, 1), b2 + hstepB, voffB); PG8_STAGE(PG8_SA(0, 0), a2, voffA);
;             PG8_WAIT_V(8); PG8_WAIT_L(0); PG8_BAR; PG8_MMA(1, 0, At, B0); PG8_MMA(1, 1, At, B1); PG8_BAR; PG8_SCHED;
.LBB0_888:
	s_ashr_i32 s43, s42, 31
	s_lshl_b64 s[52:53], s[42:43], 19
	s_add_u32 s52, s30, s52
	s_addc_u32 s53, s31, s53
	s_and_b64 s[54:55], s[4:5], exec
	s_cselect_b32 s7, s53, s57
	s_cselect_b32 s9, s52, s56
	s_ashr_i32 s39, s38, 31
	s_lshl_b64 s[54:55], s[38:39], 19
	s_add_u32 s54, s3, s54
	s_addc_u32 s55, s33, s55
	s_and_b64 s[64:65], s[4:5], exec
	s_cselect_b32 s39, s55, s63
	s_cselect_b32 s43, s54, s62
	s_add_u32 s56, s56, 0x40080
	s_addc_u32 s57, s57, 0
	s_add_u32 s83, s62, 0x100
	s_addc_u32 s84, s63, 0
	s_mov_b32 s85, -2
	s_waitcnt lgkmcnt(0)
	s_nop 0
	ds_read_b128 v[40:43], v208
	ds_read_b128 v[44:47], v208 offset:1024
	ds_read_b128 v[56:59], v208 offset:2048
	ds_read_b128 v[60:63], v208 offset:3072
	ds_read_b128 v[144:147], v209
	ds_read_b128 v[148:151], v209 offset:1024
	ds_read_b128 v[152:155], v209 offset:2048
	ds_read_b128 v[156:159], v209 offset:3072
	s_add_u32 s62, s56, 0xfffc0080
	s_addc_u32 s63, s57, -1
	s_cmp_eq_u32 s85, 12
	s_cselect_b32 s65, s7, s63
	s_cselect_b32 s64, s9, s62
	s_cselect_b32 s63, s39, s84
	s_cselect_b32 s62, s43, s83
	s_add_i32 m0, s69, 0xc000
	ds_read_b128 v[160:163], v210
	ds_read_b128 v[164:167], v210 offset:1024
	ds_read_b128 v[186:189], v210 offset:2048
	ds_read_b128 v[190:193], v210 offset:3072
	ds_read_b128 v[194:197], v210 offset:4096
	ds_read_b128 v[198:201], v210 offset:5120
	ds_read_b128 v[202:205], v210 offset:6144
	ds_read_b128 v[214:217], v210 offset:7168
	global_load_lds_dwordx4 v178, s[56:57]
	s_add_i32 m0, s69, 0xe000
	s_nop 0
	global_load_lds_dwordx4 v180, s[56:57]
	s_waitcnt vmcnt(8)
	s_waitcnt lgkmcnt(0)
	s_barrier
	s_setprio 1
	s_waitcnt lgkmcnt(0)
	v_mfma_f32_16x16x32_bf16 v[140:143], v[40:43], v[160:163], 0
	v_mfma_f32_16x16x32_bf16 v[136:139], v[56:59], v[160:163], 0
	v_mfma_f32_16x16x32_bf16 v[124:127], v[40:43], v[186:189], 0
	v_mfma_f32_16x16x32_bf16 v[120:123], v[56:59], v[186:189], 0
	v_mfma_f32_16x16x32_bf16 v[108:111], v[40:43], v[194:197], 0
	v_mfma_f32_16x16x32_bf16 v[104:107], v[56:59], v[194:197], 0
	v_mfma_f32_16x16x32_bf16 v[92:95], v[40:43], v[202:205], 0
	v_mfma_f32_16x16x32_bf16 v[88:91], v[56:59], v[202:205], 0
	v_mfma_f32_16x16x32_bf16 v[140:143], v[44:47], v[164:167], v[140:143]
	v_mfma_f32_16x16x32_bf16 v[136:139], v[60:63], v[164:167], v[136:139]
	v_mfma_f32_16x16x32_bf16 v[124:127], v[44:47], v[190:193], v[124:127]
	v_mfma_f32_16x16x32_bf16 v[120:123], v[60:63], v[190:193], v[120:123]
	v_mfma_f32_16x16x32_bf16 v[108:111], v[44:47], v[198:201], v[108:111]
	v_mfma_f32_16x16x32_bf16 v[104:107], v[60:63], v[198:201], v[104:107]
	v_mfma_f32_16x16x32_bf16 v[92:95], v[44:47], v[214:217], v[92:95]
	v_mfma_f32_16x16x32_bf16 v[88:91], v[60:63], v[214:217], v[88:91]
	s_setprio 0
	s_setprio 1
	v_mfma_f32_16x16x32_bf16 v[132:135], v[144:147], v[160:163], 0
	v_mfma_f32_16x16x32_bf16 v[128:131], v[152:155], v[160:163], 0
	v_mfma_f32_16x16x32_bf16 v[116:119], v[144:147], v[186:189], 0
	v_mfma_f32_16x16x32_bf16 v[112:115], v[152:155], v[186:189], 0
	v_mfma_f32_16x16x32_bf16 v[100:103], v[144:147], v[194:197], 0
	v_mfma_f32_16x16x32_bf16 v[96:99], v[152:155], v[194:197], 0
	v_mfma_f32_16x16x32_bf16 v[84:87], v[144:147], v[202:205], 0
	v_mfma_f32_16x16x32_bf16 v[80:83], v[152:155], v[202:205], 0
	v_mfma_f32_16x16x32_bf16 v[132:135], v[148:151], v[164:167], v[132:135]
	v_mfma_f32_16x16x32_bf16 v[128:131], v[156:159], v[164:167], v[128:131]
	v_mfma_f32_16x16x32_bf16 v[116:119], v[148:151], v[190:193], v[116:119]
	v_mfma_f32_16x16x32_bf16 v[112:115], v[156:159], v[190:193], v[112:115]
	v_mfma_f32_16x16x32_bf16 v[100:103], v[148:151], v[198:201], v[100:103]
	v_mfma_f32_16x16x32_bf16 v[96:99], v[156:159], v[198:201], v[96:99]
	v_mfma_f32_16x16x32_bf16 v[84:87], v[148:151], v[214:217], v[84:87]
	v_mfma_f32_16x16x32_bf16 v[80:83], v[156:159], v[214:217], v[80:83]
	s_setprio 0
	s_barrier
	s_add_i32 s86, s81, s68
	v_lshl_add_u64 v[218:219], s[62:63], 0, v[170:171]
	s_mov_b32 m0, s86
	ds_read_b128 v[160:163], v210 offset:16384
	ds_read_b128 v[164:167], v210 offset:17408
	ds_read_b128 v[186:189], v210 offset:18432
	ds_read_b128 v[190:193], v210 offset:19456
	ds_read_b128 v[194:197], v210 offset:20480
	ds_read_b128 v[198:201], v210 offset:21504
	ds_read_b128 v[202:205], v210 offset:22528
	ds_read_b128 v[214:217], v210 offset:23552
	global_load_lds_dwordx4 v[218:219], off
	s_add_i32 m0, s86, 0x2000
	s_add_u32 s86, s62, 0x40000
	v_lshl_add_u64 v[220:221], s[62:63], 0, v[174:175]
	s_addc_u32 s87, s63, 0
	s_add_i32 s88, s82, s68
	global_load_lds_dwordx4 v[220:221], off
	s_mov_b32 m0, s88
	v_lshl_add_u64 v[226:227], s[64:65], 0, v[172:173]
	global_load_lds_dwordx4 v170, s[86:87]
	s_add_i32 m0, s88, 0x2000
	s_nop 0
	global_load_lds_dwordx4 v174, s[86:87]
	v_lshl_add_u64 v[222:223], s[64:65], 0, v[168:169]
	s_mov_b32 m0, s69
	s_nop 0
	global_load_lds_dwordx4 v[222:223], off
	s_mov_b32 m0, s70
	s_nop 0
	global_load_lds_dwordx4 v[226:227], off
	s_waitcnt vmcnt(8)
	s_waitcnt lgkmcnt(0)
	s_barrier
; #define PG8_STAGE(bufoff, gbase, voff) do { _Pragma("unroll") for (int _i = 0; _i < 2; ++_i) \
;         __builtin_amdgcn_global_load_lds((const unsigned*)((const char*)(gbase) + (voff)[_i]), (LAS unsigned*)(lds + (bufoff) + ldsw + _i * 8192), 16, 0, 0); } while (0)
; #define PG8_LDA(dst, b, h) do { _Pragma("unroll") for (int m = 0; m < 4; ++m) _Pragma("unroll") for (int k = 0; k < 2; ++k) dst[m][k] = *(const LAS bf16x8*)(lds + PG8_SA(b, h) + aoff + m * 2048 + k * 1024); } while (0)
; #define PG8_LDB(dst, b, h) do { _Pragma("unroll") for (int n = 0; n < 2; ++n) _Pragma("unroll") for (int k = 0; k < 2; ++k) dst[n][k] = *(const LAS bf16x8*)(lds + PG8_SB(b, h) + boff + n * 2048 + k * 1024); } while (0)
; #define PG8_MMA(ai, bj, At, Bt) do { __builtin_amdgcn_s_setprio(1); _Pragma("unroll") for (int m = 0; m < 4; ++m) _Pragma("unroll") for (int n = 0; n < 2; ++n) _Pragma("unroll") for (int k = 0; k < 2; ++k) \
;         acc[ai][bj][m][n] = __builtin_amdgcn_mfma_f32_16x16x32_bf16(Bt[n][k], At[m][k], acc[ai][bj][m][n], 0, 0, 0); __builtin_amdgcn_s_setprio(0); } while (0)
; #define PG8_WAIT_V(n) asm volatile("s_waitcnt vmcnt(" #n ")" ::: "memory")
; #define PG8_WAIT_L(n) asm volatile("s_waitcnt lgkmcnt(" #n ")" ::: "memory")
; #define PG8_BAR __builtin_amdgcn_s_barrier()
; #define PG8_SCHED __builtin_amdgcn_sched_barrier(0)
; template <class Epi>
; __device__ __forceinline__ void gemm_phase(LAS unsigned char* lds, const Gemm g, const StaticOrder& S, const Epi& E) {
;     ...
;             PG8_WAIT_V(8); PG8_WAIT_L(0); PG8_BAR; PG8_MMA(1, 0, At, B0); PG8_MMA(1, 1, At, B1); PG8_BAR; PG8_SCHED;
;             PG8_LDB(B0, 1, 0); PG8_LDB(B1, 1, 1); PG8_SCHED; PG8_LDA(At, 1, 0); PG8_STAGE(PG8_SA(0, 1), a2 + hstepA, voffA);
;             PG8_WAIT_V(8); PG8_WAIT_L(0); PG8_BAR; PG8_MMA(0, 0, At, B0); PG8_MMA(0, 1, At, B1); PG8_BAR; PG8_SCHED;
	s_setprio 1
	s_waitcnt lgkmcnt(0)
	v_mfma_f32_16x16x32_bf16 v[76:79], v[40:43], v[160:163], 0
	v_mfma_f32_16x16x32_bf16 v[72:75], v[56:59], v[160:163], 0
	v_mfma_f32_16x16x32_bf16 v[52:55], v[40:43], v[186:189], 0
	v_mfma_f32_16x16x32_bf16 v[48:51], v[56:59], v[186:189], 0
	v_mfma_f32_16x16x32_bf16 v[28:31], v[40:43], v[194:197], 0
	v_mfma_f32_16x16x32_bf16 v[24:27], v[56:59], v[194:197], 0
	v_mfma_f32_16x16x32_bf16 v[12:15], v[40:43], v[202:205], 0
	v_mfma_f32_16x16x32_bf16 v[8:11], v[56:59], v[202:205], 0
	v_mfma_f32_16x16x32_bf16 v[76:79], v[44:47], v[164:167], v[76:79]
	v_mfma_f32_16x16x32_bf16 v[72:75], v[60:63], v[164:167], v[72:75]
	v_mfma_f32_16x16x32_bf16 v[52:55], v[44:47], v[190:193], v[52:55]
	v_mfma_f32_16x16x32_bf16 v[48:51], v[60:63], v[190:193], v[48:51]
	v_mfma_f32_16x16x32_bf16 v[28:31], v[44:47], v[198:201], v[28:31]
	v_mfma_f32_16x16x32_bf16 v[24:27], v[60:63], v[198:201], v[24:27]
	v_mfma_f32_16x16x32_bf16 v[12:15], v[44:47], v[214:217], v[12:15]
	v_mfma_f32_16x16x32_bf16 v[8:11], v[60:63], v[214:217], v[8:11]
	s_setprio 0
	s_setprio 1
	v_mfma_f32_16x16x32_bf16 v[36:39], v[144:147], v[186:189], 0
	v_mfma_f32_16x16x32_bf16 v[32:35], v[152:155], v[186:189], 0
	v_mfma_f32_16x16x32_bf16 v[20:23], v[144:147], v[194:197], 0
	v_mfma_f32_16x16x32_bf16 v[16:19], v[152:155], v[194:197], 0
	v_mfma_f32_16x16x32_bf16 v[4:7], v[144:147], v[202:205], 0
	v_mfma_f32_16x16x32_bf16 v[0:3], v[152:155], v[202:205], 0
	v_mfma_f32_16x16x32_bf16 v[40:43], v[144:147], v[160:163], 0
	v_mfma_f32_16x16x32_bf16 v[44:47], v[152:155], v[160:163], 0
	v_mfma_f32_16x16x32_bf16 v[36:39], v[148:151], v[190:193], v[36:39]
	v_mfma_f32_16x16x32_bf16 v[32:35], v[156:159], v[190:193], v[32:35]
	v_mfma_f32_16x16x32_bf16 v[20:23], v[148:151], v[198:201], v[20:23]
	v_mfma_f32_16x16x32_bf16 v[16:19], v[156:159], v[198:201], v[16:19]
	v_mfma_f32_16x16x32_bf16 v[4:7], v[148:151], v[214:217], v[4:7]
	v_mfma_f32_16x16x32_bf16 v[0:3], v[156:159], v[214:217], v[0:3]
	v_mfma_f32_16x16x32_bf16 v[40:43], v[148:151], v[164:167], v[40:43]
	v_mfma_f32_16x16x32_bf16 v[44:47], v[156:159], v[164:167], v[44:47]
	s_setprio 0
	s_barrier
	s_add_i32 s86, 0, 0x18000
	s_add_i32 s87, 0, 0x1c000
	v_add_u32_e32 v68, s86, v207
	v_add_u32_e32 v156, s87, v207
	ds_read_b128 v[56:59], v68
	ds_read_b128 v[60:63], v68 offset:1024
	ds_read_b128 v[64:67], v68 offset:2048
	ds_read_b128 v[68:71], v68 offset:3072
	ds_read_b128 v[144:147], v156
	ds_read_b128 v[148:151], v156 offset:1024
	ds_read_b128 v[152:155], v156 offset:2048
	ds_read_b128 v[156:159], v156 offset:3072
	s_add_u32 s64, s64, 0x40000
	s_addc_u32 s65, s65, 0
	s_mov_b32 m0, s71
	ds_read_b128 v[160:163], v210 offset:32768
	ds_read_b128 v[164:167], v210 offset:33792
	ds_read_b128 v[186:189], v210 offset:34816
	ds_read_b128 v[190:193], v210 offset:35840
	ds_read_b128 v[194:197], v210 offset:36864
	ds_read_b128 v[198:201], v210 offset:37888
	ds_read_b128 v[202:205], v210 offset:38912
	ds_read_b128 v[214:217], v210 offset:39936
	global_load_lds_dwordx4 v168, s[64:65]
	s_mov_b32 m0, s72
	s_nop 0
	global_load_lds_dwordx4 v172, s[64:65]
	s_waitcnt vmcnt(8)
	s_waitcnt lgkmcnt(0)
	s_barrier
	s_setprio 1
	s_waitcnt lgkmcnt(0)
	v_mfma_f32_16x16x32_bf16 v[140:143], v[56:59], v[160:163], v[140:143]
	v_mfma_f32_16x16x32_bf16 v[136:139], v[64:67], v[160:163], v[136:139]
	v_mfma_f32_16x16x32_bf16 v[124:127], v[56:59], v[186:189], v[124:127]
	v_mfma_f32_16x16x32_bf16 v[120:123], v[64:67], v[186:189], v[120:123]
	v_mfma_f32_16x16x32_bf16 v[108:111], v[56:59], v[194:197], v[108:111]
	v_mfma_f32_16x16x32_bf16 v[104:107], v[64:67], v[194:197], v[104:107]
	v_mfma_f32_16x16x32_bf16 v[92:95], v[56:59], v[202:205], v[92:95]
	v_mfma_f32_16x16x32_bf16 v[88:91], v[64:67], v[202:205], v[88:91]
	v_mfma_f32_16x16x32_bf16 v[140:143], v[60:63], v[164:167], v[140:143]
	v_mfma_f32_16x16x32_bf16 v[136:139], v[68:71], v[164:167], v[136:139]
	v_mfma_f32_16x16x32_bf16 v[124:127], v[60:63], v[190:193], v[124:127]
	v_mfma_f32_16x16x32_bf16 v[120:123], v[68:71], v[190:193], v[120:123]
	v_mfma_f32_16x16x32_bf16 v[108:111], v[60:63], v[198:201], v[108:111]
	v_mfma_f32_16x16x32_bf16 v[104:107], v[68:71], v[198:201], v[104:107]
	v_mfma_f32_16x16x32_bf16 v[92:95], v[60:63], v[214:217], v[92:95]
	v_mfma_f32_16x16x32_bf16 v[88:91], v[68:71], v[214:217], v[88:91]
	s_setprio 0
	s_setprio 1
	v_mfma_f32_16x16x32_bf16 v[132:135], v[144:147], v[160:163], v[132:135]
	v_mfma_f32_16x16x32_bf16 v[128:131], v[152:155], v[160:163], v[128:131]
	v_mfma_f32_16x16x32_bf16 v[116:119], v[144:147], v[186:189], v[116:119]
	v_mfma_f32_16x16x32_bf16 v[112:115], v[152:155], v[186:189], v[112:115]
	v_mfma_f32_16x16x32_bf16 v[100:103], v[144:147], v[194:197], v[100:103]
	v_mfma_f32_16x16x32_bf16 v[96:99], v[152:155], v[194:197], v[96:99]
	v_mfma_f32_16x16x32_bf16 v[84:87], v[144:147], v[202:205], v[84:87]
	v_mfma_f32_16x16x32_bf16 v[80:83], v[152:155], v[202:205], v[80:83]
	v_mfma_f32_16x16x32_bf16 v[132:135], v[148:151], v[164:167], v[132:135]
	v_mfma_f32_16x16x32_bf16 v[128:131], v[156:159], v[164:167], v[128:131]
	v_mfma_f32_16x16x32_bf16 v[116:119], v[148:151], v[190:193], v[116:119]
	v_mfma_f32_16x16x32_bf16 v[112:115], v[156:159], v[190:193], v[112:115]
	v_mfma_f32_16x16x32_bf16 v[100:103], v[148:151], v[198:201], v[100:103]
	v_mfma_f32_16x16x32_bf16 v[96:99], v[156:159], v[198:201], v[96:99]
	v_mfma_f32_16x16x32_bf16 v[84:87], v[148:151], v[214:217], v[84:87]
	v_mfma_f32_16x16x32_bf16 v[80:83], v[156:159], v[214:217], v[80:83]
	s_setprio 0
	s_barrier
; #define PG8_STAGE(bufoff, gbase, voff) do { _Pragma("unroll") for (int _i = 0; _i < 2; ++_i) \
;         __builtin_amdgcn_global_load_lds((const unsigned*)((const char*)(gbase) + (voff)[_i]), (LAS unsigned*)(lds + (bufoff) + ldsw + _i * 8192), 16, 0, 0); } while (0)
; #define PG8_LDA(dst, b, h) do { _Pragma("unroll") for (int m = 0; m < 4; ++m) _Pragma("unroll") for (int k = 0; k < 2; ++k) dst[m][k] = *(const LAS bf16x8*)(lds + PG8_SA(b, h) + aoff + m * 2048 + k * 1024); } while (0)
; #define PG8_LDB(dst, b, h) do { _Pragma("unroll") for (int n = 0; n < 2; ++n) _Pragma("unroll") for (int k = 0; k < 2; ++k) dst[n][k] = *(const LAS bf16x8*)(lds + PG8_SB(b, h) + boff + n * 2048 + k * 1024); } while (0)
; #define PG8_MMA(ai, bj, At, Bt) do { __builtin_amdgcn_s_setprio(1); _Pragma("unroll") for (int m = 0; m < 4; ++m) _Pragma("unroll") for (int n = 0; n < 2; ++n) _Pragma("unroll") for (int k = 0; k < 2; ++k) \
;         acc[ai][bj][m][n] = __builtin_amdgcn_mfma_f32_16x16x32_bf16(Bt[n][k], At[m][k], acc[ai][bj][m][n], 0, 0, 0); __builtin_amdgcn_s_setprio(0); } while (0)
; #define PG8_WAIT_V(n) asm volatile("s_waitcnt vmcnt(" #n ")" ::: "memory")
; #define PG8_BAR __builtin_amdgcn_s_barrier()
; template <class Epi>
; __device__ __forceinline__ void gemm_phase(LAS unsigned char* lds, const Gemm g, const StaticOrder& S, const Epi& E) {
;     ...
;             PG8_LDB(B0, 0, 0); PG8_LDB(B1, 0, 1); PG8_SCHED; PG8_LDA(At, 0, 0); PG8_STAGE(PG8_SA(1, 1), a1 + hstepA, voffA);
;             PG8_WAIT_V(8); PG8_WAIT_L(0); PG8_BAR; PG8_MMA(0, 0, At, B0); PG8_MMA(0, 1, At, B1); PG8_BAR; PG8_SCHED;
;             PG8_LDA(At, 0, 1); PG8_STAGE(PG8_SB(0, 0), b2, voffB); PG8_STAGE(PG8_SB(0, 1), b2 + hstepB, voffB); PG8_STAGE(PG8_SA(0, 0), a2, voffA);
;             PG8_WAIT_V(8); PG8_WAIT_L(0); PG8_BAR; PG8_MMA(1, 0, At, B0); PG8_MMA(1, 1, At, B1); PG8_BAR; PG8_SCHED;
;             PG8_LDB(B0, 1, 0); PG8_LDB(B1, 1, 1); PG8_SCHED; PG8_LDA(At, 1, 0); PG8_STAGE(PG8_SA(0, 1), a2 + hstepA, voffA);
;             PG8_WAIT_V(8); PG8_WAIT_L(0); PG8_BAR; PG8_MMA(0, 0, At, B0); PG8_MMA(0, 1, At, B1); PG8_BAR; PG8_SCHED;
;             PG8_LDA(At, 1, 1); PG8_STAGE(PG8_SB(1, 0), b3, voffB); PG8_STAGE(PG8_SB(1, 1), b3 + hstepB, voffB); PG8_STAGE(PG8_SA(1, 0), a3, voffA);
;             PG8_WAIT_V(8); PG8_WAIT_L(0); PG8_BAR; PG8_MMA(1, 0, At, B0); PG8_MMA(1, 1, At, B1); PG8_BAR; PG8_SCHED;
	s_add_i32 s64, s86, s68
	v_lshl_add_u64 v[218:219], v[218:219], 0, s[18:19]
	s_mov_b32 m0, s64
	ds_read_b128 v[160:163], v210 offset:49152
	ds_read_b128 v[164:167], v210 offset:50176
	ds_read_b128 v[186:189], v210 offset:51200
	ds_read_b128 v[190:193], v210 offset:52224
	ds_read_b128 v[194:197], v210 offset:53248
	ds_read_b128 v[198:201], v210 offset:54272
	ds_read_b128 v[202:205], v210 offset:55296
	ds_read_b128 v[214:217], v210 offset:56320
	global_load_lds_dwordx4 v[218:219], off
	s_add_i32 m0, s64, 0x2000
	s_add_u32 s62, s62, 0x40080
	v_lshl_add_u64 v[218:219], v[220:221], 0, s[18:19]
	s_addc_u32 s63, s63, 0
	s_add_i32 s64, s87, s68
	global_load_lds_dwordx4 v[218:219], off
	s_mov_b32 m0, s64
	s_nop 0
	global_load_lds_dwordx4 v170, s[62:63]
	s_add_i32 m0, s64, 0x2000
	s_nop 0
	global_load_lds_dwordx4 v174, s[62:63]
	v_lshl_add_u64 v[218:219], v[222:223], 0, s[18:19]
	s_mov_b32 m0, s76
	s_nop 0
	global_load_lds_dwordx4 v[218:219], off
	v_lshl_add_u64 v[218:219], v[226:227], 0, s[18:19]
	s_mov_b32 m0, s77
	s_nop 0
	global_load_lds_dwordx4 v[218:219], off
	s_waitcnt vmcnt(8)
	s_waitcnt lgkmcnt(0)
	s_barrier
	s_setprio 1
	s_waitcnt lgkmcnt(0)
	v_mfma_f32_16x16x32_bf16 v[76:79], v[56:59], v[160:163], v[76:79]
	v_mfma_f32_16x16x32_bf16 v[72:75], v[64:67], v[160:163], v[72:75]
	v_mfma_f32_16x16x32_bf16 v[52:55], v[56:59], v[186:189], v[52:55]
	v_mfma_f32_16x16x32_bf16 v[48:51], v[64:67], v[186:189], v[48:51]
	v_mfma_f32_16x16x32_bf16 v[28:31], v[56:59], v[194:197], v[28:31]
	v_mfma_f32_16x16x32_bf16 v[24:27], v[64:67], v[194:197], v[24:27]
	v_mfma_f32_16x16x32_bf16 v[12:15], v[56:59], v[202:205], v[12:15]
	v_mfma_f32_16x16x32_bf16 v[8:11], v[64:67], v[202:205], v[8:11]
	v_mfma_f32_16x16x32_bf16 v[76:79], v[60:63], v[164:167], v[76:79]
	v_mfma_f32_16x16x32_bf16 v[72:75], v[68:71], v[164:167], v[72:75]
	v_mfma_f32_16x16x32_bf16 v[52:55], v[60:63], v[190:193], v[52:55]
	v_mfma_f32_16x16x32_bf16 v[48:51], v[68:71], v[190:193], v[48:51]
	v_mfma_f32_16x16x32_bf16 v[28:31], v[60:63], v[198:201], v[28:31]
	v_mfma_f32_16x16x32_bf16 v[24:27], v[68:71], v[198:201], v[24:27]
	v_mfma_f32_16x16x32_bf16 v[12:15], v[60:63], v[214:217], v[12:15]
	v_mfma_f32_16x16x32_bf16 v[8:11], v[68:71], v[214:217], v[8:11]
	s_setprio 0
	s_setprio 1
	v_mfma_f32_16x16x32_bf16 v[40:43], v[144:147], v[160:163], v[40:43]
	v_mfma_f32_16x16x32_bf16 v[68:71], v[148:151], v[164:167], v[40:43]
	v_mfma_f32_16x16x32_bf16 v[40:43], v[152:155], v[160:163], v[44:47]
	v_mfma_f32_16x16x32_bf16 v[36:39], v[144:147], v[186:189], v[36:39]
	v_mfma_f32_16x16x32_bf16 v[32:35], v[152:155], v[186:189], v[32:35]
	v_mfma_f32_16x16x32_bf16 v[20:23], v[144:147], v[194:197], v[20:23]
	v_mfma_f32_16x16x32_bf16 v[16:19], v[152:155], v[194:197], v[16:19]
	v_mfma_f32_16x16x32_bf16 v[4:7], v[144:147], v[202:205], v[4:7]
	v_mfma_f32_16x16x32_bf16 v[0:3], v[152:155], v[202:205], v[0:3]
	v_mfma_f32_16x16x32_bf16 v[64:67], v[156:159], v[164:167], v[40:43]
	v_mfma_f32_16x16x32_bf16 v[36:39], v[148:151], v[190:193], v[36:39]
	v_mfma_f32_16x16x32_bf16 v[32:35], v[156:159], v[190:193], v[32:35]
	v_mfma_f32_16x16x32_bf16 v[20:23], v[148:151], v[198:201], v[20:23]
	v_mfma_f32_16x16x32_bf16 v[16:19], v[156:159], v[198:201], v[16:19]
	v_mfma_f32_16x16x32_bf16 v[4:7], v[148:151], v[214:217], v[4:7]
	v_mfma_f32_16x16x32_bf16 v[0:3], v[156:159], v[214:217], v[0:3]
	s_setprio 0
	s_barrier
	s_add_i32 s85, s85, 2
	s_add_u32 s56, s56, 0x100
	s_addc_u32 s57, s57, 0
	s_add_u32 s83, s83, 0x100
	s_addc_u32 s84, s84, 0
	s_cmp_gt_u32 s85, 13
.LBB0_889:
	ds_read_b128 v[40:43], v208
	ds_read_b128 v[44:47], v208 offset:1024
	ds_read_b128 v[56:59], v208 offset:2048
	ds_read_b128 v[60:63], v208 offset:3072
	ds_read_b128 v[144:147], v209
	ds_read_b128 v[148:151], v209 offset:1024
	ds_read_b128 v[152:155], v209 offset:2048
	ds_read_b128 v[156:159], v209 offset:3072
	s_add_u32 s62, s56, 0xfffc0080
	s_addc_u32 s63, s57, -1
	s_cmp_eq_u32 s85, 12
	s_cselect_b32 s65, s7, s63
	s_cselect_b32 s64, s9, s62
	s_cselect_b32 s63, s39, s84
	s_cselect_b32 s62, s43, s83
	s_add_i32 m0, s69, 0xc000
	ds_read_b128 v[160:163], v210
	ds_read_b128 v[164:167], v210 offset:1024
	ds_read_b128 v[186:189], v210 offset:2048
	ds_read_b128 v[190:193], v210 offset:3072
	ds_read_b128 v[194:197], v210 offset:4096
	ds_read_b128 v[198:201], v210 offset:5120
	ds_read_b128 v[202:205], v210 offset:6144
	ds_read_b128 v[214:217], v210 offset:7168
	global_load_lds_dwordx4 v178, s[56:57]
	s_add_i32 m0, s69, 0xe000
	s_nop 0
	global_load_lds_dwordx4 v180, s[56:57]
	s_waitcnt vmcnt(8)
	s_waitcnt lgkmcnt(0)
	s_barrier
; #define PG8_STAGE(bufoff, gbase, voff) do { _Pragma("unroll") for (int _i = 0; _i < 2; ++_i) \
;         __builtin_amdgcn_global_load_lds((const unsigned*)((const char*)(gbase) + (voff)[_i]), (LAS unsigned*)(lds + (bufoff) + ldsw + _i * 8192), 16, 0, 0); } while (0)
; #define PG8_LDA(dst, b, h) do { _Pragma("unroll") for (int m = 0; m < 4; ++m) _Pragma("unroll") for (int k = 0; k < 2; ++k) dst[m][k] = *(const LAS bf16x8*)(lds + PG8_SA(b, h) + aoff + m * 2048 + k * 1024); } while (0)
; #define PG8_MMA(ai, bj, At, Bt) do { __builtin_amdgcn_s_setprio(1); _Pragma("unroll") for (int m = 0; m < 4; ++m) _Pragma("unroll") for (int n = 0; n < 2; ++n) _Pragma("unroll") for (int k = 0; k < 2; ++k) \
;         acc[ai][bj][m][n] = __builtin_amdgcn_mfma_f32_16x16x32_bf16(Bt[n][k], At[m][k], acc[ai][bj][m][n], 0, 0, 0); __builtin_amdgcn_s_setprio(0); } while (0)
; #define PG8_WAIT_V(n) asm volatile("s_waitcnt vmcnt(" #n ")" ::: "memory")
; #define PG8_WAIT_L(n) asm volatile("s_waitcnt lgkmcnt(" #n ")" ::: "memory")
; #define PG8_BAR __builtin_amdgcn_s_barrier()
; #define PG8_SCHED __builtin_amdgcn_sched_barrier(0)
; template <class Epi>
; __device__ __forceinline__ void gemm_phase(LAS unsigned char* lds, const Gemm g, const StaticOrder& S, const Epi& E) {
;     ...
;             PG8_WAIT_V(8); PG8_WAIT_L(0); PG8_BAR; PG8_MMA(0, 0, At, B0); PG8_MMA(0, 1, At, B1); PG8_BAR; PG8_SCHED;
;             PG8_LDA(At, 0, 1); PG8_STAGE(PG8_SB(0, 0), b2, voffB); PG8_STAGE(PG8_SB(0, 1), b2 + hstepB, voffB); PG8_STAGE(PG8_SA(0, 0), a2, voffA);
;             PG8_WAIT_V(8); PG8_WAIT_L(0); PG8_BAR; PG8_MMA(1, 0, At, B0); PG8_MMA(1, 1, At, B1); PG8_BAR; PG8_SCHED;
	s_setprio 1
	s_waitcnt lgkmcnt(0)
	v_mfma_f32_16x16x32_bf16 v[140:143], v[40:43], v[160:163], v[140:143]
	v_mfma_f32_16x16x32_bf16 v[136:139], v[56:59], v[160:163], v[136:139]
	v_mfma_f32_16x16x32_bf16 v[124:127], v[40:43], v[186:189], v[124:127]
	v_mfma_f32_16x16x32_bf16 v[120:123], v[56:59], v[186:189], v[120:123]
	v_mfma_f32_16x16x32_bf16 v[108:111], v[40:43], v[194:197], v[108:111]
	v_mfma_f32_16x16x32_bf16 v[104:107], v[56:59], v[194:197], v[104:107]
	v_mfma_f32_16x16x32_bf16 v[92:95], v[40:43], v[202:205], v[92:95]
	v_mfma_f32_16x16x32_bf16 v[88:91], v[56:59], v[202:205], v[88:91]
	v_mfma_f32_16x16x32_bf16 v[140:143], v[44:47], v[164:167], v[140:143]
	v_mfma_f32_16x16x32_bf16 v[136:139], v[60:63], v[164:167], v[136:139]
	v_mfma_f32_16x16x32_bf16 v[124:127], v[44:47], v[190:193], v[124:127]
	v_mfma_f32_16x16x32_bf16 v[120:123], v[60:63], v[190:193], v[120:123]
	v_mfma_f32_16x16x32_bf16 v[108:111], v[44:47], v[198:201], v[108:111]
	v_mfma_f32_16x16x32_bf16 v[104:107], v[60:63], v[198:201], v[104:107]
	v_mfma_f32_16x16x32_bf16 v[92:95], v[44:47], v[214:217], v[92:95]
	v_mfma_f32_16x16x32_bf16 v[88:91], v[60:63], v[214:217], v[88:91]
	s_setprio 0
	s_setprio 1
	v_mfma_f32_16x16x32_bf16 v[132:135], v[144:147], v[160:163], v[132:135]
	v_mfma_f32_16x16x32_bf16 v[128:131], v[152:155], v[160:163], v[128:131]
	v_mfma_f32_16x16x32_bf16 v[116:119], v[144:147], v[186:189], v[116:119]
	v_mfma_f32_16x16x32_bf16 v[112:115], v[152:155], v[186:189], v[112:115]
	v_mfma_f32_16x16x32_bf16 v[100:103], v[144:147], v[194:197], v[100:103]
	v_mfma_f32_16x16x32_bf16 v[96:99], v[152:155], v[194:197], v[96:99]
	v_mfma_f32_16x16x32_bf16 v[84:87], v[144:147], v[202:205], v[84:87]
	v_mfma_f32_16x16x32_bf16 v[80:83], v[152:155], v[202:205], v[80:83]
	v_mfma_f32_16x16x32_bf16 v[132:135], v[148:151], v[164:167], v[132:135]
	v_mfma_f32_16x16x32_bf16 v[128:131], v[156:159], v[164:167], v[128:131]
	v_mfma_f32_16x16x32_bf16 v[116:119], v[148:151], v[190:193], v[116:119]
	v_mfma_f32_16x16x32_bf16 v[112:115], v[156:159], v[190:193], v[112:115]
	v_mfma_f32_16x16x32_bf16 v[100:103], v[148:151], v[198:201], v[100:103]
	v_mfma_f32_16x16x32_bf16 v[96:99], v[156:159], v[198:201], v[96:99]
	v_mfma_f32_16x16x32_bf16 v[84:87], v[148:151], v[214:217], v[84:87]
	v_mfma_f32_16x16x32_bf16 v[80:83], v[156:159], v[214:217], v[80:83]
	s_setprio 0
	s_barrier
	s_add_i32 s86, s81, s68
	v_lshl_add_u64 v[218:219], s[62:63], 0, v[170:171]
	s_mov_b32 m0, s86
	ds_read_b128 v[160:163], v210 offset:16384
	ds_read_b128 v[164:167], v210 offset:17408
	ds_read_b128 v[186:189], v210 offset:18432
	ds_read_b128 v[190:193], v210 offset:19456
	ds_read_b128 v[194:197], v210 offset:20480
	ds_read_b128 v[198:201], v210 offset:21504
	ds_read_b128 v[202:205], v210 offset:22528
	ds_read_b128 v[214:217], v210 offset:23552
	global_load_lds_dwordx4 v[218:219], off
	s_add_i32 m0, s86, 0x2000
	s_add_u32 s86, s62, 0x40000
	v_lshl_add_u64 v[220:221], s[62:63], 0, v[174:175]
	s_addc_u32 s87, s63, 0
	s_add_i32 s88, s82, s68
	global_load_lds_dwordx4 v[220:221], off
	s_mov_b32 m0, s88
	v_lshl_add_u64 v[226:227], s[64:65], 0, v[172:173]
	global_load_lds_dwordx4 v170, s[86:87]
	s_add_i32 m0, s88, 0x2000
	s_nop 0
	global_load_lds_dwordx4 v174, s[86:87]
	v_lshl_add_u64 v[222:223], s[64:65], 0, v[168:169]
	s_mov_b32 m0, s69
	s_nop 0
	global_load_lds_dwordx4 v[222:223], off
	s_mov_b32 m0, s70
	s_nop 0
	global_load_lds_dwordx4 v[226:227], off
	s_waitcnt vmcnt(8)
	s_waitcnt lgkmcnt(0)
	s_barrier
	s_setprio 1
	s_waitcnt lgkmcnt(0)
	v_mfma_f32_16x16x32_bf16 v[76:79], v[40:43], v[160:163], v[76:79]
	v_mfma_f32_16x16x32_bf16 v[72:75], v[56:59], v[160:163], v[72:75]
	v_mfma_f32_16x16x32_bf16 v[52:55], v[40:43], v[186:189], v[52:55]
	v_mfma_f32_16x16x32_bf16 v[48:51], v[56:59], v[186:189], v[48:51]
	v_mfma_f32_16x16x32_bf16 v[28:31], v[40:43], v[194:197], v[28:31]
	v_mfma_f32_16x16x32_bf16 v[24:27], v[56:59], v[194:197], v[24:27]
	v_mfma_f32_16x16x32_bf16 v[12:15], v[40:43], v[202:205], v[12:15]
	v_mfma_f32_16x16x32_bf16 v[8:11], v[56:59], v[202:205], v[8:11]
	v_mfma_f32_16x16x32_bf16 v[76:79], v[44:47], v[164:167], v[76:79]
	v_mfma_f32_16x16x32_bf16 v[72:75], v[60:63], v[164:167], v[72:75]
	v_mfma_f32_16x16x32_bf16 v[52:55], v[44:47], v[190:193], v[52:55]
	v_mfma_f32_16x16x32_bf16 v[48:51], v[60:63], v[190:193], v[48:51]
	v_mfma_f32_16x16x32_bf16 v[28:31], v[44:47], v[198:201], v[28:31]
	v_mfma_f32_16x16x32_bf16 v[24:27], v[60:63], v[198:201], v[24:27]
	v_mfma_f32_16x16x32_bf16 v[12:15], v[44:47], v[214:217], v[12:15]
	v_mfma_f32_16x16x32_bf16 v[8:11], v[60:63], v[214:217], v[8:11]
	s_setprio 0
	s_setprio 1
	v_mfma_f32_16x16x32_bf16 v[36:39], v[144:147], v[186:189], v[36:39]
	v_mfma_f32_16x16x32_bf16 v[32:35], v[152:155], v[186:189], v[32:35]
	v_mfma_f32_16x16x32_bf16 v[20:23], v[144:147], v[194:197], v[20:23]
	v_mfma_f32_16x16x32_bf16 v[16:19], v[152:155], v[194:197], v[16:19]
	v_mfma_f32_16x16x32_bf16 v[4:7], v[144:147], v[202:205], v[4:7]
	v_mfma_f32_16x16x32_bf16 v[0:3], v[152:155], v[202:205], v[0:3]
	v_mfma_f32_16x16x32_bf16 v[40:43], v[144:147], v[160:163], v[68:71]
	v_mfma_f32_16x16x32_bf16 v[44:47], v[152:155], v[160:163], v[64:67]
	v_mfma_f32_16x16x32_bf16 v[36:39], v[148:151], v[190:193], v[36:39]
	v_mfma_f32_16x16x32_bf16 v[32:35], v[156:159], v[190:193], v[32:35]
	v_mfma_f32_16x16x32_bf16 v[20:23], v[148:151], v[198:201], v[20:23]
	v_mfma_f32_16x16x32_bf16 v[16:19], v[156:159], v[198:201], v[16:19]
	v_mfma_f32_16x16x32_bf16 v[4:7], v[148:151], v[214:217], v[4:7]
	v_mfma_f32_16x16x32_bf16 v[0:3], v[156:159], v[214:217], v[0:3]
	v_mfma_f32_16x16x32_bf16 v[40:43], v[148:151], v[164:167], v[40:43]
	v_mfma_f32_16x16x32_bf16 v[44:47], v[156:159], v[164:167], v[44:47]
	s_setprio 0
	s_barrier
; #define PG8_STAGE(bufoff, gbase, voff) do { _Pragma("unroll") for (int _i = 0; _i < 2; ++_i) \
;         __builtin_amdgcn_global_load_lds((const unsigned*)((const char*)(gbase) + (voff)[_i]), (LAS unsigned*)(lds + (bufoff) + ldsw + _i * 8192), 16, 0, 0); } while (0)
; #define PG8_LDA(dst, b, h) do { _Pragma("unroll") for (int m = 0; m < 4; ++m) _Pragma("unroll") for (int k = 0; k < 2; ++k) dst[m][k] = *(const LAS bf16x8*)(lds + PG8_SA(b, h) + aoff + m * 2048 + k * 1024); } while (0)
; #define PG8_LDB(dst, b, h) do { _Pragma("unroll") for (int n = 0; n < 2; ++n) _Pragma("unroll") for (int k = 0; k < 2; ++k) dst[n][k] = *(const LAS bf16x8*)(lds + PG8_SB(b, h) + boff + n * 2048 + k * 1024); } while (0)
; #define PG8_MMA(ai, bj, At, Bt) do { __builtin_amdgcn_s_setprio(1); _Pragma("unroll") for (int m = 0; m < 4; ++m) _Pragma("unroll") for (int n = 0; n < 2; ++n) _Pragma("unroll") for (int k = 0; k < 2; ++k) \
;         acc[ai][bj][m][n] = __builtin_amdgcn_mfma_f32_16x16x32_bf16(Bt[n][k], At[m][k], acc[ai][bj][m][n], 0, 0, 0); __builtin_amdgcn_s_setprio(0); } while (0)
; #define PG8_WAIT_V(n) asm volatile("s_waitcnt vmcnt(" #n ")" ::: "memory")
; #define PG8_WAIT_L(n) asm volatile("s_waitcnt lgkmcnt(" #n ")" ::: "memory")
; #define PG8_BAR __builtin_amdgcn_s_barrier()
; #define PG8_SCHED __builtin_amdgcn_sched_barrier(0)
; template <class Epi>
; __device__ __forceinline__ void gemm_phase(LAS unsigned char* lds, const Gemm g, const StaticOrder& S, const Epi& E) {
;     ...
;             PG8_LDB(B0, 1, 0); PG8_LDB(B1, 1, 1); PG8_SCHED; PG8_LDA(At, 1, 0); PG8_STAGE(PG8_SA(0, 1), a2 + hstepA, voffA);
;             PG8_WAIT_V(8); PG8_WAIT_L(0); PG8_BAR; PG8_MMA(0, 0, At, B0); PG8_MMA(0, 1, At, B1); PG8_BAR; PG8_SCHED;
;             PG8_LDA(At, 1, 1); PG8_STAGE(PG8_SB(1, 0), b3, voffB); PG8_STAGE(PG8_SB(1, 1), b3 + hstepB, voffB); PG8_STAGE(PG8_SA(1, 0), a3, voffA);
;             PG8_WAIT_V(8); PG8_WAIT_L(0); PG8_BAR; PG8_MMA(1, 0, At, B0); PG8_MMA(1, 1, At, B1); PG8_BAR; PG8_SCHED;
;         }
;         if (wr == 0) PG8_BAR;
	s_add_i32 s86, 0, 0x18000
	s_add_i32 s87, 0, 0x1c000
	v_add_u32_e32 v68, s86, v207
	v_add_u32_e32 v156, s87, v207
	ds_read_b128 v[56:59], v68
	ds_read_b128 v[60:63], v68 offset:1024
	ds_read_b128 v[64:67], v68 offset:2048
	ds_read_b128 v[68:71], v68 offset:3072
	ds_read_b128 v[144:147], v156
	ds_read_b128 v[148:151], v156 offset:1024
	ds_read_b128 v[152:155], v156 offset:2048
	ds_read_b128 v[156:159], v156 offset:3072
	s_add_u32 s64, s64, 0x40000
	s_addc_u32 s65, s65, 0
	s_mov_b32 m0, s71
	ds_read_b128 v[160:163], v210 offset:32768
	ds_read_b128 v[164:167], v210 offset:33792
	ds_read_b128 v[186:189], v210 offset:34816
	ds_read_b128 v[190:193], v210 offset:35840
	ds_read_b128 v[194:197], v210 offset:36864
	ds_read_b128 v[198:201], v210 offset:37888
	ds_read_b128 v[202:205], v210 offset:38912
	ds_read_b128 v[214:217], v210 offset:39936
	global_load_lds_dwordx4 v168, s[64:65]
	s_mov_b32 m0, s72
	s_nop 0
	global_load_lds_dwordx4 v172, s[64:65]
	s_waitcnt vmcnt(8)
	s_waitcnt lgkmcnt(0)
	s_barrier
	s_setprio 1
	s_waitcnt lgkmcnt(0)
	v_mfma_f32_16x16x32_bf16 v[140:143], v[56:59], v[160:163], v[140:143]
	v_mfma_f32_16x16x32_bf16 v[136:139], v[64:67], v[160:163], v[136:139]
	v_mfma_f32_16x16x32_bf16 v[124:127], v[56:59], v[186:189], v[124:127]
	v_mfma_f32_16x16x32_bf16 v[120:123], v[64:67], v[186:189], v[120:123]
	v_mfma_f32_16x16x32_bf16 v[108:111], v[56:59], v[194:197], v[108:111]
	v_mfma_f32_16x16x32_bf16 v[104:107], v[64:67], v[194:197], v[104:107]
	v_mfma_f32_16x16x32_bf16 v[92:95], v[56:59], v[202:205], v[92:95]
	v_mfma_f32_16x16x32_bf16 v[88:91], v[64:67], v[202:205], v[88:91]
	v_mfma_f32_16x16x32_bf16 v[140:143], v[60:63], v[164:167], v[140:143]
	v_mfma_f32_16x16x32_bf16 v[136:139], v[68:71], v[164:167], v[136:139]
	v_mfma_f32_16x16x32_bf16 v[124:127], v[60:63], v[190:193], v[124:127]
	v_mfma_f32_16x16x32_bf16 v[120:123], v[68:71], v[190:193], v[120:123]
	v_mfma_f32_16x16x32_bf16 v[108:111], v[60:63], v[198:201], v[108:111]
	v_mfma_f32_16x16x32_bf16 v[104:107], v[68:71], v[198:201], v[104:107]
	v_mfma_f32_16x16x32_bf16 v[92:95], v[60:63], v[214:217], v[92:95]
	v_mfma_f32_16x16x32_bf16 v[88:91], v[68:71], v[214:217], v[88:91]
	s_setprio 0
	s_setprio 1
	v_mfma_f32_16x16x32_bf16 v[132:135], v[144:147], v[160:163], v[132:135]
	v_mfma_f32_16x16x32_bf16 v[128:131], v[152:155], v[160:163], v[128:131]
	v_mfma_f32_16x16x32_bf16 v[116:119], v[144:147], v[186:189], v[116:119]
	v_mfma_f32_16x16x32_bf16 v[112:115], v[152:155], v[186:189], v[112:115]
	v_mfma_f32_16x16x32_bf16 v[100:103], v[144:147], v[194:197], v[100:103]
	v_mfma_f32_16x16x32_bf16 v[96:99], v[152:155], v[194:197], v[96:99]
	v_mfma_f32_16x16x32_bf16 v[84:87], v[144:147], v[202:205], v[84:87]
	v_mfma_f32_16x16x32_bf16 v[80:83], v[152:155], v[202:205], v[80:83]
	v_mfma_f32_16x16x32_bf16 v[132:135], v[148:151], v[164:167], v[132:135]
	v_mfma_f32_16x16x32_bf16 v[128:131], v[156:159], v[164:167], v[128:131]
	v_mfma_f32_16x16x32_bf16 v[116:119], v[148:151], v[190:193], v[116:119]
	v_mfma_f32_16x16x32_bf16 v[112:115], v[156:159], v[190:193], v[112:115]
	v_mfma_f32_16x16x32_bf16 v[100:103], v[148:151], v[198:201], v[100:103]
	v_mfma_f32_16x16x32_bf16 v[96:99], v[156:159], v[198:201], v[96:99]
	v_mfma_f32_16x16x32_bf16 v[84:87], v[148:151], v[214:217], v[84:87]
	v_mfma_f32_16x16x32_bf16 v[80:83], v[156:159], v[214:217], v[80:83]
	s_setprio 0
	s_barrier
	s_add_i32 s64, s86, s68
	v_lshl_add_u64 v[218:219], v[218:219], 0, s[18:19]
	s_mov_b32 m0, s64
	ds_read_b128 v[160:163], v210 offset:49152
	ds_read_b128 v[164:167], v210 offset:50176
	ds_read_b128 v[186:189], v210 offset:51200
	ds_read_b128 v[190:193], v210 offset:52224
	ds_read_b128 v[194:197], v210 offset:53248
	ds_read_b128 v[198:201], v210 offset:54272
	ds_read_b128 v[202:205], v210 offset:55296
	ds_read_b128 v[214:217], v210 offset:56320
	global_load_lds_dwordx4 v[218:219], off
	s_add_i32 m0, s64, 0x2000
	s_add_u32 s62, s62, 0x40080
	v_lshl_add_u64 v[218:219], v[220:221], 0, s[18:19]
	s_addc_u32 s63, s63, 0
	s_add_i32 s64, s87, s68
	global_load_lds_dwordx4 v[218:219], off
	s_mov_b32 m0, s64
	s_nop 0
	global_load_lds_dwordx4 v170, s[62:63]
	s_add_i32 m0, s64, 0x2000
	s_nop 0
	global_load_lds_dwordx4 v174, s[62:63]
	v_lshl_add_u64 v[218:219], v[222:223], 0, s[18:19]
	s_mov_b32 m0, s76
	s_nop 0
	global_load_lds_dwordx4 v[218:219], off
	v_lshl_add_u64 v[218:219], v[226:227], 0, s[18:19]
	s_mov_b32 m0, s77
	s_nop 0
	global_load_lds_dwordx4 v[218:219], off
	s_waitcnt vmcnt(8)
	s_waitcnt lgkmcnt(0)
	s_barrier
	s_setprio 1
	s_waitcnt lgkmcnt(0)
	v_mfma_f32_16x16x32_bf16 v[76:79], v[56:59], v[160:163], v[76:79]
	v_mfma_f32_16x16x32_bf16 v[72:75], v[64:67], v[160:163], v[72:75]
	v_mfma_f32_16x16x32_bf16 v[52:55], v[56:59], v[186:189], v[52:55]
	v_mfma_f32_16x16x32_bf16 v[48:51], v[64:67], v[186:189], v[48:51]
	v_mfma_f32_16x16x32_bf16 v[28:31], v[56:59], v[194:197], v[28:31]
	v_mfma_f32_16x16x32_bf16 v[24:27], v[64:67], v[194:197], v[24:27]
	v_mfma_f32_16x16x32_bf16 v[12:15], v[56:59], v[202:205], v[12:15]
	v_mfma_f32_16x16x32_bf16 v[8:11], v[64:67], v[202:205], v[8:11]
	v_mfma_f32_16x16x32_bf16 v[76:79], v[60:63], v[164:167], v[76:79]
	v_mfma_f32_16x16x32_bf16 v[72:75], v[68:71], v[164:167], v[72:75]
	v_mfma_f32_16x16x32_bf16 v[52:55], v[60:63], v[190:193], v[52:55]
	v_mfma_f32_16x16x32_bf16 v[48:51], v[68:71], v[190:193], v[48:51]
	v_mfma_f32_16x16x32_bf16 v[28:31], v[60:63], v[198:201], v[28:31]
	v_mfma_f32_16x16x32_bf16 v[24:27], v[68:71], v[198:201], v[24:27]
	v_mfma_f32_16x16x32_bf16 v[12:15], v[60:63], v[214:217], v[12:15]
	v_mfma_f32_16x16x32_bf16 v[8:11], v[68:71], v[214:217], v[8:11]
	s_setprio 0
	s_setprio 1
	v_mfma_f32_16x16x32_bf16 v[40:43], v[144:147], v[160:163], v[40:43]
	v_mfma_f32_16x16x32_bf16 v[68:71], v[148:151], v[164:167], v[40:43]
	v_mfma_f32_16x16x32_bf16 v[40:43], v[152:155], v[160:163], v[44:47]
	v_mfma_f32_16x16x32_bf16 v[36:39], v[144:147], v[186:189], v[36:39]
	v_mfma_f32_16x16x32_bf16 v[32:35], v[152:155], v[186:189], v[32:35]
	v_mfma_f32_16x16x32_bf16 v[20:23], v[144:147], v[194:197], v[20:23]
	v_mfma_f32_16x16x32_bf16 v[16:19], v[152:155], v[194:197], v[16:19]
	v_mfma_f32_16x16x32_bf16 v[4:7], v[144:147], v[202:205], v[4:7]
	v_mfma_f32_16x16x32_bf16 v[0:3], v[152:155], v[202:205], v[0:3]
	v_mfma_f32_16x16x32_bf16 v[64:67], v[156:159], v[164:167], v[40:43]
	v_mfma_f32_16x16x32_bf16 v[36:39], v[148:151], v[190:193], v[36:39]
	v_mfma_f32_16x16x32_bf16 v[32:35], v[156:159], v[190:193], v[32:35]
	v_mfma_f32_16x16x32_bf16 v[20:23], v[148:151], v[198:201], v[20:23]
	v_mfma_f32_16x16x32_bf16 v[16:19], v[156:159], v[198:201], v[16:19]
	v_mfma_f32_16x16x32_bf16 v[4:7], v[148:151], v[214:217], v[4:7]
	v_mfma_f32_16x16x32_bf16 v[0:3], v[156:159], v[214:217], v[0:3]
	s_setprio 0
	s_barrier
	s_add_i32 s85, s85, 2
	s_add_u32 s56, s56, 0x100
	s_addc_u32 s57, s57, 0
	s_add_u32 s83, s83, 0x100
	s_addc_u32 s84, s84, 0
	s_cmp_gt_u32 s85, 13
	s_cbranch_scc0 .LBB0_889
	s_and_b64 vcc, exec, s[22:23]
	s_cbranch_vccz .LBB0_892
	s_barrier

; #define PG8_STAGE(bufoff, gbase, voff) do { _Pragma("unroll") for (int _i = 0; _i < 2; ++_i) \
;         __builtin_amdgcn_global_load_lds((const unsigned*)((const char*)(gbase) + (voff)[_i]), (LAS unsigned*)(lds + (bufoff) + ldsw + _i * 8192), 16, 0, 0); } while (0)
; #define PG8_WAIT_V(n) asm volatile("s_waitcnt vmcnt(" #n ")" ::: "memory")
; #define PG8_BAR __builtin_amdgcn_s_barrier()
; template <class Epi>
; __device__ __forceinline__ void gemm_phase(LAS unsigned char* lds, const Gemm g, const StaticOrder& S, const Epi& E) {
;     const int tid = threadIdx.x, wid = __builtin_amdgcn_readfirstlane(tid >> 6), lane = tid & 63, wr = wid >> 2, wc = wid & 3, fr = lane & 15, fq = lane >> 4;
;     const int K = g.K, nt = K / BK;
;     unsigned voffA[2], voffB[2];
; #pragma unroll
;     for (int i = 0; i < 2; ++i) { int R, C; stage_rc(tid * 16 + i * 8192, R, C); const int Rb = (R & ~31) + perm32(R & 31);
;         voffA[i] = (unsigned)(R * g.lda + C) * 2u; voffB[i] = (unsigned)(Rb * g.ldb + C) * 2u; }
;     const size_t kstep = (size_t)(BK * 2);
;     const size_t hstepA = (size_t)HALF * g.lda * 2, hstepB = (size_t)HALF * g.ldb * 2;
;     const size_t tstepA = 2 * hstepA, tstepB = 2 * hstepB;
;     const unsigned ldsw = (unsigned)wid * 1024u;
;     const int aoff = lds_byte(wr * 64 + fr, fq * 8), boff = lds_byte(wc * 32 + fr, fq * 8);
;     ...
;     PG8_STAGE(PG8_SB(0, 0), cB, voffB); PG8_STAGE(PG8_SB(0, 1), cB + hstepB, voffB); PG8_STAGE(PG8_SA(0, 0), cA, voffA); PG8_STAGE(PG8_SA(0, 1), cA + hstepA, voffA);
;     if (wr == 1) PG8_BAR;
;     PG8_WAIT_V(2); PG8_BAR;
;     PG8_STAGE(PG8_SB(1, 0), cB + kstep, voffB); PG8_STAGE(PG8_SA(1, 0), cA + kstep, voffA); PG8_STAGE(PG8_SB(1, 1), cB + hstepB + kstep, voffB);
;     PG8_WAIT_V(6); PG8_BAR;
.LBB0_1008:
	s_add_u32 s10, s50, 0x60000
	s_addc_u32 s11, s51, 0
	s_lshl_b32 s74, s4, 6
	s_lshl_b32 s7, s4, 13
	s_lshl_b32 s4, s5, 5
	s_and_b32 s75, s4, 0x60
	s_lshl_b32 s19, s75, 7
	s_add_u32 s12, s50, 0x300000
	s_addc_u32 s13, s51, 0
	s_add_u32 s14, s50, 0x400000
	s_mov_b64 s[16:17], 0x80
	s_addc_u32 s15, s51, 0
	s_add_i32 m0, s68, 0x18000
	v_lshl_add_u64 v[6:7], v[6:7], 0, s[16:17]
	s_waitcnt vmcnt(2)
	s_barrier
	global_load_lds_dwordx4 v[6:7], off
	v_lshl_add_u64 v[4:5], v[4:5], 0, s[16:17]
	s_add_i32 m0, s68, 0x1a000
	s_add_i32 s76, s68, 0x8000
	s_add_i32 s77, s68, 0xa000
	global_load_lds_dwordx4 v[4:5], off
	v_lshl_add_u64 v[0:1], v[0:1], 0, s[16:17]
	s_mov_b32 m0, s76
	s_add_u32 s4, s56, 0x40080
	global_load_lds_dwordx4 v[0:1], off
	v_lshl_add_u64 v[0:1], v[2:3], 0, s[16:17]
	s_mov_b32 m0, s77
	s_addc_u32 s5, s57, 0
	global_load_lds_dwordx4 v[0:1], off
	s_add_i32 m0, s68, 0x1c000
	global_load_lds_dwordx4 v180, s[4:5]
	s_add_i32 m0, s68, 0x1e000
	v_bfe_u32 v228, v176, 4, 2
	global_load_lds_dwordx4 v184, s[4:5]
	v_and_b32_e32 v227, 15, v176
	v_lshlrev_b32_e32 v0, 4, v228
	s_movk_i32 s4, 0x3c0
	v_lshl_or_b32 v1, v227, 6, v0
	v_and_b32_e32 v2, 32, v226
	v_and_or_b32 v0, v177, s4, v0
	v_bitop3_b32 v229, s19, v0, v2 bitop3:0xf6
	v_lshlrev_b32_e32 v0, 8, v176
	v_bitop3_b32 v1, v1, s7, v2 bitop3:0xde
	v_and_b32_e32 v0, 0x38000, v0
	v_lshlrev_b32_e32 v2, 11, v10
	v_or3_b32 v0, v8, v0, v2
	v_readlane_b32 s80, v254, 6
	v_add_u32_e32 v188, v0, v9
	v_lshlrev_b32_e32 v0, 4, v11
	s_waitcnt vmcnt(6)
	s_cmpk_lt_u32 s18, 0x100
	v_readlane_b32 s81, v254, 7
	v_readlane_b32 s82, v254, 8
	v_and_b32_e32 v0, 0x78000, v0
	s_cselect_b64 s[18:19], -1, 0
	s_ashr_i32 s78, s82, 31
	s_mov_b32 s79, s82
	v_or3_b32 v0, v8, v0, v2
	s_add_i32 s81, 0, 0x10000
	s_add_i32 s82, 0, 0x14000
	s_ashr_i32 s80, s2, 31
	v_mov_b32_e32 v189, v187
	v_add_u32_e32 v190, v0, v9
	v_mov_b32_e32 v191, v187
	v_mov_b64_e32 v[192:193], 0x800
	v_mov_b64_e32 v[194:195], 0x7ff
	v_add_u32_e32 v230, s81, v229
	v_add_u32_e32 v231, s82, v229
	v_add_u32_e32 v232, 0, v1
	v_mov_b32_e32 v233, 0x358637bd
	s_barrier
	v_readlane_b32 s83, v254, 9
	s_branch .LBB0_1011

; #define PG8_STAGE(bufoff, gbase, voff) do { _Pragma("unroll") for (int _i = 0; _i < 2; ++_i) \
;         __builtin_amdgcn_global_load_lds((const unsigned*)((const char*)(gbase) + (voff)[_i]), (LAS unsigned*)(lds + (bufoff) + ldsw + _i * 8192), 16, 0, 0); } while (0)
; #define PG8_LDA(dst, b, h) do { _Pragma("unroll") for (int m = 0; m < 4; ++m) _Pragma("unroll") for (int k = 0; k < 2; ++k) dst[m][k] = *(const LAS bf16x8*)(lds + PG8_SA(b, h) + aoff + m * 2048 + k * 1024); } while (0)
; #define PG8_LDB(dst, b, h) do { _Pragma("unroll") for (int n = 0; n < 2; ++n) _Pragma("unroll") for (int k = 0; k < 2; ++k) dst[n][k] = *(const LAS bf16x8*)(lds + PG8_SB(b, h) + boff + n * 2048 + k * 1024); } while (0)
; #define PG8_MMA(ai, bj, At, Bt) do { __builtin_amdgcn_s_setprio(1); _Pragma("unroll") for (int m = 0; m < 4; ++m) _Pragma("unroll") for (int n = 0; n < 2; ++n) _Pragma("unroll") for (int k = 0; k < 2; ++k) \
;         acc[ai][bj][m][n] = __builtin_amdgcn_mfma_f32_16x16x32_bf16(Bt[n][k], At[m][k], acc[ai][bj][m][n], 0, 0, 0); __builtin_amdgcn_s_setprio(0); } while (0)
; #define PG8_BAR __builtin_amdgcn_s_barrier()
; template <class Epi>
; __device__ __forceinline__ void gemm_phase(LAS unsigned char* lds, const Gemm g, const StaticOrder& S, const Epi& E) {
;     ...
;         const bool has_next = S.next(ui + 1, nxt);
;         const char* nA = has_next ? (const char*)g.A + (size_t)nxt.pm * tstepA : cA; const char* nB = has_next ? (const char*)g.Bt + (size_t)nxt.pn * tstepB : cB;
; #pragma nounroll
;         for (int t = 0; t < nt; t += 2) {
;             const bool last = (t == nt - 2);
;             const char* a1 = cA + (size_t)(t + 1) * kstep;
;             const char* a2 = last ? nA : cA + (size_t)(t + 2) * kstep; const char* b2 = last ? nB : cB + (size_t)(t + 2) * kstep;
;             const char* a3 = a2 + kstep; const char* b3 = b2 + kstep;
;             PG8_LDB(B0, 0, 0); PG8_LDB(B1, 0, 1); PG8_SCHED; PG8_LDA(At, 0, 0); PG8_STAGE(PG8_SA(1, 1), a1 + hstepA, voffA);
;             PG8_WAIT_V(8); PG8_WAIT_L(0); PG8_BAR; PG8_MMA(0, 0, At, B0); PG8_MMA(0, 1, At, B1); PG8_BAR; PG8_SCHED;
;             PG8_LDA(At, 0, 1); PG8_STAGE(PG8_SB(0, 0), b2, voffB); PG8_STAGE(PG8_SB(0, 1), b2 + hstepB, voffB); PG8_STAGE(PG8_SA(0, 0), a2, voffA);
;             PG8_WAIT_V(8); PG8_WAIT_L(0); PG8_BAR; PG8_MMA(1, 0, At, B0); PG8_MMA(1, 1, At, B1); PG8_BAR; PG8_SCHED;
.LBB0_1017:
	s_ashr_i32 s35, s34, 31
	s_lshl_b64 s[38:39], s[34:35], 19
	s_add_u32 s38, s24, s38
	s_addc_u32 s39, s25, s39
	s_and_b64 s[42:43], s[4:5], exec
	s_cselect_b32 s7, s39, s55
	s_cselect_b32 s35, s38, s54
	s_ashr_i32 s23, s22, 31
	s_lshl_b64 s[42:43], s[22:23], 19
	s_add_u32 s42, s33, s42
	s_addc_u32 s43, s64, s43
	s_and_b64 s[62:63], s[4:5], exec
	s_cselect_b32 s23, s43, s57
	s_cselect_b32 s53, s42, s56
	s_add_u32 s54, s54, 0x40080
	s_addc_u32 s55, s55, 0
	s_add_u32 s83, s56, 0x100
	s_nop 0
	s_addc_u32 s84, s57, 0
	s_mov_b32 s85, -2
	v_lshl_add_u32 v248, s6, 8, v227
	v_add_u32_e32 v248, s74, v248
	v_ashrrev_i32_e32 v249, 31, v248
	v_lshl_add_u64 v[248:249], v[248:249], 2, s[10:11]
	global_load_dword v240, v[248:249], off
	global_load_dword v241, v[248:249], off offset:64
	global_load_dword v242, v[248:249], off offset:128
	global_load_dword v243, v[248:249], off offset:192
	global_load_dword v244, v[248:249], off offset:512
	global_load_dword v245, v[248:249], off offset:576
	global_load_dword v246, v[248:249], off offset:640
	global_load_dword v247, v[248:249], off offset:704
	ds_read_b128 v[0:3], v230
	ds_read_b128 v[4:7], v230 offset:1024
	ds_read_b128 v[8:11], v230 offset:2048
	ds_read_b128 v[12:15], v230 offset:3072
	ds_read_b128 v[144:147], v231
	ds_read_b128 v[148:151], v231 offset:1024
	ds_read_b128 v[152:155], v231 offset:2048
	ds_read_b128 v[156:159], v231 offset:3072
	s_add_u32 s56, s54, 0xfffc0080
	s_addc_u32 s57, s55, -1
	s_cmp_eq_u32 s85, 12
	s_cselect_b32 s63, s7, s57
	s_cselect_b32 s62, s35, s56
	s_cselect_b32 s57, s23, s84
	s_cselect_b32 s56, s53, s83
	s_add_i32 m0, s68, 0xc000
	ds_read_b128 v[160:163], v232
	ds_read_b128 v[164:167], v232 offset:1024
	ds_read_b128 v[168:171], v232 offset:2048
	ds_read_b128 v[172:175], v232 offset:3072
	ds_read_b128 v[196:199], v232 offset:4096
	ds_read_b128 v[200:203], v232 offset:5120
	ds_read_b128 v[204:207], v232 offset:6144
	ds_read_b128 v[208:211], v232 offset:7168
	global_load_lds_dwordx4 v188, s[54:55]
	s_add_i32 m0, s68, 0xe000
	s_nop 0
	global_load_lds_dwordx4 v190, s[54:55]
	s_waitcnt vmcnt(8)
	s_waitcnt lgkmcnt(0)
	s_barrier
	s_setprio 1
	s_waitcnt lgkmcnt(0)
	v_mfma_f32_16x16x32_bf16 v[140:143], v[0:3], v[160:163], 0
	v_mfma_f32_16x16x32_bf16 v[132:135], v[8:11], v[160:163], 0
	v_mfma_f32_16x16x32_bf16 v[124:127], v[0:3], v[168:171], 0
	v_mfma_f32_16x16x32_bf16 v[120:123], v[8:11], v[168:171], 0
	v_mfma_f32_16x16x32_bf16 v[108:111], v[0:3], v[196:199], 0
	v_mfma_f32_16x16x32_bf16 v[104:107], v[8:11], v[196:199], 0
	v_mfma_f32_16x16x32_bf16 v[92:95], v[0:3], v[204:207], 0
	v_mfma_f32_16x16x32_bf16 v[88:91], v[8:11], v[204:207], 0
	v_mfma_f32_16x16x32_bf16 v[140:143], v[4:7], v[164:167], v[140:143]
	v_mfma_f32_16x16x32_bf16 v[132:135], v[12:15], v[164:167], v[132:135]
	v_mfma_f32_16x16x32_bf16 v[124:127], v[4:7], v[172:175], v[124:127]
	v_mfma_f32_16x16x32_bf16 v[120:123], v[12:15], v[172:175], v[120:123]
	v_mfma_f32_16x16x32_bf16 v[108:111], v[4:7], v[200:203], v[108:111]
	v_mfma_f32_16x16x32_bf16 v[104:107], v[12:15], v[200:203], v[104:107]
	v_mfma_f32_16x16x32_bf16 v[92:95], v[4:7], v[208:211], v[92:95]
	v_mfma_f32_16x16x32_bf16 v[88:91], v[12:15], v[208:211], v[88:91]
	s_setprio 0
	s_setprio 1
	v_mfma_f32_16x16x32_bf16 v[136:139], v[144:147], v[160:163], 0
	v_mfma_f32_16x16x32_bf16 v[128:131], v[152:155], v[160:163], 0
	v_mfma_f32_16x16x32_bf16 v[116:119], v[144:147], v[168:171], 0
	v_mfma_f32_16x16x32_bf16 v[112:115], v[152:155], v[168:171], 0
	v_mfma_f32_16x16x32_bf16 v[100:103], v[144:147], v[196:199], 0
	v_mfma_f32_16x16x32_bf16 v[96:99], v[152:155], v[196:199], 0
	v_mfma_f32_16x16x32_bf16 v[84:87], v[144:147], v[204:207], 0
	v_mfma_f32_16x16x32_bf16 v[80:83], v[152:155], v[204:207], 0
	v_mfma_f32_16x16x32_bf16 v[136:139], v[148:151], v[164:167], v[136:139]
	v_mfma_f32_16x16x32_bf16 v[128:131], v[156:159], v[164:167], v[128:131]
	v_mfma_f32_16x16x32_bf16 v[116:119], v[148:151], v[172:175], v[116:119]
	v_mfma_f32_16x16x32_bf16 v[112:115], v[156:159], v[172:175], v[112:115]
	v_mfma_f32_16x16x32_bf16 v[100:103], v[148:151], v[200:203], v[100:103]
	v_mfma_f32_16x16x32_bf16 v[96:99], v[156:159], v[200:203], v[96:99]
	v_mfma_f32_16x16x32_bf16 v[84:87], v[148:151], v[208:211], v[84:87]
	v_mfma_f32_16x16x32_bf16 v[80:83], v[156:159], v[208:211], v[80:83]
	s_setprio 0
	s_barrier
	s_add_i32 s86, s81, s65
	v_lshl_add_u64 v[212:213], s[56:57], 0, v[180:181]
	s_mov_b32 m0, s86
	ds_read_b128 v[160:163], v232 offset:16384
	ds_read_b128 v[164:167], v232 offset:17408
	ds_read_b128 v[168:171], v232 offset:18432
	ds_read_b128 v[172:175], v232 offset:19456
	ds_read_b128 v[196:199], v232 offset:20480
	ds_read_b128 v[200:203], v232 offset:21504
	ds_read_b128 v[204:207], v232 offset:22528
	ds_read_b128 v[208:211], v232 offset:23552
	global_load_lds_dwordx4 v[212:213], off
	s_add_i32 m0, s86, 0x2000
	s_add_u32 s86, s56, 0x40000
	v_lshl_add_u64 v[214:215], s[56:57], 0, v[184:185]
	s_addc_u32 s87, s57, 0
	s_add_i32 s88, s82, s65
	global_load_lds_dwordx4 v[214:215], off
	s_mov_b32 m0, s88
	v_lshl_add_u64 v[218:219], s[62:63], 0, v[182:183]
	global_load_lds_dwordx4 v180, s[86:87]
	s_add_i32 m0, s88, 0x2000
	s_nop 0
	global_load_lds_dwordx4 v184, s[86:87]
	v_lshl_add_u64 v[216:217], s[62:63], 0, v[178:179]
	s_mov_b32 m0, s68
	s_nop 0
	global_load_lds_dwordx4 v[216:217], off
	s_mov_b32 m0, s69
	s_nop 0
	global_load_lds_dwordx4 v[218:219], off
	s_waitcnt vmcnt(8)
	s_waitcnt lgkmcnt(0)
	s_barrier
; #define PG8_STAGE(bufoff, gbase, voff) do { _Pragma("unroll") for (int _i = 0; _i < 2; ++_i) \
;         __builtin_amdgcn_global_load_lds((const unsigned*)((const char*)(gbase) + (voff)[_i]), (LAS unsigned*)(lds + (bufoff) + ldsw + _i * 8192), 16, 0, 0); } while (0)
; #define PG8_LDA(dst, b, h) do { _Pragma("unroll") for (int m = 0; m < 4; ++m) _Pragma("unroll") for (int k = 0; k < 2; ++k) dst[m][k] = *(const LAS bf16x8*)(lds + PG8_SA(b, h) + aoff + m * 2048 + k * 1024); } while (0)
; #define PG8_LDB(dst, b, h) do { _Pragma("unroll") for (int n = 0; n < 2; ++n) _Pragma("unroll") for (int k = 0; k < 2; ++k) dst[n][k] = *(const LAS bf16x8*)(lds + PG8_SB(b, h) + boff + n * 2048 + k * 1024); } while (0)
; #define PG8_MMA(ai, bj, At, Bt) do { __builtin_amdgcn_s_setprio(1); _Pragma("unroll") for (int m = 0; m < 4; ++m) _Pragma("unroll") for (int n = 0; n < 2; ++n) _Pragma("unroll") for (int k = 0; k < 2; ++k) \
;         acc[ai][bj][m][n] = __builtin_amdgcn_mfma_f32_16x16x32_bf16(Bt[n][k], At[m][k], acc[ai][bj][m][n], 0, 0, 0); __builtin_amdgcn_s_setprio(0); } while (0)
; #define PG8_WAIT_V(n) asm volatile("s_waitcnt vmcnt(" #n ")" ::: "memory")
; #define PG8_WAIT_L(n) asm volatile("s_waitcnt lgkmcnt(" #n ")" ::: "memory")
; #define PG8_BAR __builtin_amdgcn_s_barrier()
; #define PG8_SCHED __builtin_amdgcn_sched_barrier(0)
; template <class Epi>
; __device__ __forceinline__ void gemm_phase(LAS unsigned char* lds, const Gemm g, const StaticOrder& S, const Epi& E) {
;     ...
;             PG8_WAIT_V(8); PG8_WAIT_L(0); PG8_BAR; PG8_MMA(1, 0, At, B0); PG8_MMA(1, 1, At, B1); PG8_BAR; PG8_SCHED;
;             PG8_LDB(B0, 1, 0); PG8_LDB(B1, 1, 1); PG8_SCHED; PG8_LDA(At, 1, 0); PG8_STAGE(PG8_SA(0, 1), a2 + hstepA, voffA);
;             PG8_WAIT_V(8); PG8_WAIT_L(0); PG8_BAR; PG8_MMA(0, 0, At, B0); PG8_MMA(0, 1, At, B1); PG8_BAR; PG8_SCHED;
	s_setprio 1
	s_waitcnt lgkmcnt(0)
	v_mfma_f32_16x16x32_bf16 v[76:79], v[0:3], v[160:163], 0
	v_mfma_f32_16x16x32_bf16 v[72:75], v[8:11], v[160:163], 0
	v_mfma_f32_16x16x32_bf16 v[60:63], v[0:3], v[168:171], 0
	v_mfma_f32_16x16x32_bf16 v[56:59], v[8:11], v[168:171], 0
	v_mfma_f32_16x16x32_bf16 v[44:47], v[0:3], v[196:199], 0
	v_mfma_f32_16x16x32_bf16 v[40:43], v[8:11], v[196:199], 0
	v_mfma_f32_16x16x32_bf16 v[0:3], v[0:3], v[204:207], 0
	v_mfma_f32_16x16x32_bf16 v[76:79], v[4:7], v[164:167], v[76:79]
	v_mfma_f32_16x16x32_bf16 v[72:75], v[12:15], v[164:167], v[72:75]
	v_mfma_f32_16x16x32_bf16 v[60:63], v[4:7], v[172:175], v[60:63]
	v_mfma_f32_16x16x32_bf16 v[56:59], v[12:15], v[172:175], v[56:59]
	v_mfma_f32_16x16x32_bf16 v[44:47], v[4:7], v[200:203], v[44:47]
	v_mfma_f32_16x16x32_bf16 v[40:43], v[12:15], v[200:203], v[40:43]
	v_mfma_f32_16x16x32_bf16 v[0:3], v[4:7], v[208:211], v[0:3]
	v_mfma_f32_16x16x32_bf16 v[4:7], v[8:11], v[204:207], 0
	v_mfma_f32_16x16x32_bf16 v[4:7], v[12:15], v[208:211], v[4:7]
	s_setprio 0
	s_setprio 1
	v_mfma_f32_16x16x32_bf16 v[20:23], v[144:147], v[168:171], 0
	v_mfma_f32_16x16x32_bf16 v[52:55], v[148:151], v[172:175], v[20:23]
	v_mfma_f32_16x16x32_bf16 v[20:23], v[152:155], v[168:171], 0
	v_mfma_f32_16x16x32_bf16 v[48:51], v[156:159], v[172:175], v[20:23]
	v_mfma_f32_16x16x32_bf16 v[20:23], v[144:147], v[196:199], 0
	v_mfma_f32_16x16x32_bf16 v[36:39], v[148:151], v[200:203], v[20:23]
	v_mfma_f32_16x16x32_bf16 v[20:23], v[152:155], v[196:199], 0
	v_mfma_f32_16x16x32_bf16 v[32:35], v[156:159], v[200:203], v[20:23]
	v_mfma_f32_16x16x32_bf16 v[20:23], v[144:147], v[204:207], 0
	v_mfma_f32_16x16x32_bf16 v[16:19], v[152:155], v[204:207], 0
	v_mfma_f32_16x16x32_bf16 v[8:11], v[144:147], v[160:163], 0
	v_mfma_f32_16x16x32_bf16 v[12:15], v[152:155], v[160:163], 0
	v_mfma_f32_16x16x32_bf16 v[24:27], v[148:151], v[208:211], v[20:23]
	v_mfma_f32_16x16x32_bf16 v[16:19], v[156:159], v[208:211], v[16:19]
	v_mfma_f32_16x16x32_bf16 v[8:11], v[148:151], v[164:167], v[8:11]
	v_mfma_f32_16x16x32_bf16 v[12:15], v[156:159], v[164:167], v[12:15]
	s_setprio 0
	s_barrier
	s_add_i32 s86, 0, 0x18000
	s_add_i32 s87, 0, 0x1c000
	v_add_u32_e32 v68, s86, v229
	v_add_u32_e32 v156, s87, v229
	ds_read_b128 v[20:23], v68
	ds_read_b128 v[28:31], v68 offset:1024
	ds_read_b128 v[64:67], v68 offset:2048
	ds_read_b128 v[68:71], v68 offset:3072
	ds_read_b128 v[144:147], v156
	ds_read_b128 v[148:151], v156 offset:1024
	ds_read_b128 v[152:155], v156 offset:2048
	ds_read_b128 v[156:159], v156 offset:3072
	s_add_u32 s62, s62, 0x40000
	s_addc_u32 s63, s63, 0
	s_mov_b32 m0, s70
	ds_read_b128 v[160:163], v232 offset:32768
	ds_read_b128 v[164:167], v232 offset:33792
	ds_read_b128 v[168:171], v232 offset:34816
	ds_read_b128 v[172:175], v232 offset:35840
	ds_read_b128 v[196:199], v232 offset:36864
	ds_read_b128 v[200:203], v232 offset:37888
	ds_read_b128 v[204:207], v232 offset:38912
	ds_read_b128 v[208:211], v232 offset:39936
	global_load_lds_dwordx4 v178, s[62:63]
	s_mov_b32 m0, s71
	s_nop 0
	global_load_lds_dwordx4 v182, s[62:63]
	s_waitcnt vmcnt(8)
	s_waitcnt lgkmcnt(0)
	s_barrier
	s_setprio 1
	s_waitcnt lgkmcnt(0)
	v_mfma_f32_16x16x32_bf16 v[140:143], v[20:23], v[160:163], v[140:143]
	v_mfma_f32_16x16x32_bf16 v[132:135], v[64:67], v[160:163], v[132:135]
	v_mfma_f32_16x16x32_bf16 v[124:127], v[20:23], v[168:171], v[124:127]
	v_mfma_f32_16x16x32_bf16 v[120:123], v[64:67], v[168:171], v[120:123]
	v_mfma_f32_16x16x32_bf16 v[108:111], v[20:23], v[196:199], v[108:111]
	v_mfma_f32_16x16x32_bf16 v[104:107], v[64:67], v[196:199], v[104:107]
	v_mfma_f32_16x16x32_bf16 v[92:95], v[20:23], v[204:207], v[92:95]
	v_mfma_f32_16x16x32_bf16 v[88:91], v[64:67], v[204:207], v[88:91]
	v_mfma_f32_16x16x32_bf16 v[140:143], v[28:31], v[164:167], v[140:143]
	v_mfma_f32_16x16x32_bf16 v[132:135], v[68:71], v[164:167], v[132:135]
	v_mfma_f32_16x16x32_bf16 v[124:127], v[28:31], v[172:175], v[124:127]
	v_mfma_f32_16x16x32_bf16 v[120:123], v[68:71], v[172:175], v[120:123]
	v_mfma_f32_16x16x32_bf16 v[108:111], v[28:31], v[200:203], v[108:111]
	v_mfma_f32_16x16x32_bf16 v[104:107], v[68:71], v[200:203], v[104:107]
	v_mfma_f32_16x16x32_bf16 v[92:95], v[28:31], v[208:211], v[92:95]
	v_mfma_f32_16x16x32_bf16 v[88:91], v[68:71], v[208:211], v[88:91]
	s_setprio 0
	s_setprio 1
	v_mfma_f32_16x16x32_bf16 v[136:139], v[144:147], v[160:163], v[136:139]
	v_mfma_f32_16x16x32_bf16 v[128:131], v[152:155], v[160:163], v[128:131]
	v_mfma_f32_16x16x32_bf16 v[116:119], v[144:147], v[168:171], v[116:119]
	v_mfma_f32_16x16x32_bf16 v[112:115], v[152:155], v[168:171], v[112:115]
	v_mfma_f32_16x16x32_bf16 v[100:103], v[144:147], v[196:199], v[100:103]
	v_mfma_f32_16x16x32_bf16 v[96:99], v[152:155], v[196:199], v[96:99]
	v_mfma_f32_16x16x32_bf16 v[84:87], v[144:147], v[204:207], v[84:87]
	v_mfma_f32_16x16x32_bf16 v[80:83], v[152:155], v[204:207], v[80:83]
	v_mfma_f32_16x16x32_bf16 v[136:139], v[148:151], v[164:167], v[136:139]
	v_mfma_f32_16x16x32_bf16 v[128:131], v[156:159], v[164:167], v[128:131]
	v_mfma_f32_16x16x32_bf16 v[116:119], v[148:151], v[172:175], v[116:119]
	v_mfma_f32_16x16x32_bf16 v[112:115], v[156:159], v[172:175], v[112:115]
	v_mfma_f32_16x16x32_bf16 v[100:103], v[148:151], v[200:203], v[100:103]
	v_mfma_f32_16x16x32_bf16 v[96:99], v[156:159], v[200:203], v[96:99]
	v_mfma_f32_16x16x32_bf16 v[84:87], v[148:151], v[208:211], v[84:87]
	v_mfma_f32_16x16x32_bf16 v[80:83], v[156:159], v[208:211], v[80:83]
	s_setprio 0
	s_barrier
; #define PG8_STAGE(bufoff, gbase, voff) do { _Pragma("unroll") for (int _i = 0; _i < 2; ++_i) \
;         __builtin_amdgcn_global_load_lds((const unsigned*)((const char*)(gbase) + (voff)[_i]), (LAS unsigned*)(lds + (bufoff) + ldsw + _i * 8192), 16, 0, 0); } while (0)
; #define PG8_LDA(dst, b, h) do { _Pragma("unroll") for (int m = 0; m < 4; ++m) _Pragma("unroll") for (int k = 0; k < 2; ++k) dst[m][k] = *(const LAS bf16x8*)(lds + PG8_SA(b, h) + aoff + m * 2048 + k * 1024); } while (0)
; #define PG8_LDB(dst, b, h) do { _Pragma("unroll") for (int n = 0; n < 2; ++n) _Pragma("unroll") for (int k = 0; k < 2; ++k) dst[n][k] = *(const LAS bf16x8*)(lds + PG8_SB(b, h) + boff + n * 2048 + k * 1024); } while (0)
; #define PG8_MMA(ai, bj, At, Bt) do { __builtin_amdgcn_s_setprio(1); _Pragma("unroll") for (int m = 0; m < 4; ++m) _Pragma("unroll") for (int n = 0; n < 2; ++n) _Pragma("unroll") for (int k = 0; k < 2; ++k) \
;         acc[ai][bj][m][n] = __builtin_amdgcn_mfma_f32_16x16x32_bf16(Bt[n][k], At[m][k], acc[ai][bj][m][n], 0, 0, 0); __builtin_amdgcn_s_setprio(0); } while (0)
; #define PG8_WAIT_V(n) asm volatile("s_waitcnt vmcnt(" #n ")" ::: "memory")
; #define PG8_BAR __builtin_amdgcn_s_barrier()
; template <class Epi>
; __device__ __forceinline__ void gemm_phase(LAS unsigned char* lds, const Gemm g, const StaticOrder& S, const Epi& E) {
;     ...
;             PG8_LDB(B0, 0, 0); PG8_LDB(B1, 0, 1); PG8_SCHED; PG8_LDA(At, 0, 0); PG8_STAGE(PG8_SA(1, 1), a1 + hstepA, voffA);
;             PG8_WAIT_V(8); PG8_WAIT_L(0); PG8_BAR; PG8_MMA(0, 0, At, B0); PG8_MMA(0, 1, At, B1); PG8_BAR; PG8_SCHED;
;             PG8_LDA(At, 0, 1); PG8_STAGE(PG8_SB(0, 0), b2, voffB); PG8_STAGE(PG8_SB(0, 1), b2 + hstepB, voffB); PG8_STAGE(PG8_SA(0, 0), a2, voffA);
;             PG8_WAIT_V(8); PG8_WAIT_L(0); PG8_BAR; PG8_MMA(1, 0, At, B0); PG8_MMA(1, 1, At, B1); PG8_BAR; PG8_SCHED;
;             PG8_LDB(B0, 1, 0); PG8_LDB(B1, 1, 1); PG8_SCHED; PG8_LDA(At, 1, 0); PG8_STAGE(PG8_SA(0, 1), a2 + hstepA, voffA);
;             PG8_WAIT_V(8); PG8_WAIT_L(0); PG8_BAR; PG8_MMA(0, 0, At, B0); PG8_MMA(0, 1, At, B1); PG8_BAR; PG8_SCHED;
;             PG8_LDA(At, 1, 1); PG8_STAGE(PG8_SB(1, 0), b3, voffB); PG8_STAGE(PG8_SB(1, 1), b3 + hstepB, voffB); PG8_STAGE(PG8_SA(1, 0), a3, voffA);
;             PG8_WAIT_V(8); PG8_WAIT_L(0); PG8_BAR; PG8_MMA(1, 0, At, B0); PG8_MMA(1, 1, At, B1); PG8_BAR; PG8_SCHED;
	s_add_i32 s62, s86, s65
	v_lshl_add_u64 v[212:213], v[212:213], 0, s[16:17]
	s_mov_b32 m0, s62
	ds_read_b128 v[160:163], v232 offset:49152
	ds_read_b128 v[164:167], v232 offset:50176
	ds_read_b128 v[168:171], v232 offset:51200
	ds_read_b128 v[172:175], v232 offset:52224
	ds_read_b128 v[196:199], v232 offset:53248
	ds_read_b128 v[200:203], v232 offset:54272
	ds_read_b128 v[204:207], v232 offset:55296
	ds_read_b128 v[208:211], v232 offset:56320
	global_load_lds_dwordx4 v[212:213], off
	s_add_i32 m0, s62, 0x2000
	s_add_u32 s56, s56, 0x40080
	v_lshl_add_u64 v[212:213], v[214:215], 0, s[16:17]
	s_addc_u32 s57, s57, 0
	s_add_i32 s62, s87, s65
	global_load_lds_dwordx4 v[212:213], off
	s_mov_b32 m0, s62
	s_nop 0
	global_load_lds_dwordx4 v180, s[56:57]
	s_add_i32 m0, s62, 0x2000
	s_nop 0
	global_load_lds_dwordx4 v184, s[56:57]
	v_lshl_add_u64 v[212:213], v[216:217], 0, s[16:17]
	s_mov_b32 m0, s76
	s_nop 0
	global_load_lds_dwordx4 v[212:213], off
	v_lshl_add_u64 v[212:213], v[218:219], 0, s[16:17]
	s_mov_b32 m0, s77
	s_nop 0
	global_load_lds_dwordx4 v[212:213], off
	s_waitcnt vmcnt(8)
	s_waitcnt lgkmcnt(0)
	s_barrier
	s_setprio 1
	s_waitcnt lgkmcnt(0)
	v_mfma_f32_16x16x32_bf16 v[76:79], v[20:23], v[160:163], v[76:79]
	v_mfma_f32_16x16x32_bf16 v[60:63], v[20:23], v[168:171], v[60:63]
	v_mfma_f32_16x16x32_bf16 v[44:47], v[20:23], v[196:199], v[44:47]
	v_mfma_f32_16x16x32_bf16 v[0:3], v[20:23], v[204:207], v[0:3]
	v_mfma_f32_16x16x32_bf16 v[76:79], v[28:31], v[164:167], v[76:79]
	v_mfma_f32_16x16x32_bf16 v[72:75], v[64:67], v[160:163], v[72:75]
	v_mfma_f32_16x16x32_bf16 v[60:63], v[28:31], v[172:175], v[60:63]
	v_mfma_f32_16x16x32_bf16 v[56:59], v[64:67], v[168:171], v[56:59]
	v_mfma_f32_16x16x32_bf16 v[44:47], v[28:31], v[200:203], v[44:47]
	v_mfma_f32_16x16x32_bf16 v[40:43], v[64:67], v[196:199], v[40:43]
	v_mfma_f32_16x16x32_bf16 v[28:31], v[28:31], v[208:211], v[0:3]
	v_mfma_f32_16x16x32_bf16 v[0:3], v[64:67], v[204:207], v[4:7]
	v_mfma_f32_16x16x32_bf16 v[72:75], v[68:71], v[164:167], v[72:75]
	v_mfma_f32_16x16x32_bf16 v[56:59], v[68:71], v[172:175], v[56:59]
	v_mfma_f32_16x16x32_bf16 v[40:43], v[68:71], v[200:203], v[40:43]
	v_mfma_f32_16x16x32_bf16 v[20:23], v[68:71], v[208:211], v[0:3]
	s_setprio 0
	s_setprio 1
	v_mfma_f32_16x16x32_bf16 v[0:3], v[144:147], v[160:163], v[8:11]
	v_mfma_f32_16x16x32_bf16 v[68:71], v[148:151], v[164:167], v[0:3]
	v_mfma_f32_16x16x32_bf16 v[0:3], v[152:155], v[160:163], v[12:15]
	v_mfma_f32_16x16x32_bf16 v[64:67], v[156:159], v[164:167], v[0:3]
	v_mfma_f32_16x16x32_bf16 v[0:3], v[144:147], v[168:171], v[52:55]
	v_mfma_f32_16x16x32_bf16 v[52:55], v[148:151], v[172:175], v[0:3]
	v_mfma_f32_16x16x32_bf16 v[0:3], v[152:155], v[168:171], v[48:51]
	v_mfma_f32_16x16x32_bf16 v[48:51], v[156:159], v[172:175], v[0:3]
	v_mfma_f32_16x16x32_bf16 v[0:3], v[144:147], v[196:199], v[36:39]
	v_mfma_f32_16x16x32_bf16 v[36:39], v[148:151], v[200:203], v[0:3]
	v_mfma_f32_16x16x32_bf16 v[0:3], v[152:155], v[196:199], v[32:35]
	v_mfma_f32_16x16x32_bf16 v[32:35], v[156:159], v[200:203], v[0:3]
	v_mfma_f32_16x16x32_bf16 v[0:3], v[144:147], v[204:207], v[24:27]
	v_mfma_f32_16x16x32_bf16 v[24:27], v[148:151], v[208:211], v[0:3]
	v_mfma_f32_16x16x32_bf16 v[0:3], v[152:155], v[204:207], v[16:19]
	v_mfma_f32_16x16x32_bf16 v[16:19], v[156:159], v[208:211], v[0:3]
	s_setprio 0
	s_barrier
	s_add_i32 s85, s85, 2
	s_add_u32 s54, s54, 0x100
	s_addc_u32 s55, s55, 0
	s_add_u32 s83, s83, 0x100
	s_addc_u32 s84, s84, 0
	s_cmp_gt_u32 s85, 13
.LBB0_1018:
	ds_read_b128 v[0:3], v230
	ds_read_b128 v[4:7], v230 offset:1024
	ds_read_b128 v[8:11], v230 offset:2048
	ds_read_b128 v[12:15], v230 offset:3072
	ds_read_b128 v[144:147], v231
	ds_read_b128 v[148:151], v231 offset:1024
	ds_read_b128 v[152:155], v231 offset:2048
	ds_read_b128 v[156:159], v231 offset:3072
	s_add_u32 s56, s54, 0xfffc0080
	s_addc_u32 s57, s55, -1
	s_cmp_eq_u32 s85, 12
	s_cselect_b32 s63, s7, s57
	s_cselect_b32 s62, s35, s56
	s_cselect_b32 s57, s23, s84
	s_cselect_b32 s56, s53, s83
	s_add_i32 m0, s68, 0xc000
	ds_read_b128 v[160:163], v232
	ds_read_b128 v[164:167], v232 offset:1024
	ds_read_b128 v[168:171], v232 offset:2048
	ds_read_b128 v[172:175], v232 offset:3072
	ds_read_b128 v[196:199], v232 offset:4096
	ds_read_b128 v[200:203], v232 offset:5120
	ds_read_b128 v[204:207], v232 offset:6144
	ds_read_b128 v[208:211], v232 offset:7168
	global_load_lds_dwordx4 v188, s[54:55]
	s_add_i32 m0, s68, 0xe000
	s_nop 0
	global_load_lds_dwordx4 v190, s[54:55]
	s_waitcnt vmcnt(8)
	s_waitcnt lgkmcnt(0)
	s_barrier
; #define PG8_STAGE(bufoff, gbase, voff) do { _Pragma("unroll") for (int _i = 0; _i < 2; ++_i) \
;         __builtin_amdgcn_global_load_lds((const unsigned*)((const char*)(gbase) + (voff)[_i]), (LAS unsigned*)(lds + (bufoff) + ldsw + _i * 8192), 16, 0, 0); } while (0)
; #define PG8_LDA(dst, b, h) do { _Pragma("unroll") for (int m = 0; m < 4; ++m) _Pragma("unroll") for (int k = 0; k < 2; ++k) dst[m][k] = *(const LAS bf16x8*)(lds + PG8_SA(b, h) + aoff + m * 2048 + k * 1024); } while (0)
; #define PG8_MMA(ai, bj, At, Bt) do { __builtin_amdgcn_s_setprio(1); _Pragma("unroll") for (int m = 0; m < 4; ++m) _Pragma("unroll") for (int n = 0; n < 2; ++n) _Pragma("unroll") for (int k = 0; k < 2; ++k) \
;         acc[ai][bj][m][n] = __builtin_amdgcn_mfma_f32_16x16x32_bf16(Bt[n][k], At[m][k], acc[ai][bj][m][n], 0, 0, 0); __builtin_amdgcn_s_setprio(0); } while (0)
; #define PG8_WAIT_V(n) asm volatile("s_waitcnt vmcnt(" #n ")" ::: "memory")
; #define PG8_WAIT_L(n) asm volatile("s_waitcnt lgkmcnt(" #n ")" ::: "memory")
; #define PG8_BAR __builtin_amdgcn_s_barrier()
; #define PG8_SCHED __builtin_amdgcn_sched_barrier(0)
; template <class Epi>
; __device__ __forceinline__ void gemm_phase(LAS unsigned char* lds, const Gemm g, const StaticOrder& S, const Epi& E) {
;     ...
;             PG8_WAIT_V(8); PG8_WAIT_L(0); PG8_BAR; PG8_MMA(0, 0, At, B0); PG8_MMA(0, 1, At, B1); PG8_BAR; PG8_SCHED;
;             PG8_LDA(At, 0, 1); PG8_STAGE(PG8_SB(0, 0), b2, voffB); PG8_STAGE(PG8_SB(0, 1), b2 + hstepB, voffB); PG8_STAGE(PG8_SA(0, 0), a2, voffA);
;             PG8_WAIT_V(8); PG8_WAIT_L(0); PG8_BAR; PG8_MMA(1, 0, At, B0); PG8_MMA(1, 1, At, B1); PG8_BAR; PG8_SCHED;
	s_setprio 1
	s_waitcnt lgkmcnt(0)
	v_mfma_f32_16x16x32_bf16 v[140:143], v[0:3], v[160:163], v[140:143]
	v_mfma_f32_16x16x32_bf16 v[132:135], v[8:11], v[160:163], v[132:135]
	v_mfma_f32_16x16x32_bf16 v[124:127], v[0:3], v[168:171], v[124:127]
	v_mfma_f32_16x16x32_bf16 v[120:123], v[8:11], v[168:171], v[120:123]
	v_mfma_f32_16x16x32_bf16 v[108:111], v[0:3], v[196:199], v[108:111]
	v_mfma_f32_16x16x32_bf16 v[104:107], v[8:11], v[196:199], v[104:107]
	v_mfma_f32_16x16x32_bf16 v[92:95], v[0:3], v[204:207], v[92:95]
	v_mfma_f32_16x16x32_bf16 v[88:91], v[8:11], v[204:207], v[88:91]
	v_mfma_f32_16x16x32_bf16 v[140:143], v[4:7], v[164:167], v[140:143]
	v_mfma_f32_16x16x32_bf16 v[132:135], v[12:15], v[164:167], v[132:135]
	v_mfma_f32_16x16x32_bf16 v[124:127], v[4:7], v[172:175], v[124:127]
	v_mfma_f32_16x16x32_bf16 v[120:123], v[12:15], v[172:175], v[120:123]
	v_mfma_f32_16x16x32_bf16 v[108:111], v[4:7], v[200:203], v[108:111]
	v_mfma_f32_16x16x32_bf16 v[104:107], v[12:15], v[200:203], v[104:107]
	v_mfma_f32_16x16x32_bf16 v[92:95], v[4:7], v[208:211], v[92:95]
	v_mfma_f32_16x16x32_bf16 v[88:91], v[12:15], v[208:211], v[88:91]
	s_setprio 0
	s_setprio 1
	v_mfma_f32_16x16x32_bf16 v[136:139], v[144:147], v[160:163], v[136:139]
	v_mfma_f32_16x16x32_bf16 v[128:131], v[152:155], v[160:163], v[128:131]
	v_mfma_f32_16x16x32_bf16 v[116:119], v[144:147], v[168:171], v[116:119]
	v_mfma_f32_16x16x32_bf16 v[112:115], v[152:155], v[168:171], v[112:115]
	v_mfma_f32_16x16x32_bf16 v[100:103], v[144:147], v[196:199], v[100:103]
	v_mfma_f32_16x16x32_bf16 v[96:99], v[152:155], v[196:199], v[96:99]
	v_mfma_f32_16x16x32_bf16 v[84:87], v[144:147], v[204:207], v[84:87]
	v_mfma_f32_16x16x32_bf16 v[80:83], v[152:155], v[204:207], v[80:83]
	v_mfma_f32_16x16x32_bf16 v[136:139], v[148:151], v[164:167], v[136:139]
	v_mfma_f32_16x16x32_bf16 v[128:131], v[156:159], v[164:167], v[128:131]
	v_mfma_f32_16x16x32_bf16 v[116:119], v[148:151], v[172:175], v[116:119]
	v_mfma_f32_16x16x32_bf16 v[112:115], v[156:159], v[172:175], v[112:115]
	v_mfma_f32_16x16x32_bf16 v[100:103], v[148:151], v[200:203], v[100:103]
	v_mfma_f32_16x16x32_bf16 v[96:99], v[156:159], v[200:203], v[96:99]
	v_mfma_f32_16x16x32_bf16 v[84:87], v[148:151], v[208:211], v[84:87]
	v_mfma_f32_16x16x32_bf16 v[80:83], v[156:159], v[208:211], v[80:83]
	s_setprio 0
	s_barrier
	s_add_i32 s86, s81, s65
	v_lshl_add_u64 v[212:213], s[56:57], 0, v[180:181]
	s_mov_b32 m0, s86
	ds_read_b128 v[160:163], v232 offset:16384
	ds_read_b128 v[164:167], v232 offset:17408
	ds_read_b128 v[168:171], v232 offset:18432
	ds_read_b128 v[172:175], v232 offset:19456
	ds_read_b128 v[196:199], v232 offset:20480
	ds_read_b128 v[200:203], v232 offset:21504
	ds_read_b128 v[204:207], v232 offset:22528
	ds_read_b128 v[208:211], v232 offset:23552
	global_load_lds_dwordx4 v[212:213], off
	s_add_i32 m0, s86, 0x2000
	s_add_u32 s86, s56, 0x40000
	v_lshl_add_u64 v[214:215], s[56:57], 0, v[184:185]
	s_addc_u32 s87, s57, 0
	s_add_i32 s88, s82, s65
	global_load_lds_dwordx4 v[214:215], off
	s_mov_b32 m0, s88
	v_lshl_add_u64 v[218:219], s[62:63], 0, v[182:183]
	global_load_lds_dwordx4 v180, s[86:87]
	s_add_i32 m0, s88, 0x2000
	s_nop 0
	global_load_lds_dwordx4 v184, s[86:87]
	v_lshl_add_u64 v[216:217], s[62:63], 0, v[178:179]
	s_mov_b32 m0, s68
	s_nop 0
	global_load_lds_dwordx4 v[216:217], off
	s_mov_b32 m0, s69
	s_nop 0
	global_load_lds_dwordx4 v[218:219], off
	s_waitcnt vmcnt(8)
	s_waitcnt lgkmcnt(0)
	s_barrier
	s_setprio 1
	s_waitcnt lgkmcnt(0)
	v_mfma_f32_16x16x32_bf16 v[76:79], v[0:3], v[160:163], v[76:79]
	v_mfma_f32_16x16x32_bf16 v[72:75], v[8:11], v[160:163], v[72:75]
	v_mfma_f32_16x16x32_bf16 v[60:63], v[0:3], v[168:171], v[60:63]
	v_mfma_f32_16x16x32_bf16 v[56:59], v[8:11], v[168:171], v[56:59]
	v_mfma_f32_16x16x32_bf16 v[44:47], v[0:3], v[196:199], v[44:47]
	v_mfma_f32_16x16x32_bf16 v[40:43], v[8:11], v[196:199], v[40:43]
	v_mfma_f32_16x16x32_bf16 v[0:3], v[0:3], v[204:207], v[28:31]
	v_mfma_f32_16x16x32_bf16 v[76:79], v[4:7], v[164:167], v[76:79]
	v_mfma_f32_16x16x32_bf16 v[72:75], v[12:15], v[164:167], v[72:75]
	v_mfma_f32_16x16x32_bf16 v[60:63], v[4:7], v[172:175], v[60:63]
	v_mfma_f32_16x16x32_bf16 v[56:59], v[12:15], v[172:175], v[56:59]
	v_mfma_f32_16x16x32_bf16 v[44:47], v[4:7], v[200:203], v[44:47]
	v_mfma_f32_16x16x32_bf16 v[40:43], v[12:15], v[200:203], v[40:43]
	v_mfma_f32_16x16x32_bf16 v[0:3], v[4:7], v[208:211], v[0:3]
	v_mfma_f32_16x16x32_bf16 v[4:7], v[8:11], v[204:207], v[20:23]
	v_mfma_f32_16x16x32_bf16 v[4:7], v[12:15], v[208:211], v[4:7]
	s_setprio 0
	s_setprio 1
	v_mfma_f32_16x16x32_bf16 v[20:23], v[144:147], v[168:171], v[52:55]
	v_mfma_f32_16x16x32_bf16 v[52:55], v[148:151], v[172:175], v[20:23]
	v_mfma_f32_16x16x32_bf16 v[20:23], v[152:155], v[168:171], v[48:51]
	v_mfma_f32_16x16x32_bf16 v[48:51], v[156:159], v[172:175], v[20:23]
	v_mfma_f32_16x16x32_bf16 v[20:23], v[144:147], v[196:199], v[36:39]
	v_mfma_f32_16x16x32_bf16 v[36:39], v[148:151], v[200:203], v[20:23]
	v_mfma_f32_16x16x32_bf16 v[20:23], v[152:155], v[196:199], v[32:35]
	v_mfma_f32_16x16x32_bf16 v[32:35], v[156:159], v[200:203], v[20:23]
	v_mfma_f32_16x16x32_bf16 v[20:23], v[144:147], v[204:207], v[24:27]
	v_mfma_f32_16x16x32_bf16 v[16:19], v[152:155], v[204:207], v[16:19]
	v_mfma_f32_16x16x32_bf16 v[8:11], v[144:147], v[160:163], v[68:71]
	v_mfma_f32_16x16x32_bf16 v[12:15], v[152:155], v[160:163], v[64:67]
	v_mfma_f32_16x16x32_bf16 v[24:27], v[148:151], v[208:211], v[20:23]
	v_mfma_f32_16x16x32_bf16 v[16:19], v[156:159], v[208:211], v[16:19]
	v_mfma_f32_16x16x32_bf16 v[8:11], v[148:151], v[164:167], v[8:11]
	v_mfma_f32_16x16x32_bf16 v[12:15], v[156:159], v[164:167], v[12:15]
	s_setprio 0
	s_barrier
; #define PG8_STAGE(bufoff, gbase, voff) do { _Pragma("unroll") for (int _i = 0; _i < 2; ++_i) \
;         __builtin_amdgcn_global_load_lds((const unsigned*)((const char*)(gbase) + (voff)[_i]), (LAS unsigned*)(lds + (bufoff) + ldsw + _i * 8192), 16, 0, 0); } while (0)
; #define PG8_LDA(dst, b, h) do { _Pragma("unroll") for (int m = 0; m < 4; ++m) _Pragma("unroll") for (int k = 0; k < 2; ++k) dst[m][k] = *(const LAS bf16x8*)(lds + PG8_SA(b, h) + aoff + m * 2048 + k * 1024); } while (0)
; #define PG8_LDB(dst, b, h) do { _Pragma("unroll") for (int n = 0; n < 2; ++n) _Pragma("unroll") for (int k = 0; k < 2; ++k) dst[n][k] = *(const LAS bf16x8*)(lds + PG8_SB(b, h) + boff + n * 2048 + k * 1024); } while (0)
; #define PG8_MMA(ai, bj, At, Bt) do { __builtin_amdgcn_s_setprio(1); _Pragma("unroll") for (int m = 0; m < 4; ++m) _Pragma("unroll") for (int n = 0; n < 2; ++n) _Pragma("unroll") for (int k = 0; k < 2; ++k) \
;         acc[ai][bj][m][n] = __builtin_amdgcn_mfma_f32_16x16x32_bf16(Bt[n][k], At[m][k], acc[ai][bj][m][n], 0, 0, 0); __builtin_amdgcn_s_setprio(0); } while (0)
; #define PG8_WAIT_V(n) asm volatile("s_waitcnt vmcnt(" #n ")" ::: "memory")
; #define PG8_WAIT_L(n) asm volatile("s_waitcnt lgkmcnt(" #n ")" ::: "memory")
; #define PG8_BAR __builtin_amdgcn_s_barrier()
; #define PG8_SCHED __builtin_amdgcn_sched_barrier(0)
; template <class Epi>
; __device__ __forceinline__ void gemm_phase(LAS unsigned char* lds, const Gemm g, const StaticOrder& S, const Epi& E) {
;     ...
;             PG8_LDB(B0, 1, 0); PG8_LDB(B1, 1, 1); PG8_SCHED; PG8_LDA(At, 1, 0); PG8_STAGE(PG8_SA(0, 1), a2 + hstepA, voffA);
;             PG8_WAIT_V(8); PG8_WAIT_L(0); PG8_BAR; PG8_MMA(0, 0, At, B0); PG8_MMA(0, 1, At, B1); PG8_BAR; PG8_SCHED;
;             PG8_LDA(At, 1, 1); PG8_STAGE(PG8_SB(1, 0), b3, voffB); PG8_STAGE(PG8_SB(1, 1), b3 + hstepB, voffB); PG8_STAGE(PG8_SA(1, 0), a3, voffA);
;             PG8_WAIT_V(8); PG8_WAIT_L(0); PG8_BAR; PG8_MMA(1, 0, At, B0); PG8_MMA(1, 1, At, B1); PG8_BAR; PG8_SCHED;
;         }
;         if (wr == 0) PG8_BAR;
	s_add_i32 s86, 0, 0x18000
	s_add_i32 s87, 0, 0x1c000
	v_add_u32_e32 v68, s86, v229
	v_add_u32_e32 v156, s87, v229
	ds_read_b128 v[20:23], v68
	ds_read_b128 v[28:31], v68 offset:1024
	ds_read_b128 v[64:67], v68 offset:2048
	ds_read_b128 v[68:71], v68 offset:3072
	ds_read_b128 v[144:147], v156
	ds_read_b128 v[148:151], v156 offset:1024
	ds_read_b128 v[152:155], v156 offset:2048
	ds_read_b128 v[156:159], v156 offset:3072
	s_add_u32 s62, s62, 0x40000
	s_addc_u32 s63, s63, 0
	s_mov_b32 m0, s70
	ds_read_b128 v[160:163], v232 offset:32768
	ds_read_b128 v[164:167], v232 offset:33792
	ds_read_b128 v[168:171], v232 offset:34816
	ds_read_b128 v[172:175], v232 offset:35840
	ds_read_b128 v[196:199], v232 offset:36864
	ds_read_b128 v[200:203], v232 offset:37888
	ds_read_b128 v[204:207], v232 offset:38912
	ds_read_b128 v[208:211], v232 offset:39936
	global_load_lds_dwordx4 v178, s[62:63]
	s_mov_b32 m0, s71
	s_nop 0
	global_load_lds_dwordx4 v182, s[62:63]
	s_waitcnt vmcnt(8)
	s_waitcnt lgkmcnt(0)
	s_barrier
	s_setprio 1
	s_waitcnt lgkmcnt(0)
	v_mfma_f32_16x16x32_bf16 v[140:143], v[20:23], v[160:163], v[140:143]
	v_mfma_f32_16x16x32_bf16 v[132:135], v[64:67], v[160:163], v[132:135]
	v_mfma_f32_16x16x32_bf16 v[124:127], v[20:23], v[168:171], v[124:127]
	v_mfma_f32_16x16x32_bf16 v[120:123], v[64:67], v[168:171], v[120:123]
	v_mfma_f32_16x16x32_bf16 v[108:111], v[20:23], v[196:199], v[108:111]
	v_mfma_f32_16x16x32_bf16 v[104:107], v[64:67], v[196:199], v[104:107]
	v_mfma_f32_16x16x32_bf16 v[92:95], v[20:23], v[204:207], v[92:95]
	v_mfma_f32_16x16x32_bf16 v[88:91], v[64:67], v[204:207], v[88:91]
	v_mfma_f32_16x16x32_bf16 v[140:143], v[28:31], v[164:167], v[140:143]
	v_mfma_f32_16x16x32_bf16 v[132:135], v[68:71], v[164:167], v[132:135]
	v_mfma_f32_16x16x32_bf16 v[124:127], v[28:31], v[172:175], v[124:127]
	v_mfma_f32_16x16x32_bf16 v[120:123], v[68:71], v[172:175], v[120:123]
	v_mfma_f32_16x16x32_bf16 v[108:111], v[28:31], v[200:203], v[108:111]
	v_mfma_f32_16x16x32_bf16 v[104:107], v[68:71], v[200:203], v[104:107]
	v_mfma_f32_16x16x32_bf16 v[92:95], v[28:31], v[208:211], v[92:95]
	v_mfma_f32_16x16x32_bf16 v[88:91], v[68:71], v[208:211], v[88:91]
	s_setprio 0
	s_setprio 1
	v_mfma_f32_16x16x32_bf16 v[136:139], v[144:147], v[160:163], v[136:139]
	v_mfma_f32_16x16x32_bf16 v[128:131], v[152:155], v[160:163], v[128:131]
	v_mfma_f32_16x16x32_bf16 v[116:119], v[144:147], v[168:171], v[116:119]
	v_mfma_f32_16x16x32_bf16 v[112:115], v[152:155], v[168:171], v[112:115]
	v_mfma_f32_16x16x32_bf16 v[100:103], v[144:147], v[196:199], v[100:103]
	v_mfma_f32_16x16x32_bf16 v[96:99], v[152:155], v[196:199], v[96:99]
	v_mfma_f32_16x16x32_bf16 v[84:87], v[144:147], v[204:207], v[84:87]
	v_mfma_f32_16x16x32_bf16 v[80:83], v[152:155], v[204:207], v[80:83]
	v_mfma_f32_16x16x32_bf16 v[136:139], v[148:151], v[164:167], v[136:139]
	v_mfma_f32_16x16x32_bf16 v[128:131], v[156:159], v[164:167], v[128:131]
	v_mfma_f32_16x16x32_bf16 v[116:119], v[148:151], v[172:175], v[116:119]
	v_mfma_f32_16x16x32_bf16 v[112:115], v[156:159], v[172:175], v[112:115]
	v_mfma_f32_16x16x32_bf16 v[100:103], v[148:151], v[200:203], v[100:103]
	v_mfma_f32_16x16x32_bf16 v[96:99], v[156:159], v[200:203], v[96:99]
	v_mfma_f32_16x16x32_bf16 v[84:87], v[148:151], v[208:211], v[84:87]
	v_mfma_f32_16x16x32_bf16 v[80:83], v[156:159], v[208:211], v[80:83]
	s_setprio 0
	s_barrier
	s_add_i32 s62, s86, s65
	v_lshl_add_u64 v[212:213], v[212:213], 0, s[16:17]
	s_mov_b32 m0, s62
	ds_read_b128 v[160:163], v232 offset:49152
	ds_read_b128 v[164:167], v232 offset:50176
	ds_read_b128 v[168:171], v232 offset:51200
	ds_read_b128 v[172:175], v232 offset:52224
	ds_read_b128 v[196:199], v232 offset:53248
	ds_read_b128 v[200:203], v232 offset:54272
	ds_read_b128 v[204:207], v232 offset:55296
	ds_read_b128 v[208:211], v232 offset:56320
	global_load_lds_dwordx4 v[212:213], off
	s_add_i32 m0, s62, 0x2000
	s_add_u32 s56, s56, 0x40080
	v_lshl_add_u64 v[212:213], v[214:215], 0, s[16:17]
	s_addc_u32 s57, s57, 0
	s_add_i32 s62, s87, s65
	global_load_lds_dwordx4 v[212:213], off
	s_mov_b32 m0, s62
	s_nop 0
	global_load_lds_dwordx4 v180, s[56:57]
	s_add_i32 m0, s62, 0x2000
	s_nop 0
	global_load_lds_dwordx4 v184, s[56:57]
	v_lshl_add_u64 v[212:213], v[216:217], 0, s[16:17]
	s_mov_b32 m0, s76
	s_nop 0
	global_load_lds_dwordx4 v[212:213], off
	v_lshl_add_u64 v[212:213], v[218:219], 0, s[16:17]
	s_mov_b32 m0, s77
	s_nop 0
	global_load_lds_dwordx4 v[212:213], off
	s_waitcnt vmcnt(8)
	s_waitcnt lgkmcnt(0)
	s_barrier
	s_setprio 1
	s_waitcnt lgkmcnt(0)
	v_mfma_f32_16x16x32_bf16 v[76:79], v[20:23], v[160:163], v[76:79]
	v_mfma_f32_16x16x32_bf16 v[60:63], v[20:23], v[168:171], v[60:63]
	v_mfma_f32_16x16x32_bf16 v[44:47], v[20:23], v[196:199], v[44:47]
	v_mfma_f32_16x16x32_bf16 v[0:3], v[20:23], v[204:207], v[0:3]
	v_mfma_f32_16x16x32_bf16 v[76:79], v[28:31], v[164:167], v[76:79]
	v_mfma_f32_16x16x32_bf16 v[72:75], v[64:67], v[160:163], v[72:75]
	v_mfma_f32_16x16x32_bf16 v[60:63], v[28:31], v[172:175], v[60:63]
	v_mfma_f32_16x16x32_bf16 v[56:59], v[64:67], v[168:171], v[56:59]
	v_mfma_f32_16x16x32_bf16 v[44:47], v[28:31], v[200:203], v[44:47]
	v_mfma_f32_16x16x32_bf16 v[40:43], v[64:67], v[196:199], v[40:43]
	v_mfma_f32_16x16x32_bf16 v[28:31], v[28:31], v[208:211], v[0:3]
	v_mfma_f32_16x16x32_bf16 v[0:3], v[64:67], v[204:207], v[4:7]
	v_mfma_f32_16x16x32_bf16 v[72:75], v[68:71], v[164:167], v[72:75]
	v_mfma_f32_16x16x32_bf16 v[56:59], v[68:71], v[172:175], v[56:59]
	v_mfma_f32_16x16x32_bf16 v[40:43], v[68:71], v[200:203], v[40:43]
	v_mfma_f32_16x16x32_bf16 v[20:23], v[68:71], v[208:211], v[0:3]
	s_setprio 0
	s_setprio 1
	v_mfma_f32_16x16x32_bf16 v[0:3], v[144:147], v[160:163], v[8:11]
	v_mfma_f32_16x16x32_bf16 v[68:71], v[148:151], v[164:167], v[0:3]
	v_mfma_f32_16x16x32_bf16 v[0:3], v[152:155], v[160:163], v[12:15]
	v_mfma_f32_16x16x32_bf16 v[64:67], v[156:159], v[164:167], v[0:3]
	v_mfma_f32_16x16x32_bf16 v[0:3], v[144:147], v[168:171], v[52:55]
	v_mfma_f32_16x16x32_bf16 v[52:55], v[148:151], v[172:175], v[0:3]
	v_mfma_f32_16x16x32_bf16 v[0:3], v[152:155], v[168:171], v[48:51]
	v_mfma_f32_16x16x32_bf16 v[48:51], v[156:159], v[172:175], v[0:3]
	v_mfma_f32_16x16x32_bf16 v[0:3], v[144:147], v[196:199], v[36:39]
	v_mfma_f32_16x16x32_bf16 v[36:39], v[148:151], v[200:203], v[0:3]
	v_mfma_f32_16x16x32_bf16 v[0:3], v[152:155], v[196:199], v[32:35]
	v_mfma_f32_16x16x32_bf16 v[32:35], v[156:159], v[200:203], v[0:3]
	v_mfma_f32_16x16x32_bf16 v[0:3], v[144:147], v[204:207], v[24:27]
	v_mfma_f32_16x16x32_bf16 v[24:27], v[148:151], v[208:211], v[0:3]
	v_mfma_f32_16x16x32_bf16 v[0:3], v[152:155], v[204:207], v[16:19]
	v_mfma_f32_16x16x32_bf16 v[16:19], v[156:159], v[208:211], v[0:3]
	s_setprio 0
	s_barrier
	s_add_i32 s85, s85, 2
	s_add_u32 s54, s54, 0x100
	s_addc_u32 s55, s55, 0
	s_add_u32 s83, s83, 0x100
	s_addc_u32 s84, s84, 0
	s_cmp_gt_u32 s85, 13
	s_cbranch_scc0 .LBB0_1018
	s_and_b64 vcc, exec, s[18:19]
	s_cbranch_vccz .LBB0_1021
	s_barrier

; #define PG8_STAGE(bufoff, gbase, voff) do { _Pragma("unroll") for (int _i = 0; _i < 2; ++_i) \
;         __builtin_amdgcn_global_load_lds((const unsigned*)((const char*)(gbase) + (voff)[_i]), (LAS unsigned*)(lds + (bufoff) + ldsw + _i * 8192), 16, 0, 0); } while (0)
; #define PG8_WAIT_V(n) asm volatile("s_waitcnt vmcnt(" #n ")" ::: "memory")
; #define PG8_BAR __builtin_amdgcn_s_barrier()
; template <class Epi>
; __device__ __forceinline__ void gemm_phase(LAS unsigned char* lds, const Gemm g, const StaticOrder& S, const Epi& E) {
;     const int tid = threadIdx.x, wid = __builtin_amdgcn_readfirstlane(tid >> 6), lane = tid & 63, wr = wid >> 2, wc = wid & 3, fr = lane & 15, fq = lane >> 4;
;     const int K = g.K, nt = K / BK;
;     unsigned voffA[2], voffB[2];
; #pragma unroll
;     for (int i = 0; i < 2; ++i) { int R, C; stage_rc(tid * 16 + i * 8192, R, C); const int Rb = (R & ~31) + perm32(R & 31);
;         voffA[i] = (unsigned)(R * g.lda + C) * 2u; voffB[i] = (unsigned)(Rb * g.ldb + C) * 2u; }
;     const size_t kstep = (size_t)(BK * 2);
;     const size_t hstepA = (size_t)HALF * g.lda * 2, hstepB = (size_t)HALF * g.ldb * 2;
;     const size_t tstepA = 2 * hstepA, tstepB = 2 * hstepB;
;     const unsigned ldsw = (unsigned)wid * 1024u;
;     const int aoff = lds_byte(wr * 64 + fr, fq * 8), boff = lds_byte(wc * 32 + fr, fq * 8);
;     ...
;     PG8_STAGE(PG8_SB(0, 0), cB, voffB); PG8_STAGE(PG8_SB(0, 1), cB + hstepB, voffB); PG8_STAGE(PG8_SA(0, 0), cA, voffA); PG8_STAGE(PG8_SA(0, 1), cA + hstepA, voffA);
;     if (wr == 1) PG8_BAR;
;     PG8_WAIT_V(2); PG8_BAR;
;     PG8_STAGE(PG8_SB(1, 0), cB + kstep, voffB); PG8_STAGE(PG8_SA(1, 0), cA + kstep, voffA); PG8_STAGE(PG8_SB(1, 1), cB + hstepB + kstep, voffB);
;     PG8_WAIT_V(6); PG8_BAR;
.LBB0_1223:
	s_add_u32 s10, s50, 0x60000
	s_addc_u32 s11, s51, 0
	s_lshl_b32 s12, s12, 5
	s_and_b32 s68, s12, 0x60
	s_mov_b64 s[12:13], 0x80
	s_add_i32 m0, s43, 0x18000
	v_lshl_add_u64 v[6:7], v[6:7], 0, s[12:13]
	s_lshl_b32 s65, s5, 6
	s_lshl_b32 s5, s5, 13
	s_lshl_b32 s15, s68, 7
	s_waitcnt vmcnt(2)
	s_barrier
	global_load_lds_dwordx4 v[6:7], off
	v_lshl_add_u64 v[4:5], v[4:5], 0, s[12:13]
	s_add_i32 m0, s43, 0x1a000
	s_add_i32 s69, s43, 0x8000
	s_add_i32 s70, s43, 0xa000
	global_load_lds_dwordx4 v[4:5], off
	v_lshl_add_u64 v[0:1], v[0:1], 0, s[12:13]
	s_mov_b32 m0, s69
	s_add_u32 s16, s54, 0x40080
	global_load_lds_dwordx4 v[0:1], off
	v_lshl_add_u64 v[0:1], v[2:3], 0, s[12:13]
	s_mov_b32 m0, s70
	s_addc_u32 s17, s55, 0
	global_load_lds_dwordx4 v[0:1], off
	s_add_i32 m0, s43, 0x1c000
	global_load_lds_dwordx4 v154, s[16:17]
	s_add_i32 m0, s43, 0x1e000
	v_bfe_u32 v177, v176, 4, 2
	global_load_lds_dwordx4 v158, s[16:17]
	s_sext_i32_i8 s75, s4
	v_and_b32_e32 v173, 15, v176
	v_lshlrev_b32_e32 v0, 4, v177
	v_lshlrev_b32_e32 v2, 2, v176
	v_lshlrev_b32_e32 v3, 6, v176
	s_movk_i32 s4, 0x3c0
	v_lshl_or_b32 v1, v173, 6, v0
	v_and_b32_e32 v2, 32, v2
	v_and_or_b32 v0, v3, s4, v0
	v_bitop3_b32 v183, s15, v0, v2 bitop3:0xf6
	v_lshlrev_b32_e32 v0, 8, v176
	v_bitop3_b32 v1, v1, s5, v2 bitop3:0xde
	v_and_b32_e32 v0, 0x38000, v0
	v_lshlrev_b32_e32 v2, 11, v10
	v_or3_b32 v0, v8, v0, v2
	v_add_u32_e32 v160, v0, v9
	v_lshlrev_b32_e32 v0, 4, v11
	s_waitcnt vmcnt(6)
	s_cmpk_lt_u32 s14, 0x100
	v_readlane_b32 s20, v254, 6
	v_and_b32_e32 v0, 0x78000, v0
	s_cselect_b64 s[14:15], -1, 0
	v_readlane_b32 s22, v254, 8
	v_or3_b32 v0, v8, v0, v2
	s_add_i32 s73, 0, 0x10000
	s_add_i32 s74, 0, 0x14000
	s_ashr_i32 s71, s22, 31
	s_mov_b32 s72, s22
	v_mov_b32_e32 v161, v155
	v_add_u32_e32 v162, v0, v9
	v_mov_b32_e32 v163, v155
	v_mov_b64_e32 v[164:165], 0x400
	v_mov_b64_e32 v[166:167], 0x3ff
	v_add_u32_e32 v189, s73, v183
	v_add_u32_e32 v195, s74, v183
	v_add_u32_e32 v201, 0, v1
	v_mov_b32_e32 v207, 0x358637bd
	s_mov_b64 s[16:17], 0x1000
	s_mov_b32 s18, 0x3b000000
	s_barrier
	v_readlane_b32 s21, v254, 7
	v_readlane_b32 s23, v254, 9
	s_branch .LBB0_1226

; #define PG8_STAGE(bufoff, gbase, voff) do { _Pragma("unroll") for (int _i = 0; _i < 2; ++_i) \
;         __builtin_amdgcn_global_load_lds((const unsigned*)((const char*)(gbase) + (voff)[_i]), (LAS unsigned*)(lds + (bufoff) + ldsw + _i * 8192), 16, 0, 0); } while (0)
; #define PG8_LDA(dst, b, h) do { _Pragma("unroll") for (int m = 0; m < 4; ++m) _Pragma("unroll") for (int k = 0; k < 2; ++k) dst[m][k] = *(const LAS bf16x8*)(lds + PG8_SA(b, h) + aoff + m * 2048 + k * 1024); } while (0)
; #define PG8_LDB(dst, b, h) do { _Pragma("unroll") for (int n = 0; n < 2; ++n) _Pragma("unroll") for (int k = 0; k < 2; ++k) dst[n][k] = *(const LAS bf16x8*)(lds + PG8_SB(b, h) + boff + n * 2048 + k * 1024); } while (0)
; #define PG8_MMA(ai, bj, At, Bt) do { __builtin_amdgcn_s_setprio(1); _Pragma("unroll") for (int m = 0; m < 4; ++m) _Pragma("unroll") for (int n = 0; n < 2; ++n) _Pragma("unroll") for (int k = 0; k < 2; ++k) \
;         acc[ai][bj][m][n] = __builtin_amdgcn_mfma_f32_16x16x32_bf16(Bt[n][k], At[m][k], acc[ai][bj][m][n], 0, 0, 0); __builtin_amdgcn_s_setprio(0); } while (0)
; #define PG8_BAR __builtin_amdgcn_s_barrier()
; template <class Epi>
; __device__ __forceinline__ void gemm_phase(LAS unsigned char* lds, const Gemm g, const StaticOrder& S, const Epi& E) {
;     ...
;         const bool has_next = S.next(ui + 1, nxt);
;         const char* nA = has_next ? (const char*)g.A + (size_t)nxt.pm * tstepA : cA; const char* nB = has_next ? (const char*)g.Bt + (size_t)nxt.pn * tstepB : cB;
; #pragma nounroll
;         for (int t = 0; t < nt; t += 2) {
;             const bool last = (t == nt - 2);
;             const char* a1 = cA + (size_t)(t + 1) * kstep;
;             const char* a2 = last ? nA : cA + (size_t)(t + 2) * kstep; const char* b2 = last ? nB : cB + (size_t)(t + 2) * kstep;
;             const char* a3 = a2 + kstep; const char* b3 = b2 + kstep;
;             PG8_LDB(B0, 0, 0); PG8_LDB(B1, 0, 1); PG8_SCHED; PG8_LDA(At, 0, 0); PG8_STAGE(PG8_SA(1, 1), a1 + hstepA, voffA);
;             PG8_WAIT_V(8); PG8_WAIT_L(0); PG8_BAR; PG8_MMA(0, 0, At, B0); PG8_MMA(0, 1, At, B1); PG8_BAR; PG8_SCHED;
;             PG8_LDA(At, 0, 1); PG8_STAGE(PG8_SB(0, 0), b2, voffB); PG8_STAGE(PG8_SB(0, 1), b2 + hstepB, voffB); PG8_STAGE(PG8_SA(0, 0), a2, voffA);
;             PG8_WAIT_V(8); PG8_WAIT_L(0); PG8_BAR; PG8_MMA(1, 0, At, B0); PG8_MMA(1, 1, At, B1); PG8_BAR; PG8_SCHED;
.LBB0_1232:
	s_ashr_i32 s23, s22, 31
	s_lshl_b64 s[34:35], s[22:23], 19
	s_add_u32 s34, s24, s34
	s_addc_u32 s35, s25, s35
	s_and_b64 s[38:39], s[4:5], exec
	s_cselect_b32 s23, s35, s53
	s_cselect_b32 s76, s34, s52
	s_ashr_i32 s21, s20, 31
	s_lshl_b64 s[38:39], s[20:21], 19
	s_add_u32 s38, s19, s38
	s_addc_u32 s39, s33, s39
	s_and_b64 s[56:57], s[4:5], exec
	s_cselect_b32 s21, s39, s55
	s_cselect_b32 s77, s38, s54
	s_add_u32 s52, s52, 0x40080
	s_addc_u32 s53, s53, 0
	s_add_u32 s78, s54, 0x100
	s_addc_u32 s79, s55, 0
	s_mov_b32 s80, -2
	ds_read_b128 v[56:59], v189
	ds_read_b128 v[60:63], v189 offset:1024
	ds_read_b128 v[72:75], v189 offset:2048
	ds_read_b128 v[76:79], v189 offset:3072
	ds_read_b128 v[144:147], v195
	ds_read_b128 v[148:151], v195 offset:1024
	ds_read_b128 v[168:171], v195 offset:2048
	ds_read_b128 v[178:181], v195 offset:3072
	s_add_u32 s54, s52, 0xfffc0080
	s_addc_u32 s55, s53, -1
	s_cmp_eq_u32 s80, 12
	s_cselect_b32 s57, s23, s55
	s_cselect_b32 s56, s76, s54
	s_cselect_b32 s55, s21, s79
	s_cselect_b32 s54, s77, s78
	s_add_i32 m0, s43, 0xc000
	ds_read_b128 v[184:187], v201
	ds_read_b128 v[190:193], v201 offset:1024
	ds_read_b128 v[196:199], v201 offset:2048
	ds_read_b128 v[202:205], v201 offset:3072
	ds_read_b128 v[208:211], v201 offset:4096
	ds_read_b128 v[212:215], v201 offset:5120
	ds_read_b128 v[216:219], v201 offset:6144
	ds_read_b128 v[220:223], v201 offset:7168
	global_load_lds_dwordx4 v160, s[52:53]
	s_add_i32 m0, s43, 0xe000
	s_nop 0
	global_load_lds_dwordx4 v162, s[52:53]
	s_waitcnt vmcnt(8)
	s_waitcnt lgkmcnt(0)
	s_barrier
	s_setprio 1
	s_waitcnt lgkmcnt(0)
	v_mfma_f32_16x16x32_bf16 v[140:143], v[56:59], v[184:187], 0
	v_mfma_f32_16x16x32_bf16 v[136:139], v[72:75], v[184:187], 0
	v_mfma_f32_16x16x32_bf16 v[124:127], v[56:59], v[196:199], 0
	v_mfma_f32_16x16x32_bf16 v[120:123], v[72:75], v[196:199], 0
	v_mfma_f32_16x16x32_bf16 v[108:111], v[56:59], v[208:211], 0
	v_mfma_f32_16x16x32_bf16 v[104:107], v[72:75], v[208:211], 0
	v_mfma_f32_16x16x32_bf16 v[92:95], v[56:59], v[216:219], 0
	v_mfma_f32_16x16x32_bf16 v[88:91], v[72:75], v[216:219], 0
	v_mfma_f32_16x16x32_bf16 v[140:143], v[60:63], v[190:193], v[140:143]
	v_mfma_f32_16x16x32_bf16 v[136:139], v[76:79], v[190:193], v[136:139]
	v_mfma_f32_16x16x32_bf16 v[124:127], v[60:63], v[202:205], v[124:127]
	v_mfma_f32_16x16x32_bf16 v[120:123], v[76:79], v[202:205], v[120:123]
	v_mfma_f32_16x16x32_bf16 v[108:111], v[60:63], v[212:215], v[108:111]
	v_mfma_f32_16x16x32_bf16 v[104:107], v[76:79], v[212:215], v[104:107]
	v_mfma_f32_16x16x32_bf16 v[92:95], v[60:63], v[220:223], v[92:95]
	v_mfma_f32_16x16x32_bf16 v[88:91], v[76:79], v[220:223], v[88:91]
	s_setprio 0
	s_setprio 1
	v_mfma_f32_16x16x32_bf16 v[132:135], v[144:147], v[184:187], 0
	v_mfma_f32_16x16x32_bf16 v[128:131], v[168:171], v[184:187], 0
	v_mfma_f32_16x16x32_bf16 v[116:119], v[144:147], v[196:199], 0
	v_mfma_f32_16x16x32_bf16 v[112:115], v[168:171], v[196:199], 0
	v_mfma_f32_16x16x32_bf16 v[100:103], v[144:147], v[208:211], 0
	v_mfma_f32_16x16x32_bf16 v[96:99], v[168:171], v[208:211], 0
	v_mfma_f32_16x16x32_bf16 v[84:87], v[144:147], v[216:219], 0
	v_mfma_f32_16x16x32_bf16 v[80:83], v[168:171], v[216:219], 0
	v_mfma_f32_16x16x32_bf16 v[132:135], v[148:151], v[190:193], v[132:135]
	v_mfma_f32_16x16x32_bf16 v[128:131], v[178:181], v[190:193], v[128:131]
	v_mfma_f32_16x16x32_bf16 v[116:119], v[148:151], v[202:205], v[116:119]
	v_mfma_f32_16x16x32_bf16 v[112:115], v[178:181], v[202:205], v[112:115]
	v_mfma_f32_16x16x32_bf16 v[100:103], v[148:151], v[212:215], v[100:103]
	v_mfma_f32_16x16x32_bf16 v[96:99], v[178:181], v[212:215], v[96:99]
	v_mfma_f32_16x16x32_bf16 v[84:87], v[148:151], v[220:223], v[84:87]
	v_mfma_f32_16x16x32_bf16 v[80:83], v[178:181], v[220:223], v[80:83]
	s_setprio 0
	s_barrier
	s_add_i32 s81, s73, s58
	v_lshl_add_u64 v[174:175], s[54:55], 0, v[154:155]
	s_mov_b32 m0, s81
	ds_read_b128 v[184:187], v201 offset:16384
	ds_read_b128 v[190:193], v201 offset:17408
	ds_read_b128 v[196:199], v201 offset:18432
	ds_read_b128 v[202:205], v201 offset:19456
	ds_read_b128 v[208:211], v201 offset:20480
	ds_read_b128 v[212:215], v201 offset:21504
	ds_read_b128 v[216:219], v201 offset:22528
	ds_read_b128 v[220:223], v201 offset:23552
	global_load_lds_dwordx4 v[174:175], off
	s_add_i32 m0, s81, 0x2000
	s_add_u32 s82, s54, 0x40000
	v_lshl_add_u64 v[224:225], s[54:55], 0, v[158:159]
	s_addc_u32 s83, s55, 0
	s_add_i32 s81, s74, s58
	global_load_lds_dwordx4 v[224:225], off
	s_mov_b32 m0, s81
	v_lshl_add_u64 v[228:229], s[56:57], 0, v[156:157]
	global_load_lds_dwordx4 v154, s[82:83]
	s_add_i32 m0, s81, 0x2000
	s_nop 0
	global_load_lds_dwordx4 v158, s[82:83]
	v_lshl_add_u64 v[226:227], s[56:57], 0, v[152:153]
	s_mov_b32 m0, s43
	s_nop 0
	global_load_lds_dwordx4 v[226:227], off
	s_mov_b32 m0, s59
	s_nop 0
	global_load_lds_dwordx4 v[228:229], off
	s_waitcnt vmcnt(8)
	s_waitcnt lgkmcnt(0)
	s_barrier
; #define PG8_STAGE(bufoff, gbase, voff) do { _Pragma("unroll") for (int _i = 0; _i < 2; ++_i) \
;         __builtin_amdgcn_global_load_lds((const unsigned*)((const char*)(gbase) + (voff)[_i]), (LAS unsigned*)(lds + (bufoff) + ldsw + _i * 8192), 16, 0, 0); } while (0)
; #define PG8_LDA(dst, b, h) do { _Pragma("unroll") for (int m = 0; m < 4; ++m) _Pragma("unroll") for (int k = 0; k < 2; ++k) dst[m][k] = *(const LAS bf16x8*)(lds + PG8_SA(b, h) + aoff + m * 2048 + k * 1024); } while (0)
; #define PG8_LDB(dst, b, h) do { _Pragma("unroll") for (int n = 0; n < 2; ++n) _Pragma("unroll") for (int k = 0; k < 2; ++k) dst[n][k] = *(const LAS bf16x8*)(lds + PG8_SB(b, h) + boff + n * 2048 + k * 1024); } while (0)
; #define PG8_MMA(ai, bj, At, Bt) do { __builtin_amdgcn_s_setprio(1); _Pragma("unroll") for (int m = 0; m < 4; ++m) _Pragma("unroll") for (int n = 0; n < 2; ++n) _Pragma("unroll") for (int k = 0; k < 2; ++k) \
;         acc[ai][bj][m][n] = __builtin_amdgcn_mfma_f32_16x16x32_bf16(Bt[n][k], At[m][k], acc[ai][bj][m][n], 0, 0, 0); __builtin_amdgcn_s_setprio(0); } while (0)
; #define PG8_WAIT_V(n) asm volatile("s_waitcnt vmcnt(" #n ")" ::: "memory")
; #define PG8_WAIT_L(n) asm volatile("s_waitcnt lgkmcnt(" #n ")" ::: "memory")
; #define PG8_BAR __builtin_amdgcn_s_barrier()
; #define PG8_SCHED __builtin_amdgcn_sched_barrier(0)
; template <class Epi>
; __device__ __forceinline__ void gemm_phase(LAS unsigned char* lds, const Gemm g, const StaticOrder& S, const Epi& E) {
;     ...
;             PG8_WAIT_V(8); PG8_WAIT_L(0); PG8_BAR; PG8_MMA(1, 0, At, B0); PG8_MMA(1, 1, At, B1); PG8_BAR; PG8_SCHED;
;             PG8_LDB(B0, 1, 0); PG8_LDB(B1, 1, 1); PG8_SCHED; PG8_LDA(At, 1, 0); PG8_STAGE(PG8_SA(0, 1), a2 + hstepA, voffA);
;             PG8_WAIT_V(8); PG8_WAIT_L(0); PG8_BAR; PG8_MMA(0, 0, At, B0); PG8_MMA(0, 1, At, B1); PG8_BAR; PG8_SCHED;
	s_setprio 1
	s_waitcnt lgkmcnt(0)
	v_mfma_f32_16x16x32_bf16 v[68:71], v[56:59], v[184:187], 0
	v_mfma_f32_16x16x32_bf16 v[64:67], v[72:75], v[184:187], 0
	v_mfma_f32_16x16x32_bf16 v[44:47], v[56:59], v[196:199], 0
	v_mfma_f32_16x16x32_bf16 v[40:43], v[72:75], v[196:199], 0
	v_mfma_f32_16x16x32_bf16 v[28:31], v[56:59], v[208:211], 0
	v_mfma_f32_16x16x32_bf16 v[24:27], v[72:75], v[208:211], 0
	v_mfma_f32_16x16x32_bf16 v[12:15], v[56:59], v[216:219], 0
	v_mfma_f32_16x16x32_bf16 v[8:11], v[72:75], v[216:219], 0
	v_mfma_f32_16x16x32_bf16 v[68:71], v[60:63], v[190:193], v[68:71]
	v_mfma_f32_16x16x32_bf16 v[64:67], v[76:79], v[190:193], v[64:67]
	v_mfma_f32_16x16x32_bf16 v[44:47], v[60:63], v[202:205], v[44:47]
	v_mfma_f32_16x16x32_bf16 v[40:43], v[76:79], v[202:205], v[40:43]
	v_mfma_f32_16x16x32_bf16 v[28:31], v[60:63], v[212:215], v[28:31]
	v_mfma_f32_16x16x32_bf16 v[24:27], v[76:79], v[212:215], v[24:27]
	v_mfma_f32_16x16x32_bf16 v[12:15], v[60:63], v[220:223], v[12:15]
	v_mfma_f32_16x16x32_bf16 v[8:11], v[76:79], v[220:223], v[8:11]
	s_setprio 0
	s_setprio 1
	v_mfma_f32_16x16x32_bf16 v[52:55], v[144:147], v[184:187], 0
	v_mfma_f32_16x16x32_bf16 v[48:51], v[168:171], v[184:187], 0
	v_mfma_f32_16x16x32_bf16 v[36:39], v[144:147], v[196:199], 0
	v_mfma_f32_16x16x32_bf16 v[32:35], v[168:171], v[196:199], 0
	v_mfma_f32_16x16x32_bf16 v[20:23], v[144:147], v[208:211], 0
	v_mfma_f32_16x16x32_bf16 v[16:19], v[168:171], v[208:211], 0
	v_mfma_f32_16x16x32_bf16 v[4:7], v[144:147], v[216:219], 0
	v_mfma_f32_16x16x32_bf16 v[0:3], v[168:171], v[216:219], 0
	v_mfma_f32_16x16x32_bf16 v[52:55], v[148:151], v[190:193], v[52:55]
	v_mfma_f32_16x16x32_bf16 v[48:51], v[178:181], v[190:193], v[48:51]
	v_mfma_f32_16x16x32_bf16 v[36:39], v[148:151], v[202:205], v[36:39]
	v_mfma_f32_16x16x32_bf16 v[32:35], v[178:181], v[202:205], v[32:35]
	v_mfma_f32_16x16x32_bf16 v[20:23], v[148:151], v[212:215], v[20:23]
	v_mfma_f32_16x16x32_bf16 v[16:19], v[178:181], v[212:215], v[16:19]
	v_mfma_f32_16x16x32_bf16 v[4:7], v[148:151], v[220:223], v[4:7]
	v_mfma_f32_16x16x32_bf16 v[0:3], v[178:181], v[220:223], v[0:3]
	s_setprio 0
	s_barrier
	s_add_i32 s81, 0, 0x18000
	s_add_i32 s82, 0, 0x1c000
	v_add_u32_e32 v76, s81, v183
	v_add_u32_e32 v172, s82, v183
	ds_read_b128 v[56:59], v76
	ds_read_b128 v[60:63], v76 offset:1024
	ds_read_b128 v[72:75], v76 offset:2048
	ds_read_b128 v[76:79], v76 offset:3072
	ds_read_b128 v[144:147], v172
	ds_read_b128 v[148:151], v172 offset:1024
	ds_read_b128 v[168:171], v172 offset:2048
	ds_read_b128 v[178:181], v172 offset:3072
	s_add_u32 s56, s56, 0x40000
	s_addc_u32 s57, s57, 0
	s_mov_b32 m0, s62
	ds_read_b128 v[184:187], v201 offset:32768
	ds_read_b128 v[190:193], v201 offset:33792
	ds_read_b128 v[196:199], v201 offset:34816
	ds_read_b128 v[202:205], v201 offset:35840
	ds_read_b128 v[208:211], v201 offset:36864
	ds_read_b128 v[212:215], v201 offset:37888
	ds_read_b128 v[216:219], v201 offset:38912
	ds_read_b128 v[220:223], v201 offset:39936
	global_load_lds_dwordx4 v152, s[56:57]
	s_mov_b32 m0, s63
	s_nop 0
	global_load_lds_dwordx4 v156, s[56:57]
	s_waitcnt vmcnt(8)
	s_waitcnt lgkmcnt(0)
	s_barrier
	s_setprio 1
	s_waitcnt lgkmcnt(0)
	v_mfma_f32_16x16x32_bf16 v[140:143], v[56:59], v[184:187], v[140:143]
	v_mfma_f32_16x16x32_bf16 v[136:139], v[72:75], v[184:187], v[136:139]
	v_mfma_f32_16x16x32_bf16 v[124:127], v[56:59], v[196:199], v[124:127]
	v_mfma_f32_16x16x32_bf16 v[120:123], v[72:75], v[196:199], v[120:123]
	v_mfma_f32_16x16x32_bf16 v[108:111], v[56:59], v[208:211], v[108:111]
	v_mfma_f32_16x16x32_bf16 v[104:107], v[72:75], v[208:211], v[104:107]
	v_mfma_f32_16x16x32_bf16 v[92:95], v[56:59], v[216:219], v[92:95]
	v_mfma_f32_16x16x32_bf16 v[88:91], v[72:75], v[216:219], v[88:91]
	v_mfma_f32_16x16x32_bf16 v[140:143], v[60:63], v[190:193], v[140:143]
	v_mfma_f32_16x16x32_bf16 v[136:139], v[76:79], v[190:193], v[136:139]
	v_mfma_f32_16x16x32_bf16 v[124:127], v[60:63], v[202:205], v[124:127]
	v_mfma_f32_16x16x32_bf16 v[120:123], v[76:79], v[202:205], v[120:123]
	v_mfma_f32_16x16x32_bf16 v[108:111], v[60:63], v[212:215], v[108:111]
	v_mfma_f32_16x16x32_bf16 v[104:107], v[76:79], v[212:215], v[104:107]
	v_mfma_f32_16x16x32_bf16 v[92:95], v[60:63], v[220:223], v[92:95]
	v_mfma_f32_16x16x32_bf16 v[88:91], v[76:79], v[220:223], v[88:91]
	s_setprio 0
	s_setprio 1
	v_mfma_f32_16x16x32_bf16 v[132:135], v[144:147], v[184:187], v[132:135]
	v_mfma_f32_16x16x32_bf16 v[128:131], v[168:171], v[184:187], v[128:131]
	v_mfma_f32_16x16x32_bf16 v[116:119], v[144:147], v[196:199], v[116:119]
	v_mfma_f32_16x16x32_bf16 v[112:115], v[168:171], v[196:199], v[112:115]
	v_mfma_f32_16x16x32_bf16 v[100:103], v[144:147], v[208:211], v[100:103]
	v_mfma_f32_16x16x32_bf16 v[96:99], v[168:171], v[208:211], v[96:99]
	v_mfma_f32_16x16x32_bf16 v[84:87], v[144:147], v[216:219], v[84:87]
	v_mfma_f32_16x16x32_bf16 v[80:83], v[168:171], v[216:219], v[80:83]
	v_mfma_f32_16x16x32_bf16 v[132:135], v[148:151], v[190:193], v[132:135]
	v_mfma_f32_16x16x32_bf16 v[128:131], v[178:181], v[190:193], v[128:131]
	v_mfma_f32_16x16x32_bf16 v[116:119], v[148:151], v[202:205], v[116:119]
	v_mfma_f32_16x16x32_bf16 v[112:115], v[178:181], v[202:205], v[112:115]
	v_mfma_f32_16x16x32_bf16 v[100:103], v[148:151], v[212:215], v[100:103]
	v_mfma_f32_16x16x32_bf16 v[96:99], v[178:181], v[212:215], v[96:99]
	v_mfma_f32_16x16x32_bf16 v[84:87], v[148:151], v[220:223], v[84:87]
	v_mfma_f32_16x16x32_bf16 v[80:83], v[178:181], v[220:223], v[80:83]
	s_setprio 0
	s_barrier
; #define PG8_STAGE(bufoff, gbase, voff) do { _Pragma("unroll") for (int _i = 0; _i < 2; ++_i) \
;         __builtin_amdgcn_global_load_lds((const unsigned*)((const char*)(gbase) + (voff)[_i]), (LAS unsigned*)(lds + (bufoff) + ldsw + _i * 8192), 16, 0, 0); } while (0)
; #define PG8_LDA(dst, b, h) do { _Pragma("unroll") for (int m = 0; m < 4; ++m) _Pragma("unroll") for (int k = 0; k < 2; ++k) dst[m][k] = *(const LAS bf16x8*)(lds + PG8_SA(b, h) + aoff + m * 2048 + k * 1024); } while (0)
; #define PG8_LDB(dst, b, h) do { _Pragma("unroll") for (int n = 0; n < 2; ++n) _Pragma("unroll") for (int k = 0; k < 2; ++k) dst[n][k] = *(const LAS bf16x8*)(lds + PG8_SB(b, h) + boff + n * 2048 + k * 1024); } while (0)
; #define PG8_MMA(ai, bj, At, Bt) do { __builtin_amdgcn_s_setprio(1); _Pragma("unroll") for (int m = 0; m < 4; ++m) _Pragma("unroll") for (int n = 0; n < 2; ++n) _Pragma("unroll") for (int k = 0; k < 2; ++k) \
;         acc[ai][bj][m][n] = __builtin_amdgcn_mfma_f32_16x16x32_bf16(Bt[n][k], At[m][k], acc[ai][bj][m][n], 0, 0, 0); __builtin_amdgcn_s_setprio(0); } while (0)
; #define PG8_WAIT_V(n) asm volatile("s_waitcnt vmcnt(" #n ")" ::: "memory")
; #define PG8_BAR __builtin_amdgcn_s_barrier()
; template <class Epi>
; __device__ __forceinline__ void gemm_phase(LAS unsigned char* lds, const Gemm g, const StaticOrder& S, const Epi& E) {
;     ...
;             PG8_LDB(B0, 0, 0); PG8_LDB(B1, 0, 1); PG8_SCHED; PG8_LDA(At, 0, 0); PG8_STAGE(PG8_SA(1, 1), a1 + hstepA, voffA);
;             PG8_WAIT_V(8); PG8_WAIT_L(0); PG8_BAR; PG8_MMA(0, 0, At, B0); PG8_MMA(0, 1, At, B1); PG8_BAR; PG8_SCHED;
;             PG8_LDA(At, 0, 1); PG8_STAGE(PG8_SB(0, 0), b2, voffB); PG8_STAGE(PG8_SB(0, 1), b2 + hstepB, voffB); PG8_STAGE(PG8_SA(0, 0), a2, voffA);
;             PG8_WAIT_V(8); PG8_WAIT_L(0); PG8_BAR; PG8_MMA(1, 0, At, B0); PG8_MMA(1, 1, At, B1); PG8_BAR; PG8_SCHED;
;             PG8_LDB(B0, 1, 0); PG8_LDB(B1, 1, 1); PG8_SCHED; PG8_LDA(At, 1, 0); PG8_STAGE(PG8_SA(0, 1), a2 + hstepA, voffA);
;             PG8_WAIT_V(8); PG8_WAIT_L(0); PG8_BAR; PG8_MMA(0, 0, At, B0); PG8_MMA(0, 1, At, B1); PG8_BAR; PG8_SCHED;
;             PG8_LDA(At, 1, 1); PG8_STAGE(PG8_SB(1, 0), b3, voffB); PG8_STAGE(PG8_SB(1, 1), b3 + hstepB, voffB); PG8_STAGE(PG8_SA(1, 0), a3, voffA);
;             PG8_WAIT_V(8); PG8_WAIT_L(0); PG8_BAR; PG8_MMA(1, 0, At, B0); PG8_MMA(1, 1, At, B1); PG8_BAR; PG8_SCHED;
	s_add_i32 s56, s81, s58
	v_lshl_add_u64 v[174:175], v[174:175], 0, s[12:13]
	s_mov_b32 m0, s56
	ds_read_b128 v[184:187], v201 offset:49152
	ds_read_b128 v[190:193], v201 offset:50176
	ds_read_b128 v[196:199], v201 offset:51200
	ds_read_b128 v[202:205], v201 offset:52224
	ds_read_b128 v[208:211], v201 offset:53248
	ds_read_b128 v[212:215], v201 offset:54272
	ds_read_b128 v[216:219], v201 offset:55296
	ds_read_b128 v[220:223], v201 offset:56320
	global_load_lds_dwordx4 v[174:175], off
	s_add_i32 m0, s56, 0x2000
	s_add_u32 s54, s54, 0x40080
	v_lshl_add_u64 v[174:175], v[224:225], 0, s[12:13]
	s_addc_u32 s55, s55, 0
	s_add_i32 s56, s82, s58
	global_load_lds_dwordx4 v[174:175], off
	s_mov_b32 m0, s56
	s_nop 0
	global_load_lds_dwordx4 v154, s[54:55]
	s_add_i32 m0, s56, 0x2000
	s_nop 0
	global_load_lds_dwordx4 v158, s[54:55]
	v_lshl_add_u64 v[174:175], v[226:227], 0, s[12:13]
	s_mov_b32 m0, s69
	s_nop 0
	global_load_lds_dwordx4 v[174:175], off
	v_lshl_add_u64 v[174:175], v[228:229], 0, s[12:13]
	s_mov_b32 m0, s70
	s_nop 0
	global_load_lds_dwordx4 v[174:175], off
	s_waitcnt vmcnt(8)
	s_waitcnt lgkmcnt(0)
	s_barrier
	s_setprio 1
	s_waitcnt lgkmcnt(0)
	v_mfma_f32_16x16x32_bf16 v[68:71], v[56:59], v[184:187], v[68:71]
	v_mfma_f32_16x16x32_bf16 v[64:67], v[72:75], v[184:187], v[64:67]
	v_mfma_f32_16x16x32_bf16 v[44:47], v[56:59], v[196:199], v[44:47]
	v_mfma_f32_16x16x32_bf16 v[40:43], v[72:75], v[196:199], v[40:43]
	v_mfma_f32_16x16x32_bf16 v[28:31], v[56:59], v[208:211], v[28:31]
	v_mfma_f32_16x16x32_bf16 v[24:27], v[72:75], v[208:211], v[24:27]
	v_mfma_f32_16x16x32_bf16 v[12:15], v[56:59], v[216:219], v[12:15]
	v_mfma_f32_16x16x32_bf16 v[8:11], v[72:75], v[216:219], v[8:11]
	v_mfma_f32_16x16x32_bf16 v[68:71], v[60:63], v[190:193], v[68:71]
	v_mfma_f32_16x16x32_bf16 v[64:67], v[76:79], v[190:193], v[64:67]
	v_mfma_f32_16x16x32_bf16 v[44:47], v[60:63], v[202:205], v[44:47]
	v_mfma_f32_16x16x32_bf16 v[40:43], v[76:79], v[202:205], v[40:43]
	v_mfma_f32_16x16x32_bf16 v[28:31], v[60:63], v[212:215], v[28:31]
	v_mfma_f32_16x16x32_bf16 v[24:27], v[76:79], v[212:215], v[24:27]
	v_mfma_f32_16x16x32_bf16 v[12:15], v[60:63], v[220:223], v[12:15]
	v_mfma_f32_16x16x32_bf16 v[8:11], v[76:79], v[220:223], v[8:11]
	s_setprio 0
	s_setprio 1
	v_mfma_f32_16x16x32_bf16 v[52:55], v[144:147], v[184:187], v[52:55]
	v_mfma_f32_16x16x32_bf16 v[48:51], v[168:171], v[184:187], v[48:51]
	v_mfma_f32_16x16x32_bf16 v[36:39], v[144:147], v[196:199], v[36:39]
	v_mfma_f32_16x16x32_bf16 v[32:35], v[168:171], v[196:199], v[32:35]
	v_mfma_f32_16x16x32_bf16 v[20:23], v[144:147], v[208:211], v[20:23]
	v_mfma_f32_16x16x32_bf16 v[16:19], v[168:171], v[208:211], v[16:19]
	v_mfma_f32_16x16x32_bf16 v[4:7], v[144:147], v[216:219], v[4:7]
	v_mfma_f32_16x16x32_bf16 v[0:3], v[168:171], v[216:219], v[0:3]
	v_mfma_f32_16x16x32_bf16 v[52:55], v[148:151], v[190:193], v[52:55]
	v_mfma_f32_16x16x32_bf16 v[48:51], v[178:181], v[190:193], v[48:51]
	v_mfma_f32_16x16x32_bf16 v[36:39], v[148:151], v[202:205], v[36:39]
	v_mfma_f32_16x16x32_bf16 v[32:35], v[178:181], v[202:205], v[32:35]
	v_mfma_f32_16x16x32_bf16 v[20:23], v[148:151], v[212:215], v[20:23]
	v_mfma_f32_16x16x32_bf16 v[16:19], v[178:181], v[212:215], v[16:19]
	v_mfma_f32_16x16x32_bf16 v[4:7], v[148:151], v[220:223], v[4:7]
	v_mfma_f32_16x16x32_bf16 v[0:3], v[178:181], v[220:223], v[0:3]
	s_setprio 0
	s_barrier
	s_add_i32 s80, s80, 2
	s_add_u32 s52, s52, 0x100
	s_addc_u32 s53, s53, 0
	s_add_u32 s78, s78, 0x100
	s_addc_u32 s79, s79, 0
	s_cmp_gt_u32 s80, 13
.LBB0_1233:
	ds_read_b128 v[56:59], v189
	ds_read_b128 v[60:63], v189 offset:1024
	ds_read_b128 v[72:75], v189 offset:2048
	ds_read_b128 v[76:79], v189 offset:3072
	ds_read_b128 v[144:147], v195
	ds_read_b128 v[148:151], v195 offset:1024
	ds_read_b128 v[168:171], v195 offset:2048
	ds_read_b128 v[178:181], v195 offset:3072
	s_add_u32 s54, s52, 0xfffc0080
	s_addc_u32 s55, s53, -1
	s_cmp_eq_u32 s80, 12
	s_cselect_b32 s57, s23, s55
	s_cselect_b32 s56, s76, s54
	s_cselect_b32 s55, s21, s79
	s_cselect_b32 s54, s77, s78
	s_add_i32 m0, s43, 0xc000
	ds_read_b128 v[184:187], v201
	ds_read_b128 v[190:193], v201 offset:1024
	ds_read_b128 v[196:199], v201 offset:2048
	ds_read_b128 v[202:205], v201 offset:3072
	ds_read_b128 v[208:211], v201 offset:4096
	ds_read_b128 v[212:215], v201 offset:5120
	ds_read_b128 v[216:219], v201 offset:6144
	ds_read_b128 v[220:223], v201 offset:7168
	global_load_lds_dwordx4 v160, s[52:53]
	s_add_i32 m0, s43, 0xe000
	s_nop 0
	global_load_lds_dwordx4 v162, s[52:53]
	s_waitcnt vmcnt(8)
	s_waitcnt lgkmcnt(0)
	s_barrier
; #define PG8_STAGE(bufoff, gbase, voff) do { _Pragma("unroll") for (int _i = 0; _i < 2; ++_i) \
;         __builtin_amdgcn_global_load_lds((const unsigned*)((const char*)(gbase) + (voff)[_i]), (LAS unsigned*)(lds + (bufoff) + ldsw + _i * 8192), 16, 0, 0); } while (0)
; #define PG8_LDA(dst, b, h) do { _Pragma("unroll") for (int m = 0; m < 4; ++m) _Pragma("unroll") for (int k = 0; k < 2; ++k) dst[m][k] = *(const LAS bf16x8*)(lds + PG8_SA(b, h) + aoff + m * 2048 + k * 1024); } while (0)
; #define PG8_MMA(ai, bj, At, Bt) do { __builtin_amdgcn_s_setprio(1); _Pragma("unroll") for (int m = 0; m < 4; ++m) _Pragma("unroll") for (int n = 0; n < 2; ++n) _Pragma("unroll") for (int k = 0; k < 2; ++k) \
;         acc[ai][bj][m][n] = __builtin_amdgcn_mfma_f32_16x16x32_bf16(Bt[n][k], At[m][k], acc[ai][bj][m][n], 0, 0, 0); __builtin_amdgcn_s_setprio(0); } while (0)
; #define PG8_WAIT_V(n) asm volatile("s_waitcnt vmcnt(" #n ")" ::: "memory")
; #define PG8_WAIT_L(n) asm volatile("s_waitcnt lgkmcnt(" #n ")" ::: "memory")
; #define PG8_BAR __builtin_amdgcn_s_barrier()
; #define PG8_SCHED __builtin_amdgcn_sched_barrier(0)
; template <class Epi>
; __device__ __forceinline__ void gemm_phase(LAS unsigned char* lds, const Gemm g, const StaticOrder& S, const Epi& E) {
;     ...
;             PG8_WAIT_V(8); PG8_WAIT_L(0); PG8_BAR; PG8_MMA(0, 0, At, B0); PG8_MMA(0, 1, At, B1); PG8_BAR; PG8_SCHED;
;             PG8_LDA(At, 0, 1); PG8_STAGE(PG8_SB(0, 0), b2, voffB); PG8_STAGE(PG8_SB(0, 1), b2 + hstepB, voffB); PG8_STAGE(PG8_SA(0, 0), a2, voffA);
;             PG8_WAIT_V(8); PG8_WAIT_L(0); PG8_BAR; PG8_MMA(1, 0, At, B0); PG8_MMA(1, 1, At, B1); PG8_BAR; PG8_SCHED;
	s_setprio 1
	s_waitcnt lgkmcnt(0)
	v_mfma_f32_16x16x32_bf16 v[140:143], v[56:59], v[184:187], v[140:143]
	v_mfma_f32_16x16x32_bf16 v[136:139], v[72:75], v[184:187], v[136:139]
	v_mfma_f32_16x16x32_bf16 v[124:127], v[56:59], v[196:199], v[124:127]
	v_mfma_f32_16x16x32_bf16 v[120:123], v[72:75], v[196:199], v[120:123]
	v_mfma_f32_16x16x32_bf16 v[108:111], v[56:59], v[208:211], v[108:111]
	v_mfma_f32_16x16x32_bf16 v[104:107], v[72:75], v[208:211], v[104:107]
	v_mfma_f32_16x16x32_bf16 v[92:95], v[56:59], v[216:219], v[92:95]
	v_mfma_f32_16x16x32_bf16 v[88:91], v[72:75], v[216:219], v[88:91]
	v_mfma_f32_16x16x32_bf16 v[140:143], v[60:63], v[190:193], v[140:143]
	v_mfma_f32_16x16x32_bf16 v[136:139], v[76:79], v[190:193], v[136:139]
	v_mfma_f32_16x16x32_bf16 v[124:127], v[60:63], v[202:205], v[124:127]
	v_mfma_f32_16x16x32_bf16 v[120:123], v[76:79], v[202:205], v[120:123]
	v_mfma_f32_16x16x32_bf16 v[108:111], v[60:63], v[212:215], v[108:111]
	v_mfma_f32_16x16x32_bf16 v[104:107], v[76:79], v[212:215], v[104:107]
	v_mfma_f32_16x16x32_bf16 v[92:95], v[60:63], v[220:223], v[92:95]
	v_mfma_f32_16x16x32_bf16 v[88:91], v[76:79], v[220:223], v[88:91]
	s_setprio 0
	s_setprio 1
	v_mfma_f32_16x16x32_bf16 v[132:135], v[144:147], v[184:187], v[132:135]
	v_mfma_f32_16x16x32_bf16 v[128:131], v[168:171], v[184:187], v[128:131]
	v_mfma_f32_16x16x32_bf16 v[116:119], v[144:147], v[196:199], v[116:119]
	v_mfma_f32_16x16x32_bf16 v[112:115], v[168:171], v[196:199], v[112:115]
	v_mfma_f32_16x16x32_bf16 v[100:103], v[144:147], v[208:211], v[100:103]
	v_mfma_f32_16x16x32_bf16 v[96:99], v[168:171], v[208:211], v[96:99]
	v_mfma_f32_16x16x32_bf16 v[84:87], v[144:147], v[216:219], v[84:87]
	v_mfma_f32_16x16x32_bf16 v[80:83], v[168:171], v[216:219], v[80:83]
	v_mfma_f32_16x16x32_bf16 v[132:135], v[148:151], v[190:193], v[132:135]
	v_mfma_f32_16x16x32_bf16 v[128:131], v[178:181], v[190:193], v[128:131]
	v_mfma_f32_16x16x32_bf16 v[116:119], v[148:151], v[202:205], v[116:119]
	v_mfma_f32_16x16x32_bf16 v[112:115], v[178:181], v[202:205], v[112:115]
	v_mfma_f32_16x16x32_bf16 v[100:103], v[148:151], v[212:215], v[100:103]
	v_mfma_f32_16x16x32_bf16 v[96:99], v[178:181], v[212:215], v[96:99]
	v_mfma_f32_16x16x32_bf16 v[84:87], v[148:151], v[220:223], v[84:87]
	v_mfma_f32_16x16x32_bf16 v[80:83], v[178:181], v[220:223], v[80:83]
	s_setprio 0
	s_barrier
	s_add_i32 s81, s73, s58
	v_lshl_add_u64 v[174:175], s[54:55], 0, v[154:155]
	s_mov_b32 m0, s81
	ds_read_b128 v[184:187], v201 offset:16384
	ds_read_b128 v[190:193], v201 offset:17408
	ds_read_b128 v[196:199], v201 offset:18432
	ds_read_b128 v[202:205], v201 offset:19456
	ds_read_b128 v[208:211], v201 offset:20480
	ds_read_b128 v[212:215], v201 offset:21504
	ds_read_b128 v[216:219], v201 offset:22528
	ds_read_b128 v[220:223], v201 offset:23552
	global_load_lds_dwordx4 v[174:175], off
	s_add_i32 m0, s81, 0x2000
	s_add_u32 s82, s54, 0x40000
	v_lshl_add_u64 v[224:225], s[54:55], 0, v[158:159]
	s_addc_u32 s83, s55, 0
	s_add_i32 s81, s74, s58
	global_load_lds_dwordx4 v[224:225], off
	s_mov_b32 m0, s81
	v_lshl_add_u64 v[228:229], s[56:57], 0, v[156:157]
	global_load_lds_dwordx4 v154, s[82:83]
	s_add_i32 m0, s81, 0x2000
	s_nop 0
	global_load_lds_dwordx4 v158, s[82:83]
	v_lshl_add_u64 v[226:227], s[56:57], 0, v[152:153]
	s_mov_b32 m0, s43
	s_nop 0
	global_load_lds_dwordx4 v[226:227], off
	s_mov_b32 m0, s59
	s_nop 0
	global_load_lds_dwordx4 v[228:229], off
	s_waitcnt vmcnt(8)
	s_waitcnt lgkmcnt(0)
	s_barrier
	s_setprio 1
	s_waitcnt lgkmcnt(0)
	v_mfma_f32_16x16x32_bf16 v[68:71], v[56:59], v[184:187], v[68:71]
	v_mfma_f32_16x16x32_bf16 v[64:67], v[72:75], v[184:187], v[64:67]
	v_mfma_f32_16x16x32_bf16 v[44:47], v[56:59], v[196:199], v[44:47]
	v_mfma_f32_16x16x32_bf16 v[40:43], v[72:75], v[196:199], v[40:43]
	v_mfma_f32_16x16x32_bf16 v[28:31], v[56:59], v[208:211], v[28:31]
	v_mfma_f32_16x16x32_bf16 v[24:27], v[72:75], v[208:211], v[24:27]
	v_mfma_f32_16x16x32_bf16 v[12:15], v[56:59], v[216:219], v[12:15]
	v_mfma_f32_16x16x32_bf16 v[8:11], v[72:75], v[216:219], v[8:11]
	v_mfma_f32_16x16x32_bf16 v[68:71], v[60:63], v[190:193], v[68:71]
	v_mfma_f32_16x16x32_bf16 v[64:67], v[76:79], v[190:193], v[64:67]
	v_mfma_f32_16x16x32_bf16 v[44:47], v[60:63], v[202:205], v[44:47]
	v_mfma_f32_16x16x32_bf16 v[40:43], v[76:79], v[202:205], v[40:43]
	v_mfma_f32_16x16x32_bf16 v[28:31], v[60:63], v[212:215], v[28:31]
	v_mfma_f32_16x16x32_bf16 v[24:27], v[76:79], v[212:215], v[24:27]
	v_mfma_f32_16x16x32_bf16 v[12:15], v[60:63], v[220:223], v[12:15]
	v_mfma_f32_16x16x32_bf16 v[8:11], v[76:79], v[220:223], v[8:11]
	s_setprio 0
	s_setprio 1
	v_mfma_f32_16x16x32_bf16 v[52:55], v[144:147], v[184:187], v[52:55]
	v_mfma_f32_16x16x32_bf16 v[48:51], v[168:171], v[184:187], v[48:51]
	v_mfma_f32_16x16x32_bf16 v[36:39], v[144:147], v[196:199], v[36:39]
	v_mfma_f32_16x16x32_bf16 v[32:35], v[168:171], v[196:199], v[32:35]
	v_mfma_f32_16x16x32_bf16 v[20:23], v[144:147], v[208:211], v[20:23]
	v_mfma_f32_16x16x32_bf16 v[16:19], v[168:171], v[208:211], v[16:19]
	v_mfma_f32_16x16x32_bf16 v[4:7], v[144:147], v[216:219], v[4:7]
	v_mfma_f32_16x16x32_bf16 v[0:3], v[168:171], v[216:219], v[0:3]
	v_mfma_f32_16x16x32_bf16 v[52:55], v[148:151], v[190:193], v[52:55]
	v_mfma_f32_16x16x32_bf16 v[48:51], v[178:181], v[190:193], v[48:51]
	v_mfma_f32_16x16x32_bf16 v[36:39], v[148:151], v[202:205], v[36:39]
	v_mfma_f32_16x16x32_bf16 v[32:35], v[178:181], v[202:205], v[32:35]
	v_mfma_f32_16x16x32_bf16 v[20:23], v[148:151], v[212:215], v[20:23]
	v_mfma_f32_16x16x32_bf16 v[16:19], v[178:181], v[212:215], v[16:19]
	v_mfma_f32_16x16x32_bf16 v[4:7], v[148:151], v[220:223], v[4:7]
	v_mfma_f32_16x16x32_bf16 v[0:3], v[178:181], v[220:223], v[0:3]
	s_setprio 0
	s_barrier
; #define PG8_STAGE(bufoff, gbase, voff) do { _Pragma("unroll") for (int _i = 0; _i < 2; ++_i) \
;         __builtin_amdgcn_global_load_lds((const unsigned*)((const char*)(gbase) + (voff)[_i]), (LAS unsigned*)(lds + (bufoff) + ldsw + _i * 8192), 16, 0, 0); } while (0)
; #define PG8_LDA(dst, b, h) do { _Pragma("unroll") for (int m = 0; m < 4; ++m) _Pragma("unroll") for (int k = 0; k < 2; ++k) dst[m][k] = *(const LAS bf16x8*)(lds + PG8_SA(b, h) + aoff + m * 2048 + k * 1024); } while (0)
; #define PG8_LDB(dst, b, h) do { _Pragma("unroll") for (int n = 0; n < 2; ++n) _Pragma("unroll") for (int k = 0; k < 2; ++k) dst[n][k] = *(const LAS bf16x8*)(lds + PG8_SB(b, h) + boff + n * 2048 + k * 1024); } while (0)
; #define PG8_MMA(ai, bj, At, Bt) do { __builtin_amdgcn_s_setprio(1); _Pragma("unroll") for (int m = 0; m < 4; ++m) _Pragma("unroll") for (int n = 0; n < 2; ++n) _Pragma("unroll") for (int k = 0; k < 2; ++k) \
;         acc[ai][bj][m][n] = __builtin_amdgcn_mfma_f32_16x16x32_bf16(Bt[n][k], At[m][k], acc[ai][bj][m][n], 0, 0, 0); __builtin_amdgcn_s_setprio(0); } while (0)
; #define PG8_WAIT_V(n) asm volatile("s_waitcnt vmcnt(" #n ")" ::: "memory")
; #define PG8_WAIT_L(n) asm volatile("s_waitcnt lgkmcnt(" #n ")" ::: "memory")
; #define PG8_BAR __builtin_amdgcn_s_barrier()
; #define PG8_SCHED __builtin_amdgcn_sched_barrier(0)
; template <class Epi>
; __device__ __forceinline__ void gemm_phase(LAS unsigned char* lds, const Gemm g, const StaticOrder& S, const Epi& E) {
;     ...
;             PG8_LDB(B0, 1, 0); PG8_LDB(B1, 1, 1); PG8_SCHED; PG8_LDA(At, 1, 0); PG8_STAGE(PG8_SA(0, 1), a2 + hstepA, voffA);
;             PG8_WAIT_V(8); PG8_WAIT_L(0); PG8_BAR; PG8_MMA(0, 0, At, B0); PG8_MMA(0, 1, At, B1); PG8_BAR; PG8_SCHED;
;             PG8_LDA(At, 1, 1); PG8_STAGE(PG8_SB(1, 0), b3, voffB); PG8_STAGE(PG8_SB(1, 1), b3 + hstepB, voffB); PG8_STAGE(PG8_SA(1, 0), a3, voffA);
;             PG8_WAIT_V(8); PG8_WAIT_L(0); PG8_BAR; PG8_MMA(1, 0, At, B0); PG8_MMA(1, 1, At, B1); PG8_BAR; PG8_SCHED;
;         }
;         if (wr == 0) PG8_BAR;
	s_add_i32 s81, 0, 0x18000
	s_add_i32 s82, 0, 0x1c000
	v_add_u32_e32 v76, s81, v183
	v_add_u32_e32 v172, s82, v183
	ds_read_b128 v[56:59], v76
	ds_read_b128 v[60:63], v76 offset:1024
	ds_read_b128 v[72:75], v76 offset:2048
	ds_read_b128 v[76:79], v76 offset:3072
	ds_read_b128 v[144:147], v172
	ds_read_b128 v[148:151], v172 offset:1024
	ds_read_b128 v[168:171], v172 offset:2048
	ds_read_b128 v[178:181], v172 offset:3072
	s_add_u32 s56, s56, 0x40000
	s_addc_u32 s57, s57, 0
	s_mov_b32 m0, s62
	ds_read_b128 v[184:187], v201 offset:32768
	ds_read_b128 v[190:193], v201 offset:33792
	ds_read_b128 v[196:199], v201 offset:34816
	ds_read_b128 v[202:205], v201 offset:35840
	ds_read_b128 v[208:211], v201 offset:36864
	ds_read_b128 v[212:215], v201 offset:37888
	ds_read_b128 v[216:219], v201 offset:38912
	ds_read_b128 v[220:223], v201 offset:39936
	global_load_lds_dwordx4 v152, s[56:57]
	s_mov_b32 m0, s63
	s_nop 0
	global_load_lds_dwordx4 v156, s[56:57]
	s_waitcnt vmcnt(8)
	s_waitcnt lgkmcnt(0)
	s_barrier
	s_setprio 1
	s_waitcnt lgkmcnt(0)
	v_mfma_f32_16x16x32_bf16 v[140:143], v[56:59], v[184:187], v[140:143]
	v_mfma_f32_16x16x32_bf16 v[136:139], v[72:75], v[184:187], v[136:139]
	v_mfma_f32_16x16x32_bf16 v[124:127], v[56:59], v[196:199], v[124:127]
	v_mfma_f32_16x16x32_bf16 v[120:123], v[72:75], v[196:199], v[120:123]
	v_mfma_f32_16x16x32_bf16 v[108:111], v[56:59], v[208:211], v[108:111]
	v_mfma_f32_16x16x32_bf16 v[104:107], v[72:75], v[208:211], v[104:107]
	v_mfma_f32_16x16x32_bf16 v[92:95], v[56:59], v[216:219], v[92:95]
	v_mfma_f32_16x16x32_bf16 v[88:91], v[72:75], v[216:219], v[88:91]
	v_mfma_f32_16x16x32_bf16 v[140:143], v[60:63], v[190:193], v[140:143]
	v_mfma_f32_16x16x32_bf16 v[136:139], v[76:79], v[190:193], v[136:139]
	v_mfma_f32_16x16x32_bf16 v[124:127], v[60:63], v[202:205], v[124:127]
	v_mfma_f32_16x16x32_bf16 v[120:123], v[76:79], v[202:205], v[120:123]
	v_mfma_f32_16x16x32_bf16 v[108:111], v[60:63], v[212:215], v[108:111]
	v_mfma_f32_16x16x32_bf16 v[104:107], v[76:79], v[212:215], v[104:107]
	v_mfma_f32_16x16x32_bf16 v[92:95], v[60:63], v[220:223], v[92:95]
	v_mfma_f32_16x16x32_bf16 v[88:91], v[76:79], v[220:223], v[88:91]
	s_setprio 0
	s_setprio 1
	v_mfma_f32_16x16x32_bf16 v[132:135], v[144:147], v[184:187], v[132:135]
	v_mfma_f32_16x16x32_bf16 v[128:131], v[168:171], v[184:187], v[128:131]
	v_mfma_f32_16x16x32_bf16 v[116:119], v[144:147], v[196:199], v[116:119]
	v_mfma_f32_16x16x32_bf16 v[112:115], v[168:171], v[196:199], v[112:115]
	v_mfma_f32_16x16x32_bf16 v[100:103], v[144:147], v[208:211], v[100:103]
	v_mfma_f32_16x16x32_bf16 v[96:99], v[168:171], v[208:211], v[96:99]
	v_mfma_f32_16x16x32_bf16 v[84:87], v[144:147], v[216:219], v[84:87]
	v_mfma_f32_16x16x32_bf16 v[80:83], v[168:171], v[216:219], v[80:83]
	v_mfma_f32_16x16x32_bf16 v[132:135], v[148:151], v[190:193], v[132:135]
	v_mfma_f32_16x16x32_bf16 v[128:131], v[178:181], v[190:193], v[128:131]
	v_mfma_f32_16x16x32_bf16 v[116:119], v[148:151], v[202:205], v[116:119]
	v_mfma_f32_16x16x32_bf16 v[112:115], v[178:181], v[202:205], v[112:115]
	v_mfma_f32_16x16x32_bf16 v[100:103], v[148:151], v[212:215], v[100:103]
	v_mfma_f32_16x16x32_bf16 v[96:99], v[178:181], v[212:215], v[96:99]
	v_mfma_f32_16x16x32_bf16 v[84:87], v[148:151], v[220:223], v[84:87]
	v_mfma_f32_16x16x32_bf16 v[80:83], v[178:181], v[220:223], v[80:83]
	s_setprio 0
	s_barrier
	s_add_i32 s56, s81, s58
	v_lshl_add_u64 v[174:175], v[174:175], 0, s[12:13]
	s_mov_b32 m0, s56
	ds_read_b128 v[184:187], v201 offset:49152
	ds_read_b128 v[190:193], v201 offset:50176
	ds_read_b128 v[196:199], v201 offset:51200
	ds_read_b128 v[202:205], v201 offset:52224
	ds_read_b128 v[208:211], v201 offset:53248
	ds_read_b128 v[212:215], v201 offset:54272
	ds_read_b128 v[216:219], v201 offset:55296
	ds_read_b128 v[220:223], v201 offset:56320
	global_load_lds_dwordx4 v[174:175], off
	s_add_i32 m0, s56, 0x2000
	s_add_u32 s54, s54, 0x40080
	v_lshl_add_u64 v[174:175], v[224:225], 0, s[12:13]
	s_addc_u32 s55, s55, 0
	s_add_i32 s56, s82, s58
	global_load_lds_dwordx4 v[174:175], off
	s_mov_b32 m0, s56
	s_nop 0
	global_load_lds_dwordx4 v154, s[54:55]
	s_add_i32 m0, s56, 0x2000
	s_nop 0
	global_load_lds_dwordx4 v158, s[54:55]
	v_lshl_add_u64 v[174:175], v[226:227], 0, s[12:13]
	s_mov_b32 m0, s69
	s_nop 0
	global_load_lds_dwordx4 v[174:175], off
	v_lshl_add_u64 v[174:175], v[228:229], 0, s[12:13]
	s_mov_b32 m0, s70
	s_nop 0
	global_load_lds_dwordx4 v[174:175], off
	s_waitcnt vmcnt(8)
	s_waitcnt lgkmcnt(0)
	s_barrier
	s_setprio 1
	s_waitcnt lgkmcnt(0)
	v_mfma_f32_16x16x32_bf16 v[68:71], v[56:59], v[184:187], v[68:71]
	v_mfma_f32_16x16x32_bf16 v[64:67], v[72:75], v[184:187], v[64:67]
	v_mfma_f32_16x16x32_bf16 v[44:47], v[56:59], v[196:199], v[44:47]
	v_mfma_f32_16x16x32_bf16 v[40:43], v[72:75], v[196:199], v[40:43]
	v_mfma_f32_16x16x32_bf16 v[28:31], v[56:59], v[208:211], v[28:31]
	v_mfma_f32_16x16x32_bf16 v[24:27], v[72:75], v[208:211], v[24:27]
	v_mfma_f32_16x16x32_bf16 v[12:15], v[56:59], v[216:219], v[12:15]
	v_mfma_f32_16x16x32_bf16 v[8:11], v[72:75], v[216:219], v[8:11]
	v_mfma_f32_16x16x32_bf16 v[68:71], v[60:63], v[190:193], v[68:71]
	v_mfma_f32_16x16x32_bf16 v[64:67], v[76:79], v[190:193], v[64:67]
	v_mfma_f32_16x16x32_bf16 v[44:47], v[60:63], v[202:205], v[44:47]
	v_mfma_f32_16x16x32_bf16 v[40:43], v[76:79], v[202:205], v[40:43]
	v_mfma_f32_16x16x32_bf16 v[28:31], v[60:63], v[212:215], v[28:31]
	v_mfma_f32_16x16x32_bf16 v[24:27], v[76:79], v[212:215], v[24:27]
	v_mfma_f32_16x16x32_bf16 v[12:15], v[60:63], v[220:223], v[12:15]
	v_mfma_f32_16x16x32_bf16 v[8:11], v[76:79], v[220:223], v[8:11]
	s_setprio 0
	s_setprio 1
	v_mfma_f32_16x16x32_bf16 v[52:55], v[144:147], v[184:187], v[52:55]
	v_mfma_f32_16x16x32_bf16 v[48:51], v[168:171], v[184:187], v[48:51]
	v_mfma_f32_16x16x32_bf16 v[36:39], v[144:147], v[196:199], v[36:39]
	v_mfma_f32_16x16x32_bf16 v[32:35], v[168:171], v[196:199], v[32:35]
	v_mfma_f32_16x16x32_bf16 v[20:23], v[144:147], v[208:211], v[20:23]
	v_mfma_f32_16x16x32_bf16 v[16:19], v[168:171], v[208:211], v[16:19]
	v_mfma_f32_16x16x32_bf16 v[4:7], v[144:147], v[216:219], v[4:7]
	v_mfma_f32_16x16x32_bf16 v[0:3], v[168:171], v[216:219], v[0:3]
	v_mfma_f32_16x16x32_bf16 v[52:55], v[148:151], v[190:193], v[52:55]
	v_mfma_f32_16x16x32_bf16 v[48:51], v[178:181], v[190:193], v[48:51]
	v_mfma_f32_16x16x32_bf16 v[36:39], v[148:151], v[202:205], v[36:39]
	v_mfma_f32_16x16x32_bf16 v[32:35], v[178:181], v[202:205], v[32:35]
	v_mfma_f32_16x16x32_bf16 v[20:23], v[148:151], v[212:215], v[20:23]
	v_mfma_f32_16x16x32_bf16 v[16:19], v[178:181], v[212:215], v[16:19]
	v_mfma_f32_16x16x32_bf16 v[4:7], v[148:151], v[220:223], v[4:7]
	v_mfma_f32_16x16x32_bf16 v[0:3], v[178:181], v[220:223], v[0:3]
	s_setprio 0
	s_barrier
	s_add_i32 s80, s80, 2
	s_add_u32 s52, s52, 0x100
	s_addc_u32 s53, s53, 0
	s_add_u32 s78, s78, 0x100
	s_addc_u32 s79, s79, 0
	s_cmp_gt_u32 s80, 13
	s_cbranch_scc0 .LBB0_1233
	s_and_b64 vcc, exec, s[14:15]
	s_cbranch_vccz .LBB0_1236
	s_barrier

; #define PG8_STAGE(bufoff, gbase, voff) do { _Pragma("unroll") for (int _i = 0; _i < 2; ++_i) \
;         __builtin_amdgcn_global_load_lds((const unsigned*)((const char*)(gbase) + (voff)[_i]), (LAS unsigned*)(lds + (bufoff) + ldsw + _i * 8192), 16, 0, 0); } while (0)
; #define PG8_WAIT_V(n) asm volatile("s_waitcnt vmcnt(" #n ")" ::: "memory")
; #define PG8_BAR __builtin_amdgcn_s_barrier()
; template <class Epi>
; __device__ __forceinline__ void gemm_phase(LAS unsigned char* lds, const Gemm g, const StaticOrder& S, const Epi& E) {
;     const int tid = threadIdx.x, wid = __builtin_amdgcn_readfirstlane(tid >> 6), lane = tid & 63, wr = wid >> 2, wc = wid & 3, fr = lane & 15, fq = lane >> 4;
;     const int K = g.K, nt = K / BK;
;     unsigned voffA[2], voffB[2];
; #pragma unroll
;     for (int i = 0; i < 2; ++i) { int R, C; stage_rc(tid * 16 + i * 8192, R, C); const int Rb = (R & ~31) + perm32(R & 31);
;         voffA[i] = (unsigned)(R * g.lda + C) * 2u; voffB[i] = (unsigned)(Rb * g.ldb + C) * 2u; }
;     const size_t kstep = (size_t)(BK * 2);
;     const size_t hstepA = (size_t)HALF * g.lda * 2, hstepB = (size_t)HALF * g.ldb * 2;
;     const size_t tstepA = 2 * hstepA, tstepB = 2 * hstepB;
;     const unsigned ldsw = (unsigned)wid * 1024u;
;     const int aoff = lds_byte(wr * 64 + fr, fq * 8), boff = lds_byte(wc * 32 + fr, fq * 8);
;     ...
;     PG8_STAGE(PG8_SB(0, 0), cB, voffB); PG8_STAGE(PG8_SB(0, 1), cB + hstepB, voffB); PG8_STAGE(PG8_SA(0, 0), cA, voffA); PG8_STAGE(PG8_SA(0, 1), cA + hstepA, voffA);
;     if (wr == 1) PG8_BAR;
;     PG8_WAIT_V(2); PG8_BAR;
;     PG8_STAGE(PG8_SB(1, 0), cB + kstep, voffB); PG8_STAGE(PG8_SA(1, 0), cA + kstep, voffA); PG8_STAGE(PG8_SB(1, 1), cB + hstepB + kstep, voffB);
;     PG8_WAIT_V(6); PG8_BAR;
.LBB0_1304:
	s_add_u32 s10, s50, 0x80000
	s_addc_u32 s11, s51, 0
	s_lshl_b32 s59, s4, 6
	s_lshl_b32 s1, s4, 13
	s_lshl_b32 s4, s5, 5
	s_mov_b64 s[12:13], 0x80
	s_and_b32 s60, s4, 0x60
	s_add_i32 m0, s35, 0x18000
	v_lshl_add_u64 v[6:7], v[6:7], 0, s[12:13]
	s_lshl_b32 s15, s60, 7
	s_waitcnt vmcnt(2)
	s_barrier
	global_load_lds_dwordx4 v[6:7], off
	v_lshl_add_u64 v[4:5], v[4:5], 0, s[12:13]
	s_add_i32 m0, s35, 0x1a000
	s_add_i32 s61, s35, 0x8000
	s_add_i32 s62, s35, 0xa000
	global_load_lds_dwordx4 v[4:5], off
	v_lshl_add_u64 v[0:1], v[0:1], 0, s[12:13]
	s_mov_b32 m0, s61
	s_add_u32 s4, s42, 0x80080
	global_load_lds_dwordx4 v[0:1], off
	v_lshl_add_u64 v[0:1], v[2:3], 0, s[12:13]
	s_mov_b32 m0, s62
	s_addc_u32 s5, s43, 0
	global_load_lds_dwordx4 v[0:1], off
	s_add_i32 m0, s35, 0x1c000
	global_load_lds_dwordx4 v146, s[4:5]
	s_add_i32 m0, s35, 0x1e000
	v_bfe_u32 v177, v176, 4, 2
	global_load_lds_dwordx4 v150, s[4:5]
	v_and_b32_e32 v180, 15, v176
	v_lshlrev_b32_e32 v0, 4, v177
	v_lshlrev_b32_e32 v2, 2, v176
	v_lshl_or_b32 v1, v180, 6, v0
	v_and_b32_e32 v2, 32, v2
	v_bitop3_b32 v1, v1, s1, v2 bitop3:0xde
	v_lshlrev_b32_e32 v3, 6, v176
	s_movk_i32 s1, 0x3c0
	v_and_or_b32 v0, v3, s1, v0
	v_bitop3_b32 v181, s15, v0, v2 bitop3:0xf6
	v_lshlrev_b32_e32 v0, 10, v176
	v_and_b32_e32 v0, 0xe0000, v0
	v_lshlrev_b32_e32 v2, 13, v10
	v_or3_b32 v0, v8, v0, v2
	v_add_u32_e32 v152, v0, v9
	v_lshlrev_b32_e32 v0, 6, v11
	v_and_b32_e32 v0, 0x1e0000, v0
	s_waitcnt vmcnt(6)
	s_cmpk_lt_u32 s14, 0x100
	v_or3_b32 v0, v8, v0, v2
	s_cselect_b64 s[14:15], -1, 0
	v_add_u32_e32 v154, v0, v9
	s_add_i32 s68, 0, 0x10000
	s_add_i32 s69, 0, 0x14000
	v_mbcnt_lo_u32_b32 v0, -1, 0
	s_ashr_i32 s63, s74, 31
	s_mov_b32 s64, s74
	s_ashr_i32 s65, s2, 31
	v_mov_b32_e32 v153, v147
	v_mov_b32_e32 v155, v147
	v_mov_b64_e32 v[156:157], 0x200
	v_mov_b64_e32 v[158:159], 0x1ff
	v_add_u32_e32 v182, s68, v181
	v_add_u32_e32 v183, s69, v181
	v_add_u32_e32 v184, 0, v1
	v_mbcnt_hi_u32_b32 v185, -1, v0
	s_barrier
	s_branch .LBB0_1307

; #define PG8_STAGE(bufoff, gbase, voff) do { _Pragma("unroll") for (int _i = 0; _i < 2; ++_i) \
;         __builtin_amdgcn_global_load_lds((const unsigned*)((const char*)(gbase) + (voff)[_i]), (LAS unsigned*)(lds + (bufoff) + ldsw + _i * 8192), 16, 0, 0); } while (0)
; #define PG8_LDA(dst, b, h) do { _Pragma("unroll") for (int m = 0; m < 4; ++m) _Pragma("unroll") for (int k = 0; k < 2; ++k) dst[m][k] = *(const LAS bf16x8*)(lds + PG8_SA(b, h) + aoff + m * 2048 + k * 1024); } while (0)
; #define PG8_LDB(dst, b, h) do { _Pragma("unroll") for (int n = 0; n < 2; ++n) _Pragma("unroll") for (int k = 0; k < 2; ++k) dst[n][k] = *(const LAS bf16x8*)(lds + PG8_SB(b, h) + boff + n * 2048 + k * 1024); } while (0)
; #define PG8_MMA(ai, bj, At, Bt) do { __builtin_amdgcn_s_setprio(1); _Pragma("unroll") for (int m = 0; m < 4; ++m) _Pragma("unroll") for (int n = 0; n < 2; ++n) _Pragma("unroll") for (int k = 0; k < 2; ++k) \
;         acc[ai][bj][m][n] = __builtin_amdgcn_mfma_f32_16x16x32_bf16(Bt[n][k], At[m][k], acc[ai][bj][m][n], 0, 0, 0); __builtin_amdgcn_s_setprio(0); } while (0)
; #define PG8_BAR __builtin_amdgcn_s_barrier()
; template <class Epi>
; __device__ __forceinline__ void gemm_phase(LAS unsigned char* lds, const Gemm g, const StaticOrder& S, const Epi& E) {
;     ...
;         const bool has_next = S.next(ui + 1, nxt);
;         const char* nA = has_next ? (const char*)g.A + (size_t)nxt.pm * tstepA : cA; const char* nB = has_next ? (const char*)g.Bt + (size_t)nxt.pn * tstepB : cB;
; #pragma nounroll
;         for (int t = 0; t < nt; t += 2) {
;             const bool last = (t == nt - 2);
;             const char* a1 = cA + (size_t)(t + 1) * kstep;
;             const char* a2 = last ? nA : cA + (size_t)(t + 2) * kstep; const char* b2 = last ? nB : cB + (size_t)(t + 2) * kstep;
;             const char* a3 = a2 + kstep; const char* b3 = b2 + kstep;
;             PG8_LDB(B0, 0, 0); PG8_LDB(B1, 0, 1); PG8_SCHED; PG8_LDA(At, 0, 0); PG8_STAGE(PG8_SA(1, 1), a1 + hstepA, voffA);
;             PG8_WAIT_V(8); PG8_WAIT_L(0); PG8_BAR; PG8_MMA(0, 0, At, B0); PG8_MMA(0, 1, At, B1); PG8_BAR; PG8_SCHED;
;             PG8_LDA(At, 0, 1); PG8_STAGE(PG8_SB(0, 0), b2, voffB); PG8_STAGE(PG8_SB(0, 1), b2 + hstepB, voffB); PG8_STAGE(PG8_SA(0, 0), a2, voffA);
;             PG8_WAIT_V(8); PG8_WAIT_L(0); PG8_BAR; PG8_MMA(1, 0, At, B0); PG8_MMA(1, 1, At, B1); PG8_BAR; PG8_SCHED;
.LBB0_1313:
	s_ashr_i32 s19, s18, 31
	s_lshl_b64 s[20:21], s[18:19], 21
	s_add_u32 s20, s26, s20
	s_addc_u32 s21, s27, s21
	s_and_b64 s[22:23], s[4:5], exec
	s_cselect_b32 s1, s21, s39
	s_cselect_b32 s19, s20, s38
	s_ashr_i32 s17, s16, 31
	s_lshl_b64 s[22:23], s[16:17], 20
	s_add_u32 s22, s3, s22
	s_addc_u32 s23, s33, s23
	s_and_b64 s[52:53], s[4:5], exec
	s_cselect_b32 s17, s23, s43
	s_cselect_b32 s70, s22, s42
	s_add_u32 s38, s38, 0x100080
	s_addc_u32 s39, s39, 0
	s_add_u32 s71, s42, 0x100
	s_addc_u32 s72, s43, 0
	s_mov_b32 s73, -2
	s_waitcnt lgkmcnt(0)
	ds_read_b128 v[128:131], v182
	ds_read_b128 v[132:135], v182 offset:1024
	ds_read_b128 v[136:139], v182 offset:2048
	ds_read_b128 v[140:143], v182 offset:3072
	ds_read_b128 v[160:163], v183
	ds_read_b128 v[164:167], v183 offset:1024
	ds_read_b128 v[168:171], v183 offset:2048
	ds_read_b128 v[172:175], v183 offset:3072
	s_add_u32 s42, s38, 0xfff00080
	s_addc_u32 s43, s39, -1
	s_cmp_eq_u32 s73, 28
	s_cselect_b32 s53, s1, s43
	s_cselect_b32 s52, s19, s42
	s_cselect_b32 s43, s17, s72
	s_cselect_b32 s42, s70, s71
	s_add_i32 m0, s35, 0xc000
	ds_read_b128 v[186:189], v184
	ds_read_b128 v[190:193], v184 offset:1024
	ds_read_b128 v[194:197], v184 offset:2048
	ds_read_b128 v[198:201], v184 offset:3072
	ds_read_b128 v[202:205], v184 offset:4096
	ds_read_b128 v[206:209], v184 offset:5120
	ds_read_b128 v[210:213], v184 offset:6144
	ds_read_b128 v[214:217], v184 offset:7168
	global_load_lds_dwordx4 v152, s[38:39]
	s_add_i32 m0, s35, 0xe000
	s_nop 0
	global_load_lds_dwordx4 v154, s[38:39]
	s_waitcnt vmcnt(8)
	s_waitcnt lgkmcnt(0)
	s_barrier
	s_setprio 1
	s_waitcnt lgkmcnt(0)
	v_mfma_f32_16x16x32_bf16 v[124:127], v[128:131], v[186:189], 0
	v_mfma_f32_16x16x32_bf16 v[120:123], v[136:139], v[186:189], 0
	v_mfma_f32_16x16x32_bf16 v[108:111], v[128:131], v[194:197], 0
	v_mfma_f32_16x16x32_bf16 v[104:107], v[136:139], v[194:197], 0
	v_mfma_f32_16x16x32_bf16 v[92:95], v[128:131], v[202:205], 0
	v_mfma_f32_16x16x32_bf16 v[88:91], v[136:139], v[202:205], 0
	v_mfma_f32_16x16x32_bf16 v[76:79], v[128:131], v[210:213], 0
	v_mfma_f32_16x16x32_bf16 v[72:75], v[136:139], v[210:213], 0
	v_mfma_f32_16x16x32_bf16 v[124:127], v[132:135], v[190:193], v[124:127]
	v_mfma_f32_16x16x32_bf16 v[120:123], v[140:143], v[190:193], v[120:123]
	v_mfma_f32_16x16x32_bf16 v[108:111], v[132:135], v[198:201], v[108:111]
	v_mfma_f32_16x16x32_bf16 v[104:107], v[140:143], v[198:201], v[104:107]
	v_mfma_f32_16x16x32_bf16 v[92:95], v[132:135], v[206:209], v[92:95]
	v_mfma_f32_16x16x32_bf16 v[88:91], v[140:143], v[206:209], v[88:91]
	v_mfma_f32_16x16x32_bf16 v[76:79], v[132:135], v[214:217], v[76:79]
	v_mfma_f32_16x16x32_bf16 v[72:75], v[140:143], v[214:217], v[72:75]
	s_setprio 0
	s_setprio 1
	v_mfma_f32_16x16x32_bf16 v[116:119], v[160:163], v[186:189], 0
	v_mfma_f32_16x16x32_bf16 v[112:115], v[168:171], v[186:189], 0
	v_mfma_f32_16x16x32_bf16 v[100:103], v[160:163], v[194:197], 0
	v_mfma_f32_16x16x32_bf16 v[96:99], v[168:171], v[194:197], 0
	v_mfma_f32_16x16x32_bf16 v[84:87], v[160:163], v[202:205], 0
	v_mfma_f32_16x16x32_bf16 v[80:83], v[168:171], v[202:205], 0
	v_mfma_f32_16x16x32_bf16 v[68:71], v[160:163], v[210:213], 0
	v_mfma_f32_16x16x32_bf16 v[64:67], v[168:171], v[210:213], 0
	v_mfma_f32_16x16x32_bf16 v[116:119], v[164:167], v[190:193], v[116:119]
	v_mfma_f32_16x16x32_bf16 v[112:115], v[172:175], v[190:193], v[112:115]
	v_mfma_f32_16x16x32_bf16 v[100:103], v[164:167], v[198:201], v[100:103]
	v_mfma_f32_16x16x32_bf16 v[96:99], v[172:175], v[198:201], v[96:99]
	v_mfma_f32_16x16x32_bf16 v[84:87], v[164:167], v[206:209], v[84:87]
	v_mfma_f32_16x16x32_bf16 v[80:83], v[172:175], v[206:209], v[80:83]
	v_mfma_f32_16x16x32_bf16 v[68:71], v[164:167], v[214:217], v[68:71]
	v_mfma_f32_16x16x32_bf16 v[64:67], v[172:175], v[214:217], v[64:67]
	s_setprio 0
	s_barrier
	s_add_i32 s74, s68, s54
	v_lshl_add_u64 v[178:179], s[42:43], 0, v[146:147]
	s_mov_b32 m0, s74
	ds_read_b128 v[186:189], v184 offset:16384
	ds_read_b128 v[190:193], v184 offset:17408
	ds_read_b128 v[194:197], v184 offset:18432
	ds_read_b128 v[198:201], v184 offset:19456
	ds_read_b128 v[202:205], v184 offset:20480
	ds_read_b128 v[206:209], v184 offset:21504
	ds_read_b128 v[210:213], v184 offset:22528
	ds_read_b128 v[214:217], v184 offset:23552
	global_load_lds_dwordx4 v[178:179], off
	s_add_i32 m0, s74, 0x2000
	s_add_u32 s74, s42, 0x80000
	v_lshl_add_u64 v[218:219], s[42:43], 0, v[150:151]
	s_addc_u32 s75, s43, 0
	s_add_i32 s76, s69, s54
	global_load_lds_dwordx4 v[218:219], off
	s_mov_b32 m0, s76
	v_lshl_add_u64 v[222:223], s[52:53], 0, v[148:149]
	global_load_lds_dwordx4 v146, s[74:75]
	s_add_i32 m0, s76, 0x2000
	s_nop 0
	global_load_lds_dwordx4 v150, s[74:75]
	v_lshl_add_u64 v[220:221], s[52:53], 0, v[144:145]
	s_mov_b32 m0, s35
	s_nop 0
	global_load_lds_dwordx4 v[220:221], off
	s_mov_b32 m0, s55
	s_nop 0
	global_load_lds_dwordx4 v[222:223], off
	s_waitcnt vmcnt(8)
	s_waitcnt lgkmcnt(0)
	s_barrier
; #define PG8_STAGE(bufoff, gbase, voff) do { _Pragma("unroll") for (int _i = 0; _i < 2; ++_i) \
;         __builtin_amdgcn_global_load_lds((const unsigned*)((const char*)(gbase) + (voff)[_i]), (LAS unsigned*)(lds + (bufoff) + ldsw + _i * 8192), 16, 0, 0); } while (0)
; #define PG8_LDA(dst, b, h) do { _Pragma("unroll") for (int m = 0; m < 4; ++m) _Pragma("unroll") for (int k = 0; k < 2; ++k) dst[m][k] = *(const LAS bf16x8*)(lds + PG8_SA(b, h) + aoff + m * 2048 + k * 1024); } while (0)
; #define PG8_LDB(dst, b, h) do { _Pragma("unroll") for (int n = 0; n < 2; ++n) _Pragma("unroll") for (int k = 0; k < 2; ++k) dst[n][k] = *(const LAS bf16x8*)(lds + PG8_SB(b, h) + boff + n * 2048 + k * 1024); } while (0)
; #define PG8_MMA(ai, bj, At, Bt) do { __builtin_amdgcn_s_setprio(1); _Pragma("unroll") for (int m = 0; m < 4; ++m) _Pragma("unroll") for (int n = 0; n < 2; ++n) _Pragma("unroll") for (int k = 0; k < 2; ++k) \
;         acc[ai][bj][m][n] = __builtin_amdgcn_mfma_f32_16x16x32_bf16(Bt[n][k], At[m][k], acc[ai][bj][m][n], 0, 0, 0); __builtin_amdgcn_s_setprio(0); } while (0)
; #define PG8_WAIT_V(n) asm volatile("s_waitcnt vmcnt(" #n ")" ::: "memory")
; #define PG8_WAIT_L(n) asm volatile("s_waitcnt lgkmcnt(" #n ")" ::: "memory")
; #define PG8_BAR __builtin_amdgcn_s_barrier()
; #define PG8_SCHED __builtin_amdgcn_sched_barrier(0)
; template <class Epi>
; __device__ __forceinline__ void gemm_phase(LAS unsigned char* lds, const Gemm g, const StaticOrder& S, const Epi& E) {
;     ...
;             PG8_WAIT_V(8); PG8_WAIT_L(0); PG8_BAR; PG8_MMA(1, 0, At, B0); PG8_MMA(1, 1, At, B1); PG8_BAR; PG8_SCHED;
;             PG8_LDB(B0, 1, 0); PG8_LDB(B1, 1, 1); PG8_SCHED; PG8_LDA(At, 1, 0); PG8_STAGE(PG8_SA(0, 1), a2 + hstepA, voffA);
;             PG8_WAIT_V(8); PG8_WAIT_L(0); PG8_BAR; PG8_MMA(0, 0, At, B0); PG8_MMA(0, 1, At, B1); PG8_BAR; PG8_SCHED;
	s_setprio 1
	s_waitcnt lgkmcnt(0)
	v_mfma_f32_16x16x32_bf16 v[60:63], v[128:131], v[186:189], 0
	v_mfma_f32_16x16x32_bf16 v[56:59], v[136:139], v[186:189], 0
	v_mfma_f32_16x16x32_bf16 v[44:47], v[128:131], v[194:197], 0
	v_mfma_f32_16x16x32_bf16 v[40:43], v[136:139], v[194:197], 0
	v_mfma_f32_16x16x32_bf16 v[28:31], v[128:131], v[202:205], 0
	v_mfma_f32_16x16x32_bf16 v[24:27], v[136:139], v[202:205], 0
	v_mfma_f32_16x16x32_bf16 v[12:15], v[128:131], v[210:213], 0
	v_mfma_f32_16x16x32_bf16 v[8:11], v[136:139], v[210:213], 0
	v_mfma_f32_16x16x32_bf16 v[60:63], v[132:135], v[190:193], v[60:63]
	v_mfma_f32_16x16x32_bf16 v[56:59], v[140:143], v[190:193], v[56:59]
	v_mfma_f32_16x16x32_bf16 v[44:47], v[132:135], v[198:201], v[44:47]
	v_mfma_f32_16x16x32_bf16 v[40:43], v[140:143], v[198:201], v[40:43]
	v_mfma_f32_16x16x32_bf16 v[28:31], v[132:135], v[206:209], v[28:31]
	v_mfma_f32_16x16x32_bf16 v[24:27], v[140:143], v[206:209], v[24:27]
	v_mfma_f32_16x16x32_bf16 v[12:15], v[132:135], v[214:217], v[12:15]
	v_mfma_f32_16x16x32_bf16 v[8:11], v[140:143], v[214:217], v[8:11]
	s_setprio 0
	s_setprio 1
	v_mfma_f32_16x16x32_bf16 v[52:55], v[160:163], v[186:189], 0
	v_mfma_f32_16x16x32_bf16 v[48:51], v[168:171], v[186:189], 0
	v_mfma_f32_16x16x32_bf16 v[36:39], v[160:163], v[194:197], 0
	v_mfma_f32_16x16x32_bf16 v[32:35], v[168:171], v[194:197], 0
	v_mfma_f32_16x16x32_bf16 v[20:23], v[160:163], v[202:205], 0
	v_mfma_f32_16x16x32_bf16 v[16:19], v[168:171], v[202:205], 0
	v_mfma_f32_16x16x32_bf16 v[4:7], v[160:163], v[210:213], 0
	v_mfma_f32_16x16x32_bf16 v[0:3], v[168:171], v[210:213], 0
	v_mfma_f32_16x16x32_bf16 v[52:55], v[164:167], v[190:193], v[52:55]
	v_mfma_f32_16x16x32_bf16 v[48:51], v[172:175], v[190:193], v[48:51]
	v_mfma_f32_16x16x32_bf16 v[36:39], v[164:167], v[198:201], v[36:39]
	v_mfma_f32_16x16x32_bf16 v[32:35], v[172:175], v[198:201], v[32:35]
	v_mfma_f32_16x16x32_bf16 v[20:23], v[164:167], v[206:209], v[20:23]
	v_mfma_f32_16x16x32_bf16 v[16:19], v[172:175], v[206:209], v[16:19]
	v_mfma_f32_16x16x32_bf16 v[4:7], v[164:167], v[214:217], v[4:7]
	v_mfma_f32_16x16x32_bf16 v[0:3], v[172:175], v[214:217], v[0:3]
	s_setprio 0
	s_barrier
	s_add_i32 s74, 0, 0x18000
	s_add_i32 s75, 0, 0x1c000
	v_add_u32_e32 v140, s74, v181
	v_add_u32_e32 v172, s75, v181
	ds_read_b128 v[128:131], v140
	ds_read_b128 v[132:135], v140 offset:1024
	ds_read_b128 v[136:139], v140 offset:2048
	ds_read_b128 v[140:143], v140 offset:3072
	ds_read_b128 v[160:163], v172
	ds_read_b128 v[164:167], v172 offset:1024
	ds_read_b128 v[168:171], v172 offset:2048
	ds_read_b128 v[172:175], v172 offset:3072
	s_add_u32 s52, s52, 0x100000
	s_addc_u32 s53, s53, 0
	s_mov_b32 m0, s56
	ds_read_b128 v[186:189], v184 offset:32768
	ds_read_b128 v[190:193], v184 offset:33792
	ds_read_b128 v[194:197], v184 offset:34816
	ds_read_b128 v[198:201], v184 offset:35840
	ds_read_b128 v[202:205], v184 offset:36864
	ds_read_b128 v[206:209], v184 offset:37888
	ds_read_b128 v[210:213], v184 offset:38912
	ds_read_b128 v[214:217], v184 offset:39936
	global_load_lds_dwordx4 v144, s[52:53]
	s_mov_b32 m0, s57
	s_nop 0
	global_load_lds_dwordx4 v148, s[52:53]
	s_waitcnt vmcnt(8)
	s_waitcnt lgkmcnt(0)
	s_barrier
	s_setprio 1
	s_waitcnt lgkmcnt(0)
	v_mfma_f32_16x16x32_bf16 v[124:127], v[128:131], v[186:189], v[124:127]
	v_mfma_f32_16x16x32_bf16 v[120:123], v[136:139], v[186:189], v[120:123]
	v_mfma_f32_16x16x32_bf16 v[108:111], v[128:131], v[194:197], v[108:111]
	v_mfma_f32_16x16x32_bf16 v[104:107], v[136:139], v[194:197], v[104:107]
	v_mfma_f32_16x16x32_bf16 v[92:95], v[128:131], v[202:205], v[92:95]
	v_mfma_f32_16x16x32_bf16 v[88:91], v[136:139], v[202:205], v[88:91]
	v_mfma_f32_16x16x32_bf16 v[76:79], v[128:131], v[210:213], v[76:79]
	v_mfma_f32_16x16x32_bf16 v[72:75], v[136:139], v[210:213], v[72:75]
	v_mfma_f32_16x16x32_bf16 v[124:127], v[132:135], v[190:193], v[124:127]
	v_mfma_f32_16x16x32_bf16 v[120:123], v[140:143], v[190:193], v[120:123]
	v_mfma_f32_16x16x32_bf16 v[108:111], v[132:135], v[198:201], v[108:111]
	v_mfma_f32_16x16x32_bf16 v[104:107], v[140:143], v[198:201], v[104:107]
	v_mfma_f32_16x16x32_bf16 v[92:95], v[132:135], v[206:209], v[92:95]
	v_mfma_f32_16x16x32_bf16 v[88:91], v[140:143], v[206:209], v[88:91]
	v_mfma_f32_16x16x32_bf16 v[76:79], v[132:135], v[214:217], v[76:79]
	v_mfma_f32_16x16x32_bf16 v[72:75], v[140:143], v[214:217], v[72:75]
	s_setprio 0
	s_setprio 1
	v_mfma_f32_16x16x32_bf16 v[116:119], v[160:163], v[186:189], v[116:119]
	v_mfma_f32_16x16x32_bf16 v[112:115], v[168:171], v[186:189], v[112:115]
	v_mfma_f32_16x16x32_bf16 v[100:103], v[160:163], v[194:197], v[100:103]
	v_mfma_f32_16x16x32_bf16 v[96:99], v[168:171], v[194:197], v[96:99]
	v_mfma_f32_16x16x32_bf16 v[84:87], v[160:163], v[202:205], v[84:87]
	v_mfma_f32_16x16x32_bf16 v[80:83], v[168:171], v[202:205], v[80:83]
	v_mfma_f32_16x16x32_bf16 v[68:71], v[160:163], v[210:213], v[68:71]
	v_mfma_f32_16x16x32_bf16 v[64:67], v[168:171], v[210:213], v[64:67]
	v_mfma_f32_16x16x32_bf16 v[116:119], v[164:167], v[190:193], v[116:119]
	v_mfma_f32_16x16x32_bf16 v[112:115], v[172:175], v[190:193], v[112:115]
	v_mfma_f32_16x16x32_bf16 v[100:103], v[164:167], v[198:201], v[100:103]
	v_mfma_f32_16x16x32_bf16 v[96:99], v[172:175], v[198:201], v[96:99]
	v_mfma_f32_16x16x32_bf16 v[84:87], v[164:167], v[206:209], v[84:87]
	v_mfma_f32_16x16x32_bf16 v[80:83], v[172:175], v[206:209], v[80:83]
	v_mfma_f32_16x16x32_bf16 v[68:71], v[164:167], v[214:217], v[68:71]
	v_mfma_f32_16x16x32_bf16 v[64:67], v[172:175], v[214:217], v[64:67]
	s_setprio 0
	s_barrier
; #define PG8_STAGE(bufoff, gbase, voff) do { _Pragma("unroll") for (int _i = 0; _i < 2; ++_i) \
;         __builtin_amdgcn_global_load_lds((const unsigned*)((const char*)(gbase) + (voff)[_i]), (LAS unsigned*)(lds + (bufoff) + ldsw + _i * 8192), 16, 0, 0); } while (0)
; #define PG8_LDA(dst, b, h) do { _Pragma("unroll") for (int m = 0; m < 4; ++m) _Pragma("unroll") for (int k = 0; k < 2; ++k) dst[m][k] = *(const LAS bf16x8*)(lds + PG8_SA(b, h) + aoff + m * 2048 + k * 1024); } while (0)
; #define PG8_LDB(dst, b, h) do { _Pragma("unroll") for (int n = 0; n < 2; ++n) _Pragma("unroll") for (int k = 0; k < 2; ++k) dst[n][k] = *(const LAS bf16x8*)(lds + PG8_SB(b, h) + boff + n * 2048 + k * 1024); } while (0)
; #define PG8_WAIT_V(n) asm volatile("s_waitcnt vmcnt(" #n ")" ::: "memory")
; #define PG8_BAR __builtin_amdgcn_s_barrier()
; template <class Epi>
; __device__ __forceinline__ void gemm_phase(LAS unsigned char* lds, const Gemm g, const StaticOrder& S, const Epi& E) {
;     ...
;         for (int t = 0; t < nt; t += 2) {
;             const bool last = (t == nt - 2);
;             const char* a1 = cA + (size_t)(t + 1) * kstep;
;             const char* a2 = last ? nA : cA + (size_t)(t + 2) * kstep; const char* b2 = last ? nB : cB + (size_t)(t + 2) * kstep;
;             const char* a3 = a2 + kstep; const char* b3 = b2 + kstep;
;             PG8_LDB(B0, 0, 0); PG8_LDB(B1, 0, 1); PG8_SCHED; PG8_LDA(At, 0, 0); PG8_STAGE(PG8_SA(1, 1), a1 + hstepA, voffA);
;             PG8_WAIT_V(8); PG8_WAIT_L(0); PG8_BAR; PG8_MMA(0, 0, At, B0); PG8_MMA(0, 1, At, B1); PG8_BAR; PG8_SCHED;
;             PG8_LDA(At, 0, 1); PG8_STAGE(PG8_SB(0, 0), b2, voffB); PG8_STAGE(PG8_SB(0, 1), b2 + hstepB, voffB); PG8_STAGE(PG8_SA(0, 0), a2, voffA);
;             PG8_WAIT_V(8); PG8_WAIT_L(0); PG8_BAR; PG8_MMA(1, 0, At, B0); PG8_MMA(1, 1, At, B1); PG8_BAR; PG8_SCHED;
;             PG8_LDB(B0, 1, 0); PG8_LDB(B1, 1, 1); PG8_SCHED; PG8_LDA(At, 1, 0); PG8_STAGE(PG8_SA(0, 1), a2 + hstepA, voffA);
;             PG8_WAIT_V(8); PG8_WAIT_L(0); PG8_BAR; PG8_MMA(0, 0, At, B0); PG8_MMA(0, 1, At, B1); PG8_BAR; PG8_SCHED;
;             PG8_LDA(At, 1, 1); PG8_STAGE(PG8_SB(1, 0), b3, voffB); PG8_STAGE(PG8_SB(1, 1), b3 + hstepB, voffB); PG8_STAGE(PG8_SA(1, 0), a3, voffA);
;             PG8_WAIT_V(8); PG8_WAIT_L(0); PG8_BAR; PG8_MMA(1, 0, At, B0); PG8_MMA(1, 1, At, B1); PG8_BAR; PG8_SCHED;
;         }
	s_add_i32 s52, s74, s54
	v_lshl_add_u64 v[178:179], v[178:179], 0, s[12:13]
	s_mov_b32 m0, s52
	ds_read_b128 v[186:189], v184 offset:49152
	ds_read_b128 v[190:193], v184 offset:50176
	ds_read_b128 v[194:197], v184 offset:51200
	ds_read_b128 v[198:201], v184 offset:52224
	ds_read_b128 v[202:205], v184 offset:53248
	ds_read_b128 v[206:209], v184 offset:54272
	ds_read_b128 v[210:213], v184 offset:55296
	ds_read_b128 v[214:217], v184 offset:56320
	global_load_lds_dwordx4 v[178:179], off
	s_add_i32 m0, s52, 0x2000
	s_add_u32 s42, s42, 0x80080
	v_lshl_add_u64 v[178:179], v[218:219], 0, s[12:13]
	s_addc_u32 s43, s43, 0
	s_add_i32 s52, s75, s54
	global_load_lds_dwordx4 v[178:179], off
	s_mov_b32 m0, s52
	s_nop 0
	global_load_lds_dwordx4 v146, s[42:43]
	s_add_i32 m0, s52, 0x2000
	s_nop 0
	global_load_lds_dwordx4 v150, s[42:43]
	v_lshl_add_u64 v[178:179], v[220:221], 0, s[12:13]
	s_mov_b32 m0, s61
	s_nop 0
	global_load_lds_dwordx4 v[178:179], off
	v_lshl_add_u64 v[178:179], v[222:223], 0, s[12:13]
	s_mov_b32 m0, s62
	s_nop 0
	global_load_lds_dwordx4 v[178:179], off
	s_waitcnt vmcnt(8)
	s_waitcnt lgkmcnt(0)
	s_barrier
	s_setprio 1
	s_waitcnt lgkmcnt(0)
	v_mfma_f32_16x16x32_bf16 v[60:63], v[128:131], v[186:189], v[60:63]
	v_mfma_f32_16x16x32_bf16 v[56:59], v[136:139], v[186:189], v[56:59]
	v_mfma_f32_16x16x32_bf16 v[44:47], v[128:131], v[194:197], v[44:47]
	v_mfma_f32_16x16x32_bf16 v[40:43], v[136:139], v[194:197], v[40:43]
	v_mfma_f32_16x16x32_bf16 v[28:31], v[128:131], v[202:205], v[28:31]
	v_mfma_f32_16x16x32_bf16 v[24:27], v[136:139], v[202:205], v[24:27]
	v_mfma_f32_16x16x32_bf16 v[12:15], v[128:131], v[210:213], v[12:15]
	v_mfma_f32_16x16x32_bf16 v[8:11], v[136:139], v[210:213], v[8:11]
	v_mfma_f32_16x16x32_bf16 v[60:63], v[132:135], v[190:193], v[60:63]
	v_mfma_f32_16x16x32_bf16 v[56:59], v[140:143], v[190:193], v[56:59]
	v_mfma_f32_16x16x32_bf16 v[44:47], v[132:135], v[198:201], v[44:47]
	v_mfma_f32_16x16x32_bf16 v[40:43], v[140:143], v[198:201], v[40:43]
	v_mfma_f32_16x16x32_bf16 v[28:31], v[132:135], v[206:209], v[28:31]
	v_mfma_f32_16x16x32_bf16 v[24:27], v[140:143], v[206:209], v[24:27]
	v_mfma_f32_16x16x32_bf16 v[12:15], v[132:135], v[214:217], v[12:15]
	v_mfma_f32_16x16x32_bf16 v[8:11], v[140:143], v[214:217], v[8:11]
	s_setprio 0
	s_setprio 1
	v_mfma_f32_16x16x32_bf16 v[52:55], v[160:163], v[186:189], v[52:55]
	v_mfma_f32_16x16x32_bf16 v[48:51], v[168:171], v[186:189], v[48:51]
	v_mfma_f32_16x16x32_bf16 v[36:39], v[160:163], v[194:197], v[36:39]
	v_mfma_f32_16x16x32_bf16 v[32:35], v[168:171], v[194:197], v[32:35]
	v_mfma_f32_16x16x32_bf16 v[20:23], v[160:163], v[202:205], v[20:23]
	v_mfma_f32_16x16x32_bf16 v[16:19], v[168:171], v[202:205], v[16:19]
	v_mfma_f32_16x16x32_bf16 v[4:7], v[160:163], v[210:213], v[4:7]
	v_mfma_f32_16x16x32_bf16 v[0:3], v[168:171], v[210:213], v[0:3]
	v_mfma_f32_16x16x32_bf16 v[52:55], v[164:167], v[190:193], v[52:55]
	v_mfma_f32_16x16x32_bf16 v[48:51], v[172:175], v[190:193], v[48:51]
	v_mfma_f32_16x16x32_bf16 v[36:39], v[164:167], v[198:201], v[36:39]
	v_mfma_f32_16x16x32_bf16 v[32:35], v[172:175], v[198:201], v[32:35]
	v_mfma_f32_16x16x32_bf16 v[20:23], v[164:167], v[206:209], v[20:23]
	v_mfma_f32_16x16x32_bf16 v[16:19], v[172:175], v[206:209], v[16:19]
	v_mfma_f32_16x16x32_bf16 v[4:7], v[164:167], v[214:217], v[4:7]
	v_mfma_f32_16x16x32_bf16 v[0:3], v[172:175], v[214:217], v[0:3]
	s_setprio 0
	s_barrier
	s_add_i32 s73, s73, 2
	s_add_u32 s38, s38, 0x100
	s_addc_u32 s39, s39, 0
	s_add_u32 s71, s71, 0x100
	s_addc_u32 s72, s72, 0
	s_cmp_gt_u32 s73, 29
.LBB0_1314:
	ds_read_b128 v[128:131], v182
	ds_read_b128 v[132:135], v182 offset:1024
	ds_read_b128 v[136:139], v182 offset:2048
	ds_read_b128 v[140:143], v182 offset:3072
	ds_read_b128 v[160:163], v183
	ds_read_b128 v[164:167], v183 offset:1024
	ds_read_b128 v[168:171], v183 offset:2048
	ds_read_b128 v[172:175], v183 offset:3072
	s_add_u32 s42, s38, 0xfff00080
	s_addc_u32 s43, s39, -1
	s_cmp_eq_u32 s73, 28
	s_cselect_b32 s53, s1, s43
	s_cselect_b32 s52, s19, s42
	s_cselect_b32 s43, s17, s72
	s_cselect_b32 s42, s70, s71
	s_add_i32 m0, s35, 0xc000
	ds_read_b128 v[186:189], v184
	ds_read_b128 v[190:193], v184 offset:1024
	ds_read_b128 v[194:197], v184 offset:2048
	ds_read_b128 v[198:201], v184 offset:3072
	ds_read_b128 v[202:205], v184 offset:4096
	ds_read_b128 v[206:209], v184 offset:5120
	ds_read_b128 v[210:213], v184 offset:6144
	ds_read_b128 v[214:217], v184 offset:7168
	global_load_lds_dwordx4 v152, s[38:39]
	s_add_i32 m0, s35, 0xe000
	s_nop 0
	global_load_lds_dwordx4 v154, s[38:39]
	s_waitcnt vmcnt(8)
	s_waitcnt lgkmcnt(0)
	s_barrier
; #define PG8_STAGE(bufoff, gbase, voff) do { _Pragma("unroll") for (int _i = 0; _i < 2; ++_i) \
;         __builtin_amdgcn_global_load_lds((const unsigned*)((const char*)(gbase) + (voff)[_i]), (LAS unsigned*)(lds + (bufoff) + ldsw + _i * 8192), 16, 0, 0); } while (0)
; #define PG8_LDA(dst, b, h) do { _Pragma("unroll") for (int m = 0; m < 4; ++m) _Pragma("unroll") for (int k = 0; k < 2; ++k) dst[m][k] = *(const LAS bf16x8*)(lds + PG8_SA(b, h) + aoff + m * 2048 + k * 1024); } while (0)
; #define PG8_LDB(dst, b, h) do { _Pragma("unroll") for (int n = 0; n < 2; ++n) _Pragma("unroll") for (int k = 0; k < 2; ++k) dst[n][k] = *(const LAS bf16x8*)(lds + PG8_SB(b, h) + boff + n * 2048 + k * 1024); } while (0)
; #define PG8_MMA(ai, bj, At, Bt) do { __builtin_amdgcn_s_setprio(1); _Pragma("unroll") for (int m = 0; m < 4; ++m) _Pragma("unroll") for (int n = 0; n < 2; ++n) _Pragma("unroll") for (int k = 0; k < 2; ++k) \
;         acc[ai][bj][m][n] = __builtin_amdgcn_mfma_f32_16x16x32_bf16(Bt[n][k], At[m][k], acc[ai][bj][m][n], 0, 0, 0); __builtin_amdgcn_s_setprio(0); } while (0)
; #define PG8_WAIT_V(n) asm volatile("s_waitcnt vmcnt(" #n ")" ::: "memory")
; #define PG8_WAIT_L(n) asm volatile("s_waitcnt lgkmcnt(" #n ")" ::: "memory")
; #define PG8_BAR __builtin_amdgcn_s_barrier()
; #define PG8_SCHED __builtin_amdgcn_sched_barrier(0)
; template <class Epi>
; __device__ __forceinline__ void gemm_phase(LAS unsigned char* lds, const Gemm g, const StaticOrder& S, const Epi& E) {
;     ...
;             PG8_LDB(B0, 0, 0); PG8_LDB(B1, 0, 1); PG8_SCHED; PG8_LDA(At, 0, 0); PG8_STAGE(PG8_SA(1, 1), a1 + hstepA, voffA);
;             PG8_WAIT_V(8); PG8_WAIT_L(0); PG8_BAR; PG8_MMA(0, 0, At, B0); PG8_MMA(0, 1, At, B1); PG8_BAR; PG8_SCHED;
;             PG8_LDA(At, 0, 1); PG8_STAGE(PG8_SB(0, 0), b2, voffB); PG8_STAGE(PG8_SB(0, 1), b2 + hstepB, voffB); PG8_STAGE(PG8_SA(0, 0), a2, voffA);
;             PG8_WAIT_V(8); PG8_WAIT_L(0); PG8_BAR; PG8_MMA(1, 0, At, B0); PG8_MMA(1, 1, At, B1); PG8_BAR; PG8_SCHED;
	s_setprio 1
	s_waitcnt lgkmcnt(0)
	v_mfma_f32_16x16x32_bf16 v[124:127], v[128:131], v[186:189], v[124:127]
	v_mfma_f32_16x16x32_bf16 v[120:123], v[136:139], v[186:189], v[120:123]
	v_mfma_f32_16x16x32_bf16 v[108:111], v[128:131], v[194:197], v[108:111]
	v_mfma_f32_16x16x32_bf16 v[104:107], v[136:139], v[194:197], v[104:107]
	v_mfma_f32_16x16x32_bf16 v[92:95], v[128:131], v[202:205], v[92:95]
	v_mfma_f32_16x16x32_bf16 v[88:91], v[136:139], v[202:205], v[88:91]
	v_mfma_f32_16x16x32_bf16 v[76:79], v[128:131], v[210:213], v[76:79]
	v_mfma_f32_16x16x32_bf16 v[72:75], v[136:139], v[210:213], v[72:75]
	v_mfma_f32_16x16x32_bf16 v[124:127], v[132:135], v[190:193], v[124:127]
	v_mfma_f32_16x16x32_bf16 v[120:123], v[140:143], v[190:193], v[120:123]
	v_mfma_f32_16x16x32_bf16 v[108:111], v[132:135], v[198:201], v[108:111]
	v_mfma_f32_16x16x32_bf16 v[104:107], v[140:143], v[198:201], v[104:107]
	v_mfma_f32_16x16x32_bf16 v[92:95], v[132:135], v[206:209], v[92:95]
	v_mfma_f32_16x16x32_bf16 v[88:91], v[140:143], v[206:209], v[88:91]
	v_mfma_f32_16x16x32_bf16 v[76:79], v[132:135], v[214:217], v[76:79]
	v_mfma_f32_16x16x32_bf16 v[72:75], v[140:143], v[214:217], v[72:75]
	s_setprio 0
	s_setprio 1
	v_mfma_f32_16x16x32_bf16 v[116:119], v[160:163], v[186:189], v[116:119]
	v_mfma_f32_16x16x32_bf16 v[112:115], v[168:171], v[186:189], v[112:115]
	v_mfma_f32_16x16x32_bf16 v[100:103], v[160:163], v[194:197], v[100:103]
	v_mfma_f32_16x16x32_bf16 v[96:99], v[168:171], v[194:197], v[96:99]
	v_mfma_f32_16x16x32_bf16 v[84:87], v[160:163], v[202:205], v[84:87]
	v_mfma_f32_16x16x32_bf16 v[80:83], v[168:171], v[202:205], v[80:83]
	v_mfma_f32_16x16x32_bf16 v[68:71], v[160:163], v[210:213], v[68:71]
	v_mfma_f32_16x16x32_bf16 v[64:67], v[168:171], v[210:213], v[64:67]
	v_mfma_f32_16x16x32_bf16 v[116:119], v[164:167], v[190:193], v[116:119]
	v_mfma_f32_16x16x32_bf16 v[112:115], v[172:175], v[190:193], v[112:115]
	v_mfma_f32_16x16x32_bf16 v[100:103], v[164:167], v[198:201], v[100:103]
	v_mfma_f32_16x16x32_bf16 v[96:99], v[172:175], v[198:201], v[96:99]
	v_mfma_f32_16x16x32_bf16 v[84:87], v[164:167], v[206:209], v[84:87]
	v_mfma_f32_16x16x32_bf16 v[80:83], v[172:175], v[206:209], v[80:83]
	v_mfma_f32_16x16x32_bf16 v[68:71], v[164:167], v[214:217], v[68:71]
	v_mfma_f32_16x16x32_bf16 v[64:67], v[172:175], v[214:217], v[64:67]
	s_setprio 0
	s_barrier
	s_add_i32 s74, s68, s54
	v_lshl_add_u64 v[178:179], s[42:43], 0, v[146:147]
	s_mov_b32 m0, s74
	ds_read_b128 v[186:189], v184 offset:16384
	ds_read_b128 v[190:193], v184 offset:17408
	ds_read_b128 v[194:197], v184 offset:18432
	ds_read_b128 v[198:201], v184 offset:19456
	ds_read_b128 v[202:205], v184 offset:20480
	ds_read_b128 v[206:209], v184 offset:21504
	ds_read_b128 v[210:213], v184 offset:22528
	ds_read_b128 v[214:217], v184 offset:23552
	global_load_lds_dwordx4 v[178:179], off
	s_add_i32 m0, s74, 0x2000
	s_add_u32 s74, s42, 0x80000
	v_lshl_add_u64 v[218:219], s[42:43], 0, v[150:151]
	s_addc_u32 s75, s43, 0
	s_add_i32 s76, s69, s54
	global_load_lds_dwordx4 v[218:219], off
	s_mov_b32 m0, s76
	v_lshl_add_u64 v[222:223], s[52:53], 0, v[148:149]
	global_load_lds_dwordx4 v146, s[74:75]
	s_add_i32 m0, s76, 0x2000
	s_nop 0
	global_load_lds_dwordx4 v150, s[74:75]
	v_lshl_add_u64 v[220:221], s[52:53], 0, v[144:145]
	s_mov_b32 m0, s35
	s_nop 0
	global_load_lds_dwordx4 v[220:221], off
	s_mov_b32 m0, s55
	s_nop 0
	global_load_lds_dwordx4 v[222:223], off
	s_waitcnt vmcnt(8)
	s_waitcnt lgkmcnt(0)
	s_barrier
	s_setprio 1
	s_waitcnt lgkmcnt(0)
	v_mfma_f32_16x16x32_bf16 v[60:63], v[128:131], v[186:189], v[60:63]
	v_mfma_f32_16x16x32_bf16 v[56:59], v[136:139], v[186:189], v[56:59]
	v_mfma_f32_16x16x32_bf16 v[44:47], v[128:131], v[194:197], v[44:47]
	v_mfma_f32_16x16x32_bf16 v[40:43], v[136:139], v[194:197], v[40:43]
	v_mfma_f32_16x16x32_bf16 v[28:31], v[128:131], v[202:205], v[28:31]
	v_mfma_f32_16x16x32_bf16 v[24:27], v[136:139], v[202:205], v[24:27]
	v_mfma_f32_16x16x32_bf16 v[12:15], v[128:131], v[210:213], v[12:15]
	v_mfma_f32_16x16x32_bf16 v[8:11], v[136:139], v[210:213], v[8:11]
	v_mfma_f32_16x16x32_bf16 v[60:63], v[132:135], v[190:193], v[60:63]
	v_mfma_f32_16x16x32_bf16 v[56:59], v[140:143], v[190:193], v[56:59]
	v_mfma_f32_16x16x32_bf16 v[44:47], v[132:135], v[198:201], v[44:47]
	v_mfma_f32_16x16x32_bf16 v[40:43], v[140:143], v[198:201], v[40:43]
	v_mfma_f32_16x16x32_bf16 v[28:31], v[132:135], v[206:209], v[28:31]
	v_mfma_f32_16x16x32_bf16 v[24:27], v[140:143], v[206:209], v[24:27]
	v_mfma_f32_16x16x32_bf16 v[12:15], v[132:135], v[214:217], v[12:15]
	v_mfma_f32_16x16x32_bf16 v[8:11], v[140:143], v[214:217], v[8:11]
	s_setprio 0
	s_setprio 1
	v_mfma_f32_16x16x32_bf16 v[52:55], v[160:163], v[186:189], v[52:55]
	v_mfma_f32_16x16x32_bf16 v[48:51], v[168:171], v[186:189], v[48:51]
	v_mfma_f32_16x16x32_bf16 v[36:39], v[160:163], v[194:197], v[36:39]
	v_mfma_f32_16x16x32_bf16 v[32:35], v[168:171], v[194:197], v[32:35]
	v_mfma_f32_16x16x32_bf16 v[20:23], v[160:163], v[202:205], v[20:23]
	v_mfma_f32_16x16x32_bf16 v[16:19], v[168:171], v[202:205], v[16:19]
	v_mfma_f32_16x16x32_bf16 v[4:7], v[160:163], v[210:213], v[4:7]
	v_mfma_f32_16x16x32_bf16 v[0:3], v[168:171], v[210:213], v[0:3]
	v_mfma_f32_16x16x32_bf16 v[52:55], v[164:167], v[190:193], v[52:55]
	v_mfma_f32_16x16x32_bf16 v[48:51], v[172:175], v[190:193], v[48:51]
	v_mfma_f32_16x16x32_bf16 v[36:39], v[164:167], v[198:201], v[36:39]
	v_mfma_f32_16x16x32_bf16 v[32:35], v[172:175], v[198:201], v[32:35]
	v_mfma_f32_16x16x32_bf16 v[20:23], v[164:167], v[206:209], v[20:23]
	v_mfma_f32_16x16x32_bf16 v[16:19], v[172:175], v[206:209], v[16:19]
	v_mfma_f32_16x16x32_bf16 v[4:7], v[164:167], v[214:217], v[4:7]
	v_mfma_f32_16x16x32_bf16 v[0:3], v[172:175], v[214:217], v[0:3]
	s_setprio 0
	s_barrier
; #define PG8_STAGE(bufoff, gbase, voff) do { _Pragma("unroll") for (int _i = 0; _i < 2; ++_i) \
;         __builtin_amdgcn_global_load_lds((const unsigned*)((const char*)(gbase) + (voff)[_i]), (LAS unsigned*)(lds + (bufoff) + ldsw + _i * 8192), 16, 0, 0); } while (0)
; #define PG8_LDA(dst, b, h) do { _Pragma("unroll") for (int m = 0; m < 4; ++m) _Pragma("unroll") for (int k = 0; k < 2; ++k) dst[m][k] = *(const LAS bf16x8*)(lds + PG8_SA(b, h) + aoff + m * 2048 + k * 1024); } while (0)
; #define PG8_LDB(dst, b, h) do { _Pragma("unroll") for (int n = 0; n < 2; ++n) _Pragma("unroll") for (int k = 0; k < 2; ++k) dst[n][k] = *(const LAS bf16x8*)(lds + PG8_SB(b, h) + boff + n * 2048 + k * 1024); } while (0)
; #define PG8_MMA(ai, bj, At, Bt) do { __builtin_amdgcn_s_setprio(1); _Pragma("unroll") for (int m = 0; m < 4; ++m) _Pragma("unroll") for (int n = 0; n < 2; ++n) _Pragma("unroll") for (int k = 0; k < 2; ++k) \
;         acc[ai][bj][m][n] = __builtin_amdgcn_mfma_f32_16x16x32_bf16(Bt[n][k], At[m][k], acc[ai][bj][m][n], 0, 0, 0); __builtin_amdgcn_s_setprio(0); } while (0)
; #define PG8_WAIT_V(n) asm volatile("s_waitcnt vmcnt(" #n ")" ::: "memory")
; #define PG8_WAIT_L(n) asm volatile("s_waitcnt lgkmcnt(" #n ")" ::: "memory")
; #define PG8_BAR __builtin_amdgcn_s_barrier()
; #define PG8_SCHED __builtin_amdgcn_sched_barrier(0)
; template <class Epi>
; __device__ __forceinline__ void gemm_phase(LAS unsigned char* lds, const Gemm g, const StaticOrder& S, const Epi& E) {
;     ...
;             PG8_LDB(B0, 1, 0); PG8_LDB(B1, 1, 1); PG8_SCHED; PG8_LDA(At, 1, 0); PG8_STAGE(PG8_SA(0, 1), a2 + hstepA, voffA);
;             PG8_WAIT_V(8); PG8_WAIT_L(0); PG8_BAR; PG8_MMA(0, 0, At, B0); PG8_MMA(0, 1, At, B1); PG8_BAR; PG8_SCHED;
;             PG8_LDA(At, 1, 1); PG8_STAGE(PG8_SB(1, 0), b3, voffB); PG8_STAGE(PG8_SB(1, 1), b3 + hstepB, voffB); PG8_STAGE(PG8_SA(1, 0), a3, voffA);
;             PG8_WAIT_V(8); PG8_WAIT_L(0); PG8_BAR; PG8_MMA(1, 0, At, B0); PG8_MMA(1, 1, At, B1); PG8_BAR; PG8_SCHED;
;         }
	s_add_i32 s74, 0, 0x18000
	s_add_i32 s75, 0, 0x1c000
	v_add_u32_e32 v140, s74, v181
	v_add_u32_e32 v172, s75, v181
	ds_read_b128 v[128:131], v140
	ds_read_b128 v[132:135], v140 offset:1024
	ds_read_b128 v[136:139], v140 offset:2048
	ds_read_b128 v[140:143], v140 offset:3072
	ds_read_b128 v[160:163], v172
	ds_read_b128 v[164:167], v172 offset:1024
	ds_read_b128 v[168:171], v172 offset:2048
	ds_read_b128 v[172:175], v172 offset:3072
	s_add_u32 s52, s52, 0x100000
	s_addc_u32 s53, s53, 0
	s_mov_b32 m0, s56
	ds_read_b128 v[186:189], v184 offset:32768
	ds_read_b128 v[190:193], v184 offset:33792
	ds_read_b128 v[194:197], v184 offset:34816
	ds_read_b128 v[198:201], v184 offset:35840
	ds_read_b128 v[202:205], v184 offset:36864
	ds_read_b128 v[206:209], v184 offset:37888
	ds_read_b128 v[210:213], v184 offset:38912
	ds_read_b128 v[214:217], v184 offset:39936
	global_load_lds_dwordx4 v144, s[52:53]
	s_mov_b32 m0, s57
	s_nop 0
	global_load_lds_dwordx4 v148, s[52:53]
	s_waitcnt vmcnt(8)
	s_waitcnt lgkmcnt(0)
	s_barrier
	s_setprio 1
	s_waitcnt lgkmcnt(0)
	v_mfma_f32_16x16x32_bf16 v[124:127], v[128:131], v[186:189], v[124:127]
	v_mfma_f32_16x16x32_bf16 v[120:123], v[136:139], v[186:189], v[120:123]
	v_mfma_f32_16x16x32_bf16 v[108:111], v[128:131], v[194:197], v[108:111]
	v_mfma_f32_16x16x32_bf16 v[104:107], v[136:139], v[194:197], v[104:107]
	v_mfma_f32_16x16x32_bf16 v[92:95], v[128:131], v[202:205], v[92:95]
	v_mfma_f32_16x16x32_bf16 v[88:91], v[136:139], v[202:205], v[88:91]
	v_mfma_f32_16x16x32_bf16 v[76:79], v[128:131], v[210:213], v[76:79]
	v_mfma_f32_16x16x32_bf16 v[72:75], v[136:139], v[210:213], v[72:75]
	v_mfma_f32_16x16x32_bf16 v[124:127], v[132:135], v[190:193], v[124:127]
	v_mfma_f32_16x16x32_bf16 v[120:123], v[140:143], v[190:193], v[120:123]
	v_mfma_f32_16x16x32_bf16 v[108:111], v[132:135], v[198:201], v[108:111]
	v_mfma_f32_16x16x32_bf16 v[104:107], v[140:143], v[198:201], v[104:107]
	v_mfma_f32_16x16x32_bf16 v[92:95], v[132:135], v[206:209], v[92:95]
	v_mfma_f32_16x16x32_bf16 v[88:91], v[140:143], v[206:209], v[88:91]
	v_mfma_f32_16x16x32_bf16 v[76:79], v[132:135], v[214:217], v[76:79]
	v_mfma_f32_16x16x32_bf16 v[72:75], v[140:143], v[214:217], v[72:75]
	s_setprio 0
	s_setprio 1
	v_mfma_f32_16x16x32_bf16 v[116:119], v[160:163], v[186:189], v[116:119]
	v_mfma_f32_16x16x32_bf16 v[112:115], v[168:171], v[186:189], v[112:115]
	v_mfma_f32_16x16x32_bf16 v[100:103], v[160:163], v[194:197], v[100:103]
	v_mfma_f32_16x16x32_bf16 v[96:99], v[168:171], v[194:197], v[96:99]
	v_mfma_f32_16x16x32_bf16 v[84:87], v[160:163], v[202:205], v[84:87]
	v_mfma_f32_16x16x32_bf16 v[80:83], v[168:171], v[202:205], v[80:83]
	v_mfma_f32_16x16x32_bf16 v[68:71], v[160:163], v[210:213], v[68:71]
	v_mfma_f32_16x16x32_bf16 v[64:67], v[168:171], v[210:213], v[64:67]
	v_mfma_f32_16x16x32_bf16 v[116:119], v[164:167], v[190:193], v[116:119]
	v_mfma_f32_16x16x32_bf16 v[112:115], v[172:175], v[190:193], v[112:115]
	v_mfma_f32_16x16x32_bf16 v[100:103], v[164:167], v[198:201], v[100:103]
	v_mfma_f32_16x16x32_bf16 v[96:99], v[172:175], v[198:201], v[96:99]
	v_mfma_f32_16x16x32_bf16 v[84:87], v[164:167], v[206:209], v[84:87]
	v_mfma_f32_16x16x32_bf16 v[80:83], v[172:175], v[206:209], v[80:83]
	v_mfma_f32_16x16x32_bf16 v[68:71], v[164:167], v[214:217], v[68:71]
	v_mfma_f32_16x16x32_bf16 v[64:67], v[172:175], v[214:217], v[64:67]
	s_setprio 0
	s_barrier
	s_add_i32 s52, s74, s54
	v_lshl_add_u64 v[178:179], v[178:179], 0, s[12:13]
	s_mov_b32 m0, s52
	ds_read_b128 v[186:189], v184 offset:49152
	ds_read_b128 v[190:193], v184 offset:50176
	ds_read_b128 v[194:197], v184 offset:51200
	ds_read_b128 v[198:201], v184 offset:52224
	ds_read_b128 v[202:205], v184 offset:53248
	ds_read_b128 v[206:209], v184 offset:54272
	ds_read_b128 v[210:213], v184 offset:55296
	ds_read_b128 v[214:217], v184 offset:56320
	global_load_lds_dwordx4 v[178:179], off
	s_add_i32 m0, s52, 0x2000
	s_add_u32 s42, s42, 0x80080
	v_lshl_add_u64 v[178:179], v[218:219], 0, s[12:13]
	s_addc_u32 s43, s43, 0
	s_add_i32 s52, s75, s54
	global_load_lds_dwordx4 v[178:179], off
	s_mov_b32 m0, s52
	s_nop 0
	global_load_lds_dwordx4 v146, s[42:43]
	s_add_i32 m0, s52, 0x2000
	s_nop 0
	global_load_lds_dwordx4 v150, s[42:43]
	v_lshl_add_u64 v[178:179], v[220:221], 0, s[12:13]
	s_mov_b32 m0, s61
	s_nop 0
	global_load_lds_dwordx4 v[178:179], off
	v_lshl_add_u64 v[178:179], v[222:223], 0, s[12:13]
	s_mov_b32 m0, s62
	s_nop 0
	global_load_lds_dwordx4 v[178:179], off
	s_waitcnt vmcnt(8)
	s_waitcnt lgkmcnt(0)
	s_barrier
	s_setprio 1
	s_waitcnt lgkmcnt(0)
	v_mfma_f32_16x16x32_bf16 v[60:63], v[128:131], v[186:189], v[60:63]
	v_mfma_f32_16x16x32_bf16 v[56:59], v[136:139], v[186:189], v[56:59]
	v_mfma_f32_16x16x32_bf16 v[44:47], v[128:131], v[194:197], v[44:47]
	v_mfma_f32_16x16x32_bf16 v[40:43], v[136:139], v[194:197], v[40:43]
	v_mfma_f32_16x16x32_bf16 v[28:31], v[128:131], v[202:205], v[28:31]
	v_mfma_f32_16x16x32_bf16 v[24:27], v[136:139], v[202:205], v[24:27]
	v_mfma_f32_16x16x32_bf16 v[12:15], v[128:131], v[210:213], v[12:15]
	v_mfma_f32_16x16x32_bf16 v[8:11], v[136:139], v[210:213], v[8:11]
	v_mfma_f32_16x16x32_bf16 v[60:63], v[132:135], v[190:193], v[60:63]
	v_mfma_f32_16x16x32_bf16 v[56:59], v[140:143], v[190:193], v[56:59]
	v_mfma_f32_16x16x32_bf16 v[44:47], v[132:135], v[198:201], v[44:47]
	v_mfma_f32_16x16x32_bf16 v[40:43], v[140:143], v[198:201], v[40:43]
	v_mfma_f32_16x16x32_bf16 v[28:31], v[132:135], v[206:209], v[28:31]
	v_mfma_f32_16x16x32_bf16 v[24:27], v[140:143], v[206:209], v[24:27]
	v_mfma_f32_16x16x32_bf16 v[12:15], v[132:135], v[214:217], v[12:15]
	v_mfma_f32_16x16x32_bf16 v[8:11], v[140:143], v[214:217], v[8:11]
	s_setprio 0
	s_setprio 1
	v_mfma_f32_16x16x32_bf16 v[52:55], v[160:163], v[186:189], v[52:55]
	v_mfma_f32_16x16x32_bf16 v[48:51], v[168:171], v[186:189], v[48:51]
	v_mfma_f32_16x16x32_bf16 v[36:39], v[160:163], v[194:197], v[36:39]
	v_mfma_f32_16x16x32_bf16 v[32:35], v[168:171], v[194:197], v[32:35]
	v_mfma_f32_16x16x32_bf16 v[20:23], v[160:163], v[202:205], v[20:23]
	v_mfma_f32_16x16x32_bf16 v[16:19], v[168:171], v[202:205], v[16:19]
	v_mfma_f32_16x16x32_bf16 v[4:7], v[160:163], v[210:213], v[4:7]
	v_mfma_f32_16x16x32_bf16 v[0:3], v[168:171], v[210:213], v[0:3]
	v_mfma_f32_16x16x32_bf16 v[52:55], v[164:167], v[190:193], v[52:55]
	v_mfma_f32_16x16x32_bf16 v[48:51], v[172:175], v[190:193], v[48:51]
	v_mfma_f32_16x16x32_bf16 v[36:39], v[164:167], v[198:201], v[36:39]
	v_mfma_f32_16x16x32_bf16 v[32:35], v[172:175], v[198:201], v[32:35]
	v_mfma_f32_16x16x32_bf16 v[20:23], v[164:167], v[206:209], v[20:23]
	v_mfma_f32_16x16x32_bf16 v[16:19], v[172:175], v[206:209], v[16:19]
	v_mfma_f32_16x16x32_bf16 v[4:7], v[164:167], v[214:217], v[4:7]
	v_mfma_f32_16x16x32_bf16 v[0:3], v[172:175], v[214:217], v[0:3]
	s_setprio 0
	s_barrier
	s_add_i32 s73, s73, 2
	s_add_u32 s38, s38, 0x100
	s_addc_u32 s39, s39, 0
	s_add_u32 s71, s71, 0x100
	s_addc_u32 s72, s72, 0
	s_cmp_gt_u32 s73, 29
	s_cbranch_scc0 .LBB0_1314
	s_and_b64 vcc, exec, s[14:15]
	s_cbranch_vccz .LBB0_1317
	s_barrier

; #define PG8_STAGE(bufoff, gbase, voff) do { _Pragma("unroll") for (int _i = 0; _i < 2; ++_i) \
;         __builtin_amdgcn_global_load_lds((const unsigned*)((const char*)(gbase) + (voff)[_i]), (LAS unsigned*)(lds + (bufoff) + ldsw + _i * 8192), 16, 0, 0); } while (0)
; #define PG8_WAIT_V(n) asm volatile("s_waitcnt vmcnt(" #n ")" ::: "memory")
; #define PG8_BAR __builtin_amdgcn_s_barrier()
; template <class Epi>
; __device__ __forceinline__ void gemm_phase(LAS unsigned char* lds, const Gemm g, const StaticOrder& S, const Epi& E) {
;     ...
;     const char* cA = (const char*)g.A + (size_t)cur.pm * tstepA; const char* cB = (const char*)g.Bt + (size_t)cur.pn * tstepB;
;     PG8_STAGE(PG8_SB(0, 0), cB, voffB); PG8_STAGE(PG8_SB(0, 1), cB + hstepB, voffB); PG8_STAGE(PG8_SA(0, 0), cA, voffA); PG8_STAGE(PG8_SA(0, 1), cA + hstepA, voffA);
;     if (wr == 1) PG8_BAR;
;     PG8_WAIT_V(2); PG8_BAR;
;     PG8_STAGE(PG8_SB(1, 0), cB + kstep, voffB); PG8_STAGE(PG8_SA(1, 0), cA + kstep, voffA); PG8_STAGE(PG8_SB(1, 1), cB + hstepB + kstep, voffB);
;     PG8_WAIT_V(6); PG8_BAR;
;     for (;;) {
;         const bool has_next = S.next(ui + 1, nxt);
;         const char* nA = has_next ? (const char*)g.A + (size_t)nxt.pm * tstepA : cA; const char* nB = has_next ? (const char*)g.Bt + (size_t)nxt.pn * tstepB : cB;
.LBB0_1397:
	s_add_u32 s18, s50, 0x80000
	s_addc_u32 s19, s51, 0
	s_add_u32 s20, s66, 0x10800
	s_addc_u32 s21, s67, 0
	s_add_u32 s22, s36, 0x5800
	s_mov_b64 s[34:35], 0x80
	s_addc_u32 s23, s37, 0
	s_lshl_b32 s63, s4, 6
	s_lshl_b32 s1, s4, 13
	s_lshl_b32 s4, s5, 5
	s_add_i32 m0, s53, 0x18000
	v_lshl_add_u64 v[6:7], v[6:7], 0, s[34:35]
	s_and_b32 s76, s4, 0x60
	s_waitcnt vmcnt(2)
	s_barrier
	global_load_lds_dwordx4 v[6:7], off
	v_lshl_add_u64 v[4:5], v[4:5], 0, s[34:35]
	s_add_i32 m0, s53, 0x1a000
	s_add_i32 s77, s53, 0x8000
	s_add_i32 s78, s53, 0xa000
	global_load_lds_dwordx4 v[4:5], off
	v_lshl_add_u64 v[0:1], v[0:1], 0, s[34:35]
	s_mov_b32 m0, s77
	s_add_u32 s4, s10, 0x40080
	global_load_lds_dwordx4 v[0:1], off
	v_lshl_add_u64 v[0:1], v[2:3], 0, s[34:35]
	s_mov_b32 m0, s78
	s_addc_u32 s5, s11, 0
	global_load_lds_dwordx4 v[0:1], off
	s_add_i32 m0, s53, 0x1c000
	global_load_lds_dwordx4 v130, s[4:5]
	s_add_i32 m0, s53, 0x1e000
	v_lshlrev_b32_e32 v2, 11, v10
	global_load_lds_dwordx4 v134, s[4:5]
	v_lshlrev_b32_e32 v1, 2, v151
	v_lshl_or_b32 v0, v151, 6, v154
	v_and_b32_e32 v1, 32, v1
	v_bitop3_b32 v0, v0, s1, v1 bitop3:0xde
	v_lshlrev_b32_e32 v1, 8, v176
	v_and_b32_e32 v1, 0x38000, v1
	v_or3_b32 v1, v8, v1, v2
	v_add_u32_e32 v138, v1, v9
	v_lshlrev_b32_e32 v1, 4, v11
	s_waitcnt vmcnt(6)
	s_cmpk_lt_u32 s12, 0x100
	v_and_b32_e32 v1, 0x78000, v1
	v_lshl_or_b32 v161, s76, 7, v155
	s_cselect_b64 s[38:39], -1, 0
	v_or3_b32 v1, v8, v1, v2
	s_add_i32 s83, 0, 0x10000
	s_add_i32 s84, 0, 0x14000
	s_ashr_i32 s79, s74, 31
	s_mov_b32 s80, s74
	s_ashr_i32 s81, s2, 31
	v_mov_b32_e32 v139, v137
	v_add_u32_e32 v140, v1, v9
	v_mov_b32_e32 v141, v137
	v_mov_b64_e32 v[142:143], 0xb00
	v_mov_b64_e32 v[144:145], 0xaff
	s_movk_i32 s82, 0x161
	v_add_u32_e32 v162, s83, v161
	v_add_u32_e32 v163, s84, v161
	v_add_u32_e32 v164, 0, v0
	v_mov_b32_e32 v165, 0x358637bd
	s_movk_i32 s85, 0x1600
	s_movk_i32 s86, 0xb00
	s_mov_b32 s42, 0xbf38aa3b
	s_mov_b32 s52, 0x3e6d3388
	s_mov_b32 s54, 0x3f07dc22
	s_mov_b32 s56, 0xbf3a00e3
	s_mov_b32 s58, 0x3f35f0e3
	s_mov_b32 s60, 0xbe11a98e
	s_mov_b32 s62, 0x3e027906
	s_barrier
	s_branch .LBB0_1400

; #define PG8_STAGE(bufoff, gbase, voff) do { _Pragma("unroll") for (int _i = 0; _i < 2; ++_i) \
;         __builtin_amdgcn_global_load_lds((const unsigned*)((const char*)(gbase) + (voff)[_i]), (LAS unsigned*)(lds + (bufoff) + ldsw + _i * 8192), 16, 0, 0); } while (0)
; #define PG8_LDA(dst, b, h) do { _Pragma("unroll") for (int m = 0; m < 4; ++m) _Pragma("unroll") for (int k = 0; k < 2; ++k) dst[m][k] = *(const LAS bf16x8*)(lds + PG8_SA(b, h) + aoff + m * 2048 + k * 1024); } while (0)
; #define PG8_LDB(dst, b, h) do { _Pragma("unroll") for (int n = 0; n < 2; ++n) _Pragma("unroll") for (int k = 0; k < 2; ++k) dst[n][k] = *(const LAS bf16x8*)(lds + PG8_SB(b, h) + boff + n * 2048 + k * 1024); } while (0)
; #define PG8_MMA(ai, bj, At, Bt) do { __builtin_amdgcn_s_setprio(1); _Pragma("unroll") for (int m = 0; m < 4; ++m) _Pragma("unroll") for (int n = 0; n < 2; ++n) _Pragma("unroll") for (int k = 0; k < 2; ++k) \
;         acc[ai][bj][m][n] = __builtin_amdgcn_mfma_f32_16x16x32_bf16(Bt[n][k], At[m][k], acc[ai][bj][m][n], 0, 0, 0); __builtin_amdgcn_s_setprio(0); } while (0)
; #define PG8_BAR __builtin_amdgcn_s_barrier()
; template <class Epi>
; __device__ __forceinline__ void gemm_phase(LAS unsigned char* lds, const Gemm g, const StaticOrder& S, const Epi& E) {
;     ...
;     for (;;) {
;         const bool has_next = S.next(ui + 1, nxt);
;         const char* nA = has_next ? (const char*)g.A + (size_t)nxt.pm * tstepA : cA; const char* nB = has_next ? (const char*)g.Bt + (size_t)nxt.pn * tstepB : cB;
; #pragma nounroll
;         for (int t = 0; t < nt; t += 2) {
;             const bool last = (t == nt - 2);
;             const char* a1 = cA + (size_t)(t + 1) * kstep;
;             const char* a2 = last ? nA : cA + (size_t)(t + 2) * kstep; const char* b2 = last ? nB : cB + (size_t)(t + 2) * kstep;
;             const char* a3 = a2 + kstep; const char* b3 = b2 + kstep;
;             PG8_LDB(B0, 0, 0); PG8_LDB(B1, 0, 1); PG8_SCHED; PG8_LDA(At, 0, 0); PG8_STAGE(PG8_SA(1, 1), a1 + hstepA, voffA);
;             PG8_WAIT_V(8); PG8_WAIT_L(0); PG8_BAR; PG8_MMA(0, 0, At, B0); PG8_MMA(0, 1, At, B1); PG8_BAR; PG8_SCHED;
;             PG8_LDA(At, 0, 1); PG8_STAGE(PG8_SB(0, 0), b2, voffB); PG8_STAGE(PG8_SB(0, 1), b2 + hstepB, voffB); PG8_STAGE(PG8_SA(0, 0), a2, voffA);
;             PG8_WAIT_V(8); PG8_WAIT_L(0); PG8_BAR; PG8_MMA(1, 0, At, B0); PG8_MMA(1, 1, At, B1); PG8_BAR; PG8_SCHED;
.LBB0_1402:
	s_ashr_i32 s69, s68, 31
	s_lshl_b64 s[12:13], s[68:69], 19
	s_add_u32 s70, s24, s12
	s_addc_u32 s71, s25, s13
	s_and_b64 s[12:13], s[4:5], exec
	s_cselect_b32 s1, s71, s9
	s_cselect_b32 s7, s70, s8
	s_ashr_i32 s65, s64, 31
	s_lshl_b64 s[12:13], s[64:65], 19
	s_add_u32 s72, s3, s12
	s_addc_u32 s73, s33, s13
	s_and_b64 s[12:13], s[4:5], exec
	s_cselect_b32 s65, s73, s11
	s_cselect_b32 s69, s72, s10
	s_add_u32 s8, s8, 0x40080
	s_addc_u32 s9, s9, 0
	s_add_u32 s74, s10, 0x100
	s_addc_u32 s75, s11, 0
	s_mov_b32 s87, -2
	v_lshl_add_u32 v248, s6, 8, v151
	v_add_u32_e32 v248, s63, v248
	v_ashrrev_i32_e32 v249, 31, v248
	v_lshl_add_u64 v[248:249], v[248:249], 2, s[18:19]
	global_load_dword v240, v[248:249], off
	global_load_dword v241, v[248:249], off offset:64
	global_load_dword v242, v[248:249], off offset:128
	global_load_dword v243, v[248:249], off offset:192
	global_load_dword v244, v[248:249], off offset:512
	global_load_dword v245, v[248:249], off offset:576
	global_load_dword v246, v[248:249], off offset:640
	global_load_dword v247, v[248:249], off offset:704
	ds_read_b128 v[146:149], v162
	ds_read_b128 v[166:169], v162 offset:1024
	ds_read_b128 v[170:173], v162 offset:2048
	ds_read_b128 v[178:181], v162 offset:3072
	ds_read_b128 v[182:185], v163
	ds_read_b128 v[186:189], v163 offset:1024
	ds_read_b128 v[190:193], v163 offset:2048
	ds_read_b128 v[194:197], v163 offset:3072
	s_add_u32 s10, s8, 0xfffc0080
	s_addc_u32 s11, s9, -1
	s_cmp_eq_u32 s87, 12
	s_cselect_b32 s13, s1, s11
	s_cselect_b32 s12, s7, s10
	s_cselect_b32 s11, s65, s75
	s_cselect_b32 s10, s69, s74
	s_add_i32 m0, s53, 0xc000
	ds_read_b128 v[198:201], v164
	ds_read_b128 v[202:205], v164 offset:1024
	ds_read_b128 v[206:209], v164 offset:2048
	ds_read_b128 v[210:213], v164 offset:3072
	ds_read_b128 v[214:217], v164 offset:4096
	ds_read_b128 v[218:221], v164 offset:5120
	ds_read_b128 v[222:225], v164 offset:6144
	ds_read_b128 v[226:229], v164 offset:7168
	global_load_lds_dwordx4 v138, s[8:9]
	s_add_i32 m0, s53, 0xe000
	s_nop 0
	global_load_lds_dwordx4 v140, s[8:9]
	s_waitcnt vmcnt(8)
	s_waitcnt lgkmcnt(0)
	s_barrier
	s_setprio 1
	s_waitcnt lgkmcnt(0)
	v_mfma_f32_16x16x32_bf16 v[124:127], v[146:149], v[198:201], 0
	v_mfma_f32_16x16x32_bf16 v[120:123], v[170:173], v[198:201], 0
	v_mfma_f32_16x16x32_bf16 v[112:115], v[146:149], v[206:209], 0
	v_mfma_f32_16x16x32_bf16 v[104:107], v[170:173], v[206:209], 0
	v_mfma_f32_16x16x32_bf16 v[100:103], v[146:149], v[214:217], 0
	v_mfma_f32_16x16x32_bf16 v[92:95], v[170:173], v[214:217], 0
	v_mfma_f32_16x16x32_bf16 v[84:87], v[146:149], v[222:225], 0
	v_mfma_f32_16x16x32_bf16 v[76:79], v[170:173], v[222:225], 0
	v_mfma_f32_16x16x32_bf16 v[124:127], v[166:169], v[202:205], v[124:127]
	v_mfma_f32_16x16x32_bf16 v[120:123], v[178:181], v[202:205], v[120:123]
	v_mfma_f32_16x16x32_bf16 v[112:115], v[166:169], v[210:213], v[112:115]
	v_mfma_f32_16x16x32_bf16 v[104:107], v[178:181], v[210:213], v[104:107]
	v_mfma_f32_16x16x32_bf16 v[100:103], v[166:169], v[218:221], v[100:103]
	v_mfma_f32_16x16x32_bf16 v[92:95], v[178:181], v[218:221], v[92:95]
	v_mfma_f32_16x16x32_bf16 v[84:87], v[166:169], v[226:229], v[84:87]
	v_mfma_f32_16x16x32_bf16 v[76:79], v[178:181], v[226:229], v[76:79]
	s_setprio 0
	s_setprio 1
	v_mfma_f32_16x16x32_bf16 v[116:119], v[182:185], v[198:201], 0
	v_mfma_f32_16x16x32_bf16 v[108:111], v[190:193], v[198:201], 0
	v_mfma_f32_16x16x32_bf16 v[96:99], v[182:185], v[206:209], 0
	v_mfma_f32_16x16x32_bf16 v[88:91], v[190:193], v[206:209], 0
	v_mfma_f32_16x16x32_bf16 v[80:83], v[182:185], v[214:217], 0
	v_mfma_f32_16x16x32_bf16 v[72:75], v[190:193], v[214:217], 0
	v_mfma_f32_16x16x32_bf16 v[68:71], v[182:185], v[222:225], 0
	v_mfma_f32_16x16x32_bf16 v[64:67], v[190:193], v[222:225], 0
	v_mfma_f32_16x16x32_bf16 v[116:119], v[186:189], v[202:205], v[116:119]
	v_mfma_f32_16x16x32_bf16 v[108:111], v[194:197], v[202:205], v[108:111]
	v_mfma_f32_16x16x32_bf16 v[96:99], v[186:189], v[210:213], v[96:99]
	v_mfma_f32_16x16x32_bf16 v[88:91], v[194:197], v[210:213], v[88:91]
	v_mfma_f32_16x16x32_bf16 v[80:83], v[186:189], v[218:221], v[80:83]
	v_mfma_f32_16x16x32_bf16 v[72:75], v[194:197], v[218:221], v[72:75]
	v_mfma_f32_16x16x32_bf16 v[68:71], v[186:189], v[226:229], v[68:71]
	v_mfma_f32_16x16x32_bf16 v[64:67], v[194:197], v[226:229], v[64:67]
	s_setprio 0
	s_barrier
	s_add_i32 s88, s83, s43
	v_lshl_add_u64 v[174:175], s[10:11], 0, v[130:131]
	s_mov_b32 m0, s88
	ds_read_b128 v[198:201], v164 offset:16384
	ds_read_b128 v[202:205], v164 offset:17408
	ds_read_b128 v[206:209], v164 offset:18432
	ds_read_b128 v[210:213], v164 offset:19456
	ds_read_b128 v[214:217], v164 offset:20480
	ds_read_b128 v[218:221], v164 offset:21504
	ds_read_b128 v[222:225], v164 offset:22528
	ds_read_b128 v[226:229], v164 offset:23552
	global_load_lds_dwordx4 v[174:175], off
	s_add_i32 m0, s88, 0x2000
	s_add_u32 s88, s10, 0x40000
	v_lshl_add_u64 v[230:231], s[10:11], 0, v[134:135]
	s_addc_u32 s89, s11, 0
	s_add_i32 s90, s84, s43
	global_load_lds_dwordx4 v[230:231], off
	s_mov_b32 m0, s90
	v_lshl_add_u64 v[234:235], s[12:13], 0, v[132:133]
	global_load_lds_dwordx4 v130, s[88:89]
	s_add_i32 m0, s90, 0x2000
	s_nop 0
	global_load_lds_dwordx4 v134, s[88:89]
	v_lshl_add_u64 v[232:233], s[12:13], 0, v[128:129]
	s_mov_b32 m0, s53
	s_nop 0
	global_load_lds_dwordx4 v[232:233], off
	s_mov_b32 m0, s55
	s_nop 0
	global_load_lds_dwordx4 v[234:235], off
	s_waitcnt vmcnt(8)
	s_waitcnt lgkmcnt(0)
	s_barrier
; #define PG8_STAGE(bufoff, gbase, voff) do { _Pragma("unroll") for (int _i = 0; _i < 2; ++_i) \
;         __builtin_amdgcn_global_load_lds((const unsigned*)((const char*)(gbase) + (voff)[_i]), (LAS unsigned*)(lds + (bufoff) + ldsw + _i * 8192), 16, 0, 0); } while (0)
; #define PG8_LDA(dst, b, h) do { _Pragma("unroll") for (int m = 0; m < 4; ++m) _Pragma("unroll") for (int k = 0; k < 2; ++k) dst[m][k] = *(const LAS bf16x8*)(lds + PG8_SA(b, h) + aoff + m * 2048 + k * 1024); } while (0)
; #define PG8_LDB(dst, b, h) do { _Pragma("unroll") for (int n = 0; n < 2; ++n) _Pragma("unroll") for (int k = 0; k < 2; ++k) dst[n][k] = *(const LAS bf16x8*)(lds + PG8_SB(b, h) + boff + n * 2048 + k * 1024); } while (0)
; #define PG8_MMA(ai, bj, At, Bt) do { __builtin_amdgcn_s_setprio(1); _Pragma("unroll") for (int m = 0; m < 4; ++m) _Pragma("unroll") for (int n = 0; n < 2; ++n) _Pragma("unroll") for (int k = 0; k < 2; ++k) \
;         acc[ai][bj][m][n] = __builtin_amdgcn_mfma_f32_16x16x32_bf16(Bt[n][k], At[m][k], acc[ai][bj][m][n], 0, 0, 0); __builtin_amdgcn_s_setprio(0); } while (0)
; #define PG8_WAIT_V(n) asm volatile("s_waitcnt vmcnt(" #n ")" ::: "memory")
; #define PG8_WAIT_L(n) asm volatile("s_waitcnt lgkmcnt(" #n ")" ::: "memory")
; #define PG8_BAR __builtin_amdgcn_s_barrier()
; #define PG8_SCHED __builtin_amdgcn_sched_barrier(0)
; template <class Epi>
; __device__ __forceinline__ void gemm_phase(LAS unsigned char* lds, const Gemm g, const StaticOrder& S, const Epi& E) {
;     ...
;             PG8_WAIT_V(8); PG8_WAIT_L(0); PG8_BAR; PG8_MMA(1, 0, At, B0); PG8_MMA(1, 1, At, B1); PG8_BAR; PG8_SCHED;
;             PG8_LDB(B0, 1, 0); PG8_LDB(B1, 1, 1); PG8_SCHED; PG8_LDA(At, 1, 0); PG8_STAGE(PG8_SA(0, 1), a2 + hstepA, voffA);
;             PG8_WAIT_V(8); PG8_WAIT_L(0); PG8_BAR; PG8_MMA(0, 0, At, B0); PG8_MMA(0, 1, At, B1); PG8_BAR; PG8_SCHED;
;             PG8_LDA(At, 1, 1); PG8_STAGE(PG8_SB(1, 0), b3, voffB); PG8_STAGE(PG8_SB(1, 1), b3 + hstepB, voffB); PG8_STAGE(PG8_SA(1, 0), a3, voffA);
	s_setprio 1
	s_waitcnt lgkmcnt(0)
	v_mfma_f32_16x16x32_bf16 v[60:63], v[146:149], v[198:201], 0
	v_mfma_f32_16x16x32_bf16 v[56:59], v[170:173], v[198:201], 0
	v_mfma_f32_16x16x32_bf16 v[52:55], v[146:149], v[206:209], 0
	v_mfma_f32_16x16x32_bf16 v[44:47], v[170:173], v[206:209], 0
	v_mfma_f32_16x16x32_bf16 v[36:39], v[146:149], v[214:217], 0
	v_mfma_f32_16x16x32_bf16 v[28:31], v[170:173], v[214:217], 0
	v_mfma_f32_16x16x32_bf16 v[20:23], v[146:149], v[222:225], 0
	v_mfma_f32_16x16x32_bf16 v[12:15], v[170:173], v[222:225], 0
	v_mfma_f32_16x16x32_bf16 v[60:63], v[166:169], v[202:205], v[60:63]
	v_mfma_f32_16x16x32_bf16 v[56:59], v[178:181], v[202:205], v[56:59]
	v_mfma_f32_16x16x32_bf16 v[52:55], v[166:169], v[210:213], v[52:55]
	v_mfma_f32_16x16x32_bf16 v[44:47], v[178:181], v[210:213], v[44:47]
	v_mfma_f32_16x16x32_bf16 v[36:39], v[166:169], v[218:221], v[36:39]
	v_mfma_f32_16x16x32_bf16 v[28:31], v[178:181], v[218:221], v[28:31]
	v_mfma_f32_16x16x32_bf16 v[20:23], v[166:169], v[226:229], v[20:23]
	v_mfma_f32_16x16x32_bf16 v[12:15], v[178:181], v[226:229], v[12:15]
	s_setprio 0
	s_setprio 1
	v_mfma_f32_16x16x32_bf16 v[48:51], v[182:185], v[198:201], 0
	v_mfma_f32_16x16x32_bf16 v[40:43], v[190:193], v[198:201], 0
	v_mfma_f32_16x16x32_bf16 v[32:35], v[182:185], v[206:209], 0
	v_mfma_f32_16x16x32_bf16 v[24:27], v[190:193], v[206:209], 0
	v_mfma_f32_16x16x32_bf16 v[16:19], v[182:185], v[214:217], 0
	v_mfma_f32_16x16x32_bf16 v[8:11], v[190:193], v[214:217], 0
	v_mfma_f32_16x16x32_bf16 v[4:7], v[182:185], v[222:225], 0
	v_mfma_f32_16x16x32_bf16 v[0:3], v[190:193], v[222:225], 0
	v_mfma_f32_16x16x32_bf16 v[48:51], v[186:189], v[202:205], v[48:51]
	v_mfma_f32_16x16x32_bf16 v[40:43], v[194:197], v[202:205], v[40:43]
	v_mfma_f32_16x16x32_bf16 v[32:35], v[186:189], v[210:213], v[32:35]
	v_mfma_f32_16x16x32_bf16 v[24:27], v[194:197], v[210:213], v[24:27]
	v_mfma_f32_16x16x32_bf16 v[16:19], v[186:189], v[218:221], v[16:19]
	v_mfma_f32_16x16x32_bf16 v[8:11], v[194:197], v[218:221], v[8:11]
	v_mfma_f32_16x16x32_bf16 v[4:7], v[186:189], v[226:229], v[4:7]
	v_mfma_f32_16x16x32_bf16 v[0:3], v[194:197], v[226:229], v[0:3]
	s_setprio 0
	s_barrier
	s_add_i32 s88, 0, 0x18000
	v_add_u32_e32 v136, s88, v161
	s_add_i32 s89, 0, 0x1c000
	ds_read_b128 v[146:149], v136
	ds_read_b128 v[166:169], v136 offset:1024
	ds_read_b128 v[170:173], v136 offset:2048
	ds_read_b128 v[178:181], v136 offset:3072
	v_add_u32_e32 v136, s89, v161
	ds_read_b128 v[182:185], v136
	ds_read_b128 v[186:189], v136 offset:1024
	ds_read_b128 v[190:193], v136 offset:2048
	ds_read_b128 v[194:197], v136 offset:3072
	s_add_u32 s12, s12, 0x40000
	s_addc_u32 s13, s13, 0
	s_mov_b32 m0, s57
	ds_read_b128 v[198:201], v164 offset:32768
	ds_read_b128 v[202:205], v164 offset:33792
	ds_read_b128 v[206:209], v164 offset:34816
	ds_read_b128 v[210:213], v164 offset:35840
	ds_read_b128 v[214:217], v164 offset:36864
	ds_read_b128 v[218:221], v164 offset:37888
	ds_read_b128 v[222:225], v164 offset:38912
	ds_read_b128 v[226:229], v164 offset:39936
	global_load_lds_dwordx4 v128, s[12:13]
	s_mov_b32 m0, s59
	s_nop 0
	global_load_lds_dwordx4 v132, s[12:13]
	s_waitcnt vmcnt(8)
	s_waitcnt lgkmcnt(0)
	s_barrier
	s_setprio 1
	s_waitcnt lgkmcnt(0)
	v_mfma_f32_16x16x32_bf16 v[124:127], v[146:149], v[198:201], v[124:127]
	v_mfma_f32_16x16x32_bf16 v[120:123], v[170:173], v[198:201], v[120:123]
	v_mfma_f32_16x16x32_bf16 v[112:115], v[146:149], v[206:209], v[112:115]
	v_mfma_f32_16x16x32_bf16 v[104:107], v[170:173], v[206:209], v[104:107]
	v_mfma_f32_16x16x32_bf16 v[100:103], v[146:149], v[214:217], v[100:103]
	v_mfma_f32_16x16x32_bf16 v[92:95], v[170:173], v[214:217], v[92:95]
	v_mfma_f32_16x16x32_bf16 v[84:87], v[146:149], v[222:225], v[84:87]
	v_mfma_f32_16x16x32_bf16 v[76:79], v[170:173], v[222:225], v[76:79]
	v_mfma_f32_16x16x32_bf16 v[124:127], v[166:169], v[202:205], v[124:127]
	v_mfma_f32_16x16x32_bf16 v[120:123], v[178:181], v[202:205], v[120:123]
	v_mfma_f32_16x16x32_bf16 v[112:115], v[166:169], v[210:213], v[112:115]
	v_mfma_f32_16x16x32_bf16 v[104:107], v[178:181], v[210:213], v[104:107]
	v_mfma_f32_16x16x32_bf16 v[100:103], v[166:169], v[218:221], v[100:103]
	v_mfma_f32_16x16x32_bf16 v[92:95], v[178:181], v[218:221], v[92:95]
	v_mfma_f32_16x16x32_bf16 v[84:87], v[166:169], v[226:229], v[84:87]
	v_mfma_f32_16x16x32_bf16 v[76:79], v[178:181], v[226:229], v[76:79]
	s_setprio 0
	s_setprio 1
	v_mfma_f32_16x16x32_bf16 v[116:119], v[182:185], v[198:201], v[116:119]
	v_mfma_f32_16x16x32_bf16 v[108:111], v[190:193], v[198:201], v[108:111]
	v_mfma_f32_16x16x32_bf16 v[96:99], v[182:185], v[206:209], v[96:99]
	v_mfma_f32_16x16x32_bf16 v[88:91], v[190:193], v[206:209], v[88:91]
	v_mfma_f32_16x16x32_bf16 v[80:83], v[182:185], v[214:217], v[80:83]
	v_mfma_f32_16x16x32_bf16 v[72:75], v[190:193], v[214:217], v[72:75]
	v_mfma_f32_16x16x32_bf16 v[68:71], v[182:185], v[222:225], v[68:71]
	v_mfma_f32_16x16x32_bf16 v[64:67], v[190:193], v[222:225], v[64:67]
	v_mfma_f32_16x16x32_bf16 v[116:119], v[186:189], v[202:205], v[116:119]
	v_mfma_f32_16x16x32_bf16 v[108:111], v[194:197], v[202:205], v[108:111]
	v_mfma_f32_16x16x32_bf16 v[96:99], v[186:189], v[210:213], v[96:99]
	v_mfma_f32_16x16x32_bf16 v[88:91], v[194:197], v[210:213], v[88:91]
	v_mfma_f32_16x16x32_bf16 v[80:83], v[186:189], v[218:221], v[80:83]
	v_mfma_f32_16x16x32_bf16 v[72:75], v[194:197], v[218:221], v[72:75]
	v_mfma_f32_16x16x32_bf16 v[68:71], v[186:189], v[226:229], v[68:71]
	v_mfma_f32_16x16x32_bf16 v[64:67], v[194:197], v[226:229], v[64:67]
	s_setprio 0
	s_barrier
; #define PG8_STAGE(bufoff, gbase, voff) do { _Pragma("unroll") for (int _i = 0; _i < 2; ++_i) \
;         __builtin_amdgcn_global_load_lds((const unsigned*)((const char*)(gbase) + (voff)[_i]), (LAS unsigned*)(lds + (bufoff) + ldsw + _i * 8192), 16, 0, 0); } while (0)
; #define PG8_LDA(dst, b, h) do { _Pragma("unroll") for (int m = 0; m < 4; ++m) _Pragma("unroll") for (int k = 0; k < 2; ++k) dst[m][k] = *(const LAS bf16x8*)(lds + PG8_SA(b, h) + aoff + m * 2048 + k * 1024); } while (0)
; #define PG8_LDB(dst, b, h) do { _Pragma("unroll") for (int n = 0; n < 2; ++n) _Pragma("unroll") for (int k = 0; k < 2; ++k) dst[n][k] = *(const LAS bf16x8*)(lds + PG8_SB(b, h) + boff + n * 2048 + k * 1024); } while (0)
; #define PG8_WAIT_V(n) asm volatile("s_waitcnt vmcnt(" #n ")" ::: "memory")
; #define PG8_BAR __builtin_amdgcn_s_barrier()
; template <class Epi>
; __device__ __forceinline__ void gemm_phase(LAS unsigned char* lds, const Gemm g, const StaticOrder& S, const Epi& E) {
;     ...
;         for (int t = 0; t < nt; t += 2) {
;             const bool last = (t == nt - 2);
;             const char* a1 = cA + (size_t)(t + 1) * kstep;
;             const char* a2 = last ? nA : cA + (size_t)(t + 2) * kstep; const char* b2 = last ? nB : cB + (size_t)(t + 2) * kstep;
;             const char* a3 = a2 + kstep; const char* b3 = b2 + kstep;
;             PG8_LDB(B0, 0, 0); PG8_LDB(B1, 0, 1); PG8_SCHED; PG8_LDA(At, 0, 0); PG8_STAGE(PG8_SA(1, 1), a1 + hstepA, voffA);
;             PG8_WAIT_V(8); PG8_WAIT_L(0); PG8_BAR; PG8_MMA(0, 0, At, B0); PG8_MMA(0, 1, At, B1); PG8_BAR; PG8_SCHED;
;             PG8_LDA(At, 0, 1); PG8_STAGE(PG8_SB(0, 0), b2, voffB); PG8_STAGE(PG8_SB(0, 1), b2 + hstepB, voffB); PG8_STAGE(PG8_SA(0, 0), a2, voffA);
;             PG8_WAIT_V(8); PG8_WAIT_L(0); PG8_BAR; PG8_MMA(1, 0, At, B0); PG8_MMA(1, 1, At, B1); PG8_BAR; PG8_SCHED;
;             PG8_LDB(B0, 1, 0); PG8_LDB(B1, 1, 1); PG8_SCHED; PG8_LDA(At, 1, 0); PG8_STAGE(PG8_SA(0, 1), a2 + hstepA, voffA);
;             PG8_WAIT_V(8); PG8_WAIT_L(0); PG8_BAR; PG8_MMA(0, 0, At, B0); PG8_MMA(0, 1, At, B1); PG8_BAR; PG8_SCHED;
;             PG8_LDA(At, 1, 1); PG8_STAGE(PG8_SB(1, 0), b3, voffB); PG8_STAGE(PG8_SB(1, 1), b3 + hstepB, voffB); PG8_STAGE(PG8_SA(1, 0), a3, voffA);
;             PG8_WAIT_V(8); PG8_WAIT_L(0); PG8_BAR; PG8_MMA(1, 0, At, B0); PG8_MMA(1, 1, At, B1); PG8_BAR; PG8_SCHED;
;         }
	s_add_i32 s12, s88, s43
	v_lshl_add_u64 v[174:175], v[174:175], 0, s[34:35]
	s_mov_b32 m0, s12
	ds_read_b128 v[198:201], v164 offset:49152
	ds_read_b128 v[202:205], v164 offset:50176
	ds_read_b128 v[206:209], v164 offset:51200
	ds_read_b128 v[210:213], v164 offset:52224
	ds_read_b128 v[214:217], v164 offset:53248
	ds_read_b128 v[218:221], v164 offset:54272
	ds_read_b128 v[222:225], v164 offset:55296
	ds_read_b128 v[226:229], v164 offset:56320
	global_load_lds_dwordx4 v[174:175], off
	s_add_i32 m0, s12, 0x2000
	s_add_u32 s10, s10, 0x40080
	v_lshl_add_u64 v[174:175], v[230:231], 0, s[34:35]
	s_addc_u32 s11, s11, 0
	s_add_i32 s12, s89, s43
	global_load_lds_dwordx4 v[174:175], off
	s_mov_b32 m0, s12
	s_nop 0
	global_load_lds_dwordx4 v130, s[10:11]
	s_add_i32 m0, s12, 0x2000
	s_nop 0
	global_load_lds_dwordx4 v134, s[10:11]
	v_lshl_add_u64 v[174:175], v[232:233], 0, s[34:35]
	s_mov_b32 m0, s77
	s_nop 0
	global_load_lds_dwordx4 v[174:175], off
	v_lshl_add_u64 v[174:175], v[234:235], 0, s[34:35]
	s_mov_b32 m0, s78
	s_nop 0
	global_load_lds_dwordx4 v[174:175], off
	s_waitcnt vmcnt(8)
	s_waitcnt lgkmcnt(0)
	s_barrier
	s_setprio 1
	s_waitcnt lgkmcnt(0)
	v_mfma_f32_16x16x32_bf16 v[60:63], v[146:149], v[198:201], v[60:63]
	v_mfma_f32_16x16x32_bf16 v[56:59], v[170:173], v[198:201], v[56:59]
	v_mfma_f32_16x16x32_bf16 v[52:55], v[146:149], v[206:209], v[52:55]
	v_mfma_f32_16x16x32_bf16 v[44:47], v[170:173], v[206:209], v[44:47]
	v_mfma_f32_16x16x32_bf16 v[36:39], v[146:149], v[214:217], v[36:39]
	v_mfma_f32_16x16x32_bf16 v[28:31], v[170:173], v[214:217], v[28:31]
	v_mfma_f32_16x16x32_bf16 v[20:23], v[146:149], v[222:225], v[20:23]
	v_mfma_f32_16x16x32_bf16 v[12:15], v[170:173], v[222:225], v[12:15]
	v_mfma_f32_16x16x32_bf16 v[60:63], v[166:169], v[202:205], v[60:63]
	v_mfma_f32_16x16x32_bf16 v[56:59], v[178:181], v[202:205], v[56:59]
	v_mfma_f32_16x16x32_bf16 v[52:55], v[166:169], v[210:213], v[52:55]
	v_mfma_f32_16x16x32_bf16 v[44:47], v[178:181], v[210:213], v[44:47]
	v_mfma_f32_16x16x32_bf16 v[36:39], v[166:169], v[218:221], v[36:39]
	v_mfma_f32_16x16x32_bf16 v[28:31], v[178:181], v[218:221], v[28:31]
	v_mfma_f32_16x16x32_bf16 v[20:23], v[166:169], v[226:229], v[20:23]
	v_mfma_f32_16x16x32_bf16 v[12:15], v[178:181], v[226:229], v[12:15]
	s_setprio 0
	s_setprio 1
	v_mfma_f32_16x16x32_bf16 v[48:51], v[182:185], v[198:201], v[48:51]
	v_mfma_f32_16x16x32_bf16 v[40:43], v[190:193], v[198:201], v[40:43]
	v_mfma_f32_16x16x32_bf16 v[32:35], v[182:185], v[206:209], v[32:35]
	v_mfma_f32_16x16x32_bf16 v[24:27], v[190:193], v[206:209], v[24:27]
	v_mfma_f32_16x16x32_bf16 v[16:19], v[182:185], v[214:217], v[16:19]
	v_mfma_f32_16x16x32_bf16 v[8:11], v[190:193], v[214:217], v[8:11]
	v_mfma_f32_16x16x32_bf16 v[4:7], v[182:185], v[222:225], v[4:7]
	v_mfma_f32_16x16x32_bf16 v[0:3], v[190:193], v[222:225], v[0:3]
	v_mfma_f32_16x16x32_bf16 v[48:51], v[186:189], v[202:205], v[48:51]
	v_mfma_f32_16x16x32_bf16 v[40:43], v[194:197], v[202:205], v[40:43]
	v_mfma_f32_16x16x32_bf16 v[32:35], v[186:189], v[210:213], v[32:35]
	v_mfma_f32_16x16x32_bf16 v[24:27], v[194:197], v[210:213], v[24:27]
	v_mfma_f32_16x16x32_bf16 v[16:19], v[186:189], v[218:221], v[16:19]
	v_mfma_f32_16x16x32_bf16 v[8:11], v[194:197], v[218:221], v[8:11]
	v_mfma_f32_16x16x32_bf16 v[4:7], v[186:189], v[226:229], v[4:7]
	v_mfma_f32_16x16x32_bf16 v[0:3], v[194:197], v[226:229], v[0:3]
	s_setprio 0
	s_barrier
	s_add_i32 s87, s87, 2
	s_add_u32 s8, s8, 0x100
	s_addc_u32 s9, s9, 0
	s_add_u32 s74, s74, 0x100
	s_addc_u32 s75, s75, 0
	s_cmp_gt_u32 s87, 13
.LBB0_1403:
	ds_read_b128 v[146:149], v162
	ds_read_b128 v[166:169], v162 offset:1024
	ds_read_b128 v[170:173], v162 offset:2048
	ds_read_b128 v[178:181], v162 offset:3072
	ds_read_b128 v[182:185], v163
	ds_read_b128 v[186:189], v163 offset:1024
	ds_read_b128 v[190:193], v163 offset:2048
	ds_read_b128 v[194:197], v163 offset:3072
	s_add_u32 s10, s8, 0xfffc0080
	s_addc_u32 s11, s9, -1
	s_cmp_eq_u32 s87, 12
	s_cselect_b32 s13, s1, s11
	s_cselect_b32 s12, s7, s10
	s_cselect_b32 s11, s65, s75
	s_cselect_b32 s10, s69, s74
	s_add_i32 m0, s53, 0xc000
	ds_read_b128 v[198:201], v164
	ds_read_b128 v[202:205], v164 offset:1024
	ds_read_b128 v[206:209], v164 offset:2048
	ds_read_b128 v[210:213], v164 offset:3072
	ds_read_b128 v[214:217], v164 offset:4096
	ds_read_b128 v[218:221], v164 offset:5120
	ds_read_b128 v[222:225], v164 offset:6144
	ds_read_b128 v[226:229], v164 offset:7168
	global_load_lds_dwordx4 v138, s[8:9]
	s_add_i32 m0, s53, 0xe000
	s_nop 0
	global_load_lds_dwordx4 v140, s[8:9]
	s_waitcnt vmcnt(8)
	s_waitcnt lgkmcnt(0)
	s_barrier
; #define PG8_STAGE(bufoff, gbase, voff) do { _Pragma("unroll") for (int _i = 0; _i < 2; ++_i) \
;         __builtin_amdgcn_global_load_lds((const unsigned*)((const char*)(gbase) + (voff)[_i]), (LAS unsigned*)(lds + (bufoff) + ldsw + _i * 8192), 16, 0, 0); } while (0)
; #define PG8_LDA(dst, b, h) do { _Pragma("unroll") for (int m = 0; m < 4; ++m) _Pragma("unroll") for (int k = 0; k < 2; ++k) dst[m][k] = *(const LAS bf16x8*)(lds + PG8_SA(b, h) + aoff + m * 2048 + k * 1024); } while (0)
; #define PG8_LDB(dst, b, h) do { _Pragma("unroll") for (int n = 0; n < 2; ++n) _Pragma("unroll") for (int k = 0; k < 2; ++k) dst[n][k] = *(const LAS bf16x8*)(lds + PG8_SB(b, h) + boff + n * 2048 + k * 1024); } while (0)
; #define PG8_MMA(ai, bj, At, Bt) do { __builtin_amdgcn_s_setprio(1); _Pragma("unroll") for (int m = 0; m < 4; ++m) _Pragma("unroll") for (int n = 0; n < 2; ++n) _Pragma("unroll") for (int k = 0; k < 2; ++k) \
;         acc[ai][bj][m][n] = __builtin_amdgcn_mfma_f32_16x16x32_bf16(Bt[n][k], At[m][k], acc[ai][bj][m][n], 0, 0, 0); __builtin_amdgcn_s_setprio(0); } while (0)
; #define PG8_WAIT_V(n) asm volatile("s_waitcnt vmcnt(" #n ")" ::: "memory")
; #define PG8_WAIT_L(n) asm volatile("s_waitcnt lgkmcnt(" #n ")" ::: "memory")
; #define PG8_BAR __builtin_amdgcn_s_barrier()
; #define PG8_SCHED __builtin_amdgcn_sched_barrier(0)
; template <class Epi>
; __device__ __forceinline__ void gemm_phase(LAS unsigned char* lds, const Gemm g, const StaticOrder& S, const Epi& E) {
;     ...
;             PG8_LDB(B0, 0, 0); PG8_LDB(B1, 0, 1); PG8_SCHED; PG8_LDA(At, 0, 0); PG8_STAGE(PG8_SA(1, 1), a1 + hstepA, voffA);
;             PG8_WAIT_V(8); PG8_WAIT_L(0); PG8_BAR; PG8_MMA(0, 0, At, B0); PG8_MMA(0, 1, At, B1); PG8_BAR; PG8_SCHED;
;             PG8_LDA(At, 0, 1); PG8_STAGE(PG8_SB(0, 0), b2, voffB); PG8_STAGE(PG8_SB(0, 1), b2 + hstepB, voffB); PG8_STAGE(PG8_SA(0, 0), a2, voffA);
;             PG8_WAIT_V(8); PG8_WAIT_L(0); PG8_BAR; PG8_MMA(1, 0, At, B0); PG8_MMA(1, 1, At, B1); PG8_BAR; PG8_SCHED;
	s_setprio 1
	s_waitcnt lgkmcnt(0)
	v_mfma_f32_16x16x32_bf16 v[124:127], v[146:149], v[198:201], v[124:127]
	v_mfma_f32_16x16x32_bf16 v[120:123], v[170:173], v[198:201], v[120:123]
	v_mfma_f32_16x16x32_bf16 v[112:115], v[146:149], v[206:209], v[112:115]
	v_mfma_f32_16x16x32_bf16 v[104:107], v[170:173], v[206:209], v[104:107]
	v_mfma_f32_16x16x32_bf16 v[100:103], v[146:149], v[214:217], v[100:103]
	v_mfma_f32_16x16x32_bf16 v[92:95], v[170:173], v[214:217], v[92:95]
	v_mfma_f32_16x16x32_bf16 v[84:87], v[146:149], v[222:225], v[84:87]
	v_mfma_f32_16x16x32_bf16 v[76:79], v[170:173], v[222:225], v[76:79]
	v_mfma_f32_16x16x32_bf16 v[124:127], v[166:169], v[202:205], v[124:127]
	v_mfma_f32_16x16x32_bf16 v[120:123], v[178:181], v[202:205], v[120:123]
	v_mfma_f32_16x16x32_bf16 v[112:115], v[166:169], v[210:213], v[112:115]
	v_mfma_f32_16x16x32_bf16 v[104:107], v[178:181], v[210:213], v[104:107]
	v_mfma_f32_16x16x32_bf16 v[100:103], v[166:169], v[218:221], v[100:103]
	v_mfma_f32_16x16x32_bf16 v[92:95], v[178:181], v[218:221], v[92:95]
	v_mfma_f32_16x16x32_bf16 v[84:87], v[166:169], v[226:229], v[84:87]
	v_mfma_f32_16x16x32_bf16 v[76:79], v[178:181], v[226:229], v[76:79]
	s_setprio 0
	s_setprio 1
	v_mfma_f32_16x16x32_bf16 v[116:119], v[182:185], v[198:201], v[116:119]
	v_mfma_f32_16x16x32_bf16 v[108:111], v[190:193], v[198:201], v[108:111]
	v_mfma_f32_16x16x32_bf16 v[96:99], v[182:185], v[206:209], v[96:99]
	v_mfma_f32_16x16x32_bf16 v[88:91], v[190:193], v[206:209], v[88:91]
	v_mfma_f32_16x16x32_bf16 v[80:83], v[182:185], v[214:217], v[80:83]
	v_mfma_f32_16x16x32_bf16 v[72:75], v[190:193], v[214:217], v[72:75]
	v_mfma_f32_16x16x32_bf16 v[68:71], v[182:185], v[222:225], v[68:71]
	v_mfma_f32_16x16x32_bf16 v[64:67], v[190:193], v[222:225], v[64:67]
	v_mfma_f32_16x16x32_bf16 v[116:119], v[186:189], v[202:205], v[116:119]
	v_mfma_f32_16x16x32_bf16 v[108:111], v[194:197], v[202:205], v[108:111]
	v_mfma_f32_16x16x32_bf16 v[96:99], v[186:189], v[210:213], v[96:99]
	v_mfma_f32_16x16x32_bf16 v[88:91], v[194:197], v[210:213], v[88:91]
	v_mfma_f32_16x16x32_bf16 v[80:83], v[186:189], v[218:221], v[80:83]
	v_mfma_f32_16x16x32_bf16 v[72:75], v[194:197], v[218:221], v[72:75]
	v_mfma_f32_16x16x32_bf16 v[68:71], v[186:189], v[226:229], v[68:71]
	v_mfma_f32_16x16x32_bf16 v[64:67], v[194:197], v[226:229], v[64:67]
	s_setprio 0
	s_barrier
	s_add_i32 s88, s83, s43
	v_lshl_add_u64 v[174:175], s[10:11], 0, v[130:131]
	s_mov_b32 m0, s88
	ds_read_b128 v[198:201], v164 offset:16384
	ds_read_b128 v[202:205], v164 offset:17408
	ds_read_b128 v[206:209], v164 offset:18432
	ds_read_b128 v[210:213], v164 offset:19456
	ds_read_b128 v[214:217], v164 offset:20480
	ds_read_b128 v[218:221], v164 offset:21504
	ds_read_b128 v[222:225], v164 offset:22528
	ds_read_b128 v[226:229], v164 offset:23552
	global_load_lds_dwordx4 v[174:175], off
	s_add_i32 m0, s88, 0x2000
	s_add_u32 s88, s10, 0x40000
	v_lshl_add_u64 v[230:231], s[10:11], 0, v[134:135]
	s_addc_u32 s89, s11, 0
	s_add_i32 s90, s84, s43
	global_load_lds_dwordx4 v[230:231], off
	s_mov_b32 m0, s90
	v_lshl_add_u64 v[234:235], s[12:13], 0, v[132:133]
	global_load_lds_dwordx4 v130, s[88:89]
	s_add_i32 m0, s90, 0x2000
	s_nop 0
	global_load_lds_dwordx4 v134, s[88:89]
	v_lshl_add_u64 v[232:233], s[12:13], 0, v[128:129]
	s_mov_b32 m0, s53
	s_nop 0
	global_load_lds_dwordx4 v[232:233], off
	s_mov_b32 m0, s55
	s_nop 0
	global_load_lds_dwordx4 v[234:235], off
	s_waitcnt vmcnt(8)
	s_waitcnt lgkmcnt(0)
	s_barrier
	s_setprio 1
	s_waitcnt lgkmcnt(0)
	v_mfma_f32_16x16x32_bf16 v[60:63], v[146:149], v[198:201], v[60:63]
	v_mfma_f32_16x16x32_bf16 v[56:59], v[170:173], v[198:201], v[56:59]
	v_mfma_f32_16x16x32_bf16 v[52:55], v[146:149], v[206:209], v[52:55]
	v_mfma_f32_16x16x32_bf16 v[44:47], v[170:173], v[206:209], v[44:47]
	v_mfma_f32_16x16x32_bf16 v[36:39], v[146:149], v[214:217], v[36:39]
	v_mfma_f32_16x16x32_bf16 v[28:31], v[170:173], v[214:217], v[28:31]
	v_mfma_f32_16x16x32_bf16 v[20:23], v[146:149], v[222:225], v[20:23]
	v_mfma_f32_16x16x32_bf16 v[12:15], v[170:173], v[222:225], v[12:15]
	v_mfma_f32_16x16x32_bf16 v[60:63], v[166:169], v[202:205], v[60:63]
	v_mfma_f32_16x16x32_bf16 v[56:59], v[178:181], v[202:205], v[56:59]
	v_mfma_f32_16x16x32_bf16 v[52:55], v[166:169], v[210:213], v[52:55]
	v_mfma_f32_16x16x32_bf16 v[44:47], v[178:181], v[210:213], v[44:47]
	v_mfma_f32_16x16x32_bf16 v[36:39], v[166:169], v[218:221], v[36:39]
	v_mfma_f32_16x16x32_bf16 v[28:31], v[178:181], v[218:221], v[28:31]
	v_mfma_f32_16x16x32_bf16 v[20:23], v[166:169], v[226:229], v[20:23]
	v_mfma_f32_16x16x32_bf16 v[12:15], v[178:181], v[226:229], v[12:15]
	s_setprio 0
	s_setprio 1
	v_mfma_f32_16x16x32_bf16 v[48:51], v[182:185], v[198:201], v[48:51]
	v_mfma_f32_16x16x32_bf16 v[40:43], v[190:193], v[198:201], v[40:43]
	v_mfma_f32_16x16x32_bf16 v[32:35], v[182:185], v[206:209], v[32:35]
	v_mfma_f32_16x16x32_bf16 v[24:27], v[190:193], v[206:209], v[24:27]
	v_mfma_f32_16x16x32_bf16 v[16:19], v[182:185], v[214:217], v[16:19]
	v_mfma_f32_16x16x32_bf16 v[8:11], v[190:193], v[214:217], v[8:11]
	v_mfma_f32_16x16x32_bf16 v[4:7], v[182:185], v[222:225], v[4:7]
	v_mfma_f32_16x16x32_bf16 v[0:3], v[190:193], v[222:225], v[0:3]
	v_mfma_f32_16x16x32_bf16 v[48:51], v[186:189], v[202:205], v[48:51]
	v_mfma_f32_16x16x32_bf16 v[40:43], v[194:197], v[202:205], v[40:43]
	v_mfma_f32_16x16x32_bf16 v[32:35], v[186:189], v[210:213], v[32:35]
	v_mfma_f32_16x16x32_bf16 v[24:27], v[194:197], v[210:213], v[24:27]
	v_mfma_f32_16x16x32_bf16 v[16:19], v[186:189], v[218:221], v[16:19]
	v_mfma_f32_16x16x32_bf16 v[8:11], v[194:197], v[218:221], v[8:11]
	v_mfma_f32_16x16x32_bf16 v[4:7], v[186:189], v[226:229], v[4:7]
	v_mfma_f32_16x16x32_bf16 v[0:3], v[194:197], v[226:229], v[0:3]
	s_setprio 0
	s_barrier
; #define PG8_STAGE(bufoff, gbase, voff) do { _Pragma("unroll") for (int _i = 0; _i < 2; ++_i) \
;         __builtin_amdgcn_global_load_lds((const unsigned*)((const char*)(gbase) + (voff)[_i]), (LAS unsigned*)(lds + (bufoff) + ldsw + _i * 8192), 16, 0, 0); } while (0)
; #define PG8_LDA(dst, b, h) do { _Pragma("unroll") for (int m = 0; m < 4; ++m) _Pragma("unroll") for (int k = 0; k < 2; ++k) dst[m][k] = *(const LAS bf16x8*)(lds + PG8_SA(b, h) + aoff + m * 2048 + k * 1024); } while (0)
; #define PG8_LDB(dst, b, h) do { _Pragma("unroll") for (int n = 0; n < 2; ++n) _Pragma("unroll") for (int k = 0; k < 2; ++k) dst[n][k] = *(const LAS bf16x8*)(lds + PG8_SB(b, h) + boff + n * 2048 + k * 1024); } while (0)
; #define PG8_MMA(ai, bj, At, Bt) do { __builtin_amdgcn_s_setprio(1); _Pragma("unroll") for (int m = 0; m < 4; ++m) _Pragma("unroll") for (int n = 0; n < 2; ++n) _Pragma("unroll") for (int k = 0; k < 2; ++k) \
;         acc[ai][bj][m][n] = __builtin_amdgcn_mfma_f32_16x16x32_bf16(Bt[n][k], At[m][k], acc[ai][bj][m][n], 0, 0, 0); __builtin_amdgcn_s_setprio(0); } while (0)
; #define PG8_WAIT_V(n) asm volatile("s_waitcnt vmcnt(" #n ")" ::: "memory")
; #define PG8_WAIT_L(n) asm volatile("s_waitcnt lgkmcnt(" #n ")" ::: "memory")
; #define PG8_BAR __builtin_amdgcn_s_barrier()
; #define PG8_SCHED __builtin_amdgcn_sched_barrier(0)
; template <class Epi>
; __device__ __forceinline__ void gemm_phase(LAS unsigned char* lds, const Gemm g, const StaticOrder& S, const Epi& E) {
;     ...
;             PG8_LDB(B0, 1, 0); PG8_LDB(B1, 1, 1); PG8_SCHED; PG8_LDA(At, 1, 0); PG8_STAGE(PG8_SA(0, 1), a2 + hstepA, voffA);
;             PG8_WAIT_V(8); PG8_WAIT_L(0); PG8_BAR; PG8_MMA(0, 0, At, B0); PG8_MMA(0, 1, At, B1); PG8_BAR; PG8_SCHED;
	s_add_i32 s88, 0, 0x18000
	v_add_u32_e32 v136, s88, v161
	s_add_i32 s89, 0, 0x1c000
	ds_read_b128 v[146:149], v136
	ds_read_b128 v[166:169], v136 offset:1024
	ds_read_b128 v[170:173], v136 offset:2048
	ds_read_b128 v[178:181], v136 offset:3072
	v_add_u32_e32 v136, s89, v161
	ds_read_b128 v[182:185], v136
	ds_read_b128 v[186:189], v136 offset:1024
	ds_read_b128 v[190:193], v136 offset:2048
	ds_read_b128 v[194:197], v136 offset:3072
	s_add_u32 s12, s12, 0x40000
	s_addc_u32 s13, s13, 0
	s_mov_b32 m0, s57
	ds_read_b128 v[198:201], v164 offset:32768
	ds_read_b128 v[202:205], v164 offset:33792
	ds_read_b128 v[206:209], v164 offset:34816
	ds_read_b128 v[210:213], v164 offset:35840
	ds_read_b128 v[214:217], v164 offset:36864
	ds_read_b128 v[218:221], v164 offset:37888
	ds_read_b128 v[222:225], v164 offset:38912
	ds_read_b128 v[226:229], v164 offset:39936
	global_load_lds_dwordx4 v128, s[12:13]
	v_lshl_add_u64 v[236:237], s[12:13], 0, v[132:133]
	s_mov_b32 m0, s59
	s_nop 0
	global_load_lds_dwordx4 v[236:237], off
	s_waitcnt vmcnt(8)
	s_waitcnt lgkmcnt(0)
	s_barrier
	s_setprio 1
	s_waitcnt lgkmcnt(0)
	v_mfma_f32_16x16x32_bf16 v[124:127], v[146:149], v[198:201], v[124:127]
	v_mfma_f32_16x16x32_bf16 v[120:123], v[170:173], v[198:201], v[120:123]
	v_mfma_f32_16x16x32_bf16 v[112:115], v[146:149], v[206:209], v[112:115]
	v_mfma_f32_16x16x32_bf16 v[104:107], v[170:173], v[206:209], v[104:107]
	v_mfma_f32_16x16x32_bf16 v[100:103], v[146:149], v[214:217], v[100:103]
	v_mfma_f32_16x16x32_bf16 v[92:95], v[170:173], v[214:217], v[92:95]
	v_mfma_f32_16x16x32_bf16 v[84:87], v[146:149], v[222:225], v[84:87]
	v_mfma_f32_16x16x32_bf16 v[76:79], v[170:173], v[222:225], v[76:79]
	v_mfma_f32_16x16x32_bf16 v[124:127], v[166:169], v[202:205], v[124:127]
	v_mfma_f32_16x16x32_bf16 v[120:123], v[178:181], v[202:205], v[120:123]
	v_mfma_f32_16x16x32_bf16 v[112:115], v[166:169], v[210:213], v[112:115]
	v_mfma_f32_16x16x32_bf16 v[104:107], v[178:181], v[210:213], v[104:107]
	v_mfma_f32_16x16x32_bf16 v[100:103], v[166:169], v[218:221], v[100:103]
	v_mfma_f32_16x16x32_bf16 v[92:95], v[178:181], v[218:221], v[92:95]
	v_mfma_f32_16x16x32_bf16 v[84:87], v[166:169], v[226:229], v[84:87]
	v_mfma_f32_16x16x32_bf16 v[76:79], v[178:181], v[226:229], v[76:79]
	s_setprio 0
	s_setprio 1
	v_mfma_f32_16x16x32_bf16 v[116:119], v[182:185], v[198:201], v[116:119]
	v_mfma_f32_16x16x32_bf16 v[108:111], v[190:193], v[198:201], v[108:111]
	v_mfma_f32_16x16x32_bf16 v[96:99], v[182:185], v[206:209], v[96:99]
	v_mfma_f32_16x16x32_bf16 v[88:91], v[190:193], v[206:209], v[88:91]
	v_mfma_f32_16x16x32_bf16 v[80:83], v[182:185], v[214:217], v[80:83]
	v_mfma_f32_16x16x32_bf16 v[72:75], v[190:193], v[214:217], v[72:75]
	v_mfma_f32_16x16x32_bf16 v[68:71], v[182:185], v[222:225], v[68:71]
	v_mfma_f32_16x16x32_bf16 v[64:67], v[190:193], v[222:225], v[64:67]
	v_mfma_f32_16x16x32_bf16 v[116:119], v[186:189], v[202:205], v[116:119]
	v_mfma_f32_16x16x32_bf16 v[108:111], v[194:197], v[202:205], v[108:111]
	v_mfma_f32_16x16x32_bf16 v[96:99], v[186:189], v[210:213], v[96:99]
	v_mfma_f32_16x16x32_bf16 v[88:91], v[194:197], v[210:213], v[88:91]
	v_mfma_f32_16x16x32_bf16 v[80:83], v[186:189], v[218:221], v[80:83]
	v_mfma_f32_16x16x32_bf16 v[72:75], v[194:197], v[218:221], v[72:75]
	v_mfma_f32_16x16x32_bf16 v[68:71], v[186:189], v[226:229], v[68:71]
	v_mfma_f32_16x16x32_bf16 v[64:67], v[194:197], v[226:229], v[64:67]
	s_setprio 0
	s_barrier
; #define PG8_STAGE(bufoff, gbase, voff) do { _Pragma("unroll") for (int _i = 0; _i < 2; ++_i) \
;         __builtin_amdgcn_global_load_lds((const unsigned*)((const char*)(gbase) + (voff)[_i]), (LAS unsigned*)(lds + (bufoff) + ldsw + _i * 8192), 16, 0, 0); } while (0)
; #define PG8_LDA(dst, b, h) do { _Pragma("unroll") for (int m = 0; m < 4; ++m) _Pragma("unroll") for (int k = 0; k < 2; ++k) dst[m][k] = *(const LAS bf16x8*)(lds + PG8_SA(b, h) + aoff + m * 2048 + k * 1024); } while (0)
; #define PG8_MMA(ai, bj, At, Bt) do { __builtin_amdgcn_s_setprio(1); _Pragma("unroll") for (int m = 0; m < 4; ++m) _Pragma("unroll") for (int n = 0; n < 2; ++n) _Pragma("unroll") for (int k = 0; k < 2; ++k) \
;         acc[ai][bj][m][n] = __builtin_amdgcn_mfma_f32_16x16x32_bf16(Bt[n][k], At[m][k], acc[ai][bj][m][n], 0, 0, 0); __builtin_amdgcn_s_setprio(0); } while (0)
; #define PG8_WAIT_V(n) asm volatile("s_waitcnt vmcnt(" #n ")" ::: "memory")
; #define PG8_WAIT_L(n) asm volatile("s_waitcnt lgkmcnt(" #n ")" ::: "memory")
; #define PG8_BAR __builtin_amdgcn_s_barrier()
; #define PG8_SCHED __builtin_amdgcn_sched_barrier(0)
; template <class Epi>
; __device__ __forceinline__ void gemm_phase(LAS unsigned char* lds, const Gemm g, const StaticOrder& S, const Epi& E) {
;     ...
;             PG8_LDA(At, 1, 1); PG8_STAGE(PG8_SB(1, 0), b3, voffB); PG8_STAGE(PG8_SB(1, 1), b3 + hstepB, voffB); PG8_STAGE(PG8_SA(1, 0), a3, voffA);
;             PG8_WAIT_V(8); PG8_WAIT_L(0); PG8_BAR; PG8_MMA(1, 0, At, B0); PG8_MMA(1, 1, At, B1); PG8_BAR; PG8_SCHED;
;         }
;         if (wr == 0) PG8_BAR;
	s_add_i32 s12, s88, s43
	v_lshl_add_u64 v[174:175], v[174:175], 0, s[34:35]
	s_mov_b32 m0, s12
	ds_read_b128 v[198:201], v164 offset:49152
	ds_read_b128 v[202:205], v164 offset:50176
	ds_read_b128 v[206:209], v164 offset:51200
	ds_read_b128 v[210:213], v164 offset:52224
	ds_read_b128 v[214:217], v164 offset:53248
	ds_read_b128 v[218:221], v164 offset:54272
	ds_read_b128 v[222:225], v164 offset:55296
	ds_read_b128 v[226:229], v164 offset:56320
	global_load_lds_dwordx4 v[174:175], off
	s_add_i32 m0, s12, 0x2000
	s_add_u32 s10, s10, 0x40080
	v_lshl_add_u64 v[174:175], v[230:231], 0, s[34:35]
	s_addc_u32 s11, s11, 0
	s_add_i32 s12, s89, s43
	global_load_lds_dwordx4 v[174:175], off
	s_mov_b32 m0, s12
	s_nop 0
	global_load_lds_dwordx4 v130, s[10:11]
	s_add_i32 m0, s12, 0x2000
	s_nop 0
	global_load_lds_dwordx4 v134, s[10:11]
	v_lshl_add_u64 v[174:175], v[232:233], 0, s[34:35]
	s_mov_b32 m0, s77
	s_nop 0
	global_load_lds_dwordx4 v[174:175], off
	v_lshl_add_u64 v[174:175], v[234:235], 0, s[34:35]
	s_mov_b32 m0, s78
	s_nop 0
	global_load_lds_dwordx4 v[174:175], off
	s_waitcnt vmcnt(8)
	s_waitcnt lgkmcnt(0)
	s_barrier
	s_setprio 1
	s_waitcnt lgkmcnt(0)
	v_mfma_f32_16x16x32_bf16 v[60:63], v[146:149], v[198:201], v[60:63]
	v_mfma_f32_16x16x32_bf16 v[56:59], v[170:173], v[198:201], v[56:59]
	v_mfma_f32_16x16x32_bf16 v[52:55], v[146:149], v[206:209], v[52:55]
	v_mfma_f32_16x16x32_bf16 v[44:47], v[170:173], v[206:209], v[44:47]
	v_mfma_f32_16x16x32_bf16 v[36:39], v[146:149], v[214:217], v[36:39]
	v_mfma_f32_16x16x32_bf16 v[28:31], v[170:173], v[214:217], v[28:31]
	v_mfma_f32_16x16x32_bf16 v[20:23], v[146:149], v[222:225], v[20:23]
	v_mfma_f32_16x16x32_bf16 v[12:15], v[170:173], v[222:225], v[12:15]
	v_mfma_f32_16x16x32_bf16 v[60:63], v[166:169], v[202:205], v[60:63]
	v_mfma_f32_16x16x32_bf16 v[56:59], v[178:181], v[202:205], v[56:59]
	v_mfma_f32_16x16x32_bf16 v[52:55], v[166:169], v[210:213], v[52:55]
	v_mfma_f32_16x16x32_bf16 v[44:47], v[178:181], v[210:213], v[44:47]
	v_mfma_f32_16x16x32_bf16 v[36:39], v[166:169], v[218:221], v[36:39]
	v_mfma_f32_16x16x32_bf16 v[28:31], v[178:181], v[218:221], v[28:31]
	v_mfma_f32_16x16x32_bf16 v[20:23], v[166:169], v[226:229], v[20:23]
	v_mfma_f32_16x16x32_bf16 v[12:15], v[178:181], v[226:229], v[12:15]
	s_setprio 0
	s_setprio 1
	v_mfma_f32_16x16x32_bf16 v[48:51], v[182:185], v[198:201], v[48:51]
	v_mfma_f32_16x16x32_bf16 v[40:43], v[190:193], v[198:201], v[40:43]
	v_mfma_f32_16x16x32_bf16 v[32:35], v[182:185], v[206:209], v[32:35]
	v_mfma_f32_16x16x32_bf16 v[24:27], v[190:193], v[206:209], v[24:27]
	v_mfma_f32_16x16x32_bf16 v[16:19], v[182:185], v[214:217], v[16:19]
	v_mfma_f32_16x16x32_bf16 v[8:11], v[190:193], v[214:217], v[8:11]
	v_mfma_f32_16x16x32_bf16 v[4:7], v[182:185], v[222:225], v[4:7]
	v_mfma_f32_16x16x32_bf16 v[0:3], v[190:193], v[222:225], v[0:3]
	v_mfma_f32_16x16x32_bf16 v[48:51], v[186:189], v[202:205], v[48:51]
	v_mfma_f32_16x16x32_bf16 v[40:43], v[194:197], v[202:205], v[40:43]
	v_mfma_f32_16x16x32_bf16 v[32:35], v[186:189], v[210:213], v[32:35]
	v_mfma_f32_16x16x32_bf16 v[24:27], v[194:197], v[210:213], v[24:27]
	v_mfma_f32_16x16x32_bf16 v[16:19], v[186:189], v[218:221], v[16:19]
	v_mfma_f32_16x16x32_bf16 v[8:11], v[194:197], v[218:221], v[8:11]
	v_mfma_f32_16x16x32_bf16 v[4:7], v[186:189], v[226:229], v[4:7]
	v_mfma_f32_16x16x32_bf16 v[0:3], v[194:197], v[226:229], v[0:3]
	s_setprio 0
	s_barrier
	s_add_i32 s87, s87, 2
	s_add_u32 s8, s8, 0x100
	s_addc_u32 s9, s9, 0
	s_add_u32 s74, s74, 0x100
	s_addc_u32 s75, s75, 0
	s_cmp_gt_u32 s87, 13
	s_cbranch_scc0 .LBB0_1403
	s_and_b64 vcc, exec, s[38:39]
	s_cbranch_vccz .LBB0_1406
	s_barrier

; #define PG8_STAGE(bufoff, gbase, voff) do { _Pragma("unroll") for (int _i = 0; _i < 2; ++_i) \
;         __builtin_amdgcn_global_load_lds((const unsigned*)((const char*)(gbase) + (voff)[_i]), (LAS unsigned*)(lds + (bufoff) + ldsw + _i * 8192), 16, 0, 0); } while (0)
; #define PG8_WAIT_V(n) asm volatile("s_waitcnt vmcnt(" #n ")" ::: "memory")
; #define PG8_BAR __builtin_amdgcn_s_barrier()
; template <class Epi>
; __device__ __forceinline__ void gemm_phase(LAS unsigned char* lds, const Gemm g, const StaticOrder& S, const Epi& E) {
;     ...
;     const char* cA = (const char*)g.A + (size_t)cur.pm * tstepA; const char* cB = (const char*)g.Bt + (size_t)cur.pn * tstepB;
;     PG8_STAGE(PG8_SB(0, 0), cB, voffB); PG8_STAGE(PG8_SB(0, 1), cB + hstepB, voffB); PG8_STAGE(PG8_SA(0, 0), cA, voffA); PG8_STAGE(PG8_SA(0, 1), cA + hstepA, voffA);
;     if (wr == 1) PG8_BAR;
;     PG8_WAIT_V(2); PG8_BAR;
;     PG8_STAGE(PG8_SB(1, 0), cB + kstep, voffB); PG8_STAGE(PG8_SA(1, 0), cA + kstep, voffA); PG8_STAGE(PG8_SB(1, 1), cB + hstepB + kstep, voffB);
;     PG8_WAIT_V(6); PG8_BAR;
;     for (;;) {
;         const bool has_next = S.next(ui + 1, nxt);
;         const char* nA = has_next ? (const char*)g.A + (size_t)nxt.pm * tstepA : cA; const char* nB = has_next ? (const char*)g.Bt + (size_t)nxt.pn * tstepB : cB;
.LBB0_1459:
	s_add_u32 s8, s50, 0x120000
	s_mov_b64 s[10:11], 0x80
	s_addc_u32 s9, s51, 0
	s_lshl_b32 s75, s4, 6
	s_lshl_b32 s1, s4, 13
	s_lshl_b32 s4, s5, 5
	s_add_i32 m0, s35, 0x18000
	v_lshl_add_u64 v[6:7], v[6:7], 0, s[10:11]
	s_and_b32 s76, s4, 0x60
	s_waitcnt vmcnt(2)
	s_barrier
	global_load_lds_dwordx4 v[6:7], off
	v_lshl_add_u64 v[4:5], v[4:5], 0, s[10:11]
	s_add_i32 m0, s35, 0x1a000
	s_add_i32 s77, s35, 0x8000
	s_add_i32 s78, s35, 0xa000
	global_load_lds_dwordx4 v[4:5], off
	v_lshl_add_u64 v[0:1], v[0:1], 0, s[10:11]
	s_mov_b32 m0, s77
	s_add_u32 s4, s38, 0x10080
	global_load_lds_dwordx4 v[0:1], off
	v_lshl_add_u64 v[0:1], v[2:3], 0, s[10:11]
	s_mov_b32 m0, s78
	s_addc_u32 s5, s39, 0
	global_load_lds_dwordx4 v[0:1], off
	s_add_i32 m0, s35, 0x1c000
	global_load_lds_dwordx4 v130, s[4:5]
	s_add_i32 m0, s35, 0x1e000
	s_cmpk_lt_u32 s12, 0x100
	global_load_lds_dwordx4 v134, s[4:5]
	v_lshlrev_b32_e32 v1, 2, v151
	v_lshl_or_b32 v0, v151, 6, v154
	v_and_b32_e32 v1, 32, v1
	v_bitop3_b32 v0, v0, s1, v1 bitop3:0xde
	s_waitcnt vmcnt(6)
	v_readlane_b32 s16, v254, 6
	v_lshl_or_b32 v144, s76, 7, v155
	s_cselect_b64 s[12:13], -1, 0
	v_readlane_b32 s18, v254, 8
	s_add_i32 s82, 0, 0x10000
	s_add_i32 s83, 0, 0x14000
	v_add_u32_e32 v147, 0, v0
	v_mbcnt_lo_u32_b32 v0, -1, 0
	s_ashr_i32 s79, s18, 31
	s_mov_b32 s80, s18
	s_ashr_i32 s81, s2, 31
	v_mov_b64_e32 v[136:137], 0x200
	v_mov_b64_e32 v[138:139], 0x1ff
	v_add_u32_e32 v145, s82, v144
	v_add_u32_e32 v146, s83, v144
	v_mbcnt_hi_u32_b32 v148, -1, v0
	s_barrier
	v_readlane_b32 s17, v254, 7
	v_readlane_b32 s19, v254, 9
	s_branch .LBB0_1462

; #define PG8_STAGE(bufoff, gbase, voff) do { _Pragma("unroll") for (int _i = 0; _i < 2; ++_i) \
;         __builtin_amdgcn_global_load_lds((const unsigned*)((const char*)(gbase) + (voff)[_i]), (LAS unsigned*)(lds + (bufoff) + ldsw + _i * 8192), 16, 0, 0); } while (0)
; #define PG8_LDA(dst, b, h) do { _Pragma("unroll") for (int m = 0; m < 4; ++m) _Pragma("unroll") for (int k = 0; k < 2; ++k) dst[m][k] = *(const LAS bf16x8*)(lds + PG8_SA(b, h) + aoff + m * 2048 + k * 1024); } while (0)
; #define PG8_LDB(dst, b, h) do { _Pragma("unroll") for (int n = 0; n < 2; ++n) _Pragma("unroll") for (int k = 0; k < 2; ++k) dst[n][k] = *(const LAS bf16x8*)(lds + PG8_SB(b, h) + boff + n * 2048 + k * 1024); } while (0)
; #define PG8_MMA(ai, bj, At, Bt) do { __builtin_amdgcn_s_setprio(1); _Pragma("unroll") for (int m = 0; m < 4; ++m) _Pragma("unroll") for (int n = 0; n < 2; ++n) _Pragma("unroll") for (int k = 0; k < 2; ++k) \
;         acc[ai][bj][m][n] = __builtin_amdgcn_mfma_f32_16x16x32_bf16(Bt[n][k], At[m][k], acc[ai][bj][m][n], 0, 0, 0); __builtin_amdgcn_s_setprio(0); } while (0)
; #define PG8_WAIT_V(n) asm volatile("s_waitcnt vmcnt(" #n ")" ::: "memory")
; #define PG8_WAIT_L(n) asm volatile("s_waitcnt lgkmcnt(" #n ")" ::: "memory")
; #define PG8_BAR __builtin_amdgcn_s_barrier()
; #define PG8_SCHED __builtin_amdgcn_sched_barrier(0)
; template <class Epi>
; __device__ __forceinline__ void gemm_phase(LAS unsigned char* lds, const Gemm g, const StaticOrder& S, const Epi& E) {
;     ...
;         for (int t = 0; t < nt; t += 2) {
;             const bool last = (t == nt - 2);
;             const char* a1 = cA + (size_t)(t + 1) * kstep;
;             const char* a2 = last ? nA : cA + (size_t)(t + 2) * kstep; const char* b2 = last ? nB : cB + (size_t)(t + 2) * kstep;
;             const char* a3 = a2 + kstep; const char* b3 = b2 + kstep;
;             PG8_LDB(B0, 0, 0); PG8_LDB(B1, 0, 1); PG8_SCHED; PG8_LDA(At, 0, 0); PG8_STAGE(PG8_SA(1, 1), a1 + hstepA, voffA);
;             PG8_WAIT_V(8); PG8_WAIT_L(0); PG8_BAR; PG8_MMA(0, 0, At, B0); PG8_MMA(0, 1, At, B1); PG8_BAR; PG8_SCHED;
;             PG8_LDA(At, 0, 1); PG8_STAGE(PG8_SB(0, 0), b2, voffB); PG8_STAGE(PG8_SB(0, 1), b2 + hstepB, voffB); PG8_STAGE(PG8_SA(0, 0), a2, voffA);
;             PG8_WAIT_V(8); PG8_WAIT_L(0); PG8_BAR; PG8_MMA(1, 0, At, B0); PG8_MMA(1, 1, At, B1); PG8_BAR; PG8_SCHED;
.LBB0_1469:
	s_add_u32 s62, s42, s56
	s_addc_u32 s63, s43, s57
	s_add_u32 s60, s62, 0x100
	s_addc_u32 s61, s63, 0
	s_and_b64 s[58:59], s[54:55], exec
	s_cselect_b32 s59, s1, s61
	s_cselect_b32 s58, s19, s60
	s_add_u32 s56, s38, s56
	s_addc_u32 s57, s39, s57
	s_add_u32 s56, s56, 0x100
	s_addc_u32 s57, s57, 0
	s_and_b64 s[54:55], s[54:55], exec
	s_cselect_b32 s61, s17, s57
	s_cselect_b32 s60, s84, s56
	s_add_u32 s64, s62, 0x10080
	ds_read_b128 v[140:143], v145
	ds_read_b128 v[154:157], v145 offset:1024
	ds_read_b128 v[158:161], v145 offset:2048
	ds_read_b128 v[162:165], v145 offset:3072
	ds_read_b128 v[166:169], v146
	ds_read_b128 v[170:173], v146 offset:1024
	ds_read_b128 v[178:181], v146 offset:2048
	ds_read_b128 v[182:185], v146 offset:3072
	s_addc_u32 s65, s63, 0
	s_add_i32 s94, s82, s70
	s_add_i32 m0, s35, 0xc000
	s_add_i32 s95, s35, 0xe000
	s_add_i32 s91, s94, 0x2000
	s_add_u32 s62, s60, 0x10000
	s_addc_u32 s63, s61, 0
	s_add_i32 s93, s83, s70
	s_add_i32 s92, s93, 0x2000
	s_add_i32 s90, 0, 0x18000
	s_add_i32 s89, 0, 0x1c000
	s_add_u32 s56, s58, 0x10000
	s_addc_u32 s57, s59, 0
	s_add_i32 s88, s90, s70
	s_add_i32 s86, s88, 0x2000
	s_add_u32 s54, s60, 0x10080
	s_addc_u32 s55, s61, 0
	s_add_i32 s87, s89, s70
	s_add_i32 s85, s87, 0x2000
	ds_read_b128 v[186:189], v147
	ds_read_b128 v[190:193], v147 offset:1024
	ds_read_b128 v[194:197], v147 offset:2048
	ds_read_b128 v[198:201], v147 offset:3072
	ds_read_b128 v[202:205], v147 offset:4096
	ds_read_b128 v[206:209], v147 offset:5120
	ds_read_b128 v[210:213], v147 offset:6144
	ds_read_b128 v[214:217], v147 offset:7168
	global_load_lds_dwordx4 v128, s[64:65]
	s_mov_b32 m0, s95
	s_nop 0
	global_load_lds_dwordx4 v132, s[64:65]
	s_waitcnt vmcnt(8)
	s_waitcnt lgkmcnt(0)
	s_barrier
	s_setprio 1
	s_waitcnt lgkmcnt(0)
	v_mfma_f32_16x16x32_bf16 v[124:127], v[140:143], v[186:189], v[124:127]
	v_mfma_f32_16x16x32_bf16 v[120:123], v[158:161], v[186:189], v[120:123]
	v_mfma_f32_16x16x32_bf16 v[108:111], v[140:143], v[194:197], v[108:111]
	v_mfma_f32_16x16x32_bf16 v[104:107], v[158:161], v[194:197], v[104:107]
	v_mfma_f32_16x16x32_bf16 v[92:95], v[140:143], v[202:205], v[92:95]
	v_mfma_f32_16x16x32_bf16 v[88:91], v[158:161], v[202:205], v[88:91]
	v_mfma_f32_16x16x32_bf16 v[76:79], v[140:143], v[210:213], v[76:79]
	v_mfma_f32_16x16x32_bf16 v[72:75], v[158:161], v[210:213], v[72:75]
	v_mfma_f32_16x16x32_bf16 v[124:127], v[154:157], v[190:193], v[124:127]
	v_mfma_f32_16x16x32_bf16 v[120:123], v[162:165], v[190:193], v[120:123]
	v_mfma_f32_16x16x32_bf16 v[108:111], v[154:157], v[198:201], v[108:111]
	v_mfma_f32_16x16x32_bf16 v[104:107], v[162:165], v[198:201], v[104:107]
	v_mfma_f32_16x16x32_bf16 v[92:95], v[154:157], v[206:209], v[92:95]
	v_mfma_f32_16x16x32_bf16 v[88:91], v[162:165], v[206:209], v[88:91]
	v_mfma_f32_16x16x32_bf16 v[76:79], v[154:157], v[214:217], v[76:79]
	v_mfma_f32_16x16x32_bf16 v[72:75], v[162:165], v[214:217], v[72:75]
	s_setprio 0
	s_setprio 1
	v_mfma_f32_16x16x32_bf16 v[116:119], v[166:169], v[186:189], v[116:119]
	v_mfma_f32_16x16x32_bf16 v[112:115], v[178:181], v[186:189], v[112:115]
	v_mfma_f32_16x16x32_bf16 v[100:103], v[166:169], v[194:197], v[100:103]
	v_mfma_f32_16x16x32_bf16 v[96:99], v[178:181], v[194:197], v[96:99]
	v_mfma_f32_16x16x32_bf16 v[84:87], v[166:169], v[202:205], v[84:87]
	v_mfma_f32_16x16x32_bf16 v[80:83], v[178:181], v[202:205], v[80:83]
	v_mfma_f32_16x16x32_bf16 v[68:71], v[166:169], v[210:213], v[68:71]
	v_mfma_f32_16x16x32_bf16 v[64:67], v[178:181], v[210:213], v[64:67]
	v_mfma_f32_16x16x32_bf16 v[116:119], v[170:173], v[190:193], v[116:119]
	v_mfma_f32_16x16x32_bf16 v[112:115], v[182:185], v[190:193], v[112:115]
	v_mfma_f32_16x16x32_bf16 v[100:103], v[170:173], v[198:201], v[100:103]
	v_mfma_f32_16x16x32_bf16 v[96:99], v[182:185], v[198:201], v[96:99]
	v_mfma_f32_16x16x32_bf16 v[84:87], v[170:173], v[206:209], v[84:87]
	v_mfma_f32_16x16x32_bf16 v[80:83], v[182:185], v[206:209], v[80:83]
	v_mfma_f32_16x16x32_bf16 v[68:71], v[170:173], v[214:217], v[68:71]
	v_mfma_f32_16x16x32_bf16 v[64:67], v[182:185], v[214:217], v[64:67]
	s_setprio 0
	s_barrier
	s_mov_b32 m0, s94
	v_lshl_add_u64 v[174:175], s[60:61], 0, v[130:131]
	ds_read_b128 v[186:189], v147 offset:16384
	ds_read_b128 v[190:193], v147 offset:17408
	ds_read_b128 v[194:197], v147 offset:18432
	ds_read_b128 v[198:201], v147 offset:19456
	ds_read_b128 v[202:205], v147 offset:20480
	ds_read_b128 v[206:209], v147 offset:21504
	ds_read_b128 v[210:213], v147 offset:22528
	ds_read_b128 v[214:217], v147 offset:23552
	global_load_lds_dwordx4 v[174:175], off
	v_lshl_add_u64 v[218:219], s[60:61], 0, v[134:135]
	s_mov_b32 m0, s91
	global_load_lds_dwordx4 v[218:219], off
	s_mov_b32 m0, s93
	v_lshl_add_u64 v[222:223], s[58:59], 0, v[132:133]
	global_load_lds_dwordx4 v130, s[62:63]
	s_mov_b32 m0, s92
	s_nop 0
	global_load_lds_dwordx4 v134, s[62:63]
	v_lshl_add_u64 v[220:221], s[58:59], 0, v[128:129]
	s_mov_b32 m0, s35
	s_nop 0
	global_load_lds_dwordx4 v[220:221], off
	s_mov_b32 m0, s71
	s_nop 0
	global_load_lds_dwordx4 v[222:223], off
	s_waitcnt vmcnt(8)
	s_waitcnt lgkmcnt(0)
	s_barrier
; #define PG8_STAGE(bufoff, gbase, voff) do { _Pragma("unroll") for (int _i = 0; _i < 2; ++_i) \
;         __builtin_amdgcn_global_load_lds((const unsigned*)((const char*)(gbase) + (voff)[_i]), (LAS unsigned*)(lds + (bufoff) + ldsw + _i * 8192), 16, 0, 0); } while (0)
; #define PG8_LDA(dst, b, h) do { _Pragma("unroll") for (int m = 0; m < 4; ++m) _Pragma("unroll") for (int k = 0; k < 2; ++k) dst[m][k] = *(const LAS bf16x8*)(lds + PG8_SA(b, h) + aoff + m * 2048 + k * 1024); } while (0)
; #define PG8_LDB(dst, b, h) do { _Pragma("unroll") for (int n = 0; n < 2; ++n) _Pragma("unroll") for (int k = 0; k < 2; ++k) dst[n][k] = *(const LAS bf16x8*)(lds + PG8_SB(b, h) + boff + n * 2048 + k * 1024); } while (0)
; #define PG8_MMA(ai, bj, At, Bt) do { __builtin_amdgcn_s_setprio(1); _Pragma("unroll") for (int m = 0; m < 4; ++m) _Pragma("unroll") for (int n = 0; n < 2; ++n) _Pragma("unroll") for (int k = 0; k < 2; ++k) \
;         acc[ai][bj][m][n] = __builtin_amdgcn_mfma_f32_16x16x32_bf16(Bt[n][k], At[m][k], acc[ai][bj][m][n], 0, 0, 0); __builtin_amdgcn_s_setprio(0); } while (0)
; #define PG8_WAIT_V(n) asm volatile("s_waitcnt vmcnt(" #n ")" ::: "memory")
; #define PG8_WAIT_L(n) asm volatile("s_waitcnt lgkmcnt(" #n ")" ::: "memory")
; #define PG8_BAR __builtin_amdgcn_s_barrier()
; #define PG8_SCHED __builtin_amdgcn_sched_barrier(0)
; template <class Epi>
; __device__ __forceinline__ void gemm_phase(LAS unsigned char* lds, const Gemm g, const StaticOrder& S, const Epi& E) {
;     ...
;             PG8_WAIT_V(8); PG8_WAIT_L(0); PG8_BAR; PG8_MMA(1, 0, At, B0); PG8_MMA(1, 1, At, B1); PG8_BAR; PG8_SCHED;
;             PG8_LDB(B0, 1, 0); PG8_LDB(B1, 1, 1); PG8_SCHED; PG8_LDA(At, 1, 0); PG8_STAGE(PG8_SA(0, 1), a2 + hstepA, voffA);
;             PG8_WAIT_V(8); PG8_WAIT_L(0); PG8_BAR; PG8_MMA(0, 0, At, B0); PG8_MMA(0, 1, At, B1); PG8_BAR; PG8_SCHED;
	s_setprio 1
	s_waitcnt lgkmcnt(0)
	v_mfma_f32_16x16x32_bf16 v[60:63], v[140:143], v[186:189], v[60:63]
	v_mfma_f32_16x16x32_bf16 v[56:59], v[158:161], v[186:189], v[56:59]
	v_mfma_f32_16x16x32_bf16 v[44:47], v[140:143], v[194:197], v[44:47]
	v_mfma_f32_16x16x32_bf16 v[40:43], v[158:161], v[194:197], v[40:43]
	v_mfma_f32_16x16x32_bf16 v[28:31], v[140:143], v[202:205], v[28:31]
	v_mfma_f32_16x16x32_bf16 v[24:27], v[158:161], v[202:205], v[24:27]
	v_mfma_f32_16x16x32_bf16 v[12:15], v[140:143], v[210:213], v[12:15]
	v_mfma_f32_16x16x32_bf16 v[8:11], v[158:161], v[210:213], v[8:11]
	v_mfma_f32_16x16x32_bf16 v[60:63], v[154:157], v[190:193], v[60:63]
	v_mfma_f32_16x16x32_bf16 v[56:59], v[162:165], v[190:193], v[56:59]
	v_mfma_f32_16x16x32_bf16 v[44:47], v[154:157], v[198:201], v[44:47]
	v_mfma_f32_16x16x32_bf16 v[40:43], v[162:165], v[198:201], v[40:43]
	v_mfma_f32_16x16x32_bf16 v[28:31], v[154:157], v[206:209], v[28:31]
	v_mfma_f32_16x16x32_bf16 v[24:27], v[162:165], v[206:209], v[24:27]
	v_mfma_f32_16x16x32_bf16 v[12:15], v[154:157], v[214:217], v[12:15]
	v_mfma_f32_16x16x32_bf16 v[8:11], v[162:165], v[214:217], v[8:11]
	s_setprio 0
	s_setprio 1
	v_mfma_f32_16x16x32_bf16 v[52:55], v[166:169], v[186:189], v[52:55]
	v_mfma_f32_16x16x32_bf16 v[48:51], v[178:181], v[186:189], v[48:51]
	v_mfma_f32_16x16x32_bf16 v[36:39], v[166:169], v[194:197], v[36:39]
	v_mfma_f32_16x16x32_bf16 v[32:35], v[178:181], v[194:197], v[32:35]
	v_mfma_f32_16x16x32_bf16 v[20:23], v[166:169], v[202:205], v[20:23]
	v_mfma_f32_16x16x32_bf16 v[16:19], v[178:181], v[202:205], v[16:19]
	v_mfma_f32_16x16x32_bf16 v[4:7], v[166:169], v[210:213], v[4:7]
	v_mfma_f32_16x16x32_bf16 v[0:3], v[178:181], v[210:213], v[0:3]
	v_mfma_f32_16x16x32_bf16 v[52:55], v[170:173], v[190:193], v[52:55]
	v_mfma_f32_16x16x32_bf16 v[48:51], v[182:185], v[190:193], v[48:51]
	v_mfma_f32_16x16x32_bf16 v[36:39], v[170:173], v[198:201], v[36:39]
	v_mfma_f32_16x16x32_bf16 v[32:35], v[182:185], v[198:201], v[32:35]
	v_mfma_f32_16x16x32_bf16 v[20:23], v[170:173], v[206:209], v[20:23]
	v_mfma_f32_16x16x32_bf16 v[16:19], v[182:185], v[206:209], v[16:19]
	v_mfma_f32_16x16x32_bf16 v[4:7], v[170:173], v[214:217], v[4:7]
	v_mfma_f32_16x16x32_bf16 v[0:3], v[182:185], v[214:217], v[0:3]
	s_setprio 0
	s_barrier
	v_add_u32_e32 v149, s90, v144
	ds_read_b128 v[140:143], v149
	ds_read_b128 v[154:157], v149 offset:1024
	ds_read_b128 v[158:161], v149 offset:2048
	ds_read_b128 v[162:165], v149 offset:3072
	v_add_u32_e32 v149, s89, v144
	ds_read_b128 v[166:169], v149
	ds_read_b128 v[170:173], v149 offset:1024
	ds_read_b128 v[178:181], v149 offset:2048
	ds_read_b128 v[182:185], v149 offset:3072
	s_mov_b32 m0, s72
	ds_read_b128 v[186:189], v147 offset:32768
	ds_read_b128 v[190:193], v147 offset:33792
	ds_read_b128 v[194:197], v147 offset:34816
	ds_read_b128 v[198:201], v147 offset:35840
	ds_read_b128 v[202:205], v147 offset:36864
	ds_read_b128 v[206:209], v147 offset:37888
	ds_read_b128 v[210:213], v147 offset:38912
	ds_read_b128 v[214:217], v147 offset:39936
	global_load_lds_dwordx4 v128, s[56:57]
	s_mov_b32 m0, s73
	s_nop 0
	global_load_lds_dwordx4 v132, s[56:57]
	s_waitcnt vmcnt(8)
	s_waitcnt lgkmcnt(0)
	s_barrier
	s_setprio 1
	s_waitcnt lgkmcnt(0)
	v_mfma_f32_16x16x32_bf16 v[124:127], v[140:143], v[186:189], v[124:127]
	v_mfma_f32_16x16x32_bf16 v[120:123], v[158:161], v[186:189], v[120:123]
	v_mfma_f32_16x16x32_bf16 v[108:111], v[140:143], v[194:197], v[108:111]
	v_mfma_f32_16x16x32_bf16 v[104:107], v[158:161], v[194:197], v[104:107]
	v_mfma_f32_16x16x32_bf16 v[92:95], v[140:143], v[202:205], v[92:95]
	v_mfma_f32_16x16x32_bf16 v[88:91], v[158:161], v[202:205], v[88:91]
	v_mfma_f32_16x16x32_bf16 v[76:79], v[140:143], v[210:213], v[76:79]
	v_mfma_f32_16x16x32_bf16 v[72:75], v[158:161], v[210:213], v[72:75]
	v_mfma_f32_16x16x32_bf16 v[124:127], v[154:157], v[190:193], v[124:127]
	v_mfma_f32_16x16x32_bf16 v[120:123], v[162:165], v[190:193], v[120:123]
	v_mfma_f32_16x16x32_bf16 v[108:111], v[154:157], v[198:201], v[108:111]
	v_mfma_f32_16x16x32_bf16 v[104:107], v[162:165], v[198:201], v[104:107]
	v_mfma_f32_16x16x32_bf16 v[92:95], v[154:157], v[206:209], v[92:95]
	v_mfma_f32_16x16x32_bf16 v[88:91], v[162:165], v[206:209], v[88:91]
	v_mfma_f32_16x16x32_bf16 v[76:79], v[154:157], v[214:217], v[76:79]
	v_mfma_f32_16x16x32_bf16 v[72:75], v[162:165], v[214:217], v[72:75]
	s_setprio 0
	s_setprio 1
	v_mfma_f32_16x16x32_bf16 v[116:119], v[166:169], v[186:189], v[116:119]
	v_mfma_f32_16x16x32_bf16 v[112:115], v[178:181], v[186:189], v[112:115]
	v_mfma_f32_16x16x32_bf16 v[100:103], v[166:169], v[194:197], v[100:103]
	v_mfma_f32_16x16x32_bf16 v[96:99], v[178:181], v[194:197], v[96:99]
	v_mfma_f32_16x16x32_bf16 v[84:87], v[166:169], v[202:205], v[84:87]
	v_mfma_f32_16x16x32_bf16 v[80:83], v[178:181], v[202:205], v[80:83]
	v_mfma_f32_16x16x32_bf16 v[68:71], v[166:169], v[210:213], v[68:71]
	v_mfma_f32_16x16x32_bf16 v[64:67], v[178:181], v[210:213], v[64:67]
	v_mfma_f32_16x16x32_bf16 v[116:119], v[170:173], v[190:193], v[116:119]
	v_mfma_f32_16x16x32_bf16 v[112:115], v[182:185], v[190:193], v[112:115]
	v_mfma_f32_16x16x32_bf16 v[100:103], v[170:173], v[198:201], v[100:103]
	v_mfma_f32_16x16x32_bf16 v[96:99], v[182:185], v[198:201], v[96:99]
	v_mfma_f32_16x16x32_bf16 v[84:87], v[170:173], v[206:209], v[84:87]
	v_mfma_f32_16x16x32_bf16 v[80:83], v[182:185], v[206:209], v[80:83]
	v_mfma_f32_16x16x32_bf16 v[68:71], v[170:173], v[214:217], v[68:71]
	v_mfma_f32_16x16x32_bf16 v[64:67], v[182:185], v[214:217], v[64:67]
	s_setprio 0
	s_barrier
; #define PG8_STAGE(bufoff, gbase, voff) do { _Pragma("unroll") for (int _i = 0; _i < 2; ++_i) \
;         __builtin_amdgcn_global_load_lds((const unsigned*)((const char*)(gbase) + (voff)[_i]), (LAS unsigned*)(lds + (bufoff) + ldsw + _i * 8192), 16, 0, 0); } while (0)
; #define PG8_LDA(dst, b, h) do { _Pragma("unroll") for (int m = 0; m < 4; ++m) _Pragma("unroll") for (int k = 0; k < 2; ++k) dst[m][k] = *(const LAS bf16x8*)(lds + PG8_SA(b, h) + aoff + m * 2048 + k * 1024); } while (0)
; #define PG8_MMA(ai, bj, At, Bt) do { __builtin_amdgcn_s_setprio(1); _Pragma("unroll") for (int m = 0; m < 4; ++m) _Pragma("unroll") for (int n = 0; n < 2; ++n) _Pragma("unroll") for (int k = 0; k < 2; ++k) \
;         acc[ai][bj][m][n] = __builtin_amdgcn_mfma_f32_16x16x32_bf16(Bt[n][k], At[m][k], acc[ai][bj][m][n], 0, 0, 0); __builtin_amdgcn_s_setprio(0); } while (0)
; #define PG8_WAIT_V(n) asm volatile("s_waitcnt vmcnt(" #n ")" ::: "memory")
; #define PG8_WAIT_L(n) asm volatile("s_waitcnt lgkmcnt(" #n ")" ::: "memory")
; #define PG8_BAR __builtin_amdgcn_s_barrier()
; #define PG8_SCHED __builtin_amdgcn_sched_barrier(0)
; template <class Epi>
; __device__ __forceinline__ void gemm_phase(LAS unsigned char* lds, const Gemm g, const StaticOrder& S, const Epi& E) {
;     ...
;             PG8_LDA(At, 1, 1); PG8_STAGE(PG8_SB(1, 0), b3, voffB); PG8_STAGE(PG8_SB(1, 1), b3 + hstepB, voffB); PG8_STAGE(PG8_SA(1, 0), a3, voffA);
;             PG8_WAIT_V(8); PG8_WAIT_L(0); PG8_BAR; PG8_MMA(1, 0, At, B0); PG8_MMA(1, 1, At, B1); PG8_BAR; PG8_SCHED;
;         }
;         if (wr == 0) PG8_BAR;
	s_mov_b32 m0, s88
	v_lshl_add_u64 v[174:175], v[174:175], 0, s[10:11]
	ds_read_b128 v[186:189], v147 offset:49152
	ds_read_b128 v[190:193], v147 offset:50176
	ds_read_b128 v[194:197], v147 offset:51200
	ds_read_b128 v[198:201], v147 offset:52224
	ds_read_b128 v[202:205], v147 offset:53248
	ds_read_b128 v[206:209], v147 offset:54272
	ds_read_b128 v[210:213], v147 offset:55296
	ds_read_b128 v[214:217], v147 offset:56320
	global_load_lds_dwordx4 v[174:175], off
	v_lshl_add_u64 v[174:175], v[218:219], 0, s[10:11]
	s_mov_b32 m0, s86
	s_nop 0
	global_load_lds_dwordx4 v[174:175], off
	s_mov_b32 m0, s87
	s_nop 0
	global_load_lds_dwordx4 v130, s[54:55]
	s_mov_b32 m0, s85
	s_nop 0
	global_load_lds_dwordx4 v134, s[54:55]
	v_lshl_add_u64 v[174:175], v[220:221], 0, s[10:11]
	s_mov_b32 m0, s77
	s_nop 0
	global_load_lds_dwordx4 v[174:175], off
	v_lshl_add_u64 v[174:175], v[222:223], 0, s[10:11]
	s_mov_b32 m0, s78
	s_nop 0
	global_load_lds_dwordx4 v[174:175], off
	s_waitcnt vmcnt(8)
	s_waitcnt lgkmcnt(0)
	s_barrier
	s_setprio 1
	s_waitcnt lgkmcnt(0)
	v_mfma_f32_16x16x32_bf16 v[60:63], v[140:143], v[186:189], v[60:63]
	v_mfma_f32_16x16x32_bf16 v[56:59], v[158:161], v[186:189], v[56:59]
	v_mfma_f32_16x16x32_bf16 v[44:47], v[140:143], v[194:197], v[44:47]
	v_mfma_f32_16x16x32_bf16 v[40:43], v[158:161], v[194:197], v[40:43]
	v_mfma_f32_16x16x32_bf16 v[28:31], v[140:143], v[202:205], v[28:31]
	v_mfma_f32_16x16x32_bf16 v[24:27], v[158:161], v[202:205], v[24:27]
	v_mfma_f32_16x16x32_bf16 v[12:15], v[140:143], v[210:213], v[12:15]
	v_mfma_f32_16x16x32_bf16 v[8:11], v[158:161], v[210:213], v[8:11]
	v_mfma_f32_16x16x32_bf16 v[60:63], v[154:157], v[190:193], v[60:63]
	v_mfma_f32_16x16x32_bf16 v[56:59], v[162:165], v[190:193], v[56:59]
	v_mfma_f32_16x16x32_bf16 v[44:47], v[154:157], v[198:201], v[44:47]
	v_mfma_f32_16x16x32_bf16 v[40:43], v[162:165], v[198:201], v[40:43]
	v_mfma_f32_16x16x32_bf16 v[28:31], v[154:157], v[206:209], v[28:31]
	v_mfma_f32_16x16x32_bf16 v[24:27], v[162:165], v[206:209], v[24:27]
	v_mfma_f32_16x16x32_bf16 v[12:15], v[154:157], v[214:217], v[12:15]
	v_mfma_f32_16x16x32_bf16 v[8:11], v[162:165], v[214:217], v[8:11]
	s_setprio 0
	s_setprio 1
	v_mfma_f32_16x16x32_bf16 v[52:55], v[166:169], v[186:189], v[52:55]
	v_mfma_f32_16x16x32_bf16 v[48:51], v[178:181], v[186:189], v[48:51]
	v_mfma_f32_16x16x32_bf16 v[36:39], v[166:169], v[194:197], v[36:39]
	v_mfma_f32_16x16x32_bf16 v[32:35], v[178:181], v[194:197], v[32:35]
	v_mfma_f32_16x16x32_bf16 v[20:23], v[166:169], v[202:205], v[20:23]
	v_mfma_f32_16x16x32_bf16 v[16:19], v[178:181], v[202:205], v[16:19]
	v_mfma_f32_16x16x32_bf16 v[4:7], v[166:169], v[210:213], v[4:7]
	v_mfma_f32_16x16x32_bf16 v[0:3], v[178:181], v[210:213], v[0:3]
	v_mfma_f32_16x16x32_bf16 v[52:55], v[170:173], v[190:193], v[52:55]
	v_mfma_f32_16x16x32_bf16 v[48:51], v[182:185], v[190:193], v[48:51]
	v_mfma_f32_16x16x32_bf16 v[36:39], v[170:173], v[198:201], v[36:39]
	v_mfma_f32_16x16x32_bf16 v[32:35], v[182:185], v[198:201], v[32:35]
	v_mfma_f32_16x16x32_bf16 v[20:23], v[170:173], v[206:209], v[20:23]
	v_mfma_f32_16x16x32_bf16 v[16:19], v[182:185], v[206:209], v[16:19]
	v_mfma_f32_16x16x32_bf16 v[4:7], v[170:173], v[214:217], v[4:7]
	v_mfma_f32_16x16x32_bf16 v[0:3], v[182:185], v[214:217], v[0:3]
	s_setprio 0
	s_barrier
	s_andn2_b64 vcc, exec, s[52:53]
	s_mov_b64 s[54:55], -1
	s_mov_b64 s[52:53], 0
	s_mov_b64 s[56:57], 0x100
	s_cbranch_vccz .LBB0_1469
	s_and_b64 vcc, exec, s[12:13]
	s_cbranch_vccz .LBB0_1472
	s_barrier

; #define PG8_STAGE(bufoff, gbase, voff) do { _Pragma("unroll") for (int _i = 0; _i < 2; ++_i) \
;         __builtin_amdgcn_global_load_lds((const unsigned*)((const char*)(gbase) + (voff)[_i]), (LAS unsigned*)(lds + (bufoff) + ldsw + _i * 8192), 16, 0, 0); } while (0)
; #define PG8_WAIT_V(n) asm volatile("s_waitcnt vmcnt(" #n ")" ::: "memory")
; #define PG8_BAR __builtin_amdgcn_s_barrier()
; template <class Epi>
; __device__ __forceinline__ void gemm_phase(LAS unsigned char* lds, const Gemm g, const StaticOrder& S, const Epi& E) {
;     ...
;     const char* cA = (const char*)g.A + (size_t)cur.pm * tstepA; const char* cB = (const char*)g.Bt + (size_t)cur.pn * tstepB;
;     PG8_STAGE(PG8_SB(0, 0), cB, voffB); PG8_STAGE(PG8_SB(0, 1), cB + hstepB, voffB); PG8_STAGE(PG8_SA(0, 0), cA, voffA); PG8_STAGE(PG8_SA(0, 1), cA + hstepA, voffA);
;     if (wr == 1) PG8_BAR;
;     PG8_WAIT_V(2); PG8_BAR;
;     PG8_STAGE(PG8_SB(1, 0), cB + kstep, voffB); PG8_STAGE(PG8_SA(1, 0), cA + kstep, voffA); PG8_STAGE(PG8_SB(1, 1), cB + hstepB + kstep, voffB);
;     PG8_WAIT_V(6); PG8_BAR;
;     for (;;) {
;         const bool has_next = S.next(ui + 1, nxt);
;         const char* nA = has_next ? (const char*)g.A + (size_t)nxt.pm * tstepA : cA; const char* nB = has_next ? (const char*)g.Bt + (size_t)nxt.pn * tstepB : cB;
.LBB0_1635:
	s_add_u32 s12, s50, 0xa0000
	s_addc_u32 s13, s51, 0
	s_lshl_b32 s38, s4, 6
	s_lshl_b32 s7, s4, 13
	s_lshl_b32 s4, s5, 5
	s_mov_b64 s[14:15], 0x80
	s_and_b32 s39, s4, 0x60
	s_add_i32 m0, s33, 0x18000
	v_lshl_add_u64 v[6:7], v[6:7], 0, s[14:15]
	s_lshl_b32 s16, s39, 7
	s_waitcnt vmcnt(2)
	s_barrier
	global_load_lds_dwordx4 v[6:7], off
	v_lshl_add_u64 v[4:5], v[4:5], 0, s[14:15]
	s_add_i32 m0, s33, 0x1a000
	s_add_i32 s42, s33, 0x8000
	s_add_i32 s43, s33, 0xa000
	global_load_lds_dwordx4 v[4:5], off
	v_lshl_add_u64 v[0:1], v[0:1], 0, s[14:15]
	s_mov_b32 m0, s42
	s_add_u32 s4, s20, 0xb0080
	global_load_lds_dwordx4 v[0:1], off
	v_lshl_add_u64 v[0:1], v[2:3], 0, s[14:15]
	s_mov_b32 m0, s43
	s_addc_u32 s5, s21, 0
	global_load_lds_dwordx4 v[0:1], off
	s_add_i32 m0, s33, 0x1c000
	global_load_lds_dwordx4 v146, s[4:5]
	s_add_i32 m0, s33, 0x1e000
	v_bfe_u32 v177, v176, 4, 2
	global_load_lds_dwordx4 v150, s[4:5]
	v_and_b32_e32 v180, 15, v176
	v_lshlrev_b32_e32 v0, 4, v177
	v_lshlrev_b32_e32 v2, 2, v176
	v_lshlrev_b32_e32 v3, 6, v176
	s_movk_i32 s4, 0x3c0
	v_lshl_or_b32 v1, v180, 6, v0
	v_and_b32_e32 v2, 32, v2
	v_and_or_b32 v0, v3, s4, v0
	v_bitop3_b32 v181, s16, v0, v2 bitop3:0xf6
	v_add_u16_e32 v0, v8, v9
	s_waitcnt vmcnt(6)
	s_cmpk_lt_u32 s6, 0x100
	v_lshrrev_b16_e32 v0, 1, v0
	v_bitop3_b32 v1, v1, s7, v2 bitop3:0xde
	s_cselect_b64 s[16:17], -1, 0
	v_add_lshl_u32 v152, v10, v0, 1
	v_add_lshl_u32 v154, v11, v0, 1
	s_add_i32 s55, 0, 0x10000
	s_add_i32 s56, 0, 0x14000
	v_mbcnt_lo_u32_b32 v0, -1, 0
	s_ashr_i32 s52, s74, 31
	s_mov_b32 s53, s74
	s_ashr_i32 s54, s2, 31
	v_mov_b32_e32 v153, v147
	v_mov_b32_e32 v155, v147
	v_mov_b64_e32 v[156:157], 0x200
	v_mov_b64_e32 v[158:159], 0x1ff
	v_add_u32_e32 v182, s55, v181
	v_add_u32_e32 v183, s56, v181
	v_add_u32_e32 v184, 0, v1
	v_mbcnt_hi_u32_b32 v185, -1, v0
	s_barrier
	s_branch .LBB0_1638

; #define PG8_STAGE(bufoff, gbase, voff) do { _Pragma("unroll") for (int _i = 0; _i < 2; ++_i) \
;         __builtin_amdgcn_global_load_lds((const unsigned*)((const char*)(gbase) + (voff)[_i]), (LAS unsigned*)(lds + (bufoff) + ldsw + _i * 8192), 16, 0, 0); } while (0)
; #define PG8_LDA(dst, b, h) do { _Pragma("unroll") for (int m = 0; m < 4; ++m) _Pragma("unroll") for (int k = 0; k < 2; ++k) dst[m][k] = *(const LAS bf16x8*)(lds + PG8_SA(b, h) + aoff + m * 2048 + k * 1024); } while (0)
; #define PG8_LDB(dst, b, h) do { _Pragma("unroll") for (int n = 0; n < 2; ++n) _Pragma("unroll") for (int k = 0; k < 2; ++k) dst[n][k] = *(const LAS bf16x8*)(lds + PG8_SB(b, h) + boff + n * 2048 + k * 1024); } while (0)
; #define PG8_MMA(ai, bj, At, Bt) do { __builtin_amdgcn_s_setprio(1); _Pragma("unroll") for (int m = 0; m < 4; ++m) _Pragma("unroll") for (int n = 0; n < 2; ++n) _Pragma("unroll") for (int k = 0; k < 2; ++k) \
;         acc[ai][bj][m][n] = __builtin_amdgcn_mfma_f32_16x16x32_bf16(Bt[n][k], At[m][k], acc[ai][bj][m][n], 0, 0, 0); __builtin_amdgcn_s_setprio(0); } while (0)
; #define PG8_WAIT_V(n) asm volatile("s_waitcnt vmcnt(" #n ")" ::: "memory")
; #define PG8_WAIT_L(n) asm volatile("s_waitcnt lgkmcnt(" #n ")" ::: "memory")
; #define PG8_BAR __builtin_amdgcn_s_barrier()
; #define PG8_SCHED __builtin_amdgcn_sched_barrier(0)
; template <class Epi>
; __device__ __forceinline__ void gemm_phase(LAS unsigned char* lds, const Gemm g, const StaticOrder& S, const Epi& E) {
;     ...
;         for (int t = 0; t < nt; t += 2) {
;             const bool last = (t == nt - 2);
;             const char* a1 = cA + (size_t)(t + 1) * kstep;
;             const char* a2 = last ? nA : cA + (size_t)(t + 2) * kstep; const char* b2 = last ? nB : cB + (size_t)(t + 2) * kstep;
;             const char* a3 = a2 + kstep; const char* b3 = b2 + kstep;
;             PG8_LDB(B0, 0, 0); PG8_LDB(B1, 0, 1); PG8_SCHED; PG8_LDA(At, 0, 0); PG8_STAGE(PG8_SA(1, 1), a1 + hstepA, voffA);
;             PG8_WAIT_V(8); PG8_WAIT_L(0); PG8_BAR; PG8_MMA(0, 0, At, B0); PG8_MMA(0, 1, At, B1); PG8_BAR; PG8_SCHED;
;             PG8_LDA(At, 0, 1); PG8_STAGE(PG8_SB(0, 0), b2, voffB); PG8_STAGE(PG8_SB(0, 1), b2 + hstepB, voffB); PG8_STAGE(PG8_SA(0, 0), a2, voffA);
;             PG8_WAIT_V(8); PG8_WAIT_L(0); PG8_BAR; PG8_MMA(1, 0, At, B0); PG8_MMA(1, 1, At, B1); PG8_BAR; PG8_SCHED;
.LBB0_1648:
	s_add_u32 s0, s0, 0xb0080
	s_addc_u32 s1, s1, 0
	s_add_u32 s61, s20, 0x100
	s_addc_u32 s62, s21, 0
	s_mov_b32 s63, -2
	s_waitcnt lgkmcnt(0)
	ds_read_b128 v[128:131], v182
	ds_read_b128 v[132:135], v182 offset:1024
	ds_read_b128 v[136:139], v182 offset:2048
	ds_read_b128 v[140:143], v182 offset:3072
	ds_read_b128 v[160:163], v183
	ds_read_b128 v[164:167], v183 offset:1024
	ds_read_b128 v[168:171], v183 offset:2048
	ds_read_b128 v[172:175], v183 offset:3072
	s_add_u32 s20, s0, 0xfff50080
	s_addc_u32 s21, s1, -1
	s_cmp_eq_u32 s63, 40
	s_cselect_b32 s23, s7, s21
	s_cselect_b32 s22, s6, s20
	s_cselect_b32 s21, s19, s62
	s_cselect_b32 s20, s18, s61
	s_add_i32 m0, s33, 0xc000
	ds_read_b128 v[186:189], v184
	ds_read_b128 v[190:193], v184 offset:1024
	ds_read_b128 v[194:197], v184 offset:2048
	ds_read_b128 v[198:201], v184 offset:3072
	ds_read_b128 v[202:205], v184 offset:4096
	ds_read_b128 v[206:209], v184 offset:5120
	ds_read_b128 v[210:213], v184 offset:6144
	ds_read_b128 v[214:217], v184 offset:7168
	global_load_lds_dwordx4 v152, s[0:1]
	s_add_i32 m0, s33, 0xe000
	s_nop 0
	global_load_lds_dwordx4 v154, s[0:1]
	s_waitcnt vmcnt(8)
	s_waitcnt lgkmcnt(0)
	s_barrier
	s_setprio 1
	s_waitcnt lgkmcnt(0)
	v_mfma_f32_16x16x32_bf16 v[124:127], v[128:131], v[186:189], 0
	v_mfma_f32_16x16x32_bf16 v[120:123], v[136:139], v[186:189], 0
	v_mfma_f32_16x16x32_bf16 v[108:111], v[128:131], v[194:197], 0
	v_mfma_f32_16x16x32_bf16 v[104:107], v[136:139], v[194:197], 0
	v_mfma_f32_16x16x32_bf16 v[92:95], v[128:131], v[202:205], 0
	v_mfma_f32_16x16x32_bf16 v[88:91], v[136:139], v[202:205], 0
	v_mfma_f32_16x16x32_bf16 v[76:79], v[128:131], v[210:213], 0
	v_mfma_f32_16x16x32_bf16 v[72:75], v[136:139], v[210:213], 0
	v_mfma_f32_16x16x32_bf16 v[124:127], v[132:135], v[190:193], v[124:127]
	v_mfma_f32_16x16x32_bf16 v[120:123], v[140:143], v[190:193], v[120:123]
	v_mfma_f32_16x16x32_bf16 v[108:111], v[132:135], v[198:201], v[108:111]
	v_mfma_f32_16x16x32_bf16 v[104:107], v[140:143], v[198:201], v[104:107]
	v_mfma_f32_16x16x32_bf16 v[92:95], v[132:135], v[206:209], v[92:95]
	v_mfma_f32_16x16x32_bf16 v[88:91], v[140:143], v[206:209], v[88:91]
	v_mfma_f32_16x16x32_bf16 v[76:79], v[132:135], v[214:217], v[76:79]
	v_mfma_f32_16x16x32_bf16 v[72:75], v[140:143], v[214:217], v[72:75]
	s_setprio 0
	s_setprio 1
	v_mfma_f32_16x16x32_bf16 v[116:119], v[160:163], v[186:189], 0
	v_mfma_f32_16x16x32_bf16 v[112:115], v[168:171], v[186:189], 0
	v_mfma_f32_16x16x32_bf16 v[100:103], v[160:163], v[194:197], 0
	v_mfma_f32_16x16x32_bf16 v[96:99], v[168:171], v[194:197], 0
	v_mfma_f32_16x16x32_bf16 v[84:87], v[160:163], v[202:205], 0
	v_mfma_f32_16x16x32_bf16 v[80:83], v[168:171], v[202:205], 0
	v_mfma_f32_16x16x32_bf16 v[68:71], v[160:163], v[210:213], 0
	v_mfma_f32_16x16x32_bf16 v[64:67], v[168:171], v[210:213], 0
	v_mfma_f32_16x16x32_bf16 v[116:119], v[164:167], v[190:193], v[116:119]
	v_mfma_f32_16x16x32_bf16 v[112:115], v[172:175], v[190:193], v[112:115]
	v_mfma_f32_16x16x32_bf16 v[100:103], v[164:167], v[198:201], v[100:103]
	v_mfma_f32_16x16x32_bf16 v[96:99], v[172:175], v[198:201], v[96:99]
	v_mfma_f32_16x16x32_bf16 v[84:87], v[164:167], v[206:209], v[84:87]
	v_mfma_f32_16x16x32_bf16 v[80:83], v[172:175], v[206:209], v[80:83]
	v_mfma_f32_16x16x32_bf16 v[68:71], v[164:167], v[214:217], v[68:71]
	v_mfma_f32_16x16x32_bf16 v[64:67], v[172:175], v[214:217], v[64:67]
	s_setprio 0
	s_barrier
	s_add_i32 s64, s55, s29
	v_lshl_add_u64 v[178:179], s[20:21], 0, v[146:147]
	s_mov_b32 m0, s64
	ds_read_b128 v[186:189], v184 offset:16384
	ds_read_b128 v[190:193], v184 offset:17408
	ds_read_b128 v[194:197], v184 offset:18432
	ds_read_b128 v[198:201], v184 offset:19456
	ds_read_b128 v[202:205], v184 offset:20480
	ds_read_b128 v[206:209], v184 offset:21504
	ds_read_b128 v[210:213], v184 offset:22528
	ds_read_b128 v[214:217], v184 offset:23552
	global_load_lds_dwordx4 v[178:179], off
	s_add_i32 m0, s64, 0x2000
	s_add_u32 s64, s20, 0xb0000
	v_lshl_add_u64 v[218:219], s[20:21], 0, v[150:151]
	s_addc_u32 s65, s21, 0
	s_add_i32 s66, s56, s29
	global_load_lds_dwordx4 v[218:219], off
	s_mov_b32 m0, s66
	v_lshl_add_u64 v[222:223], s[22:23], 0, v[148:149]
	global_load_lds_dwordx4 v146, s[64:65]
	s_add_i32 m0, s66, 0x2000
	s_nop 0
	global_load_lds_dwordx4 v150, s[64:65]
	v_lshl_add_u64 v[220:221], s[22:23], 0, v[144:145]
	s_mov_b32 m0, s33
	s_nop 0
	global_load_lds_dwordx4 v[220:221], off
	s_mov_b32 m0, s34
	s_nop 0
	global_load_lds_dwordx4 v[222:223], off
	s_waitcnt vmcnt(8)
	s_waitcnt lgkmcnt(0)
	s_barrier
	s_setprio 1
	s_waitcnt lgkmcnt(0)
	v_mfma_f32_16x16x32_bf16 v[60:63], v[128:131], v[186:189], 0
	v_mfma_f32_16x16x32_bf16 v[56:59], v[136:139], v[186:189], 0
	v_mfma_f32_16x16x32_bf16 v[44:47], v[128:131], v[194:197], 0
	v_mfma_f32_16x16x32_bf16 v[40:43], v[136:139], v[194:197], 0
	v_mfma_f32_16x16x32_bf16 v[28:31], v[128:131], v[202:205], 0
	v_mfma_f32_16x16x32_bf16 v[24:27], v[136:139], v[202:205], 0
	v_mfma_f32_16x16x32_bf16 v[12:15], v[128:131], v[210:213], 0
	v_mfma_f32_16x16x32_bf16 v[8:11], v[136:139], v[210:213], 0
	v_mfma_f32_16x16x32_bf16 v[60:63], v[132:135], v[190:193], v[60:63]
	v_mfma_f32_16x16x32_bf16 v[56:59], v[140:143], v[190:193], v[56:59]
	v_mfma_f32_16x16x32_bf16 v[44:47], v[132:135], v[198:201], v[44:47]
	v_mfma_f32_16x16x32_bf16 v[40:43], v[140:143], v[198:201], v[40:43]
	v_mfma_f32_16x16x32_bf16 v[28:31], v[132:135], v[206:209], v[28:31]
	v_mfma_f32_16x16x32_bf16 v[24:27], v[140:143], v[206:209], v[24:27]
	v_mfma_f32_16x16x32_bf16 v[12:15], v[132:135], v[214:217], v[12:15]
	v_mfma_f32_16x16x32_bf16 v[8:11], v[140:143], v[214:217], v[8:11]
	s_setprio 0
	s_setprio 1
	v_mfma_f32_16x16x32_bf16 v[52:55], v[160:163], v[186:189], 0
	v_mfma_f32_16x16x32_bf16 v[48:51], v[168:171], v[186:189], 0
	v_mfma_f32_16x16x32_bf16 v[36:39], v[160:163], v[194:197], 0
	v_mfma_f32_16x16x32_bf16 v[32:35], v[168:171], v[194:197], 0
	v_mfma_f32_16x16x32_bf16 v[20:23], v[160:163], v[202:205], 0
	v_mfma_f32_16x16x32_bf16 v[16:19], v[168:171], v[202:205], 0
	v_mfma_f32_16x16x32_bf16 v[4:7], v[160:163], v[210:213], 0
	v_mfma_f32_16x16x32_bf16 v[0:3], v[168:171], v[210:213], 0
	v_mfma_f32_16x16x32_bf16 v[52:55], v[164:167], v[190:193], v[52:55]
	v_mfma_f32_16x16x32_bf16 v[48:51], v[172:175], v[190:193], v[48:51]
	v_mfma_f32_16x16x32_bf16 v[36:39], v[164:167], v[198:201], v[36:39]
	v_mfma_f32_16x16x32_bf16 v[32:35], v[172:175], v[198:201], v[32:35]
	v_mfma_f32_16x16x32_bf16 v[20:23], v[164:167], v[206:209], v[20:23]
	v_mfma_f32_16x16x32_bf16 v[16:19], v[172:175], v[206:209], v[16:19]
	v_mfma_f32_16x16x32_bf16 v[4:7], v[164:167], v[214:217], v[4:7]
	v_mfma_f32_16x16x32_bf16 v[0:3], v[172:175], v[214:217], v[0:3]
	s_setprio 0
	s_barrier
; #define PG8_STAGE(bufoff, gbase, voff) do { _Pragma("unroll") for (int _i = 0; _i < 2; ++_i) \
;         __builtin_amdgcn_global_load_lds((const unsigned*)((const char*)(gbase) + (voff)[_i]), (LAS unsigned*)(lds + (bufoff) + ldsw + _i * 8192), 16, 0, 0); } while (0)
; #define PG8_LDA(dst, b, h) do { _Pragma("unroll") for (int m = 0; m < 4; ++m) _Pragma("unroll") for (int k = 0; k < 2; ++k) dst[m][k] = *(const LAS bf16x8*)(lds + PG8_SA(b, h) + aoff + m * 2048 + k * 1024); } while (0)
; #define PG8_LDB(dst, b, h) do { _Pragma("unroll") for (int n = 0; n < 2; ++n) _Pragma("unroll") for (int k = 0; k < 2; ++k) dst[n][k] = *(const LAS bf16x8*)(lds + PG8_SB(b, h) + boff + n * 2048 + k * 1024); } while (0)
; #define PG8_MMA(ai, bj, At, Bt) do { __builtin_amdgcn_s_setprio(1); _Pragma("unroll") for (int m = 0; m < 4; ++m) _Pragma("unroll") for (int n = 0; n < 2; ++n) _Pragma("unroll") for (int k = 0; k < 2; ++k) \
;         acc[ai][bj][m][n] = __builtin_amdgcn_mfma_f32_16x16x32_bf16(Bt[n][k], At[m][k], acc[ai][bj][m][n], 0, 0, 0); __builtin_amdgcn_s_setprio(0); } while (0)
; #define PG8_WAIT_V(n) asm volatile("s_waitcnt vmcnt(" #n ")" ::: "memory")
; #define PG8_WAIT_L(n) asm volatile("s_waitcnt lgkmcnt(" #n ")" ::: "memory")
; #define PG8_BAR __builtin_amdgcn_s_barrier()
; #define PG8_SCHED __builtin_amdgcn_sched_barrier(0)
; template <class Epi>
; __device__ __forceinline__ void gemm_phase(LAS unsigned char* lds, const Gemm g, const StaticOrder& S, const Epi& E) {
;     ...
;             PG8_LDB(B0, 1, 0); PG8_LDB(B1, 1, 1); PG8_SCHED; PG8_LDA(At, 1, 0); PG8_STAGE(PG8_SA(0, 1), a2 + hstepA, voffA);
;             PG8_WAIT_V(8); PG8_WAIT_L(0); PG8_BAR; PG8_MMA(0, 0, At, B0); PG8_MMA(0, 1, At, B1); PG8_BAR; PG8_SCHED;
;             PG8_LDA(At, 1, 1); PG8_STAGE(PG8_SB(1, 0), b3, voffB); PG8_STAGE(PG8_SB(1, 1), b3 + hstepB, voffB); PG8_STAGE(PG8_SA(1, 0), a3, voffA);
;             PG8_WAIT_V(8); PG8_WAIT_L(0); PG8_BAR; PG8_MMA(1, 0, At, B0); PG8_MMA(1, 1, At, B1); PG8_BAR; PG8_SCHED;
;         }
	s_add_i32 s64, 0, 0x18000
	s_add_i32 s65, 0, 0x1c000
	v_add_u32_e32 v140, s64, v181
	v_add_u32_e32 v172, s65, v181
	ds_read_b128 v[128:131], v140
	ds_read_b128 v[132:135], v140 offset:1024
	ds_read_b128 v[136:139], v140 offset:2048
	ds_read_b128 v[140:143], v140 offset:3072
	ds_read_b128 v[160:163], v172
	ds_read_b128 v[164:167], v172 offset:1024
	ds_read_b128 v[168:171], v172 offset:2048
	ds_read_b128 v[172:175], v172 offset:3072
	s_add_u32 s22, s22, 0xb0000
	s_addc_u32 s23, s23, 0
	s_mov_b32 m0, s35
	ds_read_b128 v[186:189], v184 offset:32768
	ds_read_b128 v[190:193], v184 offset:33792
	ds_read_b128 v[194:197], v184 offset:34816
	ds_read_b128 v[198:201], v184 offset:35840
	ds_read_b128 v[202:205], v184 offset:36864
	ds_read_b128 v[206:209], v184 offset:37888
	ds_read_b128 v[210:213], v184 offset:38912
	ds_read_b128 v[214:217], v184 offset:39936
	global_load_lds_dwordx4 v144, s[22:23]
	s_mov_b32 m0, s36
	s_nop 0
	global_load_lds_dwordx4 v148, s[22:23]
	s_waitcnt vmcnt(8)
	s_waitcnt lgkmcnt(0)
	s_barrier
	s_setprio 1
	s_waitcnt lgkmcnt(0)
	v_mfma_f32_16x16x32_bf16 v[124:127], v[128:131], v[186:189], v[124:127]
	v_mfma_f32_16x16x32_bf16 v[120:123], v[136:139], v[186:189], v[120:123]
	v_mfma_f32_16x16x32_bf16 v[108:111], v[128:131], v[194:197], v[108:111]
	v_mfma_f32_16x16x32_bf16 v[104:107], v[136:139], v[194:197], v[104:107]
	v_mfma_f32_16x16x32_bf16 v[92:95], v[128:131], v[202:205], v[92:95]
	v_mfma_f32_16x16x32_bf16 v[88:91], v[136:139], v[202:205], v[88:91]
	v_mfma_f32_16x16x32_bf16 v[76:79], v[128:131], v[210:213], v[76:79]
	v_mfma_f32_16x16x32_bf16 v[72:75], v[136:139], v[210:213], v[72:75]
	v_mfma_f32_16x16x32_bf16 v[124:127], v[132:135], v[190:193], v[124:127]
	v_mfma_f32_16x16x32_bf16 v[120:123], v[140:143], v[190:193], v[120:123]
	v_mfma_f32_16x16x32_bf16 v[108:111], v[132:135], v[198:201], v[108:111]
	v_mfma_f32_16x16x32_bf16 v[104:107], v[140:143], v[198:201], v[104:107]
	v_mfma_f32_16x16x32_bf16 v[92:95], v[132:135], v[206:209], v[92:95]
	v_mfma_f32_16x16x32_bf16 v[88:91], v[140:143], v[206:209], v[88:91]
	v_mfma_f32_16x16x32_bf16 v[76:79], v[132:135], v[214:217], v[76:79]
	v_mfma_f32_16x16x32_bf16 v[72:75], v[140:143], v[214:217], v[72:75]
	s_setprio 0
	s_setprio 1
	v_mfma_f32_16x16x32_bf16 v[116:119], v[160:163], v[186:189], v[116:119]
	v_mfma_f32_16x16x32_bf16 v[112:115], v[168:171], v[186:189], v[112:115]
	v_mfma_f32_16x16x32_bf16 v[100:103], v[160:163], v[194:197], v[100:103]
	v_mfma_f32_16x16x32_bf16 v[96:99], v[168:171], v[194:197], v[96:99]
	v_mfma_f32_16x16x32_bf16 v[84:87], v[160:163], v[202:205], v[84:87]
	v_mfma_f32_16x16x32_bf16 v[80:83], v[168:171], v[202:205], v[80:83]
	v_mfma_f32_16x16x32_bf16 v[68:71], v[160:163], v[210:213], v[68:71]
	v_mfma_f32_16x16x32_bf16 v[64:67], v[168:171], v[210:213], v[64:67]
	v_mfma_f32_16x16x32_bf16 v[116:119], v[164:167], v[190:193], v[116:119]
	v_mfma_f32_16x16x32_bf16 v[112:115], v[172:175], v[190:193], v[112:115]
	v_mfma_f32_16x16x32_bf16 v[100:103], v[164:167], v[198:201], v[100:103]
	v_mfma_f32_16x16x32_bf16 v[96:99], v[172:175], v[198:201], v[96:99]
	v_mfma_f32_16x16x32_bf16 v[84:87], v[164:167], v[206:209], v[84:87]
	v_mfma_f32_16x16x32_bf16 v[80:83], v[172:175], v[206:209], v[80:83]
	v_mfma_f32_16x16x32_bf16 v[68:71], v[164:167], v[214:217], v[68:71]
	v_mfma_f32_16x16x32_bf16 v[64:67], v[172:175], v[214:217], v[64:67]
	s_setprio 0
	s_barrier
	s_add_i32 s22, s64, s29
	v_lshl_add_u64 v[178:179], v[178:179], 0, s[14:15]
	s_mov_b32 m0, s22
	ds_read_b128 v[186:189], v184 offset:49152
	ds_read_b128 v[190:193], v184 offset:50176
	ds_read_b128 v[194:197], v184 offset:51200
	ds_read_b128 v[198:201], v184 offset:52224
	ds_read_b128 v[202:205], v184 offset:53248
	ds_read_b128 v[206:209], v184 offset:54272
	ds_read_b128 v[210:213], v184 offset:55296
	ds_read_b128 v[214:217], v184 offset:56320
	global_load_lds_dwordx4 v[178:179], off
	s_add_i32 m0, s22, 0x2000
	s_add_u32 s20, s20, 0xb0080
	v_lshl_add_u64 v[178:179], v[218:219], 0, s[14:15]
	s_addc_u32 s21, s21, 0
	s_add_i32 s22, s65, s29
	global_load_lds_dwordx4 v[178:179], off
	s_mov_b32 m0, s22
	s_nop 0
	global_load_lds_dwordx4 v146, s[20:21]
	s_add_i32 m0, s22, 0x2000
	s_nop 0
	global_load_lds_dwordx4 v150, s[20:21]
	v_lshl_add_u64 v[178:179], v[220:221], 0, s[14:15]
	s_mov_b32 m0, s42
	s_nop 0
	global_load_lds_dwordx4 v[178:179], off
	v_lshl_add_u64 v[178:179], v[222:223], 0, s[14:15]
	s_mov_b32 m0, s43
	s_nop 0
	global_load_lds_dwordx4 v[178:179], off
	s_waitcnt vmcnt(8)
	s_waitcnt lgkmcnt(0)
	s_barrier
	s_setprio 1
	s_waitcnt lgkmcnt(0)
	v_mfma_f32_16x16x32_bf16 v[60:63], v[128:131], v[186:189], v[60:63]
	v_mfma_f32_16x16x32_bf16 v[56:59], v[136:139], v[186:189], v[56:59]
	v_mfma_f32_16x16x32_bf16 v[44:47], v[128:131], v[194:197], v[44:47]
	v_mfma_f32_16x16x32_bf16 v[40:43], v[136:139], v[194:197], v[40:43]
	v_mfma_f32_16x16x32_bf16 v[28:31], v[128:131], v[202:205], v[28:31]
	v_mfma_f32_16x16x32_bf16 v[24:27], v[136:139], v[202:205], v[24:27]
	v_mfma_f32_16x16x32_bf16 v[12:15], v[128:131], v[210:213], v[12:15]
	v_mfma_f32_16x16x32_bf16 v[8:11], v[136:139], v[210:213], v[8:11]
	v_mfma_f32_16x16x32_bf16 v[60:63], v[132:135], v[190:193], v[60:63]
	v_mfma_f32_16x16x32_bf16 v[56:59], v[140:143], v[190:193], v[56:59]
	v_mfma_f32_16x16x32_bf16 v[44:47], v[132:135], v[198:201], v[44:47]
	v_mfma_f32_16x16x32_bf16 v[40:43], v[140:143], v[198:201], v[40:43]
	v_mfma_f32_16x16x32_bf16 v[28:31], v[132:135], v[206:209], v[28:31]
	v_mfma_f32_16x16x32_bf16 v[24:27], v[140:143], v[206:209], v[24:27]
	v_mfma_f32_16x16x32_bf16 v[12:15], v[132:135], v[214:217], v[12:15]
	v_mfma_f32_16x16x32_bf16 v[8:11], v[140:143], v[214:217], v[8:11]
	s_setprio 0
	s_setprio 1
	v_mfma_f32_16x16x32_bf16 v[52:55], v[160:163], v[186:189], v[52:55]
	v_mfma_f32_16x16x32_bf16 v[48:51], v[168:171], v[186:189], v[48:51]
	v_mfma_f32_16x16x32_bf16 v[36:39], v[160:163], v[194:197], v[36:39]
	v_mfma_f32_16x16x32_bf16 v[32:35], v[168:171], v[194:197], v[32:35]
	v_mfma_f32_16x16x32_bf16 v[20:23], v[160:163], v[202:205], v[20:23]
	v_mfma_f32_16x16x32_bf16 v[16:19], v[168:171], v[202:205], v[16:19]
	v_mfma_f32_16x16x32_bf16 v[4:7], v[160:163], v[210:213], v[4:7]
	v_mfma_f32_16x16x32_bf16 v[0:3], v[168:171], v[210:213], v[0:3]
	v_mfma_f32_16x16x32_bf16 v[52:55], v[164:167], v[190:193], v[52:55]
	v_mfma_f32_16x16x32_bf16 v[48:51], v[172:175], v[190:193], v[48:51]
	v_mfma_f32_16x16x32_bf16 v[36:39], v[164:167], v[198:201], v[36:39]
	v_mfma_f32_16x16x32_bf16 v[32:35], v[172:175], v[198:201], v[32:35]
	v_mfma_f32_16x16x32_bf16 v[20:23], v[164:167], v[206:209], v[20:23]
	v_mfma_f32_16x16x32_bf16 v[16:19], v[172:175], v[206:209], v[16:19]
	v_mfma_f32_16x16x32_bf16 v[4:7], v[164:167], v[214:217], v[4:7]
	v_mfma_f32_16x16x32_bf16 v[0:3], v[172:175], v[214:217], v[0:3]
	s_setprio 0
	s_barrier
	s_add_i32 s63, s63, 2
	s_add_u32 s0, s0, 0x100
	s_addc_u32 s1, s1, 0
	s_add_u32 s61, s61, 0x100
	s_addc_u32 s62, s62, 0
	s_cmp_gt_u32 s63, 41
; #define PG8_STAGE(bufoff, gbase, voff) do { _Pragma("unroll") for (int _i = 0; _i < 2; ++_i) \
;         __builtin_amdgcn_global_load_lds((const unsigned*)((const char*)(gbase) + (voff)[_i]), (LAS unsigned*)(lds + (bufoff) + ldsw + _i * 8192), 16, 0, 0); } while (0)
; #define PG8_LDA(dst, b, h) do { _Pragma("unroll") for (int m = 0; m < 4; ++m) _Pragma("unroll") for (int k = 0; k < 2; ++k) dst[m][k] = *(const LAS bf16x8*)(lds + PG8_SA(b, h) + aoff + m * 2048 + k * 1024); } while (0)
; #define PG8_LDB(dst, b, h) do { _Pragma("unroll") for (int n = 0; n < 2; ++n) _Pragma("unroll") for (int k = 0; k < 2; ++k) dst[n][k] = *(const LAS bf16x8*)(lds + PG8_SB(b, h) + boff + n * 2048 + k * 1024); } while (0)
; #define PG8_MMA(ai, bj, At, Bt) do { __builtin_amdgcn_s_setprio(1); _Pragma("unroll") for (int m = 0; m < 4; ++m) _Pragma("unroll") for (int n = 0; n < 2; ++n) _Pragma("unroll") for (int k = 0; k < 2; ++k) \
;         acc[ai][bj][m][n] = __builtin_amdgcn_mfma_f32_16x16x32_bf16(Bt[n][k], At[m][k], acc[ai][bj][m][n], 0, 0, 0); __builtin_amdgcn_s_setprio(0); } while (0)
; #define PG8_WAIT_V(n) asm volatile("s_waitcnt vmcnt(" #n ")" ::: "memory")
; #define PG8_WAIT_L(n) asm volatile("s_waitcnt lgkmcnt(" #n ")" ::: "memory")
; #define PG8_BAR __builtin_amdgcn_s_barrier()
; #define PG8_SCHED __builtin_amdgcn_sched_barrier(0)
; template <class Epi>
; __device__ __forceinline__ void gemm_phase(LAS unsigned char* lds, const Gemm g, const StaticOrder& S, const Epi& E) {
;     ...
;             PG8_LDB(B0, 0, 0); PG8_LDB(B1, 0, 1); PG8_SCHED; PG8_LDA(At, 0, 0); PG8_STAGE(PG8_SA(1, 1), a1 + hstepA, voffA);
;             PG8_WAIT_V(8); PG8_WAIT_L(0); PG8_BAR; PG8_MMA(0, 0, At, B0); PG8_MMA(0, 1, At, B1); PG8_BAR; PG8_SCHED;
;             PG8_LDA(At, 0, 1); PG8_STAGE(PG8_SB(0, 0), b2, voffB); PG8_STAGE(PG8_SB(0, 1), b2 + hstepB, voffB); PG8_STAGE(PG8_SA(0, 0), a2, voffA);
;             PG8_WAIT_V(8); PG8_WAIT_L(0); PG8_BAR; PG8_MMA(1, 0, At, B0); PG8_MMA(1, 1, At, B1); PG8_BAR; PG8_SCHED;
.LBB0_1649:
	ds_read_b128 v[128:131], v182
	ds_read_b128 v[132:135], v182 offset:1024
	ds_read_b128 v[136:139], v182 offset:2048
	ds_read_b128 v[140:143], v182 offset:3072
	ds_read_b128 v[160:163], v183
	ds_read_b128 v[164:167], v183 offset:1024
	ds_read_b128 v[168:171], v183 offset:2048
	ds_read_b128 v[172:175], v183 offset:3072
	s_add_u32 s20, s0, 0xfff50080
	s_addc_u32 s21, s1, -1
	s_cmp_eq_u32 s63, 40
	s_cselect_b32 s23, s7, s21
	s_cselect_b32 s22, s6, s20
	s_cselect_b32 s21, s19, s62
	s_cselect_b32 s20, s18, s61
	s_add_i32 m0, s33, 0xc000
	ds_read_b128 v[186:189], v184
	ds_read_b128 v[190:193], v184 offset:1024
	ds_read_b128 v[194:197], v184 offset:2048
	ds_read_b128 v[198:201], v184 offset:3072
	ds_read_b128 v[202:205], v184 offset:4096
	ds_read_b128 v[206:209], v184 offset:5120
	ds_read_b128 v[210:213], v184 offset:6144
	ds_read_b128 v[214:217], v184 offset:7168
	global_load_lds_dwordx4 v152, s[0:1]
	s_add_i32 m0, s33, 0xe000
	s_nop 0
	global_load_lds_dwordx4 v154, s[0:1]
	s_waitcnt vmcnt(8)
	s_waitcnt lgkmcnt(0)
	s_barrier
	s_setprio 1
	s_waitcnt lgkmcnt(0)
	v_mfma_f32_16x16x32_bf16 v[124:127], v[128:131], v[186:189], v[124:127]
	v_mfma_f32_16x16x32_bf16 v[120:123], v[136:139], v[186:189], v[120:123]
	v_mfma_f32_16x16x32_bf16 v[108:111], v[128:131], v[194:197], v[108:111]
	v_mfma_f32_16x16x32_bf16 v[104:107], v[136:139], v[194:197], v[104:107]
	v_mfma_f32_16x16x32_bf16 v[92:95], v[128:131], v[202:205], v[92:95]
	v_mfma_f32_16x16x32_bf16 v[88:91], v[136:139], v[202:205], v[88:91]
	v_mfma_f32_16x16x32_bf16 v[76:79], v[128:131], v[210:213], v[76:79]
	v_mfma_f32_16x16x32_bf16 v[72:75], v[136:139], v[210:213], v[72:75]
	v_mfma_f32_16x16x32_bf16 v[124:127], v[132:135], v[190:193], v[124:127]
	v_mfma_f32_16x16x32_bf16 v[120:123], v[140:143], v[190:193], v[120:123]
	v_mfma_f32_16x16x32_bf16 v[108:111], v[132:135], v[198:201], v[108:111]
	v_mfma_f32_16x16x32_bf16 v[104:107], v[140:143], v[198:201], v[104:107]
	v_mfma_f32_16x16x32_bf16 v[92:95], v[132:135], v[206:209], v[92:95]
	v_mfma_f32_16x16x32_bf16 v[88:91], v[140:143], v[206:209], v[88:91]
	v_mfma_f32_16x16x32_bf16 v[76:79], v[132:135], v[214:217], v[76:79]
	v_mfma_f32_16x16x32_bf16 v[72:75], v[140:143], v[214:217], v[72:75]
	s_setprio 0
	s_setprio 1
	v_mfma_f32_16x16x32_bf16 v[116:119], v[160:163], v[186:189], v[116:119]
	v_mfma_f32_16x16x32_bf16 v[112:115], v[168:171], v[186:189], v[112:115]
	v_mfma_f32_16x16x32_bf16 v[100:103], v[160:163], v[194:197], v[100:103]
	v_mfma_f32_16x16x32_bf16 v[96:99], v[168:171], v[194:197], v[96:99]
	v_mfma_f32_16x16x32_bf16 v[84:87], v[160:163], v[202:205], v[84:87]
	v_mfma_f32_16x16x32_bf16 v[80:83], v[168:171], v[202:205], v[80:83]
	v_mfma_f32_16x16x32_bf16 v[68:71], v[160:163], v[210:213], v[68:71]
	v_mfma_f32_16x16x32_bf16 v[64:67], v[168:171], v[210:213], v[64:67]
	v_mfma_f32_16x16x32_bf16 v[116:119], v[164:167], v[190:193], v[116:119]
	v_mfma_f32_16x16x32_bf16 v[112:115], v[172:175], v[190:193], v[112:115]
	v_mfma_f32_16x16x32_bf16 v[100:103], v[164:167], v[198:201], v[100:103]
	v_mfma_f32_16x16x32_bf16 v[96:99], v[172:175], v[198:201], v[96:99]
	v_mfma_f32_16x16x32_bf16 v[84:87], v[164:167], v[206:209], v[84:87]
	v_mfma_f32_16x16x32_bf16 v[80:83], v[172:175], v[206:209], v[80:83]
	v_mfma_f32_16x16x32_bf16 v[68:71], v[164:167], v[214:217], v[68:71]
	v_mfma_f32_16x16x32_bf16 v[64:67], v[172:175], v[214:217], v[64:67]
	s_setprio 0
	s_barrier
	s_add_i32 s64, s55, s29
	v_lshl_add_u64 v[178:179], s[20:21], 0, v[146:147]
	s_mov_b32 m0, s64
	ds_read_b128 v[186:189], v184 offset:16384
	ds_read_b128 v[190:193], v184 offset:17408
	ds_read_b128 v[194:197], v184 offset:18432
	ds_read_b128 v[198:201], v184 offset:19456
	ds_read_b128 v[202:205], v184 offset:20480
	ds_read_b128 v[206:209], v184 offset:21504
	ds_read_b128 v[210:213], v184 offset:22528
	ds_read_b128 v[214:217], v184 offset:23552
	global_load_lds_dwordx4 v[178:179], off
	s_add_i32 m0, s64, 0x2000
	s_add_u32 s64, s20, 0xb0000
	v_lshl_add_u64 v[218:219], s[20:21], 0, v[150:151]
	s_addc_u32 s65, s21, 0
	s_add_i32 s66, s56, s29
	global_load_lds_dwordx4 v[218:219], off
	s_mov_b32 m0, s66
	v_lshl_add_u64 v[222:223], s[22:23], 0, v[148:149]
	global_load_lds_dwordx4 v146, s[64:65]
	s_add_i32 m0, s66, 0x2000
	s_nop 0
	global_load_lds_dwordx4 v150, s[64:65]
	v_lshl_add_u64 v[220:221], s[22:23], 0, v[144:145]
	s_mov_b32 m0, s33
	s_nop 0
	global_load_lds_dwordx4 v[220:221], off
	s_mov_b32 m0, s34
	s_nop 0
	global_load_lds_dwordx4 v[222:223], off
	s_waitcnt vmcnt(8)
	s_waitcnt lgkmcnt(0)
	s_barrier
; #define PG8_STAGE(bufoff, gbase, voff) do { _Pragma("unroll") for (int _i = 0; _i < 2; ++_i) \
;         __builtin_amdgcn_global_load_lds((const unsigned*)((const char*)(gbase) + (voff)[_i]), (LAS unsigned*)(lds + (bufoff) + ldsw + _i * 8192), 16, 0, 0); } while (0)
; #define PG8_LDA(dst, b, h) do { _Pragma("unroll") for (int m = 0; m < 4; ++m) _Pragma("unroll") for (int k = 0; k < 2; ++k) dst[m][k] = *(const LAS bf16x8*)(lds + PG8_SA(b, h) + aoff + m * 2048 + k * 1024); } while (0)
; #define PG8_LDB(dst, b, h) do { _Pragma("unroll") for (int n = 0; n < 2; ++n) _Pragma("unroll") for (int k = 0; k < 2; ++k) dst[n][k] = *(const LAS bf16x8*)(lds + PG8_SB(b, h) + boff + n * 2048 + k * 1024); } while (0)
; #define PG8_MMA(ai, bj, At, Bt) do { __builtin_amdgcn_s_setprio(1); _Pragma("unroll") for (int m = 0; m < 4; ++m) _Pragma("unroll") for (int n = 0; n < 2; ++n) _Pragma("unroll") for (int k = 0; k < 2; ++k) \
;         acc[ai][bj][m][n] = __builtin_amdgcn_mfma_f32_16x16x32_bf16(Bt[n][k], At[m][k], acc[ai][bj][m][n], 0, 0, 0); __builtin_amdgcn_s_setprio(0); } while (0)
; #define PG8_WAIT_V(n) asm volatile("s_waitcnt vmcnt(" #n ")" ::: "memory")
; #define PG8_WAIT_L(n) asm volatile("s_waitcnt lgkmcnt(" #n ")" ::: "memory")
; #define PG8_BAR __builtin_amdgcn_s_barrier()
; #define PG8_SCHED __builtin_amdgcn_sched_barrier(0)
; template <class Epi>
; __device__ __forceinline__ void gemm_phase(LAS unsigned char* lds, const Gemm g, const StaticOrder& S, const Epi& E) {
;     ...
;             PG8_WAIT_V(8); PG8_WAIT_L(0); PG8_BAR; PG8_MMA(1, 0, At, B0); PG8_MMA(1, 1, At, B1); PG8_BAR; PG8_SCHED;
;             PG8_LDB(B0, 1, 0); PG8_LDB(B1, 1, 1); PG8_SCHED; PG8_LDA(At, 1, 0); PG8_STAGE(PG8_SA(0, 1), a2 + hstepA, voffA);
;             PG8_WAIT_V(8); PG8_WAIT_L(0); PG8_BAR; PG8_MMA(0, 0, At, B0); PG8_MMA(0, 1, At, B1); PG8_BAR; PG8_SCHED;
	s_setprio 1
	s_waitcnt lgkmcnt(0)
	v_mfma_f32_16x16x32_bf16 v[60:63], v[128:131], v[186:189], v[60:63]
	v_mfma_f32_16x16x32_bf16 v[56:59], v[136:139], v[186:189], v[56:59]
	v_mfma_f32_16x16x32_bf16 v[44:47], v[128:131], v[194:197], v[44:47]
	v_mfma_f32_16x16x32_bf16 v[40:43], v[136:139], v[194:197], v[40:43]
	v_mfma_f32_16x16x32_bf16 v[28:31], v[128:131], v[202:205], v[28:31]
	v_mfma_f32_16x16x32_bf16 v[24:27], v[136:139], v[202:205], v[24:27]
	v_mfma_f32_16x16x32_bf16 v[12:15], v[128:131], v[210:213], v[12:15]
	v_mfma_f32_16x16x32_bf16 v[8:11], v[136:139], v[210:213], v[8:11]
	v_mfma_f32_16x16x32_bf16 v[60:63], v[132:135], v[190:193], v[60:63]
	v_mfma_f32_16x16x32_bf16 v[56:59], v[140:143], v[190:193], v[56:59]
	v_mfma_f32_16x16x32_bf16 v[44:47], v[132:135], v[198:201], v[44:47]
	v_mfma_f32_16x16x32_bf16 v[40:43], v[140:143], v[198:201], v[40:43]
	v_mfma_f32_16x16x32_bf16 v[28:31], v[132:135], v[206:209], v[28:31]
	v_mfma_f32_16x16x32_bf16 v[24:27], v[140:143], v[206:209], v[24:27]
	v_mfma_f32_16x16x32_bf16 v[12:15], v[132:135], v[214:217], v[12:15]
	v_mfma_f32_16x16x32_bf16 v[8:11], v[140:143], v[214:217], v[8:11]
	s_setprio 0
	s_setprio 1
	v_mfma_f32_16x16x32_bf16 v[52:55], v[160:163], v[186:189], v[52:55]
	v_mfma_f32_16x16x32_bf16 v[48:51], v[168:171], v[186:189], v[48:51]
	v_mfma_f32_16x16x32_bf16 v[36:39], v[160:163], v[194:197], v[36:39]
	v_mfma_f32_16x16x32_bf16 v[32:35], v[168:171], v[194:197], v[32:35]
	v_mfma_f32_16x16x32_bf16 v[20:23], v[160:163], v[202:205], v[20:23]
	v_mfma_f32_16x16x32_bf16 v[16:19], v[168:171], v[202:205], v[16:19]
	v_mfma_f32_16x16x32_bf16 v[4:7], v[160:163], v[210:213], v[4:7]
	v_mfma_f32_16x16x32_bf16 v[0:3], v[168:171], v[210:213], v[0:3]
	v_mfma_f32_16x16x32_bf16 v[52:55], v[164:167], v[190:193], v[52:55]
	v_mfma_f32_16x16x32_bf16 v[48:51], v[172:175], v[190:193], v[48:51]
	v_mfma_f32_16x16x32_bf16 v[36:39], v[164:167], v[198:201], v[36:39]
	v_mfma_f32_16x16x32_bf16 v[32:35], v[172:175], v[198:201], v[32:35]
	v_mfma_f32_16x16x32_bf16 v[20:23], v[164:167], v[206:209], v[20:23]
	v_mfma_f32_16x16x32_bf16 v[16:19], v[172:175], v[206:209], v[16:19]
	v_mfma_f32_16x16x32_bf16 v[4:7], v[164:167], v[214:217], v[4:7]
	v_mfma_f32_16x16x32_bf16 v[0:3], v[172:175], v[214:217], v[0:3]
	s_setprio 0
	s_barrier
	s_add_i32 s64, 0, 0x18000
	s_add_i32 s65, 0, 0x1c000
	v_add_u32_e32 v140, s64, v181
	v_add_u32_e32 v172, s65, v181
	ds_read_b128 v[128:131], v140
	ds_read_b128 v[132:135], v140 offset:1024
	ds_read_b128 v[136:139], v140 offset:2048
	ds_read_b128 v[140:143], v140 offset:3072
	ds_read_b128 v[160:163], v172
	ds_read_b128 v[164:167], v172 offset:1024
	ds_read_b128 v[168:171], v172 offset:2048
	ds_read_b128 v[172:175], v172 offset:3072
	s_add_u32 s22, s22, 0xb0000
	s_addc_u32 s23, s23, 0
	s_mov_b32 m0, s35
	ds_read_b128 v[186:189], v184 offset:32768
	ds_read_b128 v[190:193], v184 offset:33792
	ds_read_b128 v[194:197], v184 offset:34816
	ds_read_b128 v[198:201], v184 offset:35840
	ds_read_b128 v[202:205], v184 offset:36864
	ds_read_b128 v[206:209], v184 offset:37888
	ds_read_b128 v[210:213], v184 offset:38912
	ds_read_b128 v[214:217], v184 offset:39936
	global_load_lds_dwordx4 v144, s[22:23]
	s_mov_b32 m0, s36
	s_nop 0
	global_load_lds_dwordx4 v148, s[22:23]
	s_waitcnt vmcnt(8)
	s_waitcnt lgkmcnt(0)
	s_barrier
	s_setprio 1
	s_waitcnt lgkmcnt(0)
	v_mfma_f32_16x16x32_bf16 v[124:127], v[128:131], v[186:189], v[124:127]
	v_mfma_f32_16x16x32_bf16 v[120:123], v[136:139], v[186:189], v[120:123]
	v_mfma_f32_16x16x32_bf16 v[108:111], v[128:131], v[194:197], v[108:111]
	v_mfma_f32_16x16x32_bf16 v[104:107], v[136:139], v[194:197], v[104:107]
	v_mfma_f32_16x16x32_bf16 v[92:95], v[128:131], v[202:205], v[92:95]
	v_mfma_f32_16x16x32_bf16 v[88:91], v[136:139], v[202:205], v[88:91]
	v_mfma_f32_16x16x32_bf16 v[76:79], v[128:131], v[210:213], v[76:79]
	v_mfma_f32_16x16x32_bf16 v[72:75], v[136:139], v[210:213], v[72:75]
	v_mfma_f32_16x16x32_bf16 v[124:127], v[132:135], v[190:193], v[124:127]
	v_mfma_f32_16x16x32_bf16 v[120:123], v[140:143], v[190:193], v[120:123]
	v_mfma_f32_16x16x32_bf16 v[108:111], v[132:135], v[198:201], v[108:111]
	v_mfma_f32_16x16x32_bf16 v[104:107], v[140:143], v[198:201], v[104:107]
	v_mfma_f32_16x16x32_bf16 v[92:95], v[132:135], v[206:209], v[92:95]
	v_mfma_f32_16x16x32_bf16 v[88:91], v[140:143], v[206:209], v[88:91]
	v_mfma_f32_16x16x32_bf16 v[76:79], v[132:135], v[214:217], v[76:79]
	v_mfma_f32_16x16x32_bf16 v[72:75], v[140:143], v[214:217], v[72:75]
	s_setprio 0
	s_setprio 1
	v_mfma_f32_16x16x32_bf16 v[116:119], v[160:163], v[186:189], v[116:119]
	v_mfma_f32_16x16x32_bf16 v[112:115], v[168:171], v[186:189], v[112:115]
	v_mfma_f32_16x16x32_bf16 v[100:103], v[160:163], v[194:197], v[100:103]
	v_mfma_f32_16x16x32_bf16 v[96:99], v[168:171], v[194:197], v[96:99]
	v_mfma_f32_16x16x32_bf16 v[84:87], v[160:163], v[202:205], v[84:87]
	v_mfma_f32_16x16x32_bf16 v[80:83], v[168:171], v[202:205], v[80:83]
	v_mfma_f32_16x16x32_bf16 v[68:71], v[160:163], v[210:213], v[68:71]
	v_mfma_f32_16x16x32_bf16 v[64:67], v[168:171], v[210:213], v[64:67]
	v_mfma_f32_16x16x32_bf16 v[116:119], v[164:167], v[190:193], v[116:119]
	v_mfma_f32_16x16x32_bf16 v[112:115], v[172:175], v[190:193], v[112:115]
	v_mfma_f32_16x16x32_bf16 v[100:103], v[164:167], v[198:201], v[100:103]
	v_mfma_f32_16x16x32_bf16 v[96:99], v[172:175], v[198:201], v[96:99]
	v_mfma_f32_16x16x32_bf16 v[84:87], v[164:167], v[206:209], v[84:87]
	v_mfma_f32_16x16x32_bf16 v[80:83], v[172:175], v[206:209], v[80:83]
	v_mfma_f32_16x16x32_bf16 v[68:71], v[164:167], v[214:217], v[68:71]
	v_mfma_f32_16x16x32_bf16 v[64:67], v[172:175], v[214:217], v[64:67]
	s_setprio 0
	s_barrier
; #define PG8_STAGE(bufoff, gbase, voff) do { _Pragma("unroll") for (int _i = 0; _i < 2; ++_i) \
;         __builtin_amdgcn_global_load_lds((const unsigned*)((const char*)(gbase) + (voff)[_i]), (LAS unsigned*)(lds + (bufoff) + ldsw + _i * 8192), 16, 0, 0); } while (0)
; #define PG8_LDA(dst, b, h) do { _Pragma("unroll") for (int m = 0; m < 4; ++m) _Pragma("unroll") for (int k = 0; k < 2; ++k) dst[m][k] = *(const LAS bf16x8*)(lds + PG8_SA(b, h) + aoff + m * 2048 + k * 1024); } while (0)
; #define PG8_MMA(ai, bj, At, Bt) do { __builtin_amdgcn_s_setprio(1); _Pragma("unroll") for (int m = 0; m < 4; ++m) _Pragma("unroll") for (int n = 0; n < 2; ++n) _Pragma("unroll") for (int k = 0; k < 2; ++k) \
;         acc[ai][bj][m][n] = __builtin_amdgcn_mfma_f32_16x16x32_bf16(Bt[n][k], At[m][k], acc[ai][bj][m][n], 0, 0, 0); __builtin_amdgcn_s_setprio(0); } while (0)
; #define PG8_WAIT_V(n) asm volatile("s_waitcnt vmcnt(" #n ")" ::: "memory")
; #define PG8_WAIT_L(n) asm volatile("s_waitcnt lgkmcnt(" #n ")" ::: "memory")
; #define PG8_BAR __builtin_amdgcn_s_barrier()
; #define PG8_SCHED __builtin_amdgcn_sched_barrier(0)
; template <class Epi>
; __device__ __forceinline__ void gemm_phase(LAS unsigned char* lds, const Gemm g, const StaticOrder& S, const Epi& E) {
;     ...
;             PG8_LDA(At, 1, 1); PG8_STAGE(PG8_SB(1, 0), b3, voffB); PG8_STAGE(PG8_SB(1, 1), b3 + hstepB, voffB); PG8_STAGE(PG8_SA(1, 0), a3, voffA);
;             PG8_WAIT_V(8); PG8_WAIT_L(0); PG8_BAR; PG8_MMA(1, 0, At, B0); PG8_MMA(1, 1, At, B1); PG8_BAR; PG8_SCHED;
;         }
;         if (wr == 0) PG8_BAR;
	s_add_i32 s22, s64, s29
	v_lshl_add_u64 v[178:179], v[178:179], 0, s[14:15]
	s_mov_b32 m0, s22
	ds_read_b128 v[186:189], v184 offset:49152
	ds_read_b128 v[190:193], v184 offset:50176
	ds_read_b128 v[194:197], v184 offset:51200
	ds_read_b128 v[198:201], v184 offset:52224
	ds_read_b128 v[202:205], v184 offset:53248
	ds_read_b128 v[206:209], v184 offset:54272
	ds_read_b128 v[210:213], v184 offset:55296
	ds_read_b128 v[214:217], v184 offset:56320
	global_load_lds_dwordx4 v[178:179], off
	s_add_i32 m0, s22, 0x2000
	s_add_u32 s20, s20, 0xb0080
	v_lshl_add_u64 v[178:179], v[218:219], 0, s[14:15]
	s_addc_u32 s21, s21, 0
	s_add_i32 s22, s65, s29
	global_load_lds_dwordx4 v[178:179], off
	s_mov_b32 m0, s22
	s_nop 0
	global_load_lds_dwordx4 v146, s[20:21]
	s_add_i32 m0, s22, 0x2000
	s_nop 0
	global_load_lds_dwordx4 v150, s[20:21]
	v_lshl_add_u64 v[178:179], v[220:221], 0, s[14:15]
	s_mov_b32 m0, s42
	s_nop 0
	global_load_lds_dwordx4 v[178:179], off
	v_lshl_add_u64 v[178:179], v[222:223], 0, s[14:15]
	s_mov_b32 m0, s43
	s_nop 0
	global_load_lds_dwordx4 v[178:179], off
	s_waitcnt vmcnt(8)
	s_waitcnt lgkmcnt(0)
	s_barrier
	s_setprio 1
	s_waitcnt lgkmcnt(0)
	v_mfma_f32_16x16x32_bf16 v[60:63], v[128:131], v[186:189], v[60:63]
	v_mfma_f32_16x16x32_bf16 v[56:59], v[136:139], v[186:189], v[56:59]
	v_mfma_f32_16x16x32_bf16 v[44:47], v[128:131], v[194:197], v[44:47]
	v_mfma_f32_16x16x32_bf16 v[40:43], v[136:139], v[194:197], v[40:43]
	v_mfma_f32_16x16x32_bf16 v[28:31], v[128:131], v[202:205], v[28:31]
	v_mfma_f32_16x16x32_bf16 v[24:27], v[136:139], v[202:205], v[24:27]
	v_mfma_f32_16x16x32_bf16 v[12:15], v[128:131], v[210:213], v[12:15]
	v_mfma_f32_16x16x32_bf16 v[8:11], v[136:139], v[210:213], v[8:11]
	v_mfma_f32_16x16x32_bf16 v[60:63], v[132:135], v[190:193], v[60:63]
	v_mfma_f32_16x16x32_bf16 v[56:59], v[140:143], v[190:193], v[56:59]
	v_mfma_f32_16x16x32_bf16 v[44:47], v[132:135], v[198:201], v[44:47]
	v_mfma_f32_16x16x32_bf16 v[40:43], v[140:143], v[198:201], v[40:43]
	v_mfma_f32_16x16x32_bf16 v[28:31], v[132:135], v[206:209], v[28:31]
	v_mfma_f32_16x16x32_bf16 v[24:27], v[140:143], v[206:209], v[24:27]
	v_mfma_f32_16x16x32_bf16 v[12:15], v[132:135], v[214:217], v[12:15]
	v_mfma_f32_16x16x32_bf16 v[8:11], v[140:143], v[214:217], v[8:11]
	s_setprio 0
	s_setprio 1
	v_mfma_f32_16x16x32_bf16 v[52:55], v[160:163], v[186:189], v[52:55]
	v_mfma_f32_16x16x32_bf16 v[48:51], v[168:171], v[186:189], v[48:51]
	v_mfma_f32_16x16x32_bf16 v[36:39], v[160:163], v[194:197], v[36:39]
	v_mfma_f32_16x16x32_bf16 v[32:35], v[168:171], v[194:197], v[32:35]
	v_mfma_f32_16x16x32_bf16 v[20:23], v[160:163], v[202:205], v[20:23]
	v_mfma_f32_16x16x32_bf16 v[16:19], v[168:171], v[202:205], v[16:19]
	v_mfma_f32_16x16x32_bf16 v[4:7], v[160:163], v[210:213], v[4:7]
	v_mfma_f32_16x16x32_bf16 v[0:3], v[168:171], v[210:213], v[0:3]
	v_mfma_f32_16x16x32_bf16 v[52:55], v[164:167], v[190:193], v[52:55]
	v_mfma_f32_16x16x32_bf16 v[48:51], v[172:175], v[190:193], v[48:51]
	v_mfma_f32_16x16x32_bf16 v[36:39], v[164:167], v[198:201], v[36:39]
	v_mfma_f32_16x16x32_bf16 v[32:35], v[172:175], v[198:201], v[32:35]
	v_mfma_f32_16x16x32_bf16 v[20:23], v[164:167], v[206:209], v[20:23]
	v_mfma_f32_16x16x32_bf16 v[16:19], v[172:175], v[206:209], v[16:19]
	v_mfma_f32_16x16x32_bf16 v[4:7], v[164:167], v[214:217], v[4:7]
	v_mfma_f32_16x16x32_bf16 v[0:3], v[172:175], v[214:217], v[0:3]
	s_setprio 0
	s_barrier
	s_add_i32 s63, s63, 2
	s_add_u32 s0, s0, 0x100
	s_addc_u32 s1, s1, 0
	s_add_u32 s61, s61, 0x100
	s_addc_u32 s62, s62, 0
	s_cmp_gt_u32 s63, 41
	s_cbranch_scc0 .LBB0_1649
	s_and_b64 vcc, exec, s[16:17]
	s_cbranch_vccz .LBB0_1652
	s_barrier

; #define PG8_STAGE(bufoff, gbase, voff) do { _Pragma("unroll") for (int _i = 0; _i < 2; ++_i) \
;         __builtin_amdgcn_global_load_lds((const unsigned*)((const char*)(gbase) + (voff)[_i]), (LAS unsigned*)(lds + (bufoff) + ldsw + _i * 8192), 16, 0, 0); } while (0)
; #define PG8_WAIT_V(n) asm volatile("s_waitcnt vmcnt(" #n ")" ::: "memory")
; #define PG8_BAR __builtin_amdgcn_s_barrier()
; template <class Epi>
; __device__ __forceinline__ void gemm_phase(LAS unsigned char* lds, const Gemm g, const StaticOrder& S, const Epi& E) {
;     ...
;     const char* cA = (const char*)g.A + (size_t)cur.pm * tstepA; const char* cB = (const char*)g.Bt + (size_t)cur.pn * tstepB;
;     PG8_STAGE(PG8_SB(0, 0), cB, voffB); PG8_STAGE(PG8_SB(0, 1), cB + hstepB, voffB); PG8_STAGE(PG8_SA(0, 0), cA, voffA); PG8_STAGE(PG8_SA(0, 1), cA + hstepA, voffA);
;     if (wr == 1) PG8_BAR;
;     PG8_WAIT_V(2); PG8_BAR;
;     PG8_STAGE(PG8_SB(1, 0), cB + kstep, voffB); PG8_STAGE(PG8_SA(1, 0), cA + kstep, voffA); PG8_STAGE(PG8_SB(1, 1), cB + hstepB + kstep, voffB);
;     PG8_WAIT_V(6); PG8_BAR;
;     for (;;) {
;         const bool has_next = S.next(ui + 1, nxt);
;         const char* nA = has_next ? (const char*)g.A + (size_t)nxt.pm * tstepA : cA; const char* nB = has_next ? (const char*)g.Bt + (size_t)nxt.pn * tstepB : cB;
.LBB0_1736:
	s_add_u32 s12, s50, 0xa0000
	s_addc_u32 s13, s51, 0
	s_add_u32 s14, s50, 0xc0000
	s_addc_u32 s15, s51, 0
	s_add_u32 s16, s50, 0x120000
	s_addc_u32 s17, s51, 0
	s_add_u32 s18, s44, 0x1000
	s_addc_u32 s19, s45, 0
	s_lshl_b32 s60, s4, 6
	s_lshl_b32 s7, s4, 13
	s_lshl_b32 s4, s5, 5
	s_mov_b64 s[20:21], 0x80
	s_and_b32 s61, s4, 0x60
	s_add_i32 m0, s55, 0x18000
	v_lshl_add_u64 v[6:7], v[6:7], 0, s[20:21]
	s_lshl_b32 s9, s61, 7
	s_waitcnt vmcnt(2)
	s_barrier
	global_load_lds_dwordx4 v[6:7], off
	v_lshl_add_u64 v[4:5], v[4:5], 0, s[20:21]
	s_add_i32 m0, s55, 0x1a000
	s_add_i32 s62, s55, 0x8000
	s_add_i32 s63, s55, 0xa000
	global_load_lds_dwordx4 v[4:5], off
	v_lshl_add_u64 v[0:1], v[0:1], 0, s[20:21]
	s_mov_b32 m0, s62
	s_add_u32 s4, s52, 0x40080
	global_load_lds_dwordx4 v[0:1], off
	v_lshl_add_u64 v[0:1], v[2:3], 0, s[20:21]
	s_mov_b32 m0, s63
	s_addc_u32 s5, s53, 0
	global_load_lds_dwordx4 v[0:1], off
	s_add_i32 m0, s55, 0x1c000
	global_load_lds_dwordx4 v170, s[4:5]
	s_add_i32 m0, s55, 0x1e000
	v_bfe_u32 v206, v176, 4, 2
	global_load_lds_dwordx4 v174, s[4:5]
	v_and_b32_e32 v177, 15, v176
	v_lshlrev_b32_e32 v0, 4, v206
	v_lshlrev_b32_e32 v2, 2, v176
	v_lshlrev_b32_e32 v3, 6, v176
	s_movk_i32 s4, 0x3c0
	v_lshl_or_b32 v1, v177, 6, v0
	v_and_b32_e32 v2, 32, v2
	v_and_or_b32 v0, v3, s4, v0
	v_bitop3_b32 v207, s9, v0, v2 bitop3:0xf6
	v_lshlrev_b32_e32 v0, 8, v176
	v_bitop3_b32 v1, v1, s7, v2 bitop3:0xde
	v_and_b32_e32 v0, 0x38000, v0
	v_lshlrev_b32_e32 v2, 11, v10
	v_or3_b32 v0, v8, v0, v2
	s_cmpk_lt_u32 s22, 0x100
	v_add_u32_e32 v178, v0, v9
	v_lshlrev_b32_e32 v0, 4, v11
	s_cselect_b64 s[22:23], -1, 0
	s_ashr_i32 s64, s74, 31
	s_ashr_i32 s66, s2, 31
	v_and_b32_e32 v0, 0x78000, v0
	s_waitcnt vmcnt(6)
	s_cmp_lg_u64 s[48:49], 0
	v_or3_b32 v0, v8, v0, v2
	s_cselect_b64 s[26:27], -1, 0
	v_add_u32_e32 v180, v0, v9
	s_add_i32 s67, 0, 0x10000
	s_add_i32 s68, 0, 0x14000
	v_mbcnt_lo_u32_b32 v0, -1, 0
	s_mov_b32 s65, s74
	v_mov_b32_e32 v179, v171
	v_mov_b32_e32 v181, v171
	v_mov_b64_e32 v[182:183], 0x200
	v_mov_b64_e32 v[184:185], 0x1ff
	v_add_u32_e32 v208, s67, v207
	v_add_u32_e32 v209, s68, v207
	v_add_u32_e32 v210, 0, v1
	v_mov_b32_e32 v211, 0x358637bd
	v_mbcnt_hi_u32_b32 v212, -1, v0
	s_barrier
	s_branch .LBB0_1739

; #define PG8_STAGE(bufoff, gbase, voff) do { _Pragma("unroll") for (int _i = 0; _i < 2; ++_i) \
;         __builtin_amdgcn_global_load_lds((const unsigned*)((const char*)(gbase) + (voff)[_i]), (LAS unsigned*)(lds + (bufoff) + ldsw + _i * 8192), 16, 0, 0); } while (0)
; #define PG8_LDA(dst, b, h) do { _Pragma("unroll") for (int m = 0; m < 4; ++m) _Pragma("unroll") for (int k = 0; k < 2; ++k) dst[m][k] = *(const LAS bf16x8*)(lds + PG8_SA(b, h) + aoff + m * 2048 + k * 1024); } while (0)
; #define PG8_LDB(dst, b, h) do { _Pragma("unroll") for (int n = 0; n < 2; ++n) _Pragma("unroll") for (int k = 0; k < 2; ++k) dst[n][k] = *(const LAS bf16x8*)(lds + PG8_SB(b, h) + boff + n * 2048 + k * 1024); } while (0)
; #define PG8_MMA(ai, bj, At, Bt) do { __builtin_amdgcn_s_setprio(1); _Pragma("unroll") for (int m = 0; m < 4; ++m) _Pragma("unroll") for (int n = 0; n < 2; ++n) _Pragma("unroll") for (int k = 0; k < 2; ++k) \
;         acc[ai][bj][m][n] = __builtin_amdgcn_mfma_f32_16x16x32_bf16(Bt[n][k], At[m][k], acc[ai][bj][m][n], 0, 0, 0); __builtin_amdgcn_s_setprio(0); } while (0)
; #define PG8_BAR __builtin_amdgcn_s_barrier()
; template <class Epi>
; __device__ __forceinline__ void gemm_phase(LAS unsigned char* lds, const Gemm g, const StaticOrder& S, const Epi& E) {
;     ...
;     for (;;) {
;         const bool has_next = S.next(ui + 1, nxt);
;         const char* nA = has_next ? (const char*)g.A + (size_t)nxt.pm * tstepA : cA; const char* nB = has_next ? (const char*)g.Bt + (size_t)nxt.pn * tstepB : cB;
; #pragma nounroll
;         for (int t = 0; t < nt; t += 2) {
;             const bool last = (t == nt - 2);
;             const char* a1 = cA + (size_t)(t + 1) * kstep;
;             const char* a2 = last ? nA : cA + (size_t)(t + 2) * kstep; const char* b2 = last ? nB : cB + (size_t)(t + 2) * kstep;
;             const char* a3 = a2 + kstep; const char* b3 = b2 + kstep;
;             PG8_LDB(B0, 0, 0); PG8_LDB(B1, 0, 1); PG8_SCHED; PG8_LDA(At, 0, 0); PG8_STAGE(PG8_SA(1, 1), a1 + hstepA, voffA);
;             PG8_WAIT_V(8); PG8_WAIT_L(0); PG8_BAR; PG8_MMA(0, 0, At, B0); PG8_MMA(0, 1, At, B1); PG8_BAR; PG8_SCHED;
;             PG8_LDA(At, 0, 1); PG8_STAGE(PG8_SB(0, 0), b2, voffB); PG8_STAGE(PG8_SB(0, 1), b2 + hstepB, voffB); PG8_STAGE(PG8_SA(0, 0), a2, voffA);
;             PG8_WAIT_V(8); PG8_WAIT_L(0); PG8_BAR; PG8_MMA(1, 0, At, B0); PG8_MMA(1, 1, At, B1); PG8_BAR; PG8_SCHED;
.LBB0_1745:
	s_ashr_i32 s35, s34, 31
	s_lshl_b64 s[36:37], s[34:35], 19
	s_add_u32 s36, s30, s36
	s_addc_u32 s37, s31, s37
	s_and_b64 s[38:39], s[4:5], exec
	s_cselect_b32 s7, s37, s43
	s_cselect_b32 s9, s36, s42
	s_ashr_i32 s29, s28, 31
	s_lshl_b64 s[38:39], s[28:29], 19
	s_add_u32 s38, s3, s38
	s_addc_u32 s39, s33, s39
	s_and_b64 s[44:45], s[4:5], exec
	s_cselect_b32 s29, s39, s53
	s_cselect_b32 s35, s38, s52
	s_add_u32 s42, s42, 0x40080
	s_addc_u32 s43, s43, 0
	s_add_u32 s69, s52, 0x100
	s_addc_u32 s70, s53, 0
	s_mov_b32 s71, -2
	s_waitcnt lgkmcnt(0)
	ds_read_b128 v[40:43], v208
	ds_read_b128 v[44:47], v208 offset:1024
	ds_read_b128 v[56:59], v208 offset:2048
	ds_read_b128 v[60:63], v208 offset:3072
	ds_read_b128 v[144:147], v209
	ds_read_b128 v[148:151], v209 offset:1024
	ds_read_b128 v[152:155], v209 offset:2048
	ds_read_b128 v[156:159], v209 offset:3072
	s_add_u32 s44, s42, 0xfffc0080
	s_addc_u32 s45, s43, -1
	s_cmp_eq_u32 s71, 12
	s_cselect_b32 s53, s7, s45
	s_cselect_b32 s52, s9, s44
	s_cselect_b32 s45, s29, s70
	s_cselect_b32 s44, s35, s69
	s_add_i32 m0, s55, 0xc000
	ds_read_b128 v[160:163], v210
	ds_read_b128 v[164:167], v210 offset:1024
	ds_read_b128 v[186:189], v210 offset:2048
	ds_read_b128 v[190:193], v210 offset:3072
	ds_read_b128 v[194:197], v210 offset:4096
	ds_read_b128 v[198:201], v210 offset:5120
	ds_read_b128 v[202:205], v210 offset:6144
	ds_read_b128 v[214:217], v210 offset:7168
	global_load_lds_dwordx4 v178, s[42:43]
	s_add_i32 m0, s55, 0xe000
	s_nop 0
	global_load_lds_dwordx4 v180, s[42:43]
	s_waitcnt vmcnt(8)
	s_waitcnt lgkmcnt(0)
	s_barrier
	s_setprio 1
	s_waitcnt lgkmcnt(0)
	v_mfma_f32_16x16x32_bf16 v[140:143], v[40:43], v[160:163], 0
	v_mfma_f32_16x16x32_bf16 v[136:139], v[56:59], v[160:163], 0
	v_mfma_f32_16x16x32_bf16 v[124:127], v[40:43], v[186:189], 0
	v_mfma_f32_16x16x32_bf16 v[120:123], v[56:59], v[186:189], 0
	v_mfma_f32_16x16x32_bf16 v[108:111], v[40:43], v[194:197], 0
	v_mfma_f32_16x16x32_bf16 v[104:107], v[56:59], v[194:197], 0
	v_mfma_f32_16x16x32_bf16 v[92:95], v[40:43], v[202:205], 0
	v_mfma_f32_16x16x32_bf16 v[88:91], v[56:59], v[202:205], 0
	v_mfma_f32_16x16x32_bf16 v[140:143], v[44:47], v[164:167], v[140:143]
	v_mfma_f32_16x16x32_bf16 v[136:139], v[60:63], v[164:167], v[136:139]
	v_mfma_f32_16x16x32_bf16 v[124:127], v[44:47], v[190:193], v[124:127]
	v_mfma_f32_16x16x32_bf16 v[120:123], v[60:63], v[190:193], v[120:123]
	v_mfma_f32_16x16x32_bf16 v[108:111], v[44:47], v[198:201], v[108:111]
	v_mfma_f32_16x16x32_bf16 v[104:107], v[60:63], v[198:201], v[104:107]
	v_mfma_f32_16x16x32_bf16 v[92:95], v[44:47], v[214:217], v[92:95]
	v_mfma_f32_16x16x32_bf16 v[88:91], v[60:63], v[214:217], v[88:91]
	s_setprio 0
	s_setprio 1
	v_mfma_f32_16x16x32_bf16 v[132:135], v[144:147], v[160:163], 0
	v_mfma_f32_16x16x32_bf16 v[128:131], v[152:155], v[160:163], 0
	v_mfma_f32_16x16x32_bf16 v[116:119], v[144:147], v[186:189], 0
	v_mfma_f32_16x16x32_bf16 v[112:115], v[152:155], v[186:189], 0
	v_mfma_f32_16x16x32_bf16 v[100:103], v[144:147], v[194:197], 0
	v_mfma_f32_16x16x32_bf16 v[96:99], v[152:155], v[194:197], 0
	v_mfma_f32_16x16x32_bf16 v[84:87], v[144:147], v[202:205], 0
	v_mfma_f32_16x16x32_bf16 v[80:83], v[152:155], v[202:205], 0
	v_mfma_f32_16x16x32_bf16 v[132:135], v[148:151], v[164:167], v[132:135]
	v_mfma_f32_16x16x32_bf16 v[128:131], v[156:159], v[164:167], v[128:131]
	v_mfma_f32_16x16x32_bf16 v[116:119], v[148:151], v[190:193], v[116:119]
	v_mfma_f32_16x16x32_bf16 v[112:115], v[156:159], v[190:193], v[112:115]
	v_mfma_f32_16x16x32_bf16 v[100:103], v[148:151], v[198:201], v[100:103]
	v_mfma_f32_16x16x32_bf16 v[96:99], v[156:159], v[198:201], v[96:99]
	v_mfma_f32_16x16x32_bf16 v[84:87], v[148:151], v[214:217], v[84:87]
	v_mfma_f32_16x16x32_bf16 v[80:83], v[156:159], v[214:217], v[80:83]
	s_setprio 0
	s_barrier
	s_add_i32 s72, s67, s54
	v_lshl_add_u64 v[218:219], s[44:45], 0, v[170:171]
	s_mov_b32 m0, s72
	ds_read_b128 v[160:163], v210 offset:16384
	ds_read_b128 v[164:167], v210 offset:17408
	ds_read_b128 v[186:189], v210 offset:18432
	ds_read_b128 v[190:193], v210 offset:19456
	ds_read_b128 v[194:197], v210 offset:20480
	ds_read_b128 v[198:201], v210 offset:21504
	ds_read_b128 v[202:205], v210 offset:22528
	ds_read_b128 v[214:217], v210 offset:23552
	global_load_lds_dwordx4 v[218:219], off
	s_add_i32 m0, s72, 0x2000
	s_add_u32 s72, s44, 0x40000
	v_lshl_add_u64 v[220:221], s[44:45], 0, v[174:175]
	s_addc_u32 s73, s45, 0
	s_add_i32 s74, s68, s54
	global_load_lds_dwordx4 v[220:221], off
	s_mov_b32 m0, s74
	v_lshl_add_u64 v[224:225], s[52:53], 0, v[172:173]
	global_load_lds_dwordx4 v170, s[72:73]
	s_add_i32 m0, s74, 0x2000
	s_nop 0
	global_load_lds_dwordx4 v174, s[72:73]
	v_lshl_add_u64 v[222:223], s[52:53], 0, v[168:169]
	s_mov_b32 m0, s55
	s_nop 0
	global_load_lds_dwordx4 v[222:223], off
	s_mov_b32 m0, s56
	s_nop 0
	global_load_lds_dwordx4 v[224:225], off
	s_waitcnt vmcnt(8)
	s_waitcnt lgkmcnt(0)
	s_barrier
; #define PG8_STAGE(bufoff, gbase, voff) do { _Pragma("unroll") for (int _i = 0; _i < 2; ++_i) \
;         __builtin_amdgcn_global_load_lds((const unsigned*)((const char*)(gbase) + (voff)[_i]), (LAS unsigned*)(lds + (bufoff) + ldsw + _i * 8192), 16, 0, 0); } while (0)
; #define PG8_LDA(dst, b, h) do { _Pragma("unroll") for (int m = 0; m < 4; ++m) _Pragma("unroll") for (int k = 0; k < 2; ++k) dst[m][k] = *(const LAS bf16x8*)(lds + PG8_SA(b, h) + aoff + m * 2048 + k * 1024); } while (0)
; #define PG8_LDB(dst, b, h) do { _Pragma("unroll") for (int n = 0; n < 2; ++n) _Pragma("unroll") for (int k = 0; k < 2; ++k) dst[n][k] = *(const LAS bf16x8*)(lds + PG8_SB(b, h) + boff + n * 2048 + k * 1024); } while (0)
; #define PG8_MMA(ai, bj, At, Bt) do { __builtin_amdgcn_s_setprio(1); _Pragma("unroll") for (int m = 0; m < 4; ++m) _Pragma("unroll") for (int n = 0; n < 2; ++n) _Pragma("unroll") for (int k = 0; k < 2; ++k) \
;         acc[ai][bj][m][n] = __builtin_amdgcn_mfma_f32_16x16x32_bf16(Bt[n][k], At[m][k], acc[ai][bj][m][n], 0, 0, 0); __builtin_amdgcn_s_setprio(0); } while (0)
; #define PG8_WAIT_V(n) asm volatile("s_waitcnt vmcnt(" #n ")" ::: "memory")
; #define PG8_WAIT_L(n) asm volatile("s_waitcnt lgkmcnt(" #n ")" ::: "memory")
; #define PG8_BAR __builtin_amdgcn_s_barrier()
; #define PG8_SCHED __builtin_amdgcn_sched_barrier(0)
; template <class Epi>
; __device__ __forceinline__ void gemm_phase(LAS unsigned char* lds, const Gemm g, const StaticOrder& S, const Epi& E) {
;     ...
;             PG8_WAIT_V(8); PG8_WAIT_L(0); PG8_BAR; PG8_MMA(1, 0, At, B0); PG8_MMA(1, 1, At, B1); PG8_BAR; PG8_SCHED;
;             PG8_LDB(B0, 1, 0); PG8_LDB(B1, 1, 1); PG8_SCHED; PG8_LDA(At, 1, 0); PG8_STAGE(PG8_SA(0, 1), a2 + hstepA, voffA);
;             PG8_WAIT_V(8); PG8_WAIT_L(0); PG8_BAR; PG8_MMA(0, 0, At, B0); PG8_MMA(0, 1, At, B1); PG8_BAR; PG8_SCHED;
	s_setprio 1
	s_waitcnt lgkmcnt(0)
	v_mfma_f32_16x16x32_bf16 v[76:79], v[40:43], v[160:163], 0
	v_mfma_f32_16x16x32_bf16 v[72:75], v[56:59], v[160:163], 0
	v_mfma_f32_16x16x32_bf16 v[52:55], v[40:43], v[186:189], 0
	v_mfma_f32_16x16x32_bf16 v[48:51], v[56:59], v[186:189], 0
	v_mfma_f32_16x16x32_bf16 v[28:31], v[40:43], v[194:197], 0
	v_mfma_f32_16x16x32_bf16 v[24:27], v[56:59], v[194:197], 0
	v_mfma_f32_16x16x32_bf16 v[12:15], v[40:43], v[202:205], 0
	v_mfma_f32_16x16x32_bf16 v[8:11], v[56:59], v[202:205], 0
	v_mfma_f32_16x16x32_bf16 v[76:79], v[44:47], v[164:167], v[76:79]
	v_mfma_f32_16x16x32_bf16 v[72:75], v[60:63], v[164:167], v[72:75]
	v_mfma_f32_16x16x32_bf16 v[52:55], v[44:47], v[190:193], v[52:55]
	v_mfma_f32_16x16x32_bf16 v[48:51], v[60:63], v[190:193], v[48:51]
	v_mfma_f32_16x16x32_bf16 v[28:31], v[44:47], v[198:201], v[28:31]
	v_mfma_f32_16x16x32_bf16 v[24:27], v[60:63], v[198:201], v[24:27]
	v_mfma_f32_16x16x32_bf16 v[12:15], v[44:47], v[214:217], v[12:15]
	v_mfma_f32_16x16x32_bf16 v[8:11], v[60:63], v[214:217], v[8:11]
	s_setprio 0
	s_setprio 1
	v_mfma_f32_16x16x32_bf16 v[36:39], v[144:147], v[186:189], 0
	v_mfma_f32_16x16x32_bf16 v[32:35], v[152:155], v[186:189], 0
	v_mfma_f32_16x16x32_bf16 v[20:23], v[144:147], v[194:197], 0
	v_mfma_f32_16x16x32_bf16 v[16:19], v[152:155], v[194:197], 0
	v_mfma_f32_16x16x32_bf16 v[4:7], v[144:147], v[202:205], 0
	v_mfma_f32_16x16x32_bf16 v[0:3], v[152:155], v[202:205], 0
	v_mfma_f32_16x16x32_bf16 v[40:43], v[144:147], v[160:163], 0
	v_mfma_f32_16x16x32_bf16 v[44:47], v[152:155], v[160:163], 0
	v_mfma_f32_16x16x32_bf16 v[36:39], v[148:151], v[190:193], v[36:39]
	v_mfma_f32_16x16x32_bf16 v[32:35], v[156:159], v[190:193], v[32:35]
	v_mfma_f32_16x16x32_bf16 v[20:23], v[148:151], v[198:201], v[20:23]
	v_mfma_f32_16x16x32_bf16 v[16:19], v[156:159], v[198:201], v[16:19]
	v_mfma_f32_16x16x32_bf16 v[4:7], v[148:151], v[214:217], v[4:7]
	v_mfma_f32_16x16x32_bf16 v[0:3], v[156:159], v[214:217], v[0:3]
	v_mfma_f32_16x16x32_bf16 v[40:43], v[148:151], v[164:167], v[40:43]
	v_mfma_f32_16x16x32_bf16 v[44:47], v[156:159], v[164:167], v[44:47]
	s_setprio 0
	s_barrier
	s_add_i32 s72, 0, 0x18000
	s_add_i32 s73, 0, 0x1c000
	v_add_u32_e32 v68, s72, v207
	v_add_u32_e32 v156, s73, v207
	ds_read_b128 v[56:59], v68
	ds_read_b128 v[60:63], v68 offset:1024
	ds_read_b128 v[64:67], v68 offset:2048
	ds_read_b128 v[68:71], v68 offset:3072
	ds_read_b128 v[144:147], v156
	ds_read_b128 v[148:151], v156 offset:1024
	ds_read_b128 v[152:155], v156 offset:2048
	ds_read_b128 v[156:159], v156 offset:3072
	s_add_u32 s52, s52, 0x40000
	s_addc_u32 s53, s53, 0
	s_mov_b32 m0, s57
	ds_read_b128 v[160:163], v210 offset:32768
	ds_read_b128 v[164:167], v210 offset:33792
	ds_read_b128 v[186:189], v210 offset:34816
	ds_read_b128 v[190:193], v210 offset:35840
	ds_read_b128 v[194:197], v210 offset:36864
	ds_read_b128 v[198:201], v210 offset:37888
	ds_read_b128 v[202:205], v210 offset:38912
	ds_read_b128 v[214:217], v210 offset:39936
	global_load_lds_dwordx4 v168, s[52:53]
	s_mov_b32 m0, s58
	s_nop 0
	global_load_lds_dwordx4 v172, s[52:53]
	s_waitcnt vmcnt(8)
	s_waitcnt lgkmcnt(0)
	s_barrier
	s_setprio 1
	s_waitcnt lgkmcnt(0)
	v_mfma_f32_16x16x32_bf16 v[140:143], v[56:59], v[160:163], v[140:143]
	v_mfma_f32_16x16x32_bf16 v[136:139], v[64:67], v[160:163], v[136:139]
	v_mfma_f32_16x16x32_bf16 v[124:127], v[56:59], v[186:189], v[124:127]
	v_mfma_f32_16x16x32_bf16 v[120:123], v[64:67], v[186:189], v[120:123]
	v_mfma_f32_16x16x32_bf16 v[108:111], v[56:59], v[194:197], v[108:111]
	v_mfma_f32_16x16x32_bf16 v[104:107], v[64:67], v[194:197], v[104:107]
	v_mfma_f32_16x16x32_bf16 v[92:95], v[56:59], v[202:205], v[92:95]
	v_mfma_f32_16x16x32_bf16 v[88:91], v[64:67], v[202:205], v[88:91]
	v_mfma_f32_16x16x32_bf16 v[140:143], v[60:63], v[164:167], v[140:143]
	v_mfma_f32_16x16x32_bf16 v[136:139], v[68:71], v[164:167], v[136:139]
	v_mfma_f32_16x16x32_bf16 v[124:127], v[60:63], v[190:193], v[124:127]
	v_mfma_f32_16x16x32_bf16 v[120:123], v[68:71], v[190:193], v[120:123]
	v_mfma_f32_16x16x32_bf16 v[108:111], v[60:63], v[198:201], v[108:111]
	v_mfma_f32_16x16x32_bf16 v[104:107], v[68:71], v[198:201], v[104:107]
	v_mfma_f32_16x16x32_bf16 v[92:95], v[60:63], v[214:217], v[92:95]
	v_mfma_f32_16x16x32_bf16 v[88:91], v[68:71], v[214:217], v[88:91]
	s_setprio 0
	s_setprio 1
	v_mfma_f32_16x16x32_bf16 v[132:135], v[144:147], v[160:163], v[132:135]
	v_mfma_f32_16x16x32_bf16 v[128:131], v[152:155], v[160:163], v[128:131]
	v_mfma_f32_16x16x32_bf16 v[116:119], v[144:147], v[186:189], v[116:119]
	v_mfma_f32_16x16x32_bf16 v[112:115], v[152:155], v[186:189], v[112:115]
	v_mfma_f32_16x16x32_bf16 v[100:103], v[144:147], v[194:197], v[100:103]
	v_mfma_f32_16x16x32_bf16 v[96:99], v[152:155], v[194:197], v[96:99]
	v_mfma_f32_16x16x32_bf16 v[84:87], v[144:147], v[202:205], v[84:87]
	v_mfma_f32_16x16x32_bf16 v[80:83], v[152:155], v[202:205], v[80:83]
	v_mfma_f32_16x16x32_bf16 v[132:135], v[148:151], v[164:167], v[132:135]
	v_mfma_f32_16x16x32_bf16 v[128:131], v[156:159], v[164:167], v[128:131]
	v_mfma_f32_16x16x32_bf16 v[116:119], v[148:151], v[190:193], v[116:119]
	v_mfma_f32_16x16x32_bf16 v[112:115], v[156:159], v[190:193], v[112:115]
	v_mfma_f32_16x16x32_bf16 v[100:103], v[148:151], v[198:201], v[100:103]
	v_mfma_f32_16x16x32_bf16 v[96:99], v[156:159], v[198:201], v[96:99]
	v_mfma_f32_16x16x32_bf16 v[84:87], v[148:151], v[214:217], v[84:87]
	v_mfma_f32_16x16x32_bf16 v[80:83], v[156:159], v[214:217], v[80:83]
	s_setprio 0
	s_barrier
; #define PG8_STAGE(bufoff, gbase, voff) do { _Pragma("unroll") for (int _i = 0; _i < 2; ++_i) \
;         __builtin_amdgcn_global_load_lds((const unsigned*)((const char*)(gbase) + (voff)[_i]), (LAS unsigned*)(lds + (bufoff) + ldsw + _i * 8192), 16, 0, 0); } while (0)
; #define PG8_LDA(dst, b, h) do { _Pragma("unroll") for (int m = 0; m < 4; ++m) _Pragma("unroll") for (int k = 0; k < 2; ++k) dst[m][k] = *(const LAS bf16x8*)(lds + PG8_SA(b, h) + aoff + m * 2048 + k * 1024); } while (0)
; #define PG8_LDB(dst, b, h) do { _Pragma("unroll") for (int n = 0; n < 2; ++n) _Pragma("unroll") for (int k = 0; k < 2; ++k) dst[n][k] = *(const LAS bf16x8*)(lds + PG8_SB(b, h) + boff + n * 2048 + k * 1024); } while (0)
; #define PG8_WAIT_V(n) asm volatile("s_waitcnt vmcnt(" #n ")" ::: "memory")
; #define PG8_BAR __builtin_amdgcn_s_barrier()
; template <class Epi>
; __device__ __forceinline__ void gemm_phase(LAS unsigned char* lds, const Gemm g, const StaticOrder& S, const Epi& E) {
;     ...
;         for (int t = 0; t < nt; t += 2) {
;             const bool last = (t == nt - 2);
;             const char* a1 = cA + (size_t)(t + 1) * kstep;
;             const char* a2 = last ? nA : cA + (size_t)(t + 2) * kstep; const char* b2 = last ? nB : cB + (size_t)(t + 2) * kstep;
;             const char* a3 = a2 + kstep; const char* b3 = b2 + kstep;
;             PG8_LDB(B0, 0, 0); PG8_LDB(B1, 0, 1); PG8_SCHED; PG8_LDA(At, 0, 0); PG8_STAGE(PG8_SA(1, 1), a1 + hstepA, voffA);
;             PG8_WAIT_V(8); PG8_WAIT_L(0); PG8_BAR; PG8_MMA(0, 0, At, B0); PG8_MMA(0, 1, At, B1); PG8_BAR; PG8_SCHED;
;             PG8_LDA(At, 0, 1); PG8_STAGE(PG8_SB(0, 0), b2, voffB); PG8_STAGE(PG8_SB(0, 1), b2 + hstepB, voffB); PG8_STAGE(PG8_SA(0, 0), a2, voffA);
;             PG8_WAIT_V(8); PG8_WAIT_L(0); PG8_BAR; PG8_MMA(1, 0, At, B0); PG8_MMA(1, 1, At, B1); PG8_BAR; PG8_SCHED;
;             PG8_LDB(B0, 1, 0); PG8_LDB(B1, 1, 1); PG8_SCHED; PG8_LDA(At, 1, 0); PG8_STAGE(PG8_SA(0, 1), a2 + hstepA, voffA);
;             PG8_WAIT_V(8); PG8_WAIT_L(0); PG8_BAR; PG8_MMA(0, 0, At, B0); PG8_MMA(0, 1, At, B1); PG8_BAR; PG8_SCHED;
;             PG8_LDA(At, 1, 1); PG8_STAGE(PG8_SB(1, 0), b3, voffB); PG8_STAGE(PG8_SB(1, 1), b3 + hstepB, voffB); PG8_STAGE(PG8_SA(1, 0), a3, voffA);
;             PG8_WAIT_V(8); PG8_WAIT_L(0); PG8_BAR; PG8_MMA(1, 0, At, B0); PG8_MMA(1, 1, At, B1); PG8_BAR; PG8_SCHED;
;         }
	s_add_i32 s52, s72, s54
	v_lshl_add_u64 v[218:219], v[218:219], 0, s[20:21]
	s_mov_b32 m0, s52
	ds_read_b128 v[160:163], v210 offset:49152
	ds_read_b128 v[164:167], v210 offset:50176
	ds_read_b128 v[186:189], v210 offset:51200
	ds_read_b128 v[190:193], v210 offset:52224
	ds_read_b128 v[194:197], v210 offset:53248
	ds_read_b128 v[198:201], v210 offset:54272
	ds_read_b128 v[202:205], v210 offset:55296
	ds_read_b128 v[214:217], v210 offset:56320
	global_load_lds_dwordx4 v[218:219], off
	s_add_i32 m0, s52, 0x2000
	s_add_u32 s44, s44, 0x40080
	v_lshl_add_u64 v[218:219], v[220:221], 0, s[20:21]
	s_addc_u32 s45, s45, 0
	s_add_i32 s52, s73, s54
	global_load_lds_dwordx4 v[218:219], off
	s_mov_b32 m0, s52
	s_nop 0
	global_load_lds_dwordx4 v170, s[44:45]
	s_add_i32 m0, s52, 0x2000
	s_nop 0
	global_load_lds_dwordx4 v174, s[44:45]
	v_lshl_add_u64 v[218:219], v[222:223], 0, s[20:21]
	s_mov_b32 m0, s62
	s_nop 0
	global_load_lds_dwordx4 v[218:219], off
	v_lshl_add_u64 v[218:219], v[224:225], 0, s[20:21]
	s_mov_b32 m0, s63
	s_nop 0
	global_load_lds_dwordx4 v[218:219], off
	s_waitcnt vmcnt(8)
	s_waitcnt lgkmcnt(0)
	s_barrier
	s_setprio 1
	s_waitcnt lgkmcnt(0)
	v_mfma_f32_16x16x32_bf16 v[76:79], v[56:59], v[160:163], v[76:79]
	v_mfma_f32_16x16x32_bf16 v[72:75], v[64:67], v[160:163], v[72:75]
	v_mfma_f32_16x16x32_bf16 v[52:55], v[56:59], v[186:189], v[52:55]
	v_mfma_f32_16x16x32_bf16 v[48:51], v[64:67], v[186:189], v[48:51]
	v_mfma_f32_16x16x32_bf16 v[28:31], v[56:59], v[194:197], v[28:31]
	v_mfma_f32_16x16x32_bf16 v[24:27], v[64:67], v[194:197], v[24:27]
	v_mfma_f32_16x16x32_bf16 v[12:15], v[56:59], v[202:205], v[12:15]
	v_mfma_f32_16x16x32_bf16 v[8:11], v[64:67], v[202:205], v[8:11]
	v_mfma_f32_16x16x32_bf16 v[76:79], v[60:63], v[164:167], v[76:79]
	v_mfma_f32_16x16x32_bf16 v[72:75], v[68:71], v[164:167], v[72:75]
	v_mfma_f32_16x16x32_bf16 v[52:55], v[60:63], v[190:193], v[52:55]
	v_mfma_f32_16x16x32_bf16 v[48:51], v[68:71], v[190:193], v[48:51]
	v_mfma_f32_16x16x32_bf16 v[28:31], v[60:63], v[198:201], v[28:31]
	v_mfma_f32_16x16x32_bf16 v[24:27], v[68:71], v[198:201], v[24:27]
	v_mfma_f32_16x16x32_bf16 v[12:15], v[60:63], v[214:217], v[12:15]
	v_mfma_f32_16x16x32_bf16 v[8:11], v[68:71], v[214:217], v[8:11]
	s_setprio 0
	s_setprio 1
	v_mfma_f32_16x16x32_bf16 v[40:43], v[144:147], v[160:163], v[40:43]
	v_mfma_f32_16x16x32_bf16 v[68:71], v[148:151], v[164:167], v[40:43]
	v_mfma_f32_16x16x32_bf16 v[40:43], v[152:155], v[160:163], v[44:47]
	v_mfma_f32_16x16x32_bf16 v[36:39], v[144:147], v[186:189], v[36:39]
	v_mfma_f32_16x16x32_bf16 v[32:35], v[152:155], v[186:189], v[32:35]
	v_mfma_f32_16x16x32_bf16 v[20:23], v[144:147], v[194:197], v[20:23]
	v_mfma_f32_16x16x32_bf16 v[16:19], v[152:155], v[194:197], v[16:19]
	v_mfma_f32_16x16x32_bf16 v[4:7], v[144:147], v[202:205], v[4:7]
	v_mfma_f32_16x16x32_bf16 v[0:3], v[152:155], v[202:205], v[0:3]
	v_mfma_f32_16x16x32_bf16 v[64:67], v[156:159], v[164:167], v[40:43]
	v_mfma_f32_16x16x32_bf16 v[36:39], v[148:151], v[190:193], v[36:39]
	v_mfma_f32_16x16x32_bf16 v[32:35], v[156:159], v[190:193], v[32:35]
	v_mfma_f32_16x16x32_bf16 v[20:23], v[148:151], v[198:201], v[20:23]
	v_mfma_f32_16x16x32_bf16 v[16:19], v[156:159], v[198:201], v[16:19]
	v_mfma_f32_16x16x32_bf16 v[4:7], v[148:151], v[214:217], v[4:7]
	v_mfma_f32_16x16x32_bf16 v[0:3], v[156:159], v[214:217], v[0:3]
	s_setprio 0
	s_barrier
	s_add_i32 s71, s71, 2
	s_add_u32 s42, s42, 0x100
	s_addc_u32 s43, s43, 0
	s_add_u32 s69, s69, 0x100
	s_addc_u32 s70, s70, 0
	s_cmp_gt_u32 s71, 13
.LBB0_1746:
	ds_read_b128 v[40:43], v208
	ds_read_b128 v[44:47], v208 offset:1024
	ds_read_b128 v[56:59], v208 offset:2048
	ds_read_b128 v[60:63], v208 offset:3072
	ds_read_b128 v[144:147], v209
	ds_read_b128 v[148:151], v209 offset:1024
	ds_read_b128 v[152:155], v209 offset:2048
	ds_read_b128 v[156:159], v209 offset:3072
	s_add_u32 s44, s42, 0xfffc0080
	s_addc_u32 s45, s43, -1
	s_cmp_eq_u32 s71, 12
	s_cselect_b32 s53, s7, s45
	s_cselect_b32 s52, s9, s44
	s_cselect_b32 s45, s29, s70
	s_cselect_b32 s44, s35, s69
	s_add_i32 m0, s55, 0xc000
	ds_read_b128 v[160:163], v210
	ds_read_b128 v[164:167], v210 offset:1024
	ds_read_b128 v[186:189], v210 offset:2048
	ds_read_b128 v[190:193], v210 offset:3072
	ds_read_b128 v[194:197], v210 offset:4096
	ds_read_b128 v[198:201], v210 offset:5120
	ds_read_b128 v[202:205], v210 offset:6144
	ds_read_b128 v[214:217], v210 offset:7168
	global_load_lds_dwordx4 v178, s[42:43]
	s_add_i32 m0, s55, 0xe000
	s_nop 0
	global_load_lds_dwordx4 v180, s[42:43]
	s_waitcnt vmcnt(8)
	s_waitcnt lgkmcnt(0)
	s_barrier
; #define PG8_STAGE(bufoff, gbase, voff) do { _Pragma("unroll") for (int _i = 0; _i < 2; ++_i) \
;         __builtin_amdgcn_global_load_lds((const unsigned*)((const char*)(gbase) + (voff)[_i]), (LAS unsigned*)(lds + (bufoff) + ldsw + _i * 8192), 16, 0, 0); } while (0)
; #define PG8_LDA(dst, b, h) do { _Pragma("unroll") for (int m = 0; m < 4; ++m) _Pragma("unroll") for (int k = 0; k < 2; ++k) dst[m][k] = *(const LAS bf16x8*)(lds + PG8_SA(b, h) + aoff + m * 2048 + k * 1024); } while (0)
; #define PG8_LDB(dst, b, h) do { _Pragma("unroll") for (int n = 0; n < 2; ++n) _Pragma("unroll") for (int k = 0; k < 2; ++k) dst[n][k] = *(const LAS bf16x8*)(lds + PG8_SB(b, h) + boff + n * 2048 + k * 1024); } while (0)
; #define PG8_MMA(ai, bj, At, Bt) do { __builtin_amdgcn_s_setprio(1); _Pragma("unroll") for (int m = 0; m < 4; ++m) _Pragma("unroll") for (int n = 0; n < 2; ++n) _Pragma("unroll") for (int k = 0; k < 2; ++k) \
;         acc[ai][bj][m][n] = __builtin_amdgcn_mfma_f32_16x16x32_bf16(Bt[n][k], At[m][k], acc[ai][bj][m][n], 0, 0, 0); __builtin_amdgcn_s_setprio(0); } while (0)
; #define PG8_WAIT_V(n) asm volatile("s_waitcnt vmcnt(" #n ")" ::: "memory")
; #define PG8_WAIT_L(n) asm volatile("s_waitcnt lgkmcnt(" #n ")" ::: "memory")
; #define PG8_BAR __builtin_amdgcn_s_barrier()
; #define PG8_SCHED __builtin_amdgcn_sched_barrier(0)
; template <class Epi>
; __device__ __forceinline__ void gemm_phase(LAS unsigned char* lds, const Gemm g, const StaticOrder& S, const Epi& E) {
;     ...
;             PG8_LDB(B0, 0, 0); PG8_LDB(B1, 0, 1); PG8_SCHED; PG8_LDA(At, 0, 0); PG8_STAGE(PG8_SA(1, 1), a1 + hstepA, voffA);
;             PG8_WAIT_V(8); PG8_WAIT_L(0); PG8_BAR; PG8_MMA(0, 0, At, B0); PG8_MMA(0, 1, At, B1); PG8_BAR; PG8_SCHED;
;             PG8_LDA(At, 0, 1); PG8_STAGE(PG8_SB(0, 0), b2, voffB); PG8_STAGE(PG8_SB(0, 1), b2 + hstepB, voffB); PG8_STAGE(PG8_SA(0, 0), a2, voffA);
;             PG8_WAIT_V(8); PG8_WAIT_L(0); PG8_BAR; PG8_MMA(1, 0, At, B0); PG8_MMA(1, 1, At, B1); PG8_BAR; PG8_SCHED;
	s_setprio 1
	s_waitcnt lgkmcnt(0)
	v_mfma_f32_16x16x32_bf16 v[140:143], v[40:43], v[160:163], v[140:143]
	v_mfma_f32_16x16x32_bf16 v[136:139], v[56:59], v[160:163], v[136:139]
	v_mfma_f32_16x16x32_bf16 v[124:127], v[40:43], v[186:189], v[124:127]
	v_mfma_f32_16x16x32_bf16 v[120:123], v[56:59], v[186:189], v[120:123]
	v_mfma_f32_16x16x32_bf16 v[108:111], v[40:43], v[194:197], v[108:111]
	v_mfma_f32_16x16x32_bf16 v[104:107], v[56:59], v[194:197], v[104:107]
	v_mfma_f32_16x16x32_bf16 v[92:95], v[40:43], v[202:205], v[92:95]
	v_mfma_f32_16x16x32_bf16 v[88:91], v[56:59], v[202:205], v[88:91]
	v_mfma_f32_16x16x32_bf16 v[140:143], v[44:47], v[164:167], v[140:143]
	v_mfma_f32_16x16x32_bf16 v[136:139], v[60:63], v[164:167], v[136:139]
	v_mfma_f32_16x16x32_bf16 v[124:127], v[44:47], v[190:193], v[124:127]
	v_mfma_f32_16x16x32_bf16 v[120:123], v[60:63], v[190:193], v[120:123]
	v_mfma_f32_16x16x32_bf16 v[108:111], v[44:47], v[198:201], v[108:111]
	v_mfma_f32_16x16x32_bf16 v[104:107], v[60:63], v[198:201], v[104:107]
	v_mfma_f32_16x16x32_bf16 v[92:95], v[44:47], v[214:217], v[92:95]
	v_mfma_f32_16x16x32_bf16 v[88:91], v[60:63], v[214:217], v[88:91]
	s_setprio 0
	s_setprio 1
	v_mfma_f32_16x16x32_bf16 v[132:135], v[144:147], v[160:163], v[132:135]
	v_mfma_f32_16x16x32_bf16 v[128:131], v[152:155], v[160:163], v[128:131]
	v_mfma_f32_16x16x32_bf16 v[116:119], v[144:147], v[186:189], v[116:119]
	v_mfma_f32_16x16x32_bf16 v[112:115], v[152:155], v[186:189], v[112:115]
	v_mfma_f32_16x16x32_bf16 v[100:103], v[144:147], v[194:197], v[100:103]
	v_mfma_f32_16x16x32_bf16 v[96:99], v[152:155], v[194:197], v[96:99]
	v_mfma_f32_16x16x32_bf16 v[84:87], v[144:147], v[202:205], v[84:87]
	v_mfma_f32_16x16x32_bf16 v[80:83], v[152:155], v[202:205], v[80:83]
	v_mfma_f32_16x16x32_bf16 v[132:135], v[148:151], v[164:167], v[132:135]
	v_mfma_f32_16x16x32_bf16 v[128:131], v[156:159], v[164:167], v[128:131]
	v_mfma_f32_16x16x32_bf16 v[116:119], v[148:151], v[190:193], v[116:119]
	v_mfma_f32_16x16x32_bf16 v[112:115], v[156:159], v[190:193], v[112:115]
	v_mfma_f32_16x16x32_bf16 v[100:103], v[148:151], v[198:201], v[100:103]
	v_mfma_f32_16x16x32_bf16 v[96:99], v[156:159], v[198:201], v[96:99]
	v_mfma_f32_16x16x32_bf16 v[84:87], v[148:151], v[214:217], v[84:87]
	v_mfma_f32_16x16x32_bf16 v[80:83], v[156:159], v[214:217], v[80:83]
	s_setprio 0
	s_barrier
	s_add_i32 s72, s67, s54
	v_lshl_add_u64 v[218:219], s[44:45], 0, v[170:171]
	s_mov_b32 m0, s72
	ds_read_b128 v[160:163], v210 offset:16384
	ds_read_b128 v[164:167], v210 offset:17408
	ds_read_b128 v[186:189], v210 offset:18432
	ds_read_b128 v[190:193], v210 offset:19456
	ds_read_b128 v[194:197], v210 offset:20480
	ds_read_b128 v[198:201], v210 offset:21504
	ds_read_b128 v[202:205], v210 offset:22528
	ds_read_b128 v[214:217], v210 offset:23552
	global_load_lds_dwordx4 v[218:219], off
	s_add_i32 m0, s72, 0x2000
	s_add_u32 s72, s44, 0x40000
	v_lshl_add_u64 v[220:221], s[44:45], 0, v[174:175]
	s_addc_u32 s73, s45, 0
	s_add_i32 s74, s68, s54
	global_load_lds_dwordx4 v[220:221], off
	s_mov_b32 m0, s74
	v_lshl_add_u64 v[224:225], s[52:53], 0, v[172:173]
	global_load_lds_dwordx4 v170, s[72:73]
	s_add_i32 m0, s74, 0x2000
	s_nop 0
	global_load_lds_dwordx4 v174, s[72:73]
	v_lshl_add_u64 v[222:223], s[52:53], 0, v[168:169]
	s_mov_b32 m0, s55
	s_nop 0
	global_load_lds_dwordx4 v[222:223], off
	s_mov_b32 m0, s56
	s_nop 0
	global_load_lds_dwordx4 v[224:225], off
	s_waitcnt vmcnt(8)
	s_waitcnt lgkmcnt(0)
	s_barrier
	s_setprio 1
	s_waitcnt lgkmcnt(0)
	v_mfma_f32_16x16x32_bf16 v[76:79], v[40:43], v[160:163], v[76:79]
	v_mfma_f32_16x16x32_bf16 v[72:75], v[56:59], v[160:163], v[72:75]
	v_mfma_f32_16x16x32_bf16 v[52:55], v[40:43], v[186:189], v[52:55]
	v_mfma_f32_16x16x32_bf16 v[48:51], v[56:59], v[186:189], v[48:51]
	v_mfma_f32_16x16x32_bf16 v[28:31], v[40:43], v[194:197], v[28:31]
	v_mfma_f32_16x16x32_bf16 v[24:27], v[56:59], v[194:197], v[24:27]
	v_mfma_f32_16x16x32_bf16 v[12:15], v[40:43], v[202:205], v[12:15]
	v_mfma_f32_16x16x32_bf16 v[8:11], v[56:59], v[202:205], v[8:11]
	v_mfma_f32_16x16x32_bf16 v[76:79], v[44:47], v[164:167], v[76:79]
	v_mfma_f32_16x16x32_bf16 v[72:75], v[60:63], v[164:167], v[72:75]
	v_mfma_f32_16x16x32_bf16 v[52:55], v[44:47], v[190:193], v[52:55]
	v_mfma_f32_16x16x32_bf16 v[48:51], v[60:63], v[190:193], v[48:51]
	v_mfma_f32_16x16x32_bf16 v[28:31], v[44:47], v[198:201], v[28:31]
	v_mfma_f32_16x16x32_bf16 v[24:27], v[60:63], v[198:201], v[24:27]
	v_mfma_f32_16x16x32_bf16 v[12:15], v[44:47], v[214:217], v[12:15]
	v_mfma_f32_16x16x32_bf16 v[8:11], v[60:63], v[214:217], v[8:11]
	s_setprio 0
	s_setprio 1
	v_mfma_f32_16x16x32_bf16 v[36:39], v[144:147], v[186:189], v[36:39]
	v_mfma_f32_16x16x32_bf16 v[32:35], v[152:155], v[186:189], v[32:35]
	v_mfma_f32_16x16x32_bf16 v[20:23], v[144:147], v[194:197], v[20:23]
	v_mfma_f32_16x16x32_bf16 v[16:19], v[152:155], v[194:197], v[16:19]
	v_mfma_f32_16x16x32_bf16 v[4:7], v[144:147], v[202:205], v[4:7]
	v_mfma_f32_16x16x32_bf16 v[0:3], v[152:155], v[202:205], v[0:3]
	v_mfma_f32_16x16x32_bf16 v[40:43], v[144:147], v[160:163], v[68:71]
	v_mfma_f32_16x16x32_bf16 v[44:47], v[152:155], v[160:163], v[64:67]
	v_mfma_f32_16x16x32_bf16 v[36:39], v[148:151], v[190:193], v[36:39]
	v_mfma_f32_16x16x32_bf16 v[32:35], v[156:159], v[190:193], v[32:35]
	v_mfma_f32_16x16x32_bf16 v[20:23], v[148:151], v[198:201], v[20:23]
	v_mfma_f32_16x16x32_bf16 v[16:19], v[156:159], v[198:201], v[16:19]
	v_mfma_f32_16x16x32_bf16 v[4:7], v[148:151], v[214:217], v[4:7]
	v_mfma_f32_16x16x32_bf16 v[0:3], v[156:159], v[214:217], v[0:3]
	v_mfma_f32_16x16x32_bf16 v[40:43], v[148:151], v[164:167], v[40:43]
	v_mfma_f32_16x16x32_bf16 v[44:47], v[156:159], v[164:167], v[44:47]
	s_setprio 0
	s_barrier
; #define PG8_STAGE(bufoff, gbase, voff) do { _Pragma("unroll") for (int _i = 0; _i < 2; ++_i) \
;         __builtin_amdgcn_global_load_lds((const unsigned*)((const char*)(gbase) + (voff)[_i]), (LAS unsigned*)(lds + (bufoff) + ldsw + _i * 8192), 16, 0, 0); } while (0)
; #define PG8_LDA(dst, b, h) do { _Pragma("unroll") for (int m = 0; m < 4; ++m) _Pragma("unroll") for (int k = 0; k < 2; ++k) dst[m][k] = *(const LAS bf16x8*)(lds + PG8_SA(b, h) + aoff + m * 2048 + k * 1024); } while (0)
; #define PG8_LDB(dst, b, h) do { _Pragma("unroll") for (int n = 0; n < 2; ++n) _Pragma("unroll") for (int k = 0; k < 2; ++k) dst[n][k] = *(const LAS bf16x8*)(lds + PG8_SB(b, h) + boff + n * 2048 + k * 1024); } while (0)
; #define PG8_MMA(ai, bj, At, Bt) do { __builtin_amdgcn_s_setprio(1); _Pragma("unroll") for (int m = 0; m < 4; ++m) _Pragma("unroll") for (int n = 0; n < 2; ++n) _Pragma("unroll") for (int k = 0; k < 2; ++k) \
;         acc[ai][bj][m][n] = __builtin_amdgcn_mfma_f32_16x16x32_bf16(Bt[n][k], At[m][k], acc[ai][bj][m][n], 0, 0, 0); __builtin_amdgcn_s_setprio(0); } while (0)
; #define PG8_WAIT_V(n) asm volatile("s_waitcnt vmcnt(" #n ")" ::: "memory")
; #define PG8_WAIT_L(n) asm volatile("s_waitcnt lgkmcnt(" #n ")" ::: "memory")
; #define PG8_BAR __builtin_amdgcn_s_barrier()
; #define PG8_SCHED __builtin_amdgcn_sched_barrier(0)
; template <class Epi>
; __device__ __forceinline__ void gemm_phase(LAS unsigned char* lds, const Gemm g, const StaticOrder& S, const Epi& E) {
;     ...
;             PG8_LDB(B0, 1, 0); PG8_LDB(B1, 1, 1); PG8_SCHED; PG8_LDA(At, 1, 0); PG8_STAGE(PG8_SA(0, 1), a2 + hstepA, voffA);
;             PG8_WAIT_V(8); PG8_WAIT_L(0); PG8_BAR; PG8_MMA(0, 0, At, B0); PG8_MMA(0, 1, At, B1); PG8_BAR; PG8_SCHED;
;             PG8_LDA(At, 1, 1); PG8_STAGE(PG8_SB(1, 0), b3, voffB); PG8_STAGE(PG8_SB(1, 1), b3 + hstepB, voffB); PG8_STAGE(PG8_SA(1, 0), a3, voffA);
;             PG8_WAIT_V(8); PG8_WAIT_L(0); PG8_BAR; PG8_MMA(1, 0, At, B0); PG8_MMA(1, 1, At, B1); PG8_BAR; PG8_SCHED;
;         }
;         if (wr == 0) PG8_BAR;
	s_add_i32 s72, 0, 0x18000
	s_add_i32 s73, 0, 0x1c000
	v_add_u32_e32 v68, s72, v207
	v_add_u32_e32 v156, s73, v207
	ds_read_b128 v[56:59], v68
	ds_read_b128 v[60:63], v68 offset:1024
	ds_read_b128 v[64:67], v68 offset:2048
	ds_read_b128 v[68:71], v68 offset:3072
	ds_read_b128 v[144:147], v156
	ds_read_b128 v[148:151], v156 offset:1024
	ds_read_b128 v[152:155], v156 offset:2048
	ds_read_b128 v[156:159], v156 offset:3072
	s_add_u32 s52, s52, 0x40000
	s_addc_u32 s53, s53, 0
	s_mov_b32 m0, s57
	ds_read_b128 v[160:163], v210 offset:32768
	ds_read_b128 v[164:167], v210 offset:33792
	ds_read_b128 v[186:189], v210 offset:34816
	ds_read_b128 v[190:193], v210 offset:35840
	ds_read_b128 v[194:197], v210 offset:36864
	ds_read_b128 v[198:201], v210 offset:37888
	ds_read_b128 v[202:205], v210 offset:38912
	ds_read_b128 v[214:217], v210 offset:39936
	global_load_lds_dwordx4 v168, s[52:53]
	v_lshl_add_u64 v[226:227], s[52:53], 0, v[172:173]
	s_mov_b32 m0, s58
	s_nop 0
	global_load_lds_dwordx4 v[226:227], off
	s_waitcnt vmcnt(8)
	s_waitcnt lgkmcnt(0)
	s_barrier
	s_setprio 1
	s_waitcnt lgkmcnt(0)
	v_mfma_f32_16x16x32_bf16 v[140:143], v[56:59], v[160:163], v[140:143]
	v_mfma_f32_16x16x32_bf16 v[136:139], v[64:67], v[160:163], v[136:139]
	v_mfma_f32_16x16x32_bf16 v[124:127], v[56:59], v[186:189], v[124:127]
	v_mfma_f32_16x16x32_bf16 v[120:123], v[64:67], v[186:189], v[120:123]
	v_mfma_f32_16x16x32_bf16 v[108:111], v[56:59], v[194:197], v[108:111]
	v_mfma_f32_16x16x32_bf16 v[104:107], v[64:67], v[194:197], v[104:107]
	v_mfma_f32_16x16x32_bf16 v[92:95], v[56:59], v[202:205], v[92:95]
	v_mfma_f32_16x16x32_bf16 v[88:91], v[64:67], v[202:205], v[88:91]
	v_mfma_f32_16x16x32_bf16 v[140:143], v[60:63], v[164:167], v[140:143]
	v_mfma_f32_16x16x32_bf16 v[136:139], v[68:71], v[164:167], v[136:139]
	v_mfma_f32_16x16x32_bf16 v[124:127], v[60:63], v[190:193], v[124:127]
	v_mfma_f32_16x16x32_bf16 v[120:123], v[68:71], v[190:193], v[120:123]
	v_mfma_f32_16x16x32_bf16 v[108:111], v[60:63], v[198:201], v[108:111]
	v_mfma_f32_16x16x32_bf16 v[104:107], v[68:71], v[198:201], v[104:107]
	v_mfma_f32_16x16x32_bf16 v[92:95], v[60:63], v[214:217], v[92:95]
	v_mfma_f32_16x16x32_bf16 v[88:91], v[68:71], v[214:217], v[88:91]
	s_setprio 0
	s_setprio 1
	v_mfma_f32_16x16x32_bf16 v[132:135], v[144:147], v[160:163], v[132:135]
	v_mfma_f32_16x16x32_bf16 v[128:131], v[152:155], v[160:163], v[128:131]
	v_mfma_f32_16x16x32_bf16 v[116:119], v[144:147], v[186:189], v[116:119]
	v_mfma_f32_16x16x32_bf16 v[112:115], v[152:155], v[186:189], v[112:115]
	v_mfma_f32_16x16x32_bf16 v[100:103], v[144:147], v[194:197], v[100:103]
	v_mfma_f32_16x16x32_bf16 v[96:99], v[152:155], v[194:197], v[96:99]
	v_mfma_f32_16x16x32_bf16 v[84:87], v[144:147], v[202:205], v[84:87]
	v_mfma_f32_16x16x32_bf16 v[80:83], v[152:155], v[202:205], v[80:83]
	v_mfma_f32_16x16x32_bf16 v[132:135], v[148:151], v[164:167], v[132:135]
	v_mfma_f32_16x16x32_bf16 v[128:131], v[156:159], v[164:167], v[128:131]
	v_mfma_f32_16x16x32_bf16 v[116:119], v[148:151], v[190:193], v[116:119]
	v_mfma_f32_16x16x32_bf16 v[112:115], v[156:159], v[190:193], v[112:115]
	v_mfma_f32_16x16x32_bf16 v[100:103], v[148:151], v[198:201], v[100:103]
	v_mfma_f32_16x16x32_bf16 v[96:99], v[156:159], v[198:201], v[96:99]
	v_mfma_f32_16x16x32_bf16 v[84:87], v[148:151], v[214:217], v[84:87]
	v_mfma_f32_16x16x32_bf16 v[80:83], v[156:159], v[214:217], v[80:83]
	s_setprio 0
	s_barrier
	s_add_i32 s52, s72, s54
	v_lshl_add_u64 v[218:219], v[218:219], 0, s[20:21]
	s_mov_b32 m0, s52
	ds_read_b128 v[160:163], v210 offset:49152
	ds_read_b128 v[164:167], v210 offset:50176
	ds_read_b128 v[186:189], v210 offset:51200
	ds_read_b128 v[190:193], v210 offset:52224
	ds_read_b128 v[194:197], v210 offset:53248
	ds_read_b128 v[198:201], v210 offset:54272
	ds_read_b128 v[202:205], v210 offset:55296
	ds_read_b128 v[214:217], v210 offset:56320
	global_load_lds_dwordx4 v[218:219], off
	s_add_i32 m0, s52, 0x2000
	s_add_u32 s44, s44, 0x40080
	v_lshl_add_u64 v[218:219], v[220:221], 0, s[20:21]
	s_addc_u32 s45, s45, 0
	s_add_i32 s52, s73, s54
	global_load_lds_dwordx4 v[218:219], off
	s_mov_b32 m0, s52
	s_nop 0
	global_load_lds_dwordx4 v170, s[44:45]
	s_add_i32 m0, s52, 0x2000
	s_nop 0
	global_load_lds_dwordx4 v174, s[44:45]
	v_lshl_add_u64 v[218:219], v[222:223], 0, s[20:21]
	s_mov_b32 m0, s62
	s_nop 0
	global_load_lds_dwordx4 v[218:219], off
	v_lshl_add_u64 v[218:219], v[224:225], 0, s[20:21]
	s_mov_b32 m0, s63
	s_nop 0
	global_load_lds_dwordx4 v[218:219], off
	s_waitcnt vmcnt(8)
	s_waitcnt lgkmcnt(0)
	s_barrier
	s_setprio 1
	s_waitcnt lgkmcnt(0)
	v_mfma_f32_16x16x32_bf16 v[76:79], v[56:59], v[160:163], v[76:79]
	v_mfma_f32_16x16x32_bf16 v[72:75], v[64:67], v[160:163], v[72:75]
	v_mfma_f32_16x16x32_bf16 v[52:55], v[56:59], v[186:189], v[52:55]
	v_mfma_f32_16x16x32_bf16 v[48:51], v[64:67], v[186:189], v[48:51]
	v_mfma_f32_16x16x32_bf16 v[28:31], v[56:59], v[194:197], v[28:31]
	v_mfma_f32_16x16x32_bf16 v[24:27], v[64:67], v[194:197], v[24:27]
	v_mfma_f32_16x16x32_bf16 v[12:15], v[56:59], v[202:205], v[12:15]
	v_mfma_f32_16x16x32_bf16 v[8:11], v[64:67], v[202:205], v[8:11]
	v_mfma_f32_16x16x32_bf16 v[76:79], v[60:63], v[164:167], v[76:79]
	v_mfma_f32_16x16x32_bf16 v[72:75], v[68:71], v[164:167], v[72:75]
	v_mfma_f32_16x16x32_bf16 v[52:55], v[60:63], v[190:193], v[52:55]
	v_mfma_f32_16x16x32_bf16 v[48:51], v[68:71], v[190:193], v[48:51]
	v_mfma_f32_16x16x32_bf16 v[28:31], v[60:63], v[198:201], v[28:31]
	v_mfma_f32_16x16x32_bf16 v[24:27], v[68:71], v[198:201], v[24:27]
	v_mfma_f32_16x16x32_bf16 v[12:15], v[60:63], v[214:217], v[12:15]
	v_mfma_f32_16x16x32_bf16 v[8:11], v[68:71], v[214:217], v[8:11]
	s_setprio 0
	s_setprio 1
	v_mfma_f32_16x16x32_bf16 v[40:43], v[144:147], v[160:163], v[40:43]
	v_mfma_f32_16x16x32_bf16 v[68:71], v[148:151], v[164:167], v[40:43]
	v_mfma_f32_16x16x32_bf16 v[40:43], v[152:155], v[160:163], v[44:47]
	v_mfma_f32_16x16x32_bf16 v[36:39], v[144:147], v[186:189], v[36:39]
	v_mfma_f32_16x16x32_bf16 v[32:35], v[152:155], v[186:189], v[32:35]
	v_mfma_f32_16x16x32_bf16 v[20:23], v[144:147], v[194:197], v[20:23]
	v_mfma_f32_16x16x32_bf16 v[16:19], v[152:155], v[194:197], v[16:19]
	v_mfma_f32_16x16x32_bf16 v[4:7], v[144:147], v[202:205], v[4:7]
	v_mfma_f32_16x16x32_bf16 v[0:3], v[152:155], v[202:205], v[0:3]
	v_mfma_f32_16x16x32_bf16 v[64:67], v[156:159], v[164:167], v[40:43]
	v_mfma_f32_16x16x32_bf16 v[36:39], v[148:151], v[190:193], v[36:39]
	v_mfma_f32_16x16x32_bf16 v[32:35], v[156:159], v[190:193], v[32:35]
	v_mfma_f32_16x16x32_bf16 v[20:23], v[148:151], v[198:201], v[20:23]
	v_mfma_f32_16x16x32_bf16 v[16:19], v[156:159], v[198:201], v[16:19]
	v_mfma_f32_16x16x32_bf16 v[4:7], v[148:151], v[214:217], v[4:7]
	v_mfma_f32_16x16x32_bf16 v[0:3], v[156:159], v[214:217], v[0:3]
	s_setprio 0
	s_barrier
	s_add_i32 s71, s71, 2
	s_add_u32 s42, s42, 0x100
	s_addc_u32 s43, s43, 0
	s_add_u32 s69, s69, 0x100
	s_addc_u32 s70, s70, 0
	s_cmp_gt_u32 s71, 13
	s_cbranch_scc0 .LBB0_1746
	s_and_b64 vcc, exec, s[22:23]
	s_cbranch_vccz .LBB0_1749
	s_barrier
